# previous + separate K-loop copy for the leading half whose vmcnt wait sits after its MFMA block (one more barrier interval of load latency tolerance); trailing half unchanged; four barriers per K-tile
# speedup vs baseline: 1.0014x; 1.0008x over previous
.Lkt_L_0:
	ds_read_b128 v[160:163], v156
	ds_read_b128 v[164:167], v156 offset:1024
	ds_read_b128 v[168:171], v156 offset:2048
	ds_read_b128 v[172:175], v156 offset:3072
	ds_read_b128 v[176:179], v157
	ds_read_b128 v[180:183], v157 offset:1024
	ds_read_b128 v[184:187], v157 offset:2048
	ds_read_b128 v[188:191], v157 offset:3072
	s_add_u32 s28, s26, 0xfff00080
	s_addc_u32 s29, s27, -1
	s_cmp_eq_u32 s58, 60
	s_cselect_b32 s31, s21, s29
	s_cselect_b32 s30, s54, s28
	s_cselect_b32 s29, s19, s57
	s_cselect_b32 s28, s55, s56
	v_lshl_add_u64 v[192:193], s[26:27], 0, v[138:139]
	s_add_i32 m0, s17, 0xc000
	ds_read_b128 v[196:199], v158
	ds_read_b128 v[200:203], v158 offset:1024
	ds_read_b128 v[204:207], v158 offset:2048
	ds_read_b128 v[208:211], v158 offset:3072
	ds_read_b128 v[212:215], v158 offset:4096
	ds_read_b128 v[216:219], v158 offset:5120
	ds_read_b128 v[220:223], v158 offset:6144
	ds_read_b128 v[224:227], v158 offset:7168
	global_load_lds_dwordx4 v[192:193], off
	v_lshl_add_u64 v[192:193], s[26:27], 0, v[140:141]
	s_add_i32 m0, s17, 0xe000
	s_nop 0
	global_load_lds_dwordx4 v[192:193], off
	s_waitcnt lgkmcnt(0)
	s_barrier
	s_setprio 1
	v_mfma_f32_16x16x32_bf16 v[126:129], v[160:163], v[196:199], v[126:129]
	v_mfma_f32_16x16x32_bf16 v[122:125], v[168:171], v[196:199], v[122:125]
	v_mfma_f32_16x16x32_bf16 v[118:121], v[160:163], v[204:207], v[118:121]
	v_mfma_f32_16x16x32_bf16 v[114:117], v[168:171], v[204:207], v[114:117]
	v_mfma_f32_16x16x32_bf16 v[102:105], v[160:163], v[212:215], v[102:105]
	v_mfma_f32_16x16x32_bf16 v[98:101], v[168:171], v[212:215], v[98:101]
	v_mfma_f32_16x16x32_bf16 v[86:89], v[160:163], v[220:223], v[86:89]
	v_mfma_f32_16x16x32_bf16 v[82:85], v[168:171], v[220:223], v[82:85]
	v_mfma_f32_16x16x32_bf16 v[126:129], v[164:167], v[200:203], v[126:129]
	v_mfma_f32_16x16x32_bf16 v[122:125], v[172:175], v[200:203], v[122:125]
	v_mfma_f32_16x16x32_bf16 v[118:121], v[164:167], v[208:211], v[118:121]
	v_mfma_f32_16x16x32_bf16 v[114:117], v[172:175], v[208:211], v[114:117]
	v_mfma_f32_16x16x32_bf16 v[102:105], v[164:167], v[216:219], v[102:105]
	v_mfma_f32_16x16x32_bf16 v[98:101], v[172:175], v[216:219], v[98:101]
	v_mfma_f32_16x16x32_bf16 v[86:89], v[164:167], v[224:227], v[86:89]
	v_mfma_f32_16x16x32_bf16 v[82:85], v[172:175], v[224:227], v[82:85]
	v_mfma_f32_16x16x32_bf16 v[110:113], v[176:179], v[196:199], v[110:113]
	v_mfma_f32_16x16x32_bf16 v[106:109], v[184:187], v[196:199], v[106:109]
	v_mfma_f32_16x16x32_bf16 v[94:97], v[176:179], v[204:207], v[94:97]
	v_mfma_f32_16x16x32_bf16 v[90:93], v[184:187], v[204:207], v[90:93]
	v_mfma_f32_16x16x32_bf16 v[78:81], v[176:179], v[212:215], v[78:81]
	v_mfma_f32_16x16x32_bf16 v[74:77], v[184:187], v[212:215], v[74:77]
	v_mfma_f32_16x16x32_bf16 v[70:73], v[176:179], v[220:223], v[70:73]
	v_mfma_f32_16x16x32_bf16 v[66:69], v[184:187], v[220:223], v[66:69]
	v_mfma_f32_16x16x32_bf16 v[110:113], v[180:183], v[200:203], v[110:113]
	v_mfma_f32_16x16x32_bf16 v[106:109], v[188:191], v[200:203], v[106:109]
	v_mfma_f32_16x16x32_bf16 v[94:97], v[180:183], v[208:211], v[94:97]
	v_mfma_f32_16x16x32_bf16 v[90:93], v[188:191], v[208:211], v[90:93]
	v_mfma_f32_16x16x32_bf16 v[78:81], v[180:183], v[216:219], v[78:81]
	v_mfma_f32_16x16x32_bf16 v[74:77], v[188:191], v[216:219], v[74:77]
	v_mfma_f32_16x16x32_bf16 v[70:73], v[180:183], v[224:227], v[70:73]
	v_mfma_f32_16x16x32_bf16 v[66:69], v[188:191], v[224:227], v[66:69]
	s_setprio 0
	s_waitcnt vmcnt(8)
	s_barrier
	s_add_i32 s59, s50, s41
	v_lshl_add_u64 v[192:193], s[28:29], 0, v[134:135]
	s_mov_b32 m0, s59
	ds_read_b128 v[196:199], v158 offset:16384
	ds_read_b128 v[200:203], v158 offset:17408
	ds_read_b128 v[204:207], v158 offset:18432
	ds_read_b128 v[208:211], v158 offset:19456
	ds_read_b128 v[212:215], v158 offset:20480
	ds_read_b128 v[216:219], v158 offset:21504
	ds_read_b128 v[220:223], v158 offset:22528
	ds_read_b128 v[224:227], v158 offset:23552
	global_load_lds_dwordx4 v[192:193], off
	s_add_i32 m0, s59, 0x2000
	s_add_u32 s60, s28, 0x100000
	v_lshl_add_u64 v[228:229], s[28:29], 0, v[136:137]
	s_addc_u32 s61, s29, 0
	s_add_i32 s59, s51, s41
	global_load_lds_dwordx4 v[228:229], off
	v_lshl_add_u64 v[230:231], s[60:61], 0, v[134:135]
	s_mov_b32 m0, s59
	v_lshl_add_u64 v[232:233], s[30:31], 0, v[132:133]
	global_load_lds_dwordx4 v[230:231], off
	v_lshl_add_u64 v[230:231], s[60:61], 0, v[136:137]
	s_add_i32 m0, s59, 0x2000
	s_nop 0
	global_load_lds_dwordx4 v[230:231], off
	v_lshl_add_u64 v[230:231], s[30:31], 0, v[130:131]
	s_mov_b32 m0, s17
	s_nop 0
	global_load_lds_dwordx4 v[230:231], off
	s_mov_b32 m0, s42
	s_nop 0
	global_load_lds_dwordx4 v[232:233], off
	s_waitcnt lgkmcnt(0)
	s_barrier
	s_setprio 1
	v_mfma_f32_16x16x32_bf16 v[62:65], v[160:163], v[196:199], v[62:65]
	v_mfma_f32_16x16x32_bf16 v[58:61], v[168:171], v[196:199], v[58:61]
	v_mfma_f32_16x16x32_bf16 v[54:57], v[160:163], v[204:207], v[54:57]
	v_mfma_f32_16x16x32_bf16 v[50:53], v[168:171], v[204:207], v[50:53]
	v_mfma_f32_16x16x32_bf16 v[38:41], v[160:163], v[212:215], v[38:41]
	v_mfma_f32_16x16x32_bf16 v[34:37], v[168:171], v[212:215], v[34:37]
	v_mfma_f32_16x16x32_bf16 v[22:25], v[160:163], v[220:223], v[22:25]
	v_mfma_f32_16x16x32_bf16 v[18:21], v[168:171], v[220:223], v[18:21]
	v_mfma_f32_16x16x32_bf16 v[62:65], v[164:167], v[200:203], v[62:65]
	v_mfma_f32_16x16x32_bf16 v[58:61], v[172:175], v[200:203], v[58:61]
	v_mfma_f32_16x16x32_bf16 v[54:57], v[164:167], v[208:211], v[54:57]
	v_mfma_f32_16x16x32_bf16 v[50:53], v[172:175], v[208:211], v[50:53]
	v_mfma_f32_16x16x32_bf16 v[38:41], v[164:167], v[216:219], v[38:41]
	v_mfma_f32_16x16x32_bf16 v[34:37], v[172:175], v[216:219], v[34:37]
	v_mfma_f32_16x16x32_bf16 v[22:25], v[164:167], v[224:227], v[22:25]
	v_mfma_f32_16x16x32_bf16 v[18:21], v[172:175], v[224:227], v[18:21]
	v_mfma_f32_16x16x32_bf16 v[46:49], v[176:179], v[196:199], v[46:49]
	v_mfma_f32_16x16x32_bf16 v[42:45], v[184:187], v[196:199], v[42:45]
	v_mfma_f32_16x16x32_bf16 v[30:33], v[176:179], v[204:207], v[30:33]
	v_mfma_f32_16x16x32_bf16 v[26:29], v[184:187], v[204:207], v[26:29]
	v_mfma_f32_16x16x32_bf16 v[14:17], v[176:179], v[212:215], v[14:17]
	v_mfma_f32_16x16x32_bf16 v[10:13], v[184:187], v[212:215], v[10:13]
	v_mfma_f32_16x16x32_bf16 v[6:9], v[176:179], v[220:223], v[6:9]
	v_mfma_f32_16x16x32_bf16 v[2:5], v[184:187], v[220:223], v[2:5]
	v_mfma_f32_16x16x32_bf16 v[46:49], v[180:183], v[200:203], v[46:49]
	v_mfma_f32_16x16x32_bf16 v[42:45], v[188:191], v[200:203], v[42:45]
	v_mfma_f32_16x16x32_bf16 v[30:33], v[180:183], v[208:211], v[30:33]
	v_mfma_f32_16x16x32_bf16 v[26:29], v[188:191], v[208:211], v[26:29]
	v_mfma_f32_16x16x32_bf16 v[14:17], v[180:183], v[216:219], v[14:17]
	v_mfma_f32_16x16x32_bf16 v[10:13], v[188:191], v[216:219], v[10:13]
	v_mfma_f32_16x16x32_bf16 v[6:9], v[180:183], v[224:227], v[6:9]
	v_mfma_f32_16x16x32_bf16 v[2:5], v[188:191], v[224:227], v[2:5]
	s_setprio 0
	s_waitcnt vmcnt(8)
	s_barrier
	s_add_i32 s59, 0, 0x18000
	v_add_u32_e32 v159, s59, v154
	s_add_i32 s60, 0, 0x1c000
	ds_read_b128 v[160:163], v159
	ds_read_b128 v[164:167], v159 offset:1024
	ds_read_b128 v[168:171], v159 offset:2048
	ds_read_b128 v[172:175], v159 offset:3072
	v_add_u32_e32 v159, s60, v154
	ds_read_b128 v[176:179], v159
	ds_read_b128 v[180:183], v159 offset:1024
	ds_read_b128 v[184:187], v159 offset:2048
	ds_read_b128 v[188:191], v159 offset:3072
	s_add_u32 s30, s30, 0x100000
	s_addc_u32 s31, s31, 0
	s_mov_b32 m0, s43
	v_lshl_add_u64 v[234:235], s[30:31], 0, v[130:131]
	ds_read_b128 v[196:199], v158 offset:32768
	ds_read_b128 v[200:203], v158 offset:33792
	ds_read_b128 v[204:207], v158 offset:34816
	ds_read_b128 v[208:211], v158 offset:35840
	ds_read_b128 v[212:215], v158 offset:36864
	ds_read_b128 v[216:219], v158 offset:37888
	ds_read_b128 v[220:223], v158 offset:38912
	ds_read_b128 v[224:227], v158 offset:39936
	global_load_lds_dwordx4 v[234:235], off
	v_lshl_add_u64 v[234:235], s[30:31], 0, v[132:133]
	s_mov_b32 m0, s45
	s_nop 0
	global_load_lds_dwordx4 v[234:235], off
	s_waitcnt lgkmcnt(0)
	s_barrier
	s_setprio 1
	v_mfma_f32_16x16x32_bf16 v[126:129], v[160:163], v[196:199], v[126:129]
	v_mfma_f32_16x16x32_bf16 v[122:125], v[168:171], v[196:199], v[122:125]
	v_mfma_f32_16x16x32_bf16 v[118:121], v[160:163], v[204:207], v[118:121]
	v_mfma_f32_16x16x32_bf16 v[114:117], v[168:171], v[204:207], v[114:117]
	v_mfma_f32_16x16x32_bf16 v[102:105], v[160:163], v[212:215], v[102:105]
	v_mfma_f32_16x16x32_bf16 v[98:101], v[168:171], v[212:215], v[98:101]
	v_mfma_f32_16x16x32_bf16 v[86:89], v[160:163], v[220:223], v[86:89]
	v_mfma_f32_16x16x32_bf16 v[82:85], v[168:171], v[220:223], v[82:85]
	v_mfma_f32_16x16x32_bf16 v[126:129], v[164:167], v[200:203], v[126:129]
	v_mfma_f32_16x16x32_bf16 v[122:125], v[172:175], v[200:203], v[122:125]
	v_mfma_f32_16x16x32_bf16 v[118:121], v[164:167], v[208:211], v[118:121]
	v_mfma_f32_16x16x32_bf16 v[114:117], v[172:175], v[208:211], v[114:117]
	v_mfma_f32_16x16x32_bf16 v[102:105], v[164:167], v[216:219], v[102:105]
	v_mfma_f32_16x16x32_bf16 v[98:101], v[172:175], v[216:219], v[98:101]
	v_mfma_f32_16x16x32_bf16 v[86:89], v[164:167], v[224:227], v[86:89]
	v_mfma_f32_16x16x32_bf16 v[82:85], v[172:175], v[224:227], v[82:85]
	v_mfma_f32_16x16x32_bf16 v[110:113], v[176:179], v[196:199], v[110:113]
	v_mfma_f32_16x16x32_bf16 v[106:109], v[184:187], v[196:199], v[106:109]
	v_mfma_f32_16x16x32_bf16 v[94:97], v[176:179], v[204:207], v[94:97]
	v_mfma_f32_16x16x32_bf16 v[90:93], v[184:187], v[204:207], v[90:93]
	v_mfma_f32_16x16x32_bf16 v[78:81], v[176:179], v[212:215], v[78:81]
	v_mfma_f32_16x16x32_bf16 v[74:77], v[184:187], v[212:215], v[74:77]
	v_mfma_f32_16x16x32_bf16 v[70:73], v[176:179], v[220:223], v[70:73]
	v_mfma_f32_16x16x32_bf16 v[66:69], v[184:187], v[220:223], v[66:69]
	v_mfma_f32_16x16x32_bf16 v[110:113], v[180:183], v[200:203], v[110:113]
	v_mfma_f32_16x16x32_bf16 v[106:109], v[188:191], v[200:203], v[106:109]
	v_mfma_f32_16x16x32_bf16 v[94:97], v[180:183], v[208:211], v[94:97]
	v_mfma_f32_16x16x32_bf16 v[90:93], v[188:191], v[208:211], v[90:93]
	v_mfma_f32_16x16x32_bf16 v[78:81], v[180:183], v[216:219], v[78:81]
	v_mfma_f32_16x16x32_bf16 v[74:77], v[188:191], v[216:219], v[74:77]
	v_mfma_f32_16x16x32_bf16 v[70:73], v[180:183], v[224:227], v[70:73]
	v_mfma_f32_16x16x32_bf16 v[66:69], v[188:191], v[224:227], v[66:69]
	s_setprio 0
	s_waitcnt vmcnt(8)
	s_barrier
	s_add_i32 s30, s59, s41
	v_lshl_add_u64 v[192:193], v[192:193], 0, s[12:13]
	s_mov_b32 m0, s30
	ds_read_b128 v[196:199], v158 offset:49152
	ds_read_b128 v[200:203], v158 offset:50176
	ds_read_b128 v[204:207], v158 offset:51200
	ds_read_b128 v[208:211], v158 offset:52224
	ds_read_b128 v[212:215], v158 offset:53248
	ds_read_b128 v[216:219], v158 offset:54272
	ds_read_b128 v[220:223], v158 offset:55296
	ds_read_b128 v[224:227], v158 offset:56320
	global_load_lds_dwordx4 v[192:193], off
	s_add_i32 m0, s30, 0x2000
	s_add_u32 s28, s28, 0x100080
	v_lshl_add_u64 v[192:193], v[228:229], 0, s[12:13]
	s_addc_u32 s29, s29, 0
	s_add_i32 s30, s60, s41
	global_load_lds_dwordx4 v[192:193], off
	v_lshl_add_u64 v[192:193], s[28:29], 0, v[134:135]
	s_mov_b32 m0, s30
	s_nop 0
	global_load_lds_dwordx4 v[192:193], off
	v_lshl_add_u64 v[192:193], s[28:29], 0, v[136:137]
	s_add_i32 m0, s30, 0x2000
	s_nop 0
	global_load_lds_dwordx4 v[192:193], off
	v_lshl_add_u64 v[192:193], v[230:231], 0, s[12:13]
	s_mov_b32 m0, s47
	s_nop 0
	global_load_lds_dwordx4 v[192:193], off
	v_lshl_add_u64 v[192:193], v[232:233], 0, s[12:13]
	s_mov_b32 m0, s48
	s_nop 0
	global_load_lds_dwordx4 v[192:193], off
	s_waitcnt lgkmcnt(0)
	s_barrier
	s_nop 0
	s_setprio 1
	v_mfma_f32_16x16x32_bf16 v[62:65], v[160:163], v[196:199], v[62:65]
	v_mfma_f32_16x16x32_bf16 v[58:61], v[168:171], v[196:199], v[58:61]
	v_mfma_f32_16x16x32_bf16 v[54:57], v[160:163], v[204:207], v[54:57]
	v_mfma_f32_16x16x32_bf16 v[50:53], v[168:171], v[204:207], v[50:53]
	v_mfma_f32_16x16x32_bf16 v[38:41], v[160:163], v[212:215], v[38:41]
	v_mfma_f32_16x16x32_bf16 v[34:37], v[168:171], v[212:215], v[34:37]
	v_mfma_f32_16x16x32_bf16 v[22:25], v[160:163], v[220:223], v[22:25]
	v_mfma_f32_16x16x32_bf16 v[18:21], v[168:171], v[220:223], v[18:21]
	v_mfma_f32_16x16x32_bf16 v[62:65], v[164:167], v[200:203], v[62:65]
	v_mfma_f32_16x16x32_bf16 v[58:61], v[172:175], v[200:203], v[58:61]
	v_mfma_f32_16x16x32_bf16 v[54:57], v[164:167], v[208:211], v[54:57]
	v_mfma_f32_16x16x32_bf16 v[50:53], v[172:175], v[208:211], v[50:53]
	v_mfma_f32_16x16x32_bf16 v[38:41], v[164:167], v[216:219], v[38:41]
	v_mfma_f32_16x16x32_bf16 v[34:37], v[172:175], v[216:219], v[34:37]
	v_mfma_f32_16x16x32_bf16 v[22:25], v[164:167], v[224:227], v[22:25]
	v_mfma_f32_16x16x32_bf16 v[18:21], v[172:175], v[224:227], v[18:21]
	v_mfma_f32_16x16x32_bf16 v[46:49], v[176:179], v[196:199], v[46:49]
	v_mfma_f32_16x16x32_bf16 v[42:45], v[184:187], v[196:199], v[42:45]
	v_mfma_f32_16x16x32_bf16 v[30:33], v[176:179], v[204:207], v[30:33]
	v_mfma_f32_16x16x32_bf16 v[26:29], v[184:187], v[204:207], v[26:29]
	v_mfma_f32_16x16x32_bf16 v[14:17], v[176:179], v[212:215], v[14:17]
	v_mfma_f32_16x16x32_bf16 v[10:13], v[184:187], v[212:215], v[10:13]
	v_mfma_f32_16x16x32_bf16 v[6:9], v[176:179], v[220:223], v[6:9]
	v_mfma_f32_16x16x32_bf16 v[2:5], v[184:187], v[220:223], v[2:5]
	v_mfma_f32_16x16x32_bf16 v[46:49], v[180:183], v[200:203], v[46:49]
	v_mfma_f32_16x16x32_bf16 v[42:45], v[188:191], v[200:203], v[42:45]
	v_mfma_f32_16x16x32_bf16 v[30:33], v[180:183], v[208:211], v[30:33]
	v_mfma_f32_16x16x32_bf16 v[26:29], v[188:191], v[208:211], v[26:29]
	v_mfma_f32_16x16x32_bf16 v[14:17], v[180:183], v[216:219], v[14:17]
	v_mfma_f32_16x16x32_bf16 v[10:13], v[188:191], v[216:219], v[10:13]
	v_mfma_f32_16x16x32_bf16 v[6:9], v[180:183], v[224:227], v[6:9]
	v_mfma_f32_16x16x32_bf16 v[2:5], v[188:191], v[224:227], v[2:5]
	s_setprio 0
	s_waitcnt vmcnt(8)
	s_barrier
	s_add_i32 s58, s58, 2
	s_add_u32 s26, s26, 0x100
	s_addc_u32 s27, s27, 0
	s_add_u32 s56, s56, 0x100
	s_addc_u32 s57, s57, 0
	s_cmp_gt_u32 s58, 61
	s_cbranch_scc0 .Lkt_L_0
	s_branch .Lkt_exit_0
.Lkt_T_0:
	ds_read_b128 v[160:163], v156
	ds_read_b128 v[164:167], v156 offset:1024
	ds_read_b128 v[168:171], v156 offset:2048
	ds_read_b128 v[172:175], v156 offset:3072
	ds_read_b128 v[176:179], v157
	ds_read_b128 v[180:183], v157 offset:1024
	ds_read_b128 v[184:187], v157 offset:2048
	ds_read_b128 v[188:191], v157 offset:3072
	s_add_u32 s28, s26, 0xfff00080
	s_addc_u32 s29, s27, -1
	s_cmp_eq_u32 s58, 60
	s_cselect_b32 s31, s21, s29
	s_cselect_b32 s30, s54, s28
	s_cselect_b32 s29, s19, s57
	s_cselect_b32 s28, s55, s56
	v_lshl_add_u64 v[192:193], s[26:27], 0, v[138:139]
	s_add_i32 m0, s17, 0xc000
	ds_read_b128 v[196:199], v158
	ds_read_b128 v[200:203], v158 offset:1024
	ds_read_b128 v[204:207], v158 offset:2048
	ds_read_b128 v[208:211], v158 offset:3072
	ds_read_b128 v[212:215], v158 offset:4096
	ds_read_b128 v[216:219], v158 offset:5120
	ds_read_b128 v[220:223], v158 offset:6144
	ds_read_b128 v[224:227], v158 offset:7168
	global_load_lds_dwordx4 v[192:193], off
	v_lshl_add_u64 v[192:193], s[26:27], 0, v[140:141]
	s_add_i32 m0, s17, 0xe000
	s_nop 0
	global_load_lds_dwordx4 v[192:193], off
	s_waitcnt vmcnt(8)
	s_waitcnt lgkmcnt(0)
	s_barrier
	s_setprio 1
	v_mfma_f32_16x16x32_bf16 v[126:129], v[160:163], v[196:199], v[126:129]
	v_mfma_f32_16x16x32_bf16 v[122:125], v[168:171], v[196:199], v[122:125]
	v_mfma_f32_16x16x32_bf16 v[118:121], v[160:163], v[204:207], v[118:121]
	v_mfma_f32_16x16x32_bf16 v[114:117], v[168:171], v[204:207], v[114:117]
	v_mfma_f32_16x16x32_bf16 v[102:105], v[160:163], v[212:215], v[102:105]
	v_mfma_f32_16x16x32_bf16 v[98:101], v[168:171], v[212:215], v[98:101]
	v_mfma_f32_16x16x32_bf16 v[86:89], v[160:163], v[220:223], v[86:89]
	v_mfma_f32_16x16x32_bf16 v[82:85], v[168:171], v[220:223], v[82:85]
	v_mfma_f32_16x16x32_bf16 v[126:129], v[164:167], v[200:203], v[126:129]
	v_mfma_f32_16x16x32_bf16 v[122:125], v[172:175], v[200:203], v[122:125]
	v_mfma_f32_16x16x32_bf16 v[118:121], v[164:167], v[208:211], v[118:121]
	v_mfma_f32_16x16x32_bf16 v[114:117], v[172:175], v[208:211], v[114:117]
	v_mfma_f32_16x16x32_bf16 v[102:105], v[164:167], v[216:219], v[102:105]
	v_mfma_f32_16x16x32_bf16 v[98:101], v[172:175], v[216:219], v[98:101]
	v_mfma_f32_16x16x32_bf16 v[86:89], v[164:167], v[224:227], v[86:89]
	v_mfma_f32_16x16x32_bf16 v[82:85], v[172:175], v[224:227], v[82:85]
	v_mfma_f32_16x16x32_bf16 v[110:113], v[176:179], v[196:199], v[110:113]
	v_mfma_f32_16x16x32_bf16 v[106:109], v[184:187], v[196:199], v[106:109]
	v_mfma_f32_16x16x32_bf16 v[94:97], v[176:179], v[204:207], v[94:97]
	v_mfma_f32_16x16x32_bf16 v[90:93], v[184:187], v[204:207], v[90:93]
	v_mfma_f32_16x16x32_bf16 v[78:81], v[176:179], v[212:215], v[78:81]
	v_mfma_f32_16x16x32_bf16 v[74:77], v[184:187], v[212:215], v[74:77]
	v_mfma_f32_16x16x32_bf16 v[70:73], v[176:179], v[220:223], v[70:73]
	v_mfma_f32_16x16x32_bf16 v[66:69], v[184:187], v[220:223], v[66:69]
	v_mfma_f32_16x16x32_bf16 v[110:113], v[180:183], v[200:203], v[110:113]
	v_mfma_f32_16x16x32_bf16 v[106:109], v[188:191], v[200:203], v[106:109]
	v_mfma_f32_16x16x32_bf16 v[94:97], v[180:183], v[208:211], v[94:97]
	v_mfma_f32_16x16x32_bf16 v[90:93], v[188:191], v[208:211], v[90:93]
	v_mfma_f32_16x16x32_bf16 v[78:81], v[180:183], v[216:219], v[78:81]
	v_mfma_f32_16x16x32_bf16 v[74:77], v[188:191], v[216:219], v[74:77]
	v_mfma_f32_16x16x32_bf16 v[70:73], v[180:183], v[224:227], v[70:73]
	v_mfma_f32_16x16x32_bf16 v[66:69], v[188:191], v[224:227], v[66:69]
	s_setprio 0
	s_barrier
	s_add_i32 s59, s50, s41
	v_lshl_add_u64 v[192:193], s[28:29], 0, v[134:135]
	s_mov_b32 m0, s59
	ds_read_b128 v[196:199], v158 offset:16384
	ds_read_b128 v[200:203], v158 offset:17408
	ds_read_b128 v[204:207], v158 offset:18432
	ds_read_b128 v[208:211], v158 offset:19456
	ds_read_b128 v[212:215], v158 offset:20480
	ds_read_b128 v[216:219], v158 offset:21504
	ds_read_b128 v[220:223], v158 offset:22528
	ds_read_b128 v[224:227], v158 offset:23552
	global_load_lds_dwordx4 v[192:193], off
	s_add_i32 m0, s59, 0x2000
	s_add_u32 s60, s28, 0x100000
	v_lshl_add_u64 v[228:229], s[28:29], 0, v[136:137]
	s_addc_u32 s61, s29, 0
	s_add_i32 s59, s51, s41
	global_load_lds_dwordx4 v[228:229], off
	v_lshl_add_u64 v[230:231], s[60:61], 0, v[134:135]
	s_mov_b32 m0, s59
	v_lshl_add_u64 v[232:233], s[30:31], 0, v[132:133]
	global_load_lds_dwordx4 v[230:231], off
	v_lshl_add_u64 v[230:231], s[60:61], 0, v[136:137]
	s_add_i32 m0, s59, 0x2000
	s_nop 0
	global_load_lds_dwordx4 v[230:231], off
	v_lshl_add_u64 v[230:231], s[30:31], 0, v[130:131]
	s_mov_b32 m0, s17
	s_nop 0
	global_load_lds_dwordx4 v[230:231], off
	s_mov_b32 m0, s42
	s_nop 0
	global_load_lds_dwordx4 v[232:233], off
	s_waitcnt vmcnt(8)
	s_waitcnt lgkmcnt(0)
	s_barrier
	s_setprio 1
	v_mfma_f32_16x16x32_bf16 v[62:65], v[160:163], v[196:199], v[62:65]
	v_mfma_f32_16x16x32_bf16 v[58:61], v[168:171], v[196:199], v[58:61]
	v_mfma_f32_16x16x32_bf16 v[54:57], v[160:163], v[204:207], v[54:57]
	v_mfma_f32_16x16x32_bf16 v[50:53], v[168:171], v[204:207], v[50:53]
	v_mfma_f32_16x16x32_bf16 v[38:41], v[160:163], v[212:215], v[38:41]
	v_mfma_f32_16x16x32_bf16 v[34:37], v[168:171], v[212:215], v[34:37]
	v_mfma_f32_16x16x32_bf16 v[22:25], v[160:163], v[220:223], v[22:25]
	v_mfma_f32_16x16x32_bf16 v[18:21], v[168:171], v[220:223], v[18:21]
	v_mfma_f32_16x16x32_bf16 v[62:65], v[164:167], v[200:203], v[62:65]
	v_mfma_f32_16x16x32_bf16 v[58:61], v[172:175], v[200:203], v[58:61]
	v_mfma_f32_16x16x32_bf16 v[54:57], v[164:167], v[208:211], v[54:57]
	v_mfma_f32_16x16x32_bf16 v[50:53], v[172:175], v[208:211], v[50:53]
	v_mfma_f32_16x16x32_bf16 v[38:41], v[164:167], v[216:219], v[38:41]
	v_mfma_f32_16x16x32_bf16 v[34:37], v[172:175], v[216:219], v[34:37]
	v_mfma_f32_16x16x32_bf16 v[22:25], v[164:167], v[224:227], v[22:25]
	v_mfma_f32_16x16x32_bf16 v[18:21], v[172:175], v[224:227], v[18:21]
	v_mfma_f32_16x16x32_bf16 v[46:49], v[176:179], v[196:199], v[46:49]
	v_mfma_f32_16x16x32_bf16 v[42:45], v[184:187], v[196:199], v[42:45]
	v_mfma_f32_16x16x32_bf16 v[30:33], v[176:179], v[204:207], v[30:33]
	v_mfma_f32_16x16x32_bf16 v[26:29], v[184:187], v[204:207], v[26:29]
	v_mfma_f32_16x16x32_bf16 v[14:17], v[176:179], v[212:215], v[14:17]
	v_mfma_f32_16x16x32_bf16 v[10:13], v[184:187], v[212:215], v[10:13]
	v_mfma_f32_16x16x32_bf16 v[6:9], v[176:179], v[220:223], v[6:9]
	v_mfma_f32_16x16x32_bf16 v[2:5], v[184:187], v[220:223], v[2:5]
	v_mfma_f32_16x16x32_bf16 v[46:49], v[180:183], v[200:203], v[46:49]
	v_mfma_f32_16x16x32_bf16 v[42:45], v[188:191], v[200:203], v[42:45]
	v_mfma_f32_16x16x32_bf16 v[30:33], v[180:183], v[208:211], v[30:33]
	v_mfma_f32_16x16x32_bf16 v[26:29], v[188:191], v[208:211], v[26:29]
	v_mfma_f32_16x16x32_bf16 v[14:17], v[180:183], v[216:219], v[14:17]
	v_mfma_f32_16x16x32_bf16 v[10:13], v[188:191], v[216:219], v[10:13]
	v_mfma_f32_16x16x32_bf16 v[6:9], v[180:183], v[224:227], v[6:9]
	v_mfma_f32_16x16x32_bf16 v[2:5], v[188:191], v[224:227], v[2:5]
	s_setprio 0
	s_barrier
	s_add_i32 s59, 0, 0x18000
	v_add_u32_e32 v159, s59, v154
	s_add_i32 s60, 0, 0x1c000
	ds_read_b128 v[160:163], v159
	ds_read_b128 v[164:167], v159 offset:1024
	ds_read_b128 v[168:171], v159 offset:2048
	ds_read_b128 v[172:175], v159 offset:3072
	v_add_u32_e32 v159, s60, v154
	ds_read_b128 v[176:179], v159
	ds_read_b128 v[180:183], v159 offset:1024
	ds_read_b128 v[184:187], v159 offset:2048
	ds_read_b128 v[188:191], v159 offset:3072
	s_add_u32 s30, s30, 0x100000
	s_addc_u32 s31, s31, 0
	s_mov_b32 m0, s43
	v_lshl_add_u64 v[234:235], s[30:31], 0, v[130:131]
	ds_read_b128 v[196:199], v158 offset:32768
	ds_read_b128 v[200:203], v158 offset:33792
	ds_read_b128 v[204:207], v158 offset:34816
	ds_read_b128 v[208:211], v158 offset:35840
	ds_read_b128 v[212:215], v158 offset:36864
	ds_read_b128 v[216:219], v158 offset:37888
	ds_read_b128 v[220:223], v158 offset:38912
	ds_read_b128 v[224:227], v158 offset:39936
	global_load_lds_dwordx4 v[234:235], off
	v_lshl_add_u64 v[234:235], s[30:31], 0, v[132:133]
	s_mov_b32 m0, s45
	s_nop 0
	global_load_lds_dwordx4 v[234:235], off
	s_waitcnt vmcnt(8)
	s_waitcnt lgkmcnt(0)
	s_barrier
	s_setprio 1
	v_mfma_f32_16x16x32_bf16 v[126:129], v[160:163], v[196:199], v[126:129]
	v_mfma_f32_16x16x32_bf16 v[122:125], v[168:171], v[196:199], v[122:125]
	v_mfma_f32_16x16x32_bf16 v[118:121], v[160:163], v[204:207], v[118:121]
	v_mfma_f32_16x16x32_bf16 v[114:117], v[168:171], v[204:207], v[114:117]
	v_mfma_f32_16x16x32_bf16 v[102:105], v[160:163], v[212:215], v[102:105]
	v_mfma_f32_16x16x32_bf16 v[98:101], v[168:171], v[212:215], v[98:101]
	v_mfma_f32_16x16x32_bf16 v[86:89], v[160:163], v[220:223], v[86:89]
	v_mfma_f32_16x16x32_bf16 v[82:85], v[168:171], v[220:223], v[82:85]
	v_mfma_f32_16x16x32_bf16 v[126:129], v[164:167], v[200:203], v[126:129]
	v_mfma_f32_16x16x32_bf16 v[122:125], v[172:175], v[200:203], v[122:125]
	v_mfma_f32_16x16x32_bf16 v[118:121], v[164:167], v[208:211], v[118:121]
	v_mfma_f32_16x16x32_bf16 v[114:117], v[172:175], v[208:211], v[114:117]
	v_mfma_f32_16x16x32_bf16 v[102:105], v[164:167], v[216:219], v[102:105]
	v_mfma_f32_16x16x32_bf16 v[98:101], v[172:175], v[216:219], v[98:101]
	v_mfma_f32_16x16x32_bf16 v[86:89], v[164:167], v[224:227], v[86:89]
	v_mfma_f32_16x16x32_bf16 v[82:85], v[172:175], v[224:227], v[82:85]
	v_mfma_f32_16x16x32_bf16 v[110:113], v[176:179], v[196:199], v[110:113]
	v_mfma_f32_16x16x32_bf16 v[106:109], v[184:187], v[196:199], v[106:109]
	v_mfma_f32_16x16x32_bf16 v[94:97], v[176:179], v[204:207], v[94:97]
	v_mfma_f32_16x16x32_bf16 v[90:93], v[184:187], v[204:207], v[90:93]
	v_mfma_f32_16x16x32_bf16 v[78:81], v[176:179], v[212:215], v[78:81]
	v_mfma_f32_16x16x32_bf16 v[74:77], v[184:187], v[212:215], v[74:77]
	v_mfma_f32_16x16x32_bf16 v[70:73], v[176:179], v[220:223], v[70:73]
	v_mfma_f32_16x16x32_bf16 v[66:69], v[184:187], v[220:223], v[66:69]
	v_mfma_f32_16x16x32_bf16 v[110:113], v[180:183], v[200:203], v[110:113]
	v_mfma_f32_16x16x32_bf16 v[106:109], v[188:191], v[200:203], v[106:109]
	v_mfma_f32_16x16x32_bf16 v[94:97], v[180:183], v[208:211], v[94:97]
	v_mfma_f32_16x16x32_bf16 v[90:93], v[188:191], v[208:211], v[90:93]
	v_mfma_f32_16x16x32_bf16 v[78:81], v[180:183], v[216:219], v[78:81]
	v_mfma_f32_16x16x32_bf16 v[74:77], v[188:191], v[216:219], v[74:77]
	v_mfma_f32_16x16x32_bf16 v[70:73], v[180:183], v[224:227], v[70:73]
	v_mfma_f32_16x16x32_bf16 v[66:69], v[188:191], v[224:227], v[66:69]
	s_setprio 0
	s_barrier
	s_add_i32 s30, s59, s41
	v_lshl_add_u64 v[192:193], v[192:193], 0, s[12:13]
	s_mov_b32 m0, s30
	ds_read_b128 v[196:199], v158 offset:49152
	ds_read_b128 v[200:203], v158 offset:50176
	ds_read_b128 v[204:207], v158 offset:51200
	ds_read_b128 v[208:211], v158 offset:52224
	ds_read_b128 v[212:215], v158 offset:53248
	ds_read_b128 v[216:219], v158 offset:54272
	ds_read_b128 v[220:223], v158 offset:55296
	ds_read_b128 v[224:227], v158 offset:56320
	global_load_lds_dwordx4 v[192:193], off
	s_add_i32 m0, s30, 0x2000
	s_add_u32 s28, s28, 0x100080
	v_lshl_add_u64 v[192:193], v[228:229], 0, s[12:13]
	s_addc_u32 s29, s29, 0
	s_add_i32 s30, s60, s41
	global_load_lds_dwordx4 v[192:193], off
	v_lshl_add_u64 v[192:193], s[28:29], 0, v[134:135]
	s_mov_b32 m0, s30
	s_nop 0
	global_load_lds_dwordx4 v[192:193], off
	v_lshl_add_u64 v[192:193], s[28:29], 0, v[136:137]
	s_add_i32 m0, s30, 0x2000
	s_nop 0
	global_load_lds_dwordx4 v[192:193], off
	v_lshl_add_u64 v[192:193], v[230:231], 0, s[12:13]
	s_mov_b32 m0, s47
	s_nop 0
	global_load_lds_dwordx4 v[192:193], off
	v_lshl_add_u64 v[192:193], v[232:233], 0, s[12:13]
	s_mov_b32 m0, s48
	s_nop 0
	global_load_lds_dwordx4 v[192:193], off
	s_nop 0
	s_waitcnt vmcnt(8)
	s_waitcnt lgkmcnt(0)
	s_barrier
	s_setprio 1
	v_mfma_f32_16x16x32_bf16 v[62:65], v[160:163], v[196:199], v[62:65]
	v_mfma_f32_16x16x32_bf16 v[58:61], v[168:171], v[196:199], v[58:61]
	v_mfma_f32_16x16x32_bf16 v[54:57], v[160:163], v[204:207], v[54:57]
	v_mfma_f32_16x16x32_bf16 v[50:53], v[168:171], v[204:207], v[50:53]
	v_mfma_f32_16x16x32_bf16 v[38:41], v[160:163], v[212:215], v[38:41]
	v_mfma_f32_16x16x32_bf16 v[34:37], v[168:171], v[212:215], v[34:37]
	v_mfma_f32_16x16x32_bf16 v[22:25], v[160:163], v[220:223], v[22:25]
	v_mfma_f32_16x16x32_bf16 v[18:21], v[168:171], v[220:223], v[18:21]
	v_mfma_f32_16x16x32_bf16 v[62:65], v[164:167], v[200:203], v[62:65]
	v_mfma_f32_16x16x32_bf16 v[58:61], v[172:175], v[200:203], v[58:61]
	v_mfma_f32_16x16x32_bf16 v[54:57], v[164:167], v[208:211], v[54:57]
	v_mfma_f32_16x16x32_bf16 v[50:53], v[172:175], v[208:211], v[50:53]
	v_mfma_f32_16x16x32_bf16 v[38:41], v[164:167], v[216:219], v[38:41]
	v_mfma_f32_16x16x32_bf16 v[34:37], v[172:175], v[216:219], v[34:37]
	v_mfma_f32_16x16x32_bf16 v[22:25], v[164:167], v[224:227], v[22:25]
	v_mfma_f32_16x16x32_bf16 v[18:21], v[172:175], v[224:227], v[18:21]
	v_mfma_f32_16x16x32_bf16 v[46:49], v[176:179], v[196:199], v[46:49]
	v_mfma_f32_16x16x32_bf16 v[42:45], v[184:187], v[196:199], v[42:45]
	v_mfma_f32_16x16x32_bf16 v[30:33], v[176:179], v[204:207], v[30:33]
	v_mfma_f32_16x16x32_bf16 v[26:29], v[184:187], v[204:207], v[26:29]
	v_mfma_f32_16x16x32_bf16 v[14:17], v[176:179], v[212:215], v[14:17]
	v_mfma_f32_16x16x32_bf16 v[10:13], v[184:187], v[212:215], v[10:13]
	v_mfma_f32_16x16x32_bf16 v[6:9], v[176:179], v[220:223], v[6:9]
	v_mfma_f32_16x16x32_bf16 v[2:5], v[184:187], v[220:223], v[2:5]
	v_mfma_f32_16x16x32_bf16 v[46:49], v[180:183], v[200:203], v[46:49]
	v_mfma_f32_16x16x32_bf16 v[42:45], v[188:191], v[200:203], v[42:45]
	v_mfma_f32_16x16x32_bf16 v[30:33], v[180:183], v[208:211], v[30:33]
	v_mfma_f32_16x16x32_bf16 v[26:29], v[188:191], v[208:211], v[26:29]
	v_mfma_f32_16x16x32_bf16 v[14:17], v[180:183], v[216:219], v[14:17]
	v_mfma_f32_16x16x32_bf16 v[10:13], v[188:191], v[216:219], v[10:13]
	v_mfma_f32_16x16x32_bf16 v[6:9], v[180:183], v[224:227], v[6:9]
	v_mfma_f32_16x16x32_bf16 v[2:5], v[188:191], v[224:227], v[2:5]
	s_setprio 0
	s_barrier
	s_add_i32 s58, s58, 2
	s_add_u32 s26, s26, 0x100
	s_addc_u32 s27, s27, 0
	s_add_u32 s56, s56, 0x100
	s_addc_u32 s57, s57, 0
	s_cmp_gt_u32 s58, 61
	s_cbranch_scc0 .Lkt_T_0
	s_nop 7
.Lkt_exit_0:
	s_and_b64 vcc, exec, s[14:15]
	s_cbranch_vccz .LBB0_290
	s_barrier

.Lkt_L_1:
	ds_read_b128 v[152:155], v144
	ds_read_b128 v[156:159], v144 offset:1024
	ds_read_b128 v[160:163], v144 offset:2048
	ds_read_b128 v[164:167], v144 offset:3072
	ds_read_b128 v[168:171], v145
	ds_read_b128 v[172:175], v145 offset:1024
	ds_read_b128 v[176:179], v145 offset:2048
	ds_read_b128 v[180:183], v145 offset:3072
	s_add_u32 s42, s40, 0xfff00080
	s_addc_u32 s43, s41, -1
	s_cmp_eq_u32 s70, 60
	s_cselect_b32 s47, s27, s43
	s_cselect_b32 s46, s66, s42
	s_cselect_b32 s43, s25, s69
	s_cselect_b32 s42, s67, s68
	v_lshl_add_u64 v[192:193], s[40:41], 0, v[134:135]
	s_add_i32 m0, s29, 0xc000
	ds_read_b128 v[184:187], v151
	ds_read_b128 v[188:191], v151 offset:1024
	ds_read_b128 v[196:199], v151 offset:2048
	ds_read_b128 v[200:203], v151 offset:3072
	ds_read_b128 v[204:207], v151 offset:4096
	ds_read_b128 v[208:211], v151 offset:5120
	ds_read_b128 v[212:215], v151 offset:6144
	ds_read_b128 v[216:219], v151 offset:7168
	global_load_lds_dwordx4 v[192:193], off
	v_lshl_add_u64 v[192:193], s[40:41], 0, v[136:137]
	s_add_i32 m0, s29, 0xe000
	s_nop 0
	global_load_lds_dwordx4 v[192:193], off
	s_waitcnt lgkmcnt(0)
	s_barrier
	s_setprio 1
	v_mfma_f32_16x16x32_bf16 v[126:129], v[152:155], v[184:187], v[126:129]
	v_mfma_f32_16x16x32_bf16 v[122:125], v[160:163], v[184:187], v[122:125]
	v_mfma_f32_16x16x32_bf16 v[118:121], v[152:155], v[196:199], v[118:121]
	v_mfma_f32_16x16x32_bf16 v[110:113], v[160:163], v[196:199], v[110:113]
	v_mfma_f32_16x16x32_bf16 v[102:105], v[152:155], v[204:207], v[102:105]
	v_mfma_f32_16x16x32_bf16 v[94:97], v[160:163], v[204:207], v[94:97]
	v_mfma_f32_16x16x32_bf16 v[86:89], v[152:155], v[212:215], v[86:89]
	v_mfma_f32_16x16x32_bf16 v[78:81], v[160:163], v[212:215], v[78:81]
	v_mfma_f32_16x16x32_bf16 v[126:129], v[156:159], v[188:191], v[126:129]
	v_mfma_f32_16x16x32_bf16 v[122:125], v[164:167], v[188:191], v[122:125]
	v_mfma_f32_16x16x32_bf16 v[118:121], v[156:159], v[200:203], v[118:121]
	v_mfma_f32_16x16x32_bf16 v[110:113], v[164:167], v[200:203], v[110:113]
	v_mfma_f32_16x16x32_bf16 v[102:105], v[156:159], v[208:211], v[102:105]
	v_mfma_f32_16x16x32_bf16 v[94:97], v[164:167], v[208:211], v[94:97]
	v_mfma_f32_16x16x32_bf16 v[86:89], v[156:159], v[216:219], v[86:89]
	v_mfma_f32_16x16x32_bf16 v[78:81], v[164:167], v[216:219], v[78:81]
	v_mfma_f32_16x16x32_bf16 v[114:117], v[168:171], v[184:187], v[114:117]
	v_mfma_f32_16x16x32_bf16 v[106:109], v[176:179], v[184:187], v[106:109]
	v_mfma_f32_16x16x32_bf16 v[98:101], v[168:171], v[196:199], v[98:101]
	v_mfma_f32_16x16x32_bf16 v[90:93], v[176:179], v[196:199], v[90:93]
	v_mfma_f32_16x16x32_bf16 v[82:85], v[168:171], v[204:207], v[82:85]
	v_mfma_f32_16x16x32_bf16 v[74:77], v[176:179], v[204:207], v[74:77]
	v_mfma_f32_16x16x32_bf16 v[70:73], v[168:171], v[212:215], v[70:73]
	v_mfma_f32_16x16x32_bf16 v[66:69], v[176:179], v[212:215], v[66:69]
	v_mfma_f32_16x16x32_bf16 v[114:117], v[172:175], v[188:191], v[114:117]
	v_mfma_f32_16x16x32_bf16 v[106:109], v[180:183], v[188:191], v[106:109]
	v_mfma_f32_16x16x32_bf16 v[98:101], v[172:175], v[200:203], v[98:101]
	v_mfma_f32_16x16x32_bf16 v[90:93], v[180:183], v[200:203], v[90:93]
	v_mfma_f32_16x16x32_bf16 v[82:85], v[172:175], v[208:211], v[82:85]
	v_mfma_f32_16x16x32_bf16 v[74:77], v[180:183], v[208:211], v[74:77]
	v_mfma_f32_16x16x32_bf16 v[70:73], v[172:175], v[216:219], v[70:73]
	v_mfma_f32_16x16x32_bf16 v[66:69], v[180:183], v[216:219], v[66:69]
	s_setprio 0
	s_waitcnt vmcnt(8)
	s_barrier
	s_add_i32 s71, s62, s54
	v_lshl_add_u64 v[192:193], s[42:43], 0, v[130:131]
	s_mov_b32 m0, s71
	ds_read_b128 v[184:187], v151 offset:16384
	ds_read_b128 v[188:191], v151 offset:17408
	ds_read_b128 v[196:199], v151 offset:18432
	ds_read_b128 v[200:203], v151 offset:19456
	ds_read_b128 v[204:207], v151 offset:20480
	ds_read_b128 v[208:211], v151 offset:21504
	ds_read_b128 v[212:215], v151 offset:22528
	ds_read_b128 v[216:219], v151 offset:23552
	global_load_lds_dwordx4 v[192:193], off
	s_add_i32 m0, s71, 0x2000
	s_add_u32 s72, s42, 0x100000
	v_lshl_add_u64 v[220:221], s[42:43], 0, v[132:133]
	s_addc_u32 s73, s43, 0
	s_add_i32 s71, s63, s54
	global_load_lds_dwordx4 v[220:221], off
	v_lshl_add_u64 v[222:223], s[72:73], 0, v[130:131]
	s_mov_b32 m0, s71
	v_lshl_add_u64 v[224:225], s[46:47], 0, v[132:133]
	global_load_lds_dwordx4 v[222:223], off
	v_lshl_add_u64 v[222:223], s[72:73], 0, v[132:133]
	s_add_i32 m0, s71, 0x2000
	s_nop 0
	global_load_lds_dwordx4 v[222:223], off
	v_lshl_add_u64 v[222:223], s[46:47], 0, v[130:131]
	s_mov_b32 m0, s29
	s_nop 0
	global_load_lds_dwordx4 v[222:223], off
	s_mov_b32 m0, s55
	s_nop 0
	global_load_lds_dwordx4 v[224:225], off
	s_waitcnt lgkmcnt(0)
	s_barrier
	s_setprio 1
	v_mfma_f32_16x16x32_bf16 v[62:65], v[152:155], v[184:187], v[62:65]
	v_mfma_f32_16x16x32_bf16 v[58:61], v[160:163], v[184:187], v[58:61]
	v_mfma_f32_16x16x32_bf16 v[54:57], v[152:155], v[196:199], v[54:57]
	v_mfma_f32_16x16x32_bf16 v[46:49], v[160:163], v[196:199], v[46:49]
	v_mfma_f32_16x16x32_bf16 v[38:41], v[152:155], v[204:207], v[38:41]
	v_mfma_f32_16x16x32_bf16 v[30:33], v[160:163], v[204:207], v[30:33]
	v_mfma_f32_16x16x32_bf16 v[22:25], v[152:155], v[212:215], v[22:25]
	v_mfma_f32_16x16x32_bf16 v[14:17], v[160:163], v[212:215], v[14:17]
	v_mfma_f32_16x16x32_bf16 v[62:65], v[156:159], v[188:191], v[62:65]
	v_mfma_f32_16x16x32_bf16 v[58:61], v[164:167], v[188:191], v[58:61]
	v_mfma_f32_16x16x32_bf16 v[54:57], v[156:159], v[200:203], v[54:57]
	v_mfma_f32_16x16x32_bf16 v[46:49], v[164:167], v[200:203], v[46:49]
	v_mfma_f32_16x16x32_bf16 v[38:41], v[156:159], v[208:211], v[38:41]
	v_mfma_f32_16x16x32_bf16 v[30:33], v[164:167], v[208:211], v[30:33]
	v_mfma_f32_16x16x32_bf16 v[22:25], v[156:159], v[216:219], v[22:25]
	v_mfma_f32_16x16x32_bf16 v[14:17], v[164:167], v[216:219], v[14:17]
	v_mfma_f32_16x16x32_bf16 v[50:53], v[168:171], v[184:187], v[50:53]
	v_mfma_f32_16x16x32_bf16 v[42:45], v[176:179], v[184:187], v[42:45]
	v_mfma_f32_16x16x32_bf16 v[34:37], v[168:171], v[196:199], v[34:37]
	v_mfma_f32_16x16x32_bf16 v[26:29], v[176:179], v[196:199], v[26:29]
	v_mfma_f32_16x16x32_bf16 v[18:21], v[168:171], v[204:207], v[18:21]
	v_mfma_f32_16x16x32_bf16 v[10:13], v[176:179], v[204:207], v[10:13]
	v_mfma_f32_16x16x32_bf16 v[6:9], v[168:171], v[212:215], v[6:9]
	v_mfma_f32_16x16x32_bf16 v[2:5], v[176:179], v[212:215], v[2:5]
	v_mfma_f32_16x16x32_bf16 v[50:53], v[172:175], v[188:191], v[50:53]
	v_mfma_f32_16x16x32_bf16 v[42:45], v[180:183], v[188:191], v[42:45]
	v_mfma_f32_16x16x32_bf16 v[34:37], v[172:175], v[200:203], v[34:37]
	v_mfma_f32_16x16x32_bf16 v[26:29], v[180:183], v[200:203], v[26:29]
	v_mfma_f32_16x16x32_bf16 v[18:21], v[172:175], v[208:211], v[18:21]
	v_mfma_f32_16x16x32_bf16 v[10:13], v[180:183], v[208:211], v[10:13]
	v_mfma_f32_16x16x32_bf16 v[6:9], v[172:175], v[216:219], v[6:9]
	v_mfma_f32_16x16x32_bf16 v[2:5], v[180:183], v[216:219], v[2:5]
	s_setprio 0
	s_waitcnt vmcnt(8)
	s_barrier
	s_add_i32 s71, 0, 0x18000
	s_add_i32 s72, 0, 0x1c000
	v_add_u32_e32 v164, s71, v142
	v_add_u32_e32 v180, s72, v142
	ds_read_b128 v[152:155], v164
	ds_read_b128 v[156:159], v164 offset:1024
	ds_read_b128 v[160:163], v164 offset:2048
	ds_read_b128 v[164:167], v164 offset:3072
	ds_read_b128 v[168:171], v180
	ds_read_b128 v[172:175], v180 offset:1024
	ds_read_b128 v[176:179], v180 offset:2048
	ds_read_b128 v[180:183], v180 offset:3072
	s_add_u32 s46, s46, 0x100000
	s_addc_u32 s47, s47, 0
	s_mov_b32 m0, s56
	v_lshl_add_u64 v[226:227], s[46:47], 0, v[130:131]
	ds_read_b128 v[184:187], v151 offset:32768
	ds_read_b128 v[188:191], v151 offset:33792
	ds_read_b128 v[196:199], v151 offset:34816
	ds_read_b128 v[200:203], v151 offset:35840
	ds_read_b128 v[204:207], v151 offset:36864
	ds_read_b128 v[208:211], v151 offset:37888
	ds_read_b128 v[212:215], v151 offset:38912
	ds_read_b128 v[216:219], v151 offset:39936
	global_load_lds_dwordx4 v[226:227], off
	v_lshl_add_u64 v[226:227], s[46:47], 0, v[132:133]
	s_mov_b32 m0, s57
	s_nop 0
	global_load_lds_dwordx4 v[226:227], off
	s_waitcnt lgkmcnt(0)
	s_barrier
	s_setprio 1
	v_mfma_f32_16x16x32_bf16 v[126:129], v[152:155], v[184:187], v[126:129]
	v_mfma_f32_16x16x32_bf16 v[122:125], v[160:163], v[184:187], v[122:125]
	v_mfma_f32_16x16x32_bf16 v[118:121], v[152:155], v[196:199], v[118:121]
	v_mfma_f32_16x16x32_bf16 v[110:113], v[160:163], v[196:199], v[110:113]
	v_mfma_f32_16x16x32_bf16 v[102:105], v[152:155], v[204:207], v[102:105]
	v_mfma_f32_16x16x32_bf16 v[94:97], v[160:163], v[204:207], v[94:97]
	v_mfma_f32_16x16x32_bf16 v[86:89], v[152:155], v[212:215], v[86:89]
	v_mfma_f32_16x16x32_bf16 v[78:81], v[160:163], v[212:215], v[78:81]
	v_mfma_f32_16x16x32_bf16 v[126:129], v[156:159], v[188:191], v[126:129]
	v_mfma_f32_16x16x32_bf16 v[122:125], v[164:167], v[188:191], v[122:125]
	v_mfma_f32_16x16x32_bf16 v[118:121], v[156:159], v[200:203], v[118:121]
	v_mfma_f32_16x16x32_bf16 v[110:113], v[164:167], v[200:203], v[110:113]
	v_mfma_f32_16x16x32_bf16 v[102:105], v[156:159], v[208:211], v[102:105]
	v_mfma_f32_16x16x32_bf16 v[94:97], v[164:167], v[208:211], v[94:97]
	v_mfma_f32_16x16x32_bf16 v[86:89], v[156:159], v[216:219], v[86:89]
	v_mfma_f32_16x16x32_bf16 v[78:81], v[164:167], v[216:219], v[78:81]
	v_mfma_f32_16x16x32_bf16 v[114:117], v[168:171], v[184:187], v[114:117]
	v_mfma_f32_16x16x32_bf16 v[106:109], v[176:179], v[184:187], v[106:109]
	v_mfma_f32_16x16x32_bf16 v[98:101], v[168:171], v[196:199], v[98:101]
	v_mfma_f32_16x16x32_bf16 v[90:93], v[176:179], v[196:199], v[90:93]
	v_mfma_f32_16x16x32_bf16 v[82:85], v[168:171], v[204:207], v[82:85]
	v_mfma_f32_16x16x32_bf16 v[74:77], v[176:179], v[204:207], v[74:77]
	v_mfma_f32_16x16x32_bf16 v[70:73], v[168:171], v[212:215], v[70:73]
	v_mfma_f32_16x16x32_bf16 v[66:69], v[176:179], v[212:215], v[66:69]
	v_mfma_f32_16x16x32_bf16 v[114:117], v[172:175], v[188:191], v[114:117]
	v_mfma_f32_16x16x32_bf16 v[106:109], v[180:183], v[188:191], v[106:109]
	v_mfma_f32_16x16x32_bf16 v[98:101], v[172:175], v[200:203], v[98:101]
	v_mfma_f32_16x16x32_bf16 v[90:93], v[180:183], v[200:203], v[90:93]
	v_mfma_f32_16x16x32_bf16 v[82:85], v[172:175], v[208:211], v[82:85]
	v_mfma_f32_16x16x32_bf16 v[74:77], v[180:183], v[208:211], v[74:77]
	v_mfma_f32_16x16x32_bf16 v[70:73], v[172:175], v[216:219], v[70:73]
	v_mfma_f32_16x16x32_bf16 v[66:69], v[180:183], v[216:219], v[66:69]
	s_setprio 0
	s_waitcnt vmcnt(8)
	s_barrier
	s_add_i32 s46, s71, s54
	v_lshl_add_u64 v[192:193], v[192:193], 0, s[10:11]
	s_mov_b32 m0, s46
	ds_read_b128 v[184:187], v151 offset:49152
	ds_read_b128 v[188:191], v151 offset:50176
	ds_read_b128 v[196:199], v151 offset:51200
	ds_read_b128 v[200:203], v151 offset:52224
	ds_read_b128 v[204:207], v151 offset:53248
	ds_read_b128 v[208:211], v151 offset:54272
	ds_read_b128 v[212:215], v151 offset:55296
	ds_read_b128 v[216:219], v151 offset:56320
	global_load_lds_dwordx4 v[192:193], off
	s_add_i32 m0, s46, 0x2000
	s_add_u32 s42, s42, 0x100080
	v_lshl_add_u64 v[192:193], v[220:221], 0, s[10:11]
	s_addc_u32 s43, s43, 0
	s_add_i32 s46, s72, s54
	global_load_lds_dwordx4 v[192:193], off
	v_lshl_add_u64 v[192:193], s[42:43], 0, v[130:131]
	s_mov_b32 m0, s46
	s_nop 0
	global_load_lds_dwordx4 v[192:193], off
	v_lshl_add_u64 v[192:193], s[42:43], 0, v[132:133]
	s_add_i32 m0, s46, 0x2000
	s_nop 0
	global_load_lds_dwordx4 v[192:193], off
	v_lshl_add_u64 v[192:193], v[222:223], 0, s[10:11]
	s_mov_b32 m0, s59
	s_nop 0
	global_load_lds_dwordx4 v[192:193], off
	v_lshl_add_u64 v[192:193], v[224:225], 0, s[10:11]
	s_mov_b32 m0, s60
	s_nop 0
	global_load_lds_dwordx4 v[192:193], off
	s_waitcnt lgkmcnt(0)
	s_barrier
	s_nop 0
	s_setprio 1
	v_mfma_f32_16x16x32_bf16 v[62:65], v[152:155], v[184:187], v[62:65]
	v_mfma_f32_16x16x32_bf16 v[58:61], v[160:163], v[184:187], v[58:61]
	v_mfma_f32_16x16x32_bf16 v[54:57], v[152:155], v[196:199], v[54:57]
	v_mfma_f32_16x16x32_bf16 v[46:49], v[160:163], v[196:199], v[46:49]
	v_mfma_f32_16x16x32_bf16 v[38:41], v[152:155], v[204:207], v[38:41]
	v_mfma_f32_16x16x32_bf16 v[30:33], v[160:163], v[204:207], v[30:33]
	v_mfma_f32_16x16x32_bf16 v[22:25], v[152:155], v[212:215], v[22:25]
	v_mfma_f32_16x16x32_bf16 v[14:17], v[160:163], v[212:215], v[14:17]
	v_mfma_f32_16x16x32_bf16 v[62:65], v[156:159], v[188:191], v[62:65]
	v_mfma_f32_16x16x32_bf16 v[58:61], v[164:167], v[188:191], v[58:61]
	v_mfma_f32_16x16x32_bf16 v[54:57], v[156:159], v[200:203], v[54:57]
	v_mfma_f32_16x16x32_bf16 v[46:49], v[164:167], v[200:203], v[46:49]
	v_mfma_f32_16x16x32_bf16 v[38:41], v[156:159], v[208:211], v[38:41]
	v_mfma_f32_16x16x32_bf16 v[30:33], v[164:167], v[208:211], v[30:33]
	v_mfma_f32_16x16x32_bf16 v[22:25], v[156:159], v[216:219], v[22:25]
	v_mfma_f32_16x16x32_bf16 v[14:17], v[164:167], v[216:219], v[14:17]
	v_mfma_f32_16x16x32_bf16 v[50:53], v[168:171], v[184:187], v[50:53]
	v_mfma_f32_16x16x32_bf16 v[42:45], v[176:179], v[184:187], v[42:45]
	v_mfma_f32_16x16x32_bf16 v[34:37], v[168:171], v[196:199], v[34:37]
	v_mfma_f32_16x16x32_bf16 v[26:29], v[176:179], v[196:199], v[26:29]
	v_mfma_f32_16x16x32_bf16 v[18:21], v[168:171], v[204:207], v[18:21]
	v_mfma_f32_16x16x32_bf16 v[10:13], v[176:179], v[204:207], v[10:13]
	v_mfma_f32_16x16x32_bf16 v[6:9], v[168:171], v[212:215], v[6:9]
	v_mfma_f32_16x16x32_bf16 v[2:5], v[176:179], v[212:215], v[2:5]
	v_mfma_f32_16x16x32_bf16 v[50:53], v[172:175], v[188:191], v[50:53]
	v_mfma_f32_16x16x32_bf16 v[42:45], v[180:183], v[188:191], v[42:45]
	v_mfma_f32_16x16x32_bf16 v[34:37], v[172:175], v[200:203], v[34:37]
	v_mfma_f32_16x16x32_bf16 v[26:29], v[180:183], v[200:203], v[26:29]
	v_mfma_f32_16x16x32_bf16 v[18:21], v[172:175], v[208:211], v[18:21]
	v_mfma_f32_16x16x32_bf16 v[10:13], v[180:183], v[208:211], v[10:13]
	v_mfma_f32_16x16x32_bf16 v[6:9], v[172:175], v[216:219], v[6:9]
	v_mfma_f32_16x16x32_bf16 v[2:5], v[180:183], v[216:219], v[2:5]
	s_setprio 0
	s_waitcnt vmcnt(8)
	s_barrier
	s_add_i32 s70, s70, 2
	s_add_u32 s40, s40, 0x100
	s_addc_u32 s41, s41, 0
	s_add_u32 s68, s68, 0x100
	s_addc_u32 s69, s69, 0
	s_cmp_gt_u32 s70, 61
	s_cbranch_scc0 .Lkt_L_1
	s_branch .Lkt_exit_1
.Lkt_T_1:
	ds_read_b128 v[152:155], v144
	ds_read_b128 v[156:159], v144 offset:1024
	ds_read_b128 v[160:163], v144 offset:2048
	ds_read_b128 v[164:167], v144 offset:3072
	ds_read_b128 v[168:171], v145
	ds_read_b128 v[172:175], v145 offset:1024
	ds_read_b128 v[176:179], v145 offset:2048
	ds_read_b128 v[180:183], v145 offset:3072
	s_add_u32 s42, s40, 0xfff00080
	s_addc_u32 s43, s41, -1
	s_cmp_eq_u32 s70, 60
	s_cselect_b32 s47, s27, s43
	s_cselect_b32 s46, s66, s42
	s_cselect_b32 s43, s25, s69
	s_cselect_b32 s42, s67, s68
	v_lshl_add_u64 v[192:193], s[40:41], 0, v[134:135]
	s_add_i32 m0, s29, 0xc000
	ds_read_b128 v[184:187], v151
	ds_read_b128 v[188:191], v151 offset:1024
	ds_read_b128 v[196:199], v151 offset:2048
	ds_read_b128 v[200:203], v151 offset:3072
	ds_read_b128 v[204:207], v151 offset:4096
	ds_read_b128 v[208:211], v151 offset:5120
	ds_read_b128 v[212:215], v151 offset:6144
	ds_read_b128 v[216:219], v151 offset:7168
	global_load_lds_dwordx4 v[192:193], off
	v_lshl_add_u64 v[192:193], s[40:41], 0, v[136:137]
	s_add_i32 m0, s29, 0xe000
	s_nop 0
	global_load_lds_dwordx4 v[192:193], off
	s_waitcnt vmcnt(8)
	s_waitcnt lgkmcnt(0)
	s_barrier
	s_setprio 1
	v_mfma_f32_16x16x32_bf16 v[126:129], v[152:155], v[184:187], v[126:129]
	v_mfma_f32_16x16x32_bf16 v[122:125], v[160:163], v[184:187], v[122:125]
	v_mfma_f32_16x16x32_bf16 v[118:121], v[152:155], v[196:199], v[118:121]
	v_mfma_f32_16x16x32_bf16 v[110:113], v[160:163], v[196:199], v[110:113]
	v_mfma_f32_16x16x32_bf16 v[102:105], v[152:155], v[204:207], v[102:105]
	v_mfma_f32_16x16x32_bf16 v[94:97], v[160:163], v[204:207], v[94:97]
	v_mfma_f32_16x16x32_bf16 v[86:89], v[152:155], v[212:215], v[86:89]
	v_mfma_f32_16x16x32_bf16 v[78:81], v[160:163], v[212:215], v[78:81]
	v_mfma_f32_16x16x32_bf16 v[126:129], v[156:159], v[188:191], v[126:129]
	v_mfma_f32_16x16x32_bf16 v[122:125], v[164:167], v[188:191], v[122:125]
	v_mfma_f32_16x16x32_bf16 v[118:121], v[156:159], v[200:203], v[118:121]
	v_mfma_f32_16x16x32_bf16 v[110:113], v[164:167], v[200:203], v[110:113]
	v_mfma_f32_16x16x32_bf16 v[102:105], v[156:159], v[208:211], v[102:105]
	v_mfma_f32_16x16x32_bf16 v[94:97], v[164:167], v[208:211], v[94:97]
	v_mfma_f32_16x16x32_bf16 v[86:89], v[156:159], v[216:219], v[86:89]
	v_mfma_f32_16x16x32_bf16 v[78:81], v[164:167], v[216:219], v[78:81]
	v_mfma_f32_16x16x32_bf16 v[114:117], v[168:171], v[184:187], v[114:117]
	v_mfma_f32_16x16x32_bf16 v[106:109], v[176:179], v[184:187], v[106:109]
	v_mfma_f32_16x16x32_bf16 v[98:101], v[168:171], v[196:199], v[98:101]
	v_mfma_f32_16x16x32_bf16 v[90:93], v[176:179], v[196:199], v[90:93]
	v_mfma_f32_16x16x32_bf16 v[82:85], v[168:171], v[204:207], v[82:85]
	v_mfma_f32_16x16x32_bf16 v[74:77], v[176:179], v[204:207], v[74:77]
	v_mfma_f32_16x16x32_bf16 v[70:73], v[168:171], v[212:215], v[70:73]
	v_mfma_f32_16x16x32_bf16 v[66:69], v[176:179], v[212:215], v[66:69]
	v_mfma_f32_16x16x32_bf16 v[114:117], v[172:175], v[188:191], v[114:117]
	v_mfma_f32_16x16x32_bf16 v[106:109], v[180:183], v[188:191], v[106:109]
	v_mfma_f32_16x16x32_bf16 v[98:101], v[172:175], v[200:203], v[98:101]
	v_mfma_f32_16x16x32_bf16 v[90:93], v[180:183], v[200:203], v[90:93]
	v_mfma_f32_16x16x32_bf16 v[82:85], v[172:175], v[208:211], v[82:85]
	v_mfma_f32_16x16x32_bf16 v[74:77], v[180:183], v[208:211], v[74:77]
	v_mfma_f32_16x16x32_bf16 v[70:73], v[172:175], v[216:219], v[70:73]
	v_mfma_f32_16x16x32_bf16 v[66:69], v[180:183], v[216:219], v[66:69]
	s_setprio 0
	s_barrier
	s_add_i32 s71, s62, s54
	v_lshl_add_u64 v[192:193], s[42:43], 0, v[130:131]
	s_mov_b32 m0, s71
	ds_read_b128 v[184:187], v151 offset:16384
	ds_read_b128 v[188:191], v151 offset:17408
	ds_read_b128 v[196:199], v151 offset:18432
	ds_read_b128 v[200:203], v151 offset:19456
	ds_read_b128 v[204:207], v151 offset:20480
	ds_read_b128 v[208:211], v151 offset:21504
	ds_read_b128 v[212:215], v151 offset:22528
	ds_read_b128 v[216:219], v151 offset:23552
	global_load_lds_dwordx4 v[192:193], off
	s_add_i32 m0, s71, 0x2000
	s_add_u32 s72, s42, 0x100000
	v_lshl_add_u64 v[220:221], s[42:43], 0, v[132:133]
	s_addc_u32 s73, s43, 0
	s_add_i32 s71, s63, s54
	global_load_lds_dwordx4 v[220:221], off
	v_lshl_add_u64 v[222:223], s[72:73], 0, v[130:131]
	s_mov_b32 m0, s71
	v_lshl_add_u64 v[224:225], s[46:47], 0, v[132:133]
	global_load_lds_dwordx4 v[222:223], off
	v_lshl_add_u64 v[222:223], s[72:73], 0, v[132:133]
	s_add_i32 m0, s71, 0x2000
	s_nop 0
	global_load_lds_dwordx4 v[222:223], off
	v_lshl_add_u64 v[222:223], s[46:47], 0, v[130:131]
	s_mov_b32 m0, s29
	s_nop 0
	global_load_lds_dwordx4 v[222:223], off
	s_mov_b32 m0, s55
	s_nop 0
	global_load_lds_dwordx4 v[224:225], off
	s_waitcnt vmcnt(8)
	s_waitcnt lgkmcnt(0)
	s_barrier
	s_setprio 1
	v_mfma_f32_16x16x32_bf16 v[62:65], v[152:155], v[184:187], v[62:65]
	v_mfma_f32_16x16x32_bf16 v[58:61], v[160:163], v[184:187], v[58:61]
	v_mfma_f32_16x16x32_bf16 v[54:57], v[152:155], v[196:199], v[54:57]
	v_mfma_f32_16x16x32_bf16 v[46:49], v[160:163], v[196:199], v[46:49]
	v_mfma_f32_16x16x32_bf16 v[38:41], v[152:155], v[204:207], v[38:41]
	v_mfma_f32_16x16x32_bf16 v[30:33], v[160:163], v[204:207], v[30:33]
	v_mfma_f32_16x16x32_bf16 v[22:25], v[152:155], v[212:215], v[22:25]
	v_mfma_f32_16x16x32_bf16 v[14:17], v[160:163], v[212:215], v[14:17]
	v_mfma_f32_16x16x32_bf16 v[62:65], v[156:159], v[188:191], v[62:65]
	v_mfma_f32_16x16x32_bf16 v[58:61], v[164:167], v[188:191], v[58:61]
	v_mfma_f32_16x16x32_bf16 v[54:57], v[156:159], v[200:203], v[54:57]
	v_mfma_f32_16x16x32_bf16 v[46:49], v[164:167], v[200:203], v[46:49]
	v_mfma_f32_16x16x32_bf16 v[38:41], v[156:159], v[208:211], v[38:41]
	v_mfma_f32_16x16x32_bf16 v[30:33], v[164:167], v[208:211], v[30:33]
	v_mfma_f32_16x16x32_bf16 v[22:25], v[156:159], v[216:219], v[22:25]
	v_mfma_f32_16x16x32_bf16 v[14:17], v[164:167], v[216:219], v[14:17]
	v_mfma_f32_16x16x32_bf16 v[50:53], v[168:171], v[184:187], v[50:53]
	v_mfma_f32_16x16x32_bf16 v[42:45], v[176:179], v[184:187], v[42:45]
	v_mfma_f32_16x16x32_bf16 v[34:37], v[168:171], v[196:199], v[34:37]
	v_mfma_f32_16x16x32_bf16 v[26:29], v[176:179], v[196:199], v[26:29]
	v_mfma_f32_16x16x32_bf16 v[18:21], v[168:171], v[204:207], v[18:21]
	v_mfma_f32_16x16x32_bf16 v[10:13], v[176:179], v[204:207], v[10:13]
	v_mfma_f32_16x16x32_bf16 v[6:9], v[168:171], v[212:215], v[6:9]
	v_mfma_f32_16x16x32_bf16 v[2:5], v[176:179], v[212:215], v[2:5]
	v_mfma_f32_16x16x32_bf16 v[50:53], v[172:175], v[188:191], v[50:53]
	v_mfma_f32_16x16x32_bf16 v[42:45], v[180:183], v[188:191], v[42:45]
	v_mfma_f32_16x16x32_bf16 v[34:37], v[172:175], v[200:203], v[34:37]
	v_mfma_f32_16x16x32_bf16 v[26:29], v[180:183], v[200:203], v[26:29]
	v_mfma_f32_16x16x32_bf16 v[18:21], v[172:175], v[208:211], v[18:21]
	v_mfma_f32_16x16x32_bf16 v[10:13], v[180:183], v[208:211], v[10:13]
	v_mfma_f32_16x16x32_bf16 v[6:9], v[172:175], v[216:219], v[6:9]
	v_mfma_f32_16x16x32_bf16 v[2:5], v[180:183], v[216:219], v[2:5]
	s_setprio 0
	s_barrier
	s_add_i32 s71, 0, 0x18000
	s_add_i32 s72, 0, 0x1c000
	v_add_u32_e32 v164, s71, v142
	v_add_u32_e32 v180, s72, v142
	ds_read_b128 v[152:155], v164
	ds_read_b128 v[156:159], v164 offset:1024
	ds_read_b128 v[160:163], v164 offset:2048
	ds_read_b128 v[164:167], v164 offset:3072
	ds_read_b128 v[168:171], v180
	ds_read_b128 v[172:175], v180 offset:1024
	ds_read_b128 v[176:179], v180 offset:2048
	ds_read_b128 v[180:183], v180 offset:3072
	s_add_u32 s46, s46, 0x100000
	s_addc_u32 s47, s47, 0
	s_mov_b32 m0, s56
	v_lshl_add_u64 v[226:227], s[46:47], 0, v[130:131]
	ds_read_b128 v[184:187], v151 offset:32768
	ds_read_b128 v[188:191], v151 offset:33792
	ds_read_b128 v[196:199], v151 offset:34816
	ds_read_b128 v[200:203], v151 offset:35840
	ds_read_b128 v[204:207], v151 offset:36864
	ds_read_b128 v[208:211], v151 offset:37888
	ds_read_b128 v[212:215], v151 offset:38912
	ds_read_b128 v[216:219], v151 offset:39936
	global_load_lds_dwordx4 v[226:227], off
	v_lshl_add_u64 v[226:227], s[46:47], 0, v[132:133]
	s_mov_b32 m0, s57
	s_nop 0
	global_load_lds_dwordx4 v[226:227], off
	s_waitcnt vmcnt(8)
	s_waitcnt lgkmcnt(0)
	s_barrier
	s_setprio 1
	v_mfma_f32_16x16x32_bf16 v[126:129], v[152:155], v[184:187], v[126:129]
	v_mfma_f32_16x16x32_bf16 v[122:125], v[160:163], v[184:187], v[122:125]
	v_mfma_f32_16x16x32_bf16 v[118:121], v[152:155], v[196:199], v[118:121]
	v_mfma_f32_16x16x32_bf16 v[110:113], v[160:163], v[196:199], v[110:113]
	v_mfma_f32_16x16x32_bf16 v[102:105], v[152:155], v[204:207], v[102:105]
	v_mfma_f32_16x16x32_bf16 v[94:97], v[160:163], v[204:207], v[94:97]
	v_mfma_f32_16x16x32_bf16 v[86:89], v[152:155], v[212:215], v[86:89]
	v_mfma_f32_16x16x32_bf16 v[78:81], v[160:163], v[212:215], v[78:81]
	v_mfma_f32_16x16x32_bf16 v[126:129], v[156:159], v[188:191], v[126:129]
	v_mfma_f32_16x16x32_bf16 v[122:125], v[164:167], v[188:191], v[122:125]
	v_mfma_f32_16x16x32_bf16 v[118:121], v[156:159], v[200:203], v[118:121]
	v_mfma_f32_16x16x32_bf16 v[110:113], v[164:167], v[200:203], v[110:113]
	v_mfma_f32_16x16x32_bf16 v[102:105], v[156:159], v[208:211], v[102:105]
	v_mfma_f32_16x16x32_bf16 v[94:97], v[164:167], v[208:211], v[94:97]
	v_mfma_f32_16x16x32_bf16 v[86:89], v[156:159], v[216:219], v[86:89]
	v_mfma_f32_16x16x32_bf16 v[78:81], v[164:167], v[216:219], v[78:81]
	v_mfma_f32_16x16x32_bf16 v[114:117], v[168:171], v[184:187], v[114:117]
	v_mfma_f32_16x16x32_bf16 v[106:109], v[176:179], v[184:187], v[106:109]
	v_mfma_f32_16x16x32_bf16 v[98:101], v[168:171], v[196:199], v[98:101]
	v_mfma_f32_16x16x32_bf16 v[90:93], v[176:179], v[196:199], v[90:93]
	v_mfma_f32_16x16x32_bf16 v[82:85], v[168:171], v[204:207], v[82:85]
	v_mfma_f32_16x16x32_bf16 v[74:77], v[176:179], v[204:207], v[74:77]
	v_mfma_f32_16x16x32_bf16 v[70:73], v[168:171], v[212:215], v[70:73]
	v_mfma_f32_16x16x32_bf16 v[66:69], v[176:179], v[212:215], v[66:69]
	v_mfma_f32_16x16x32_bf16 v[114:117], v[172:175], v[188:191], v[114:117]
	v_mfma_f32_16x16x32_bf16 v[106:109], v[180:183], v[188:191], v[106:109]
	v_mfma_f32_16x16x32_bf16 v[98:101], v[172:175], v[200:203], v[98:101]
	v_mfma_f32_16x16x32_bf16 v[90:93], v[180:183], v[200:203], v[90:93]
	v_mfma_f32_16x16x32_bf16 v[82:85], v[172:175], v[208:211], v[82:85]
	v_mfma_f32_16x16x32_bf16 v[74:77], v[180:183], v[208:211], v[74:77]
	v_mfma_f32_16x16x32_bf16 v[70:73], v[172:175], v[216:219], v[70:73]
	v_mfma_f32_16x16x32_bf16 v[66:69], v[180:183], v[216:219], v[66:69]
	s_setprio 0
	s_barrier
	s_add_i32 s46, s71, s54
	v_lshl_add_u64 v[192:193], v[192:193], 0, s[10:11]
	s_mov_b32 m0, s46
	ds_read_b128 v[184:187], v151 offset:49152
	ds_read_b128 v[188:191], v151 offset:50176
	ds_read_b128 v[196:199], v151 offset:51200
	ds_read_b128 v[200:203], v151 offset:52224
	ds_read_b128 v[204:207], v151 offset:53248
	ds_read_b128 v[208:211], v151 offset:54272
	ds_read_b128 v[212:215], v151 offset:55296
	ds_read_b128 v[216:219], v151 offset:56320
	global_load_lds_dwordx4 v[192:193], off
	s_add_i32 m0, s46, 0x2000
	s_add_u32 s42, s42, 0x100080
	v_lshl_add_u64 v[192:193], v[220:221], 0, s[10:11]
	s_addc_u32 s43, s43, 0
	s_add_i32 s46, s72, s54
	global_load_lds_dwordx4 v[192:193], off
	v_lshl_add_u64 v[192:193], s[42:43], 0, v[130:131]
	s_mov_b32 m0, s46
	s_nop 0
	global_load_lds_dwordx4 v[192:193], off
	v_lshl_add_u64 v[192:193], s[42:43], 0, v[132:133]
	s_add_i32 m0, s46, 0x2000
	s_nop 0
	global_load_lds_dwordx4 v[192:193], off
	v_lshl_add_u64 v[192:193], v[222:223], 0, s[10:11]
	s_mov_b32 m0, s59
	s_nop 0
	global_load_lds_dwordx4 v[192:193], off
	v_lshl_add_u64 v[192:193], v[224:225], 0, s[10:11]
	s_mov_b32 m0, s60
	s_nop 0
	global_load_lds_dwordx4 v[192:193], off
	s_nop 0
	s_waitcnt vmcnt(8)
	s_waitcnt lgkmcnt(0)
	s_barrier
	s_setprio 1
	v_mfma_f32_16x16x32_bf16 v[62:65], v[152:155], v[184:187], v[62:65]
	v_mfma_f32_16x16x32_bf16 v[58:61], v[160:163], v[184:187], v[58:61]
	v_mfma_f32_16x16x32_bf16 v[54:57], v[152:155], v[196:199], v[54:57]
	v_mfma_f32_16x16x32_bf16 v[46:49], v[160:163], v[196:199], v[46:49]
	v_mfma_f32_16x16x32_bf16 v[38:41], v[152:155], v[204:207], v[38:41]
	v_mfma_f32_16x16x32_bf16 v[30:33], v[160:163], v[204:207], v[30:33]
	v_mfma_f32_16x16x32_bf16 v[22:25], v[152:155], v[212:215], v[22:25]
	v_mfma_f32_16x16x32_bf16 v[14:17], v[160:163], v[212:215], v[14:17]
	v_mfma_f32_16x16x32_bf16 v[62:65], v[156:159], v[188:191], v[62:65]
	v_mfma_f32_16x16x32_bf16 v[58:61], v[164:167], v[188:191], v[58:61]
	v_mfma_f32_16x16x32_bf16 v[54:57], v[156:159], v[200:203], v[54:57]
	v_mfma_f32_16x16x32_bf16 v[46:49], v[164:167], v[200:203], v[46:49]
	v_mfma_f32_16x16x32_bf16 v[38:41], v[156:159], v[208:211], v[38:41]
	v_mfma_f32_16x16x32_bf16 v[30:33], v[164:167], v[208:211], v[30:33]
	v_mfma_f32_16x16x32_bf16 v[22:25], v[156:159], v[216:219], v[22:25]
	v_mfma_f32_16x16x32_bf16 v[14:17], v[164:167], v[216:219], v[14:17]
	v_mfma_f32_16x16x32_bf16 v[50:53], v[168:171], v[184:187], v[50:53]
	v_mfma_f32_16x16x32_bf16 v[42:45], v[176:179], v[184:187], v[42:45]
	v_mfma_f32_16x16x32_bf16 v[34:37], v[168:171], v[196:199], v[34:37]
	v_mfma_f32_16x16x32_bf16 v[26:29], v[176:179], v[196:199], v[26:29]
	v_mfma_f32_16x16x32_bf16 v[18:21], v[168:171], v[204:207], v[18:21]
	v_mfma_f32_16x16x32_bf16 v[10:13], v[176:179], v[204:207], v[10:13]
	v_mfma_f32_16x16x32_bf16 v[6:9], v[168:171], v[212:215], v[6:9]
	v_mfma_f32_16x16x32_bf16 v[2:5], v[176:179], v[212:215], v[2:5]
	v_mfma_f32_16x16x32_bf16 v[50:53], v[172:175], v[188:191], v[50:53]
	v_mfma_f32_16x16x32_bf16 v[42:45], v[180:183], v[188:191], v[42:45]
	v_mfma_f32_16x16x32_bf16 v[34:37], v[172:175], v[200:203], v[34:37]
	v_mfma_f32_16x16x32_bf16 v[26:29], v[180:183], v[200:203], v[26:29]
	v_mfma_f32_16x16x32_bf16 v[18:21], v[172:175], v[208:211], v[18:21]
	v_mfma_f32_16x16x32_bf16 v[10:13], v[180:183], v[208:211], v[10:13]
	v_mfma_f32_16x16x32_bf16 v[6:9], v[172:175], v[216:219], v[6:9]
	v_mfma_f32_16x16x32_bf16 v[2:5], v[180:183], v[216:219], v[2:5]
	s_setprio 0
	s_barrier
	s_add_i32 s70, s70, 2
	s_add_u32 s40, s40, 0x100
	s_addc_u32 s41, s41, 0
	s_add_u32 s68, s68, 0x100
	s_addc_u32 s69, s69, 0
	s_cmp_gt_u32 s70, 61
	s_cbranch_scc0 .Lkt_T_1
	s_nop 7
.Lkt_exit_1:
	s_and_b64 vcc, exec, s[12:13]
	s_cbranch_vccz .LBB0_314
	s_barrier

.Lkt_L_2:
	ds_read_b128 v[144:147], v140
	ds_read_b128 v[148:151], v140 offset:1024
	ds_read_b128 v[152:155], v140 offset:2048
	ds_read_b128 v[156:159], v140 offset:3072
	ds_read_b128 v[160:163], v142
	ds_read_b128 v[164:167], v142 offset:1024
	ds_read_b128 v[168:171], v142 offset:2048
	ds_read_b128 v[172:175], v142 offset:3072
	s_add_u32 s42, s40, 0xfff00080
	s_addc_u32 s43, s41, -1
	s_cmp_eq_u32 s67, 60
	s_cselect_b32 s47, s27, s43
	s_cselect_b32 s46, s63, s42
	s_cselect_b32 s43, s25, s66
	s_cselect_b32 s42, s64, s65
	v_lshl_add_u64 v[192:193], s[40:41], 0, v[134:135]
	s_add_i32 m0, s29, 0xc000
	ds_read_b128 v[176:179], v143
	ds_read_b128 v[180:183], v143 offset:1024
	ds_read_b128 v[184:187], v143 offset:2048
	ds_read_b128 v[188:191], v143 offset:3072
	ds_read_b128 v[196:199], v143 offset:4096
	ds_read_b128 v[200:203], v143 offset:5120
	ds_read_b128 v[204:207], v143 offset:6144
	ds_read_b128 v[208:211], v143 offset:7168
	global_load_lds_dwordx4 v[192:193], off
	v_lshl_add_u64 v[192:193], s[40:41], 0, v[136:137]
	s_add_i32 m0, s29, 0xe000
	s_nop 0
	global_load_lds_dwordx4 v[192:193], off
	s_waitcnt lgkmcnt(0)
	s_barrier
	s_setprio 1
	v_mfma_f32_16x16x32_bf16 v[126:129], v[144:147], v[176:179], v[126:129]
	v_mfma_f32_16x16x32_bf16 v[122:125], v[152:155], v[176:179], v[122:125]
	v_mfma_f32_16x16x32_bf16 v[118:121], v[144:147], v[184:187], v[118:121]
	v_mfma_f32_16x16x32_bf16 v[110:113], v[152:155], v[184:187], v[110:113]
	v_mfma_f32_16x16x32_bf16 v[102:105], v[144:147], v[196:199], v[102:105]
	v_mfma_f32_16x16x32_bf16 v[94:97], v[152:155], v[196:199], v[94:97]
	v_mfma_f32_16x16x32_bf16 v[86:89], v[144:147], v[204:207], v[86:89]
	v_mfma_f32_16x16x32_bf16 v[78:81], v[152:155], v[204:207], v[78:81]
	v_mfma_f32_16x16x32_bf16 v[126:129], v[148:151], v[180:183], v[126:129]
	v_mfma_f32_16x16x32_bf16 v[122:125], v[156:159], v[180:183], v[122:125]
	v_mfma_f32_16x16x32_bf16 v[118:121], v[148:151], v[188:191], v[118:121]
	v_mfma_f32_16x16x32_bf16 v[110:113], v[156:159], v[188:191], v[110:113]
	v_mfma_f32_16x16x32_bf16 v[102:105], v[148:151], v[200:203], v[102:105]
	v_mfma_f32_16x16x32_bf16 v[94:97], v[156:159], v[200:203], v[94:97]
	v_mfma_f32_16x16x32_bf16 v[86:89], v[148:151], v[208:211], v[86:89]
	v_mfma_f32_16x16x32_bf16 v[78:81], v[156:159], v[208:211], v[78:81]
	v_mfma_f32_16x16x32_bf16 v[114:117], v[160:163], v[176:179], v[114:117]
	v_mfma_f32_16x16x32_bf16 v[106:109], v[168:171], v[176:179], v[106:109]
	v_mfma_f32_16x16x32_bf16 v[98:101], v[160:163], v[184:187], v[98:101]
	v_mfma_f32_16x16x32_bf16 v[90:93], v[168:171], v[184:187], v[90:93]
	v_mfma_f32_16x16x32_bf16 v[82:85], v[160:163], v[196:199], v[82:85]
	v_mfma_f32_16x16x32_bf16 v[74:77], v[168:171], v[196:199], v[74:77]
	v_mfma_f32_16x16x32_bf16 v[70:73], v[160:163], v[204:207], v[70:73]
	v_mfma_f32_16x16x32_bf16 v[66:69], v[168:171], v[204:207], v[66:69]
	v_mfma_f32_16x16x32_bf16 v[114:117], v[164:167], v[180:183], v[114:117]
	v_mfma_f32_16x16x32_bf16 v[106:109], v[172:175], v[180:183], v[106:109]
	v_mfma_f32_16x16x32_bf16 v[98:101], v[164:167], v[188:191], v[98:101]
	v_mfma_f32_16x16x32_bf16 v[90:93], v[172:175], v[188:191], v[90:93]
	v_mfma_f32_16x16x32_bf16 v[82:85], v[164:167], v[200:203], v[82:85]
	v_mfma_f32_16x16x32_bf16 v[74:77], v[172:175], v[200:203], v[74:77]
	v_mfma_f32_16x16x32_bf16 v[70:73], v[164:167], v[208:211], v[70:73]
	v_mfma_f32_16x16x32_bf16 v[66:69], v[172:175], v[208:211], v[66:69]
	s_setprio 0
	s_waitcnt vmcnt(8)
	s_barrier
	s_add_i32 s68, s59, s51
	v_lshl_add_u64 v[192:193], s[42:43], 0, v[130:131]
	s_mov_b32 m0, s68
	ds_read_b128 v[176:179], v143 offset:16384
	ds_read_b128 v[180:183], v143 offset:17408
	ds_read_b128 v[184:187], v143 offset:18432
	ds_read_b128 v[188:191], v143 offset:19456
	ds_read_b128 v[196:199], v143 offset:20480
	ds_read_b128 v[200:203], v143 offset:21504
	ds_read_b128 v[204:207], v143 offset:22528
	ds_read_b128 v[208:211], v143 offset:23552
	global_load_lds_dwordx4 v[192:193], off
	s_add_i32 m0, s68, 0x2000
	s_add_u32 s68, s42, 0x100000
	v_lshl_add_u64 v[212:213], s[42:43], 0, v[132:133]
	s_addc_u32 s69, s43, 0
	s_add_i32 s70, s60, s51
	global_load_lds_dwordx4 v[212:213], off
	v_lshl_add_u64 v[214:215], s[68:69], 0, v[130:131]
	s_mov_b32 m0, s70
	v_lshl_add_u64 v[216:217], s[46:47], 0, v[132:133]
	global_load_lds_dwordx4 v[214:215], off
	v_lshl_add_u64 v[214:215], s[68:69], 0, v[132:133]
	s_add_i32 m0, s70, 0x2000
	s_nop 0
	global_load_lds_dwordx4 v[214:215], off
	v_lshl_add_u64 v[214:215], s[46:47], 0, v[130:131]
	s_mov_b32 m0, s29
	s_nop 0
	global_load_lds_dwordx4 v[214:215], off
	s_mov_b32 m0, s52
	s_nop 0
	global_load_lds_dwordx4 v[216:217], off
	s_waitcnt lgkmcnt(0)
	s_barrier
	s_setprio 1
	v_mfma_f32_16x16x32_bf16 v[62:65], v[144:147], v[176:179], v[62:65]
	v_mfma_f32_16x16x32_bf16 v[58:61], v[152:155], v[176:179], v[58:61]
	v_mfma_f32_16x16x32_bf16 v[54:57], v[144:147], v[184:187], v[54:57]
	v_mfma_f32_16x16x32_bf16 v[46:49], v[152:155], v[184:187], v[46:49]
	v_mfma_f32_16x16x32_bf16 v[38:41], v[144:147], v[196:199], v[38:41]
	v_mfma_f32_16x16x32_bf16 v[30:33], v[152:155], v[196:199], v[30:33]
	v_mfma_f32_16x16x32_bf16 v[22:25], v[144:147], v[204:207], v[22:25]
	v_mfma_f32_16x16x32_bf16 v[14:17], v[152:155], v[204:207], v[14:17]
	v_mfma_f32_16x16x32_bf16 v[62:65], v[148:151], v[180:183], v[62:65]
	v_mfma_f32_16x16x32_bf16 v[58:61], v[156:159], v[180:183], v[58:61]
	v_mfma_f32_16x16x32_bf16 v[54:57], v[148:151], v[188:191], v[54:57]
	v_mfma_f32_16x16x32_bf16 v[46:49], v[156:159], v[188:191], v[46:49]
	v_mfma_f32_16x16x32_bf16 v[38:41], v[148:151], v[200:203], v[38:41]
	v_mfma_f32_16x16x32_bf16 v[30:33], v[156:159], v[200:203], v[30:33]
	v_mfma_f32_16x16x32_bf16 v[22:25], v[148:151], v[208:211], v[22:25]
	v_mfma_f32_16x16x32_bf16 v[14:17], v[156:159], v[208:211], v[14:17]
	v_mfma_f32_16x16x32_bf16 v[50:53], v[160:163], v[176:179], v[50:53]
	v_mfma_f32_16x16x32_bf16 v[42:45], v[168:171], v[176:179], v[42:45]
	v_mfma_f32_16x16x32_bf16 v[34:37], v[160:163], v[184:187], v[34:37]
	v_mfma_f32_16x16x32_bf16 v[26:29], v[168:171], v[184:187], v[26:29]
	v_mfma_f32_16x16x32_bf16 v[18:21], v[160:163], v[196:199], v[18:21]
	v_mfma_f32_16x16x32_bf16 v[10:13], v[168:171], v[196:199], v[10:13]
	v_mfma_f32_16x16x32_bf16 v[6:9], v[160:163], v[204:207], v[6:9]
	v_mfma_f32_16x16x32_bf16 v[2:5], v[168:171], v[204:207], v[2:5]
	v_mfma_f32_16x16x32_bf16 v[50:53], v[164:167], v[180:183], v[50:53]
	v_mfma_f32_16x16x32_bf16 v[42:45], v[172:175], v[180:183], v[42:45]
	v_mfma_f32_16x16x32_bf16 v[34:37], v[164:167], v[188:191], v[34:37]
	v_mfma_f32_16x16x32_bf16 v[26:29], v[172:175], v[188:191], v[26:29]
	v_mfma_f32_16x16x32_bf16 v[18:21], v[164:167], v[200:203], v[18:21]
	v_mfma_f32_16x16x32_bf16 v[10:13], v[172:175], v[200:203], v[10:13]
	v_mfma_f32_16x16x32_bf16 v[6:9], v[164:167], v[208:211], v[6:9]
	v_mfma_f32_16x16x32_bf16 v[2:5], v[172:175], v[208:211], v[2:5]
	s_setprio 0
	s_waitcnt vmcnt(8)
	s_barrier
	s_add_i32 s68, 0, 0x18000
	s_add_i32 s69, 0, 0x1c000
	v_add_u32_e32 v156, s68, v139
	v_add_u32_e32 v172, s69, v139
	ds_read_b128 v[144:147], v156
	ds_read_b128 v[148:151], v156 offset:1024
	ds_read_b128 v[152:155], v156 offset:2048
	ds_read_b128 v[156:159], v156 offset:3072
	ds_read_b128 v[160:163], v172
	ds_read_b128 v[164:167], v172 offset:1024
	ds_read_b128 v[168:171], v172 offset:2048
	ds_read_b128 v[172:175], v172 offset:3072
	s_add_u32 s46, s46, 0x100000
	s_addc_u32 s47, s47, 0
	s_mov_b32 m0, s53
	v_lshl_add_u64 v[218:219], s[46:47], 0, v[130:131]
	ds_read_b128 v[176:179], v143 offset:32768
	ds_read_b128 v[180:183], v143 offset:33792
	ds_read_b128 v[184:187], v143 offset:34816
	ds_read_b128 v[188:191], v143 offset:35840
	ds_read_b128 v[196:199], v143 offset:36864
	ds_read_b128 v[200:203], v143 offset:37888
	ds_read_b128 v[204:207], v143 offset:38912
	ds_read_b128 v[208:211], v143 offset:39936
	global_load_lds_dwordx4 v[218:219], off
	v_lshl_add_u64 v[218:219], s[46:47], 0, v[132:133]
	s_mov_b32 m0, s54
	s_nop 0
	global_load_lds_dwordx4 v[218:219], off
	s_waitcnt lgkmcnt(0)
	s_barrier
	s_setprio 1
	v_mfma_f32_16x16x32_bf16 v[126:129], v[144:147], v[176:179], v[126:129]
	v_mfma_f32_16x16x32_bf16 v[122:125], v[152:155], v[176:179], v[122:125]
	v_mfma_f32_16x16x32_bf16 v[118:121], v[144:147], v[184:187], v[118:121]
	v_mfma_f32_16x16x32_bf16 v[110:113], v[152:155], v[184:187], v[110:113]
	v_mfma_f32_16x16x32_bf16 v[102:105], v[144:147], v[196:199], v[102:105]
	v_mfma_f32_16x16x32_bf16 v[94:97], v[152:155], v[196:199], v[94:97]
	v_mfma_f32_16x16x32_bf16 v[86:89], v[144:147], v[204:207], v[86:89]
	v_mfma_f32_16x16x32_bf16 v[78:81], v[152:155], v[204:207], v[78:81]
	v_mfma_f32_16x16x32_bf16 v[126:129], v[148:151], v[180:183], v[126:129]
	v_mfma_f32_16x16x32_bf16 v[122:125], v[156:159], v[180:183], v[122:125]
	v_mfma_f32_16x16x32_bf16 v[118:121], v[148:151], v[188:191], v[118:121]
	v_mfma_f32_16x16x32_bf16 v[110:113], v[156:159], v[188:191], v[110:113]
	v_mfma_f32_16x16x32_bf16 v[102:105], v[148:151], v[200:203], v[102:105]
	v_mfma_f32_16x16x32_bf16 v[94:97], v[156:159], v[200:203], v[94:97]
	v_mfma_f32_16x16x32_bf16 v[86:89], v[148:151], v[208:211], v[86:89]
	v_mfma_f32_16x16x32_bf16 v[78:81], v[156:159], v[208:211], v[78:81]
	v_mfma_f32_16x16x32_bf16 v[114:117], v[160:163], v[176:179], v[114:117]
	v_mfma_f32_16x16x32_bf16 v[106:109], v[168:171], v[176:179], v[106:109]
	v_mfma_f32_16x16x32_bf16 v[98:101], v[160:163], v[184:187], v[98:101]
	v_mfma_f32_16x16x32_bf16 v[90:93], v[168:171], v[184:187], v[90:93]
	v_mfma_f32_16x16x32_bf16 v[82:85], v[160:163], v[196:199], v[82:85]
	v_mfma_f32_16x16x32_bf16 v[74:77], v[168:171], v[196:199], v[74:77]
	v_mfma_f32_16x16x32_bf16 v[70:73], v[160:163], v[204:207], v[70:73]
	v_mfma_f32_16x16x32_bf16 v[66:69], v[168:171], v[204:207], v[66:69]
	v_mfma_f32_16x16x32_bf16 v[114:117], v[164:167], v[180:183], v[114:117]
	v_mfma_f32_16x16x32_bf16 v[106:109], v[172:175], v[180:183], v[106:109]
	v_mfma_f32_16x16x32_bf16 v[98:101], v[164:167], v[188:191], v[98:101]
	v_mfma_f32_16x16x32_bf16 v[90:93], v[172:175], v[188:191], v[90:93]
	v_mfma_f32_16x16x32_bf16 v[82:85], v[164:167], v[200:203], v[82:85]
	v_mfma_f32_16x16x32_bf16 v[74:77], v[172:175], v[200:203], v[74:77]
	v_mfma_f32_16x16x32_bf16 v[70:73], v[164:167], v[208:211], v[70:73]
	v_mfma_f32_16x16x32_bf16 v[66:69], v[172:175], v[208:211], v[66:69]
	s_setprio 0
	s_waitcnt vmcnt(8)
	s_barrier
	s_add_i32 s46, s68, s51
	v_lshl_add_u64 v[192:193], v[192:193], 0, s[10:11]
	s_mov_b32 m0, s46
	ds_read_b128 v[176:179], v143 offset:49152
	ds_read_b128 v[180:183], v143 offset:50176
	ds_read_b128 v[184:187], v143 offset:51200
	ds_read_b128 v[188:191], v143 offset:52224
	ds_read_b128 v[196:199], v143 offset:53248
	ds_read_b128 v[200:203], v143 offset:54272
	ds_read_b128 v[204:207], v143 offset:55296
	ds_read_b128 v[208:211], v143 offset:56320
	global_load_lds_dwordx4 v[192:193], off
	s_add_i32 m0, s46, 0x2000
	s_add_u32 s42, s42, 0x100080
	v_lshl_add_u64 v[192:193], v[212:213], 0, s[10:11]
	s_addc_u32 s43, s43, 0
	s_add_i32 s46, s69, s51
	global_load_lds_dwordx4 v[192:193], off
	v_lshl_add_u64 v[192:193], s[42:43], 0, v[130:131]
	s_mov_b32 m0, s46
	s_nop 0
	global_load_lds_dwordx4 v[192:193], off
	v_lshl_add_u64 v[192:193], s[42:43], 0, v[132:133]
	s_add_i32 m0, s46, 0x2000
	s_nop 0
	global_load_lds_dwordx4 v[192:193], off
	v_lshl_add_u64 v[192:193], v[214:215], 0, s[10:11]
	s_mov_b32 m0, s56
	s_nop 0
	global_load_lds_dwordx4 v[192:193], off
	v_lshl_add_u64 v[192:193], v[216:217], 0, s[10:11]
	s_mov_b32 m0, s57
	s_nop 0
	global_load_lds_dwordx4 v[192:193], off
	s_waitcnt lgkmcnt(0)
	s_barrier
	s_nop 0
	s_setprio 1
	v_mfma_f32_16x16x32_bf16 v[62:65], v[144:147], v[176:179], v[62:65]
	v_mfma_f32_16x16x32_bf16 v[58:61], v[152:155], v[176:179], v[58:61]
	v_mfma_f32_16x16x32_bf16 v[54:57], v[144:147], v[184:187], v[54:57]
	v_mfma_f32_16x16x32_bf16 v[46:49], v[152:155], v[184:187], v[46:49]
	v_mfma_f32_16x16x32_bf16 v[38:41], v[144:147], v[196:199], v[38:41]
	v_mfma_f32_16x16x32_bf16 v[30:33], v[152:155], v[196:199], v[30:33]
	v_mfma_f32_16x16x32_bf16 v[22:25], v[144:147], v[204:207], v[22:25]
	v_mfma_f32_16x16x32_bf16 v[14:17], v[152:155], v[204:207], v[14:17]
	v_mfma_f32_16x16x32_bf16 v[62:65], v[148:151], v[180:183], v[62:65]
	v_mfma_f32_16x16x32_bf16 v[58:61], v[156:159], v[180:183], v[58:61]
	v_mfma_f32_16x16x32_bf16 v[54:57], v[148:151], v[188:191], v[54:57]
	v_mfma_f32_16x16x32_bf16 v[46:49], v[156:159], v[188:191], v[46:49]
	v_mfma_f32_16x16x32_bf16 v[38:41], v[148:151], v[200:203], v[38:41]
	v_mfma_f32_16x16x32_bf16 v[30:33], v[156:159], v[200:203], v[30:33]
	v_mfma_f32_16x16x32_bf16 v[22:25], v[148:151], v[208:211], v[22:25]
	v_mfma_f32_16x16x32_bf16 v[14:17], v[156:159], v[208:211], v[14:17]
	v_mfma_f32_16x16x32_bf16 v[50:53], v[160:163], v[176:179], v[50:53]
	v_mfma_f32_16x16x32_bf16 v[42:45], v[168:171], v[176:179], v[42:45]
	v_mfma_f32_16x16x32_bf16 v[34:37], v[160:163], v[184:187], v[34:37]
	v_mfma_f32_16x16x32_bf16 v[26:29], v[168:171], v[184:187], v[26:29]
	v_mfma_f32_16x16x32_bf16 v[18:21], v[160:163], v[196:199], v[18:21]
	v_mfma_f32_16x16x32_bf16 v[10:13], v[168:171], v[196:199], v[10:13]
	v_mfma_f32_16x16x32_bf16 v[6:9], v[160:163], v[204:207], v[6:9]
	v_mfma_f32_16x16x32_bf16 v[2:5], v[168:171], v[204:207], v[2:5]
	v_mfma_f32_16x16x32_bf16 v[50:53], v[164:167], v[180:183], v[50:53]
	v_mfma_f32_16x16x32_bf16 v[42:45], v[172:175], v[180:183], v[42:45]
	v_mfma_f32_16x16x32_bf16 v[34:37], v[164:167], v[188:191], v[34:37]
	v_mfma_f32_16x16x32_bf16 v[26:29], v[172:175], v[188:191], v[26:29]
	v_mfma_f32_16x16x32_bf16 v[18:21], v[164:167], v[200:203], v[18:21]
	v_mfma_f32_16x16x32_bf16 v[10:13], v[172:175], v[200:203], v[10:13]
	v_mfma_f32_16x16x32_bf16 v[6:9], v[164:167], v[208:211], v[6:9]
	v_mfma_f32_16x16x32_bf16 v[2:5], v[172:175], v[208:211], v[2:5]
	s_setprio 0
	s_waitcnt vmcnt(8)
	s_barrier
	s_add_i32 s67, s67, 2
	s_add_u32 s40, s40, 0x100
	s_addc_u32 s41, s41, 0
	s_add_u32 s65, s65, 0x100
	s_addc_u32 s66, s66, 0
	s_cmp_gt_u32 s67, 61
	s_cbranch_scc0 .Lkt_L_2
	s_branch .Lkt_exit_2
.Lkt_T_2:
	ds_read_b128 v[144:147], v140
	ds_read_b128 v[148:151], v140 offset:1024
	ds_read_b128 v[152:155], v140 offset:2048
	ds_read_b128 v[156:159], v140 offset:3072
	ds_read_b128 v[160:163], v142
	ds_read_b128 v[164:167], v142 offset:1024
	ds_read_b128 v[168:171], v142 offset:2048
	ds_read_b128 v[172:175], v142 offset:3072
	s_add_u32 s42, s40, 0xfff00080
	s_addc_u32 s43, s41, -1
	s_cmp_eq_u32 s67, 60
	s_cselect_b32 s47, s27, s43
	s_cselect_b32 s46, s63, s42
	s_cselect_b32 s43, s25, s66
	s_cselect_b32 s42, s64, s65
	v_lshl_add_u64 v[192:193], s[40:41], 0, v[134:135]
	s_add_i32 m0, s29, 0xc000
	ds_read_b128 v[176:179], v143
	ds_read_b128 v[180:183], v143 offset:1024
	ds_read_b128 v[184:187], v143 offset:2048
	ds_read_b128 v[188:191], v143 offset:3072
	ds_read_b128 v[196:199], v143 offset:4096
	ds_read_b128 v[200:203], v143 offset:5120
	ds_read_b128 v[204:207], v143 offset:6144
	ds_read_b128 v[208:211], v143 offset:7168
	global_load_lds_dwordx4 v[192:193], off
	v_lshl_add_u64 v[192:193], s[40:41], 0, v[136:137]
	s_add_i32 m0, s29, 0xe000
	s_nop 0
	global_load_lds_dwordx4 v[192:193], off
	s_waitcnt vmcnt(8)
	s_waitcnt lgkmcnt(0)
	s_barrier
	s_setprio 1
	v_mfma_f32_16x16x32_bf16 v[126:129], v[144:147], v[176:179], v[126:129]
	v_mfma_f32_16x16x32_bf16 v[122:125], v[152:155], v[176:179], v[122:125]
	v_mfma_f32_16x16x32_bf16 v[118:121], v[144:147], v[184:187], v[118:121]
	v_mfma_f32_16x16x32_bf16 v[110:113], v[152:155], v[184:187], v[110:113]
	v_mfma_f32_16x16x32_bf16 v[102:105], v[144:147], v[196:199], v[102:105]
	v_mfma_f32_16x16x32_bf16 v[94:97], v[152:155], v[196:199], v[94:97]
	v_mfma_f32_16x16x32_bf16 v[86:89], v[144:147], v[204:207], v[86:89]
	v_mfma_f32_16x16x32_bf16 v[78:81], v[152:155], v[204:207], v[78:81]
	v_mfma_f32_16x16x32_bf16 v[126:129], v[148:151], v[180:183], v[126:129]
	v_mfma_f32_16x16x32_bf16 v[122:125], v[156:159], v[180:183], v[122:125]
	v_mfma_f32_16x16x32_bf16 v[118:121], v[148:151], v[188:191], v[118:121]
	v_mfma_f32_16x16x32_bf16 v[110:113], v[156:159], v[188:191], v[110:113]
	v_mfma_f32_16x16x32_bf16 v[102:105], v[148:151], v[200:203], v[102:105]
	v_mfma_f32_16x16x32_bf16 v[94:97], v[156:159], v[200:203], v[94:97]
	v_mfma_f32_16x16x32_bf16 v[86:89], v[148:151], v[208:211], v[86:89]
	v_mfma_f32_16x16x32_bf16 v[78:81], v[156:159], v[208:211], v[78:81]
	v_mfma_f32_16x16x32_bf16 v[114:117], v[160:163], v[176:179], v[114:117]
	v_mfma_f32_16x16x32_bf16 v[106:109], v[168:171], v[176:179], v[106:109]
	v_mfma_f32_16x16x32_bf16 v[98:101], v[160:163], v[184:187], v[98:101]
	v_mfma_f32_16x16x32_bf16 v[90:93], v[168:171], v[184:187], v[90:93]
	v_mfma_f32_16x16x32_bf16 v[82:85], v[160:163], v[196:199], v[82:85]
	v_mfma_f32_16x16x32_bf16 v[74:77], v[168:171], v[196:199], v[74:77]
	v_mfma_f32_16x16x32_bf16 v[70:73], v[160:163], v[204:207], v[70:73]
	v_mfma_f32_16x16x32_bf16 v[66:69], v[168:171], v[204:207], v[66:69]
	v_mfma_f32_16x16x32_bf16 v[114:117], v[164:167], v[180:183], v[114:117]
	v_mfma_f32_16x16x32_bf16 v[106:109], v[172:175], v[180:183], v[106:109]
	v_mfma_f32_16x16x32_bf16 v[98:101], v[164:167], v[188:191], v[98:101]
	v_mfma_f32_16x16x32_bf16 v[90:93], v[172:175], v[188:191], v[90:93]
	v_mfma_f32_16x16x32_bf16 v[82:85], v[164:167], v[200:203], v[82:85]
	v_mfma_f32_16x16x32_bf16 v[74:77], v[172:175], v[200:203], v[74:77]
	v_mfma_f32_16x16x32_bf16 v[70:73], v[164:167], v[208:211], v[70:73]
	v_mfma_f32_16x16x32_bf16 v[66:69], v[172:175], v[208:211], v[66:69]
	s_setprio 0
	s_barrier
	s_add_i32 s68, s59, s51
	v_lshl_add_u64 v[192:193], s[42:43], 0, v[130:131]
	s_mov_b32 m0, s68
	ds_read_b128 v[176:179], v143 offset:16384
	ds_read_b128 v[180:183], v143 offset:17408
	ds_read_b128 v[184:187], v143 offset:18432
	ds_read_b128 v[188:191], v143 offset:19456
	ds_read_b128 v[196:199], v143 offset:20480
	ds_read_b128 v[200:203], v143 offset:21504
	ds_read_b128 v[204:207], v143 offset:22528
	ds_read_b128 v[208:211], v143 offset:23552
	global_load_lds_dwordx4 v[192:193], off
	s_add_i32 m0, s68, 0x2000
	s_add_u32 s68, s42, 0x100000
	v_lshl_add_u64 v[212:213], s[42:43], 0, v[132:133]
	s_addc_u32 s69, s43, 0
	s_add_i32 s70, s60, s51
	global_load_lds_dwordx4 v[212:213], off
	v_lshl_add_u64 v[214:215], s[68:69], 0, v[130:131]
	s_mov_b32 m0, s70
	v_lshl_add_u64 v[216:217], s[46:47], 0, v[132:133]
	global_load_lds_dwordx4 v[214:215], off
	v_lshl_add_u64 v[214:215], s[68:69], 0, v[132:133]
	s_add_i32 m0, s70, 0x2000
	s_nop 0
	global_load_lds_dwordx4 v[214:215], off
	v_lshl_add_u64 v[214:215], s[46:47], 0, v[130:131]
	s_mov_b32 m0, s29
	s_nop 0
	global_load_lds_dwordx4 v[214:215], off
	s_mov_b32 m0, s52
	s_nop 0
	global_load_lds_dwordx4 v[216:217], off
	s_waitcnt vmcnt(8)
	s_waitcnt lgkmcnt(0)
	s_barrier
	s_setprio 1
	v_mfma_f32_16x16x32_bf16 v[62:65], v[144:147], v[176:179], v[62:65]
	v_mfma_f32_16x16x32_bf16 v[58:61], v[152:155], v[176:179], v[58:61]
	v_mfma_f32_16x16x32_bf16 v[54:57], v[144:147], v[184:187], v[54:57]
	v_mfma_f32_16x16x32_bf16 v[46:49], v[152:155], v[184:187], v[46:49]
	v_mfma_f32_16x16x32_bf16 v[38:41], v[144:147], v[196:199], v[38:41]
	v_mfma_f32_16x16x32_bf16 v[30:33], v[152:155], v[196:199], v[30:33]
	v_mfma_f32_16x16x32_bf16 v[22:25], v[144:147], v[204:207], v[22:25]
	v_mfma_f32_16x16x32_bf16 v[14:17], v[152:155], v[204:207], v[14:17]
	v_mfma_f32_16x16x32_bf16 v[62:65], v[148:151], v[180:183], v[62:65]
	v_mfma_f32_16x16x32_bf16 v[58:61], v[156:159], v[180:183], v[58:61]
	v_mfma_f32_16x16x32_bf16 v[54:57], v[148:151], v[188:191], v[54:57]
	v_mfma_f32_16x16x32_bf16 v[46:49], v[156:159], v[188:191], v[46:49]
	v_mfma_f32_16x16x32_bf16 v[38:41], v[148:151], v[200:203], v[38:41]
	v_mfma_f32_16x16x32_bf16 v[30:33], v[156:159], v[200:203], v[30:33]
	v_mfma_f32_16x16x32_bf16 v[22:25], v[148:151], v[208:211], v[22:25]
	v_mfma_f32_16x16x32_bf16 v[14:17], v[156:159], v[208:211], v[14:17]
	v_mfma_f32_16x16x32_bf16 v[50:53], v[160:163], v[176:179], v[50:53]
	v_mfma_f32_16x16x32_bf16 v[42:45], v[168:171], v[176:179], v[42:45]
	v_mfma_f32_16x16x32_bf16 v[34:37], v[160:163], v[184:187], v[34:37]
	v_mfma_f32_16x16x32_bf16 v[26:29], v[168:171], v[184:187], v[26:29]
	v_mfma_f32_16x16x32_bf16 v[18:21], v[160:163], v[196:199], v[18:21]
	v_mfma_f32_16x16x32_bf16 v[10:13], v[168:171], v[196:199], v[10:13]
	v_mfma_f32_16x16x32_bf16 v[6:9], v[160:163], v[204:207], v[6:9]
	v_mfma_f32_16x16x32_bf16 v[2:5], v[168:171], v[204:207], v[2:5]
	v_mfma_f32_16x16x32_bf16 v[50:53], v[164:167], v[180:183], v[50:53]
	v_mfma_f32_16x16x32_bf16 v[42:45], v[172:175], v[180:183], v[42:45]
	v_mfma_f32_16x16x32_bf16 v[34:37], v[164:167], v[188:191], v[34:37]
	v_mfma_f32_16x16x32_bf16 v[26:29], v[172:175], v[188:191], v[26:29]
	v_mfma_f32_16x16x32_bf16 v[18:21], v[164:167], v[200:203], v[18:21]
	v_mfma_f32_16x16x32_bf16 v[10:13], v[172:175], v[200:203], v[10:13]
	v_mfma_f32_16x16x32_bf16 v[6:9], v[164:167], v[208:211], v[6:9]
	v_mfma_f32_16x16x32_bf16 v[2:5], v[172:175], v[208:211], v[2:5]
	s_setprio 0
	s_barrier
	s_add_i32 s68, 0, 0x18000
	s_add_i32 s69, 0, 0x1c000
	v_add_u32_e32 v156, s68, v139
	v_add_u32_e32 v172, s69, v139
	ds_read_b128 v[144:147], v156
	ds_read_b128 v[148:151], v156 offset:1024
	ds_read_b128 v[152:155], v156 offset:2048
	ds_read_b128 v[156:159], v156 offset:3072
	ds_read_b128 v[160:163], v172
	ds_read_b128 v[164:167], v172 offset:1024
	ds_read_b128 v[168:171], v172 offset:2048
	ds_read_b128 v[172:175], v172 offset:3072
	s_add_u32 s46, s46, 0x100000
	s_addc_u32 s47, s47, 0
	s_mov_b32 m0, s53
	v_lshl_add_u64 v[218:219], s[46:47], 0, v[130:131]
	ds_read_b128 v[176:179], v143 offset:32768
	ds_read_b128 v[180:183], v143 offset:33792
	ds_read_b128 v[184:187], v143 offset:34816
	ds_read_b128 v[188:191], v143 offset:35840
	ds_read_b128 v[196:199], v143 offset:36864
	ds_read_b128 v[200:203], v143 offset:37888
	ds_read_b128 v[204:207], v143 offset:38912
	ds_read_b128 v[208:211], v143 offset:39936
	global_load_lds_dwordx4 v[218:219], off
	v_lshl_add_u64 v[218:219], s[46:47], 0, v[132:133]
	s_mov_b32 m0, s54
	s_nop 0
	global_load_lds_dwordx4 v[218:219], off
	s_waitcnt vmcnt(8)
	s_waitcnt lgkmcnt(0)
	s_barrier
	s_setprio 1
	v_mfma_f32_16x16x32_bf16 v[126:129], v[144:147], v[176:179], v[126:129]
	v_mfma_f32_16x16x32_bf16 v[122:125], v[152:155], v[176:179], v[122:125]
	v_mfma_f32_16x16x32_bf16 v[118:121], v[144:147], v[184:187], v[118:121]
	v_mfma_f32_16x16x32_bf16 v[110:113], v[152:155], v[184:187], v[110:113]
	v_mfma_f32_16x16x32_bf16 v[102:105], v[144:147], v[196:199], v[102:105]
	v_mfma_f32_16x16x32_bf16 v[94:97], v[152:155], v[196:199], v[94:97]
	v_mfma_f32_16x16x32_bf16 v[86:89], v[144:147], v[204:207], v[86:89]
	v_mfma_f32_16x16x32_bf16 v[78:81], v[152:155], v[204:207], v[78:81]
	v_mfma_f32_16x16x32_bf16 v[126:129], v[148:151], v[180:183], v[126:129]
	v_mfma_f32_16x16x32_bf16 v[122:125], v[156:159], v[180:183], v[122:125]
	v_mfma_f32_16x16x32_bf16 v[118:121], v[148:151], v[188:191], v[118:121]
	v_mfma_f32_16x16x32_bf16 v[110:113], v[156:159], v[188:191], v[110:113]
	v_mfma_f32_16x16x32_bf16 v[102:105], v[148:151], v[200:203], v[102:105]
	v_mfma_f32_16x16x32_bf16 v[94:97], v[156:159], v[200:203], v[94:97]
	v_mfma_f32_16x16x32_bf16 v[86:89], v[148:151], v[208:211], v[86:89]
	v_mfma_f32_16x16x32_bf16 v[78:81], v[156:159], v[208:211], v[78:81]
	v_mfma_f32_16x16x32_bf16 v[114:117], v[160:163], v[176:179], v[114:117]
	v_mfma_f32_16x16x32_bf16 v[106:109], v[168:171], v[176:179], v[106:109]
	v_mfma_f32_16x16x32_bf16 v[98:101], v[160:163], v[184:187], v[98:101]
	v_mfma_f32_16x16x32_bf16 v[90:93], v[168:171], v[184:187], v[90:93]
	v_mfma_f32_16x16x32_bf16 v[82:85], v[160:163], v[196:199], v[82:85]
	v_mfma_f32_16x16x32_bf16 v[74:77], v[168:171], v[196:199], v[74:77]
	v_mfma_f32_16x16x32_bf16 v[70:73], v[160:163], v[204:207], v[70:73]
	v_mfma_f32_16x16x32_bf16 v[66:69], v[168:171], v[204:207], v[66:69]
	v_mfma_f32_16x16x32_bf16 v[114:117], v[164:167], v[180:183], v[114:117]
	v_mfma_f32_16x16x32_bf16 v[106:109], v[172:175], v[180:183], v[106:109]
	v_mfma_f32_16x16x32_bf16 v[98:101], v[164:167], v[188:191], v[98:101]
	v_mfma_f32_16x16x32_bf16 v[90:93], v[172:175], v[188:191], v[90:93]
	v_mfma_f32_16x16x32_bf16 v[82:85], v[164:167], v[200:203], v[82:85]
	v_mfma_f32_16x16x32_bf16 v[74:77], v[172:175], v[200:203], v[74:77]
	v_mfma_f32_16x16x32_bf16 v[70:73], v[164:167], v[208:211], v[70:73]
	v_mfma_f32_16x16x32_bf16 v[66:69], v[172:175], v[208:211], v[66:69]
	s_setprio 0
	s_barrier
	s_add_i32 s46, s68, s51
	v_lshl_add_u64 v[192:193], v[192:193], 0, s[10:11]
	s_mov_b32 m0, s46
	ds_read_b128 v[176:179], v143 offset:49152
	ds_read_b128 v[180:183], v143 offset:50176
	ds_read_b128 v[184:187], v143 offset:51200
	ds_read_b128 v[188:191], v143 offset:52224
	ds_read_b128 v[196:199], v143 offset:53248
	ds_read_b128 v[200:203], v143 offset:54272
	ds_read_b128 v[204:207], v143 offset:55296
	ds_read_b128 v[208:211], v143 offset:56320
	global_load_lds_dwordx4 v[192:193], off
	s_add_i32 m0, s46, 0x2000
	s_add_u32 s42, s42, 0x100080
	v_lshl_add_u64 v[192:193], v[212:213], 0, s[10:11]
	s_addc_u32 s43, s43, 0
	s_add_i32 s46, s69, s51
	global_load_lds_dwordx4 v[192:193], off
	v_lshl_add_u64 v[192:193], s[42:43], 0, v[130:131]
	s_mov_b32 m0, s46
	s_nop 0
	global_load_lds_dwordx4 v[192:193], off
	v_lshl_add_u64 v[192:193], s[42:43], 0, v[132:133]
	s_add_i32 m0, s46, 0x2000
	s_nop 0
	global_load_lds_dwordx4 v[192:193], off
	v_lshl_add_u64 v[192:193], v[214:215], 0, s[10:11]
	s_mov_b32 m0, s56
	s_nop 0
	global_load_lds_dwordx4 v[192:193], off
	v_lshl_add_u64 v[192:193], v[216:217], 0, s[10:11]
	s_mov_b32 m0, s57
	s_nop 0
	global_load_lds_dwordx4 v[192:193], off
	s_nop 0
	s_waitcnt vmcnt(8)
	s_waitcnt lgkmcnt(0)
	s_barrier
	s_setprio 1
	v_mfma_f32_16x16x32_bf16 v[62:65], v[144:147], v[176:179], v[62:65]
	v_mfma_f32_16x16x32_bf16 v[58:61], v[152:155], v[176:179], v[58:61]
	v_mfma_f32_16x16x32_bf16 v[54:57], v[144:147], v[184:187], v[54:57]
	v_mfma_f32_16x16x32_bf16 v[46:49], v[152:155], v[184:187], v[46:49]
	v_mfma_f32_16x16x32_bf16 v[38:41], v[144:147], v[196:199], v[38:41]
	v_mfma_f32_16x16x32_bf16 v[30:33], v[152:155], v[196:199], v[30:33]
	v_mfma_f32_16x16x32_bf16 v[22:25], v[144:147], v[204:207], v[22:25]
	v_mfma_f32_16x16x32_bf16 v[14:17], v[152:155], v[204:207], v[14:17]
	v_mfma_f32_16x16x32_bf16 v[62:65], v[148:151], v[180:183], v[62:65]
	v_mfma_f32_16x16x32_bf16 v[58:61], v[156:159], v[180:183], v[58:61]
	v_mfma_f32_16x16x32_bf16 v[54:57], v[148:151], v[188:191], v[54:57]
	v_mfma_f32_16x16x32_bf16 v[46:49], v[156:159], v[188:191], v[46:49]
	v_mfma_f32_16x16x32_bf16 v[38:41], v[148:151], v[200:203], v[38:41]
	v_mfma_f32_16x16x32_bf16 v[30:33], v[156:159], v[200:203], v[30:33]
	v_mfma_f32_16x16x32_bf16 v[22:25], v[148:151], v[208:211], v[22:25]
	v_mfma_f32_16x16x32_bf16 v[14:17], v[156:159], v[208:211], v[14:17]
	v_mfma_f32_16x16x32_bf16 v[50:53], v[160:163], v[176:179], v[50:53]
	v_mfma_f32_16x16x32_bf16 v[42:45], v[168:171], v[176:179], v[42:45]
	v_mfma_f32_16x16x32_bf16 v[34:37], v[160:163], v[184:187], v[34:37]
	v_mfma_f32_16x16x32_bf16 v[26:29], v[168:171], v[184:187], v[26:29]
	v_mfma_f32_16x16x32_bf16 v[18:21], v[160:163], v[196:199], v[18:21]
	v_mfma_f32_16x16x32_bf16 v[10:13], v[168:171], v[196:199], v[10:13]
	v_mfma_f32_16x16x32_bf16 v[6:9], v[160:163], v[204:207], v[6:9]
	v_mfma_f32_16x16x32_bf16 v[2:5], v[168:171], v[204:207], v[2:5]
	v_mfma_f32_16x16x32_bf16 v[50:53], v[164:167], v[180:183], v[50:53]
	v_mfma_f32_16x16x32_bf16 v[42:45], v[172:175], v[180:183], v[42:45]
	v_mfma_f32_16x16x32_bf16 v[34:37], v[164:167], v[188:191], v[34:37]
	v_mfma_f32_16x16x32_bf16 v[26:29], v[172:175], v[188:191], v[26:29]
	v_mfma_f32_16x16x32_bf16 v[18:21], v[164:167], v[200:203], v[18:21]
	v_mfma_f32_16x16x32_bf16 v[10:13], v[172:175], v[200:203], v[10:13]
	v_mfma_f32_16x16x32_bf16 v[6:9], v[164:167], v[208:211], v[6:9]
	v_mfma_f32_16x16x32_bf16 v[2:5], v[172:175], v[208:211], v[2:5]
	s_setprio 0
	s_barrier
	s_add_i32 s67, s67, 2
	s_add_u32 s40, s40, 0x100
	s_addc_u32 s41, s41, 0
	s_add_u32 s65, s65, 0x100
	s_addc_u32 s66, s66, 0
	s_cmp_gt_u32 s67, 61
	s_cbranch_scc0 .Lkt_T_2
	s_nop 7

.Lkt_L_3:
	ds_read_b128 v[158:161], v155
	ds_read_b128 v[162:165], v155 offset:1024
	ds_read_b128 v[166:169], v155 offset:2048
	ds_read_b128 v[170:173], v155 offset:3072
	ds_read_b128 v[174:177], v156
	ds_read_b128 v[178:181], v156 offset:1024
	ds_read_b128 v[182:185], v156 offset:2048
	ds_read_b128 v[186:189], v156 offset:3072
	s_add_u32 s28, s26, 0xfff00080
	s_addc_u32 s29, s27, -1
	s_cmp_eq_u32 s58, 60
	s_cselect_b32 s31, s21, s29
	s_cselect_b32 s30, s54, s28
	s_cselect_b32 s29, s19, s57
	s_cselect_b32 s28, s55, s56
	v_lshl_add_u64 v[224:225], s[26:27], 0, v[138:139]
	s_add_i32 m0, s17, 0xc000
	ds_read_b128 v[190:193], v157
	ds_read_b128 v[196:199], v157 offset:1024
	ds_read_b128 v[200:203], v157 offset:2048
	ds_read_b128 v[204:207], v157 offset:3072
	ds_read_b128 v[208:211], v157 offset:4096
	ds_read_b128 v[212:215], v157 offset:5120
	ds_read_b128 v[216:219], v157 offset:6144
	ds_read_b128 v[220:223], v157 offset:7168
	global_load_lds_dwordx4 v[224:225], off
	v_lshl_add_u64 v[224:225], s[26:27], 0, v[140:141]
	s_add_i32 m0, s17, 0xe000
	s_nop 0
	global_load_lds_dwordx4 v[224:225], off
	s_waitcnt lgkmcnt(0)
	s_barrier
	s_nop 0
	s_setprio 1
	v_mfma_f32_16x16x32_bf16 v[126:129], v[158:161], v[190:193], v[126:129]
	v_mfma_f32_16x16x32_bf16 v[122:125], v[166:169], v[190:193], v[122:125]
	v_mfma_f32_16x16x32_bf16 v[118:121], v[158:161], v[200:203], v[118:121]
	v_mfma_f32_16x16x32_bf16 v[114:117], v[166:169], v[200:203], v[114:117]
	v_mfma_f32_16x16x32_bf16 v[102:105], v[158:161], v[208:211], v[102:105]
	v_mfma_f32_16x16x32_bf16 v[98:101], v[166:169], v[208:211], v[98:101]
	v_mfma_f32_16x16x32_bf16 v[86:89], v[158:161], v[216:219], v[86:89]
	v_mfma_f32_16x16x32_bf16 v[82:85], v[166:169], v[216:219], v[82:85]
	v_mfma_f32_16x16x32_bf16 v[126:129], v[162:165], v[196:199], v[126:129]
	v_mfma_f32_16x16x32_bf16 v[122:125], v[170:173], v[196:199], v[122:125]
	v_mfma_f32_16x16x32_bf16 v[118:121], v[162:165], v[204:207], v[118:121]
	v_mfma_f32_16x16x32_bf16 v[114:117], v[170:173], v[204:207], v[114:117]
	v_mfma_f32_16x16x32_bf16 v[102:105], v[162:165], v[212:215], v[102:105]
	v_mfma_f32_16x16x32_bf16 v[98:101], v[170:173], v[212:215], v[98:101]
	v_mfma_f32_16x16x32_bf16 v[86:89], v[162:165], v[220:223], v[86:89]
	v_mfma_f32_16x16x32_bf16 v[82:85], v[170:173], v[220:223], v[82:85]
	v_mfma_f32_16x16x32_bf16 v[110:113], v[174:177], v[190:193], v[110:113]
	v_mfma_f32_16x16x32_bf16 v[106:109], v[182:185], v[190:193], v[106:109]
	v_mfma_f32_16x16x32_bf16 v[94:97], v[174:177], v[200:203], v[94:97]
	v_mfma_f32_16x16x32_bf16 v[90:93], v[182:185], v[200:203], v[90:93]
	v_mfma_f32_16x16x32_bf16 v[78:81], v[174:177], v[208:211], v[78:81]
	v_mfma_f32_16x16x32_bf16 v[74:77], v[182:185], v[208:211], v[74:77]
	v_mfma_f32_16x16x32_bf16 v[70:73], v[174:177], v[216:219], v[70:73]
	v_mfma_f32_16x16x32_bf16 v[66:69], v[182:185], v[216:219], v[66:69]
	v_mfma_f32_16x16x32_bf16 v[110:113], v[178:181], v[196:199], v[110:113]
	v_mfma_f32_16x16x32_bf16 v[106:109], v[186:189], v[196:199], v[106:109]
	v_mfma_f32_16x16x32_bf16 v[94:97], v[178:181], v[204:207], v[94:97]
	v_mfma_f32_16x16x32_bf16 v[90:93], v[186:189], v[204:207], v[90:93]
	v_mfma_f32_16x16x32_bf16 v[78:81], v[178:181], v[212:215], v[78:81]
	v_mfma_f32_16x16x32_bf16 v[74:77], v[186:189], v[212:215], v[74:77]
	v_mfma_f32_16x16x32_bf16 v[70:73], v[178:181], v[220:223], v[70:73]
	v_mfma_f32_16x16x32_bf16 v[66:69], v[186:189], v[220:223], v[66:69]
	s_setprio 0
	s_waitcnt vmcnt(8)
	s_barrier
	s_add_i32 s59, s50, s41
	v_lshl_add_u64 v[224:225], s[28:29], 0, v[134:135]
	s_mov_b32 m0, s59
	ds_read_b128 v[190:193], v157 offset:16384
	ds_read_b128 v[196:199], v157 offset:17408
	ds_read_b128 v[200:203], v157 offset:18432
	ds_read_b128 v[204:207], v157 offset:19456
	ds_read_b128 v[208:211], v157 offset:20480
	ds_read_b128 v[212:215], v157 offset:21504
	ds_read_b128 v[216:219], v157 offset:22528
	ds_read_b128 v[220:223], v157 offset:23552
	global_load_lds_dwordx4 v[224:225], off
	s_add_i32 m0, s59, 0x2000
	s_add_u32 s60, s28, 0x100000
	v_lshl_add_u64 v[226:227], s[28:29], 0, v[136:137]
	s_addc_u32 s61, s29, 0
	s_add_i32 s59, s51, s41
	global_load_lds_dwordx4 v[226:227], off
	v_lshl_add_u64 v[228:229], s[60:61], 0, v[134:135]
	s_mov_b32 m0, s59
	v_lshl_add_u64 v[230:231], s[30:31], 0, v[132:133]
	global_load_lds_dwordx4 v[228:229], off
	v_lshl_add_u64 v[228:229], s[60:61], 0, v[136:137]
	s_add_i32 m0, s59, 0x2000
	s_nop 0
	global_load_lds_dwordx4 v[228:229], off
	v_lshl_add_u64 v[228:229], s[30:31], 0, v[130:131]
	s_mov_b32 m0, s17
	s_nop 0
	global_load_lds_dwordx4 v[228:229], off
	s_mov_b32 m0, s42
	s_nop 0
	global_load_lds_dwordx4 v[230:231], off
	s_waitcnt lgkmcnt(0)
	s_barrier
	s_setprio 1
	v_mfma_f32_16x16x32_bf16 v[62:65], v[158:161], v[190:193], v[62:65]
	v_mfma_f32_16x16x32_bf16 v[58:61], v[166:169], v[190:193], v[58:61]
	v_mfma_f32_16x16x32_bf16 v[54:57], v[158:161], v[200:203], v[54:57]
	v_mfma_f32_16x16x32_bf16 v[50:53], v[166:169], v[200:203], v[50:53]
	v_mfma_f32_16x16x32_bf16 v[38:41], v[158:161], v[208:211], v[38:41]
	v_mfma_f32_16x16x32_bf16 v[34:37], v[166:169], v[208:211], v[34:37]
	v_mfma_f32_16x16x32_bf16 v[22:25], v[158:161], v[216:219], v[22:25]
	v_mfma_f32_16x16x32_bf16 v[18:21], v[166:169], v[216:219], v[18:21]
	v_mfma_f32_16x16x32_bf16 v[62:65], v[162:165], v[196:199], v[62:65]
	v_mfma_f32_16x16x32_bf16 v[58:61], v[170:173], v[196:199], v[58:61]
	v_mfma_f32_16x16x32_bf16 v[54:57], v[162:165], v[204:207], v[54:57]
	v_mfma_f32_16x16x32_bf16 v[50:53], v[170:173], v[204:207], v[50:53]
	v_mfma_f32_16x16x32_bf16 v[38:41], v[162:165], v[212:215], v[38:41]
	v_mfma_f32_16x16x32_bf16 v[34:37], v[170:173], v[212:215], v[34:37]
	v_mfma_f32_16x16x32_bf16 v[22:25], v[162:165], v[220:223], v[22:25]
	v_mfma_f32_16x16x32_bf16 v[18:21], v[170:173], v[220:223], v[18:21]
	v_mfma_f32_16x16x32_bf16 v[46:49], v[174:177], v[190:193], v[46:49]
	v_mfma_f32_16x16x32_bf16 v[42:45], v[182:185], v[190:193], v[42:45]
	v_mfma_f32_16x16x32_bf16 v[30:33], v[174:177], v[200:203], v[30:33]
	v_mfma_f32_16x16x32_bf16 v[26:29], v[182:185], v[200:203], v[26:29]
	v_mfma_f32_16x16x32_bf16 v[14:17], v[174:177], v[208:211], v[14:17]
	v_mfma_f32_16x16x32_bf16 v[10:13], v[182:185], v[208:211], v[10:13]
	v_mfma_f32_16x16x32_bf16 v[6:9], v[174:177], v[216:219], v[6:9]
	v_mfma_f32_16x16x32_bf16 v[2:5], v[182:185], v[216:219], v[2:5]
	v_mfma_f32_16x16x32_bf16 v[46:49], v[178:181], v[196:199], v[46:49]
	v_mfma_f32_16x16x32_bf16 v[42:45], v[186:189], v[196:199], v[42:45]
	v_mfma_f32_16x16x32_bf16 v[30:33], v[178:181], v[204:207], v[30:33]
	v_mfma_f32_16x16x32_bf16 v[26:29], v[186:189], v[204:207], v[26:29]
	v_mfma_f32_16x16x32_bf16 v[14:17], v[178:181], v[212:215], v[14:17]
	v_mfma_f32_16x16x32_bf16 v[10:13], v[186:189], v[212:215], v[10:13]
	v_mfma_f32_16x16x32_bf16 v[6:9], v[178:181], v[220:223], v[6:9]
	v_mfma_f32_16x16x32_bf16 v[2:5], v[186:189], v[220:223], v[2:5]
	s_setprio 0
	s_waitcnt vmcnt(8)
	s_barrier
	s_add_i32 s59, 0, 0x18000
	s_add_i32 s60, 0, 0x1c000
	v_add_u32_e32 v170, s59, v153
	v_add_u32_e32 v186, s60, v153
	ds_read_b128 v[158:161], v170
	ds_read_b128 v[162:165], v170 offset:1024
	ds_read_b128 v[166:169], v170 offset:2048
	ds_read_b128 v[170:173], v170 offset:3072
	ds_read_b128 v[174:177], v186
	ds_read_b128 v[178:181], v186 offset:1024
	ds_read_b128 v[182:185], v186 offset:2048
	ds_read_b128 v[186:189], v186 offset:3072
	s_add_u32 s30, s30, 0x100000
	s_addc_u32 s31, s31, 0
	s_mov_b32 m0, s43
	v_lshl_add_u64 v[232:233], s[30:31], 0, v[130:131]
	ds_read_b128 v[190:193], v157 offset:32768
	ds_read_b128 v[196:199], v157 offset:33792
	ds_read_b128 v[200:203], v157 offset:34816
	ds_read_b128 v[204:207], v157 offset:35840
	ds_read_b128 v[208:211], v157 offset:36864
	ds_read_b128 v[212:215], v157 offset:37888
	ds_read_b128 v[216:219], v157 offset:38912
	ds_read_b128 v[220:223], v157 offset:39936
	global_load_lds_dwordx4 v[232:233], off
	v_lshl_add_u64 v[232:233], s[30:31], 0, v[132:133]
	s_mov_b32 m0, s45
	s_nop 0
	global_load_lds_dwordx4 v[232:233], off
	s_waitcnt lgkmcnt(0)
	s_barrier
	s_setprio 1
	v_mfma_f32_16x16x32_bf16 v[126:129], v[158:161], v[190:193], v[126:129]
	v_mfma_f32_16x16x32_bf16 v[122:125], v[166:169], v[190:193], v[122:125]
	v_mfma_f32_16x16x32_bf16 v[118:121], v[158:161], v[200:203], v[118:121]
	v_mfma_f32_16x16x32_bf16 v[114:117], v[166:169], v[200:203], v[114:117]
	v_mfma_f32_16x16x32_bf16 v[102:105], v[158:161], v[208:211], v[102:105]
	v_mfma_f32_16x16x32_bf16 v[98:101], v[166:169], v[208:211], v[98:101]
	v_mfma_f32_16x16x32_bf16 v[86:89], v[158:161], v[216:219], v[86:89]
	v_mfma_f32_16x16x32_bf16 v[82:85], v[166:169], v[216:219], v[82:85]
	v_mfma_f32_16x16x32_bf16 v[126:129], v[162:165], v[196:199], v[126:129]
	v_mfma_f32_16x16x32_bf16 v[122:125], v[170:173], v[196:199], v[122:125]
	v_mfma_f32_16x16x32_bf16 v[118:121], v[162:165], v[204:207], v[118:121]
	v_mfma_f32_16x16x32_bf16 v[114:117], v[170:173], v[204:207], v[114:117]
	v_mfma_f32_16x16x32_bf16 v[102:105], v[162:165], v[212:215], v[102:105]
	v_mfma_f32_16x16x32_bf16 v[98:101], v[170:173], v[212:215], v[98:101]
	v_mfma_f32_16x16x32_bf16 v[86:89], v[162:165], v[220:223], v[86:89]
	v_mfma_f32_16x16x32_bf16 v[82:85], v[170:173], v[220:223], v[82:85]
	v_mfma_f32_16x16x32_bf16 v[110:113], v[174:177], v[190:193], v[110:113]
	v_mfma_f32_16x16x32_bf16 v[106:109], v[182:185], v[190:193], v[106:109]
	v_mfma_f32_16x16x32_bf16 v[94:97], v[174:177], v[200:203], v[94:97]
	v_mfma_f32_16x16x32_bf16 v[90:93], v[182:185], v[200:203], v[90:93]
	v_mfma_f32_16x16x32_bf16 v[78:81], v[174:177], v[208:211], v[78:81]
	v_mfma_f32_16x16x32_bf16 v[74:77], v[182:185], v[208:211], v[74:77]
	v_mfma_f32_16x16x32_bf16 v[70:73], v[174:177], v[216:219], v[70:73]
	v_mfma_f32_16x16x32_bf16 v[66:69], v[182:185], v[216:219], v[66:69]
	v_mfma_f32_16x16x32_bf16 v[110:113], v[178:181], v[196:199], v[110:113]
	v_mfma_f32_16x16x32_bf16 v[106:109], v[186:189], v[196:199], v[106:109]
	v_mfma_f32_16x16x32_bf16 v[94:97], v[178:181], v[204:207], v[94:97]
	v_mfma_f32_16x16x32_bf16 v[90:93], v[186:189], v[204:207], v[90:93]
	v_mfma_f32_16x16x32_bf16 v[78:81], v[178:181], v[212:215], v[78:81]
	v_mfma_f32_16x16x32_bf16 v[74:77], v[186:189], v[212:215], v[74:77]
	v_mfma_f32_16x16x32_bf16 v[70:73], v[178:181], v[220:223], v[70:73]
	v_mfma_f32_16x16x32_bf16 v[66:69], v[186:189], v[220:223], v[66:69]
	s_setprio 0
	s_waitcnt vmcnt(8)
	s_barrier
	s_add_i32 s30, s59, s41
	v_lshl_add_u64 v[224:225], v[224:225], 0, s[12:13]
	s_mov_b32 m0, s30
	ds_read_b128 v[190:193], v157 offset:49152
	ds_read_b128 v[196:199], v157 offset:50176
	ds_read_b128 v[200:203], v157 offset:51200
	ds_read_b128 v[204:207], v157 offset:52224
	ds_read_b128 v[208:211], v157 offset:53248
	ds_read_b128 v[212:215], v157 offset:54272
	ds_read_b128 v[216:219], v157 offset:55296
	ds_read_b128 v[220:223], v157 offset:56320
	global_load_lds_dwordx4 v[224:225], off
	s_add_i32 m0, s30, 0x2000
	s_add_u32 s28, s28, 0x100080
	v_lshl_add_u64 v[224:225], v[226:227], 0, s[12:13]
	s_addc_u32 s29, s29, 0
	s_add_i32 s30, s60, s41
	global_load_lds_dwordx4 v[224:225], off
	v_lshl_add_u64 v[224:225], s[28:29], 0, v[134:135]
	s_mov_b32 m0, s30
	s_nop 0
	global_load_lds_dwordx4 v[224:225], off
	v_lshl_add_u64 v[224:225], s[28:29], 0, v[136:137]
	s_add_i32 m0, s30, 0x2000
	s_nop 0
	global_load_lds_dwordx4 v[224:225], off
	v_lshl_add_u64 v[224:225], v[228:229], 0, s[12:13]
	s_mov_b32 m0, s47
	s_nop 0
	global_load_lds_dwordx4 v[224:225], off
	v_lshl_add_u64 v[224:225], v[230:231], 0, s[12:13]
	s_mov_b32 m0, s48
	s_nop 0
	global_load_lds_dwordx4 v[224:225], off
	s_waitcnt lgkmcnt(0)
	s_barrier
	s_nop 0
	s_setprio 1
	v_mfma_f32_16x16x32_bf16 v[62:65], v[158:161], v[190:193], v[62:65]
	v_mfma_f32_16x16x32_bf16 v[58:61], v[166:169], v[190:193], v[58:61]
	v_mfma_f32_16x16x32_bf16 v[54:57], v[158:161], v[200:203], v[54:57]
	v_mfma_f32_16x16x32_bf16 v[50:53], v[166:169], v[200:203], v[50:53]
	v_mfma_f32_16x16x32_bf16 v[38:41], v[158:161], v[208:211], v[38:41]
	v_mfma_f32_16x16x32_bf16 v[34:37], v[166:169], v[208:211], v[34:37]
	v_mfma_f32_16x16x32_bf16 v[22:25], v[158:161], v[216:219], v[22:25]
	v_mfma_f32_16x16x32_bf16 v[18:21], v[166:169], v[216:219], v[18:21]
	v_mfma_f32_16x16x32_bf16 v[62:65], v[162:165], v[196:199], v[62:65]
	v_mfma_f32_16x16x32_bf16 v[58:61], v[170:173], v[196:199], v[58:61]
	v_mfma_f32_16x16x32_bf16 v[54:57], v[162:165], v[204:207], v[54:57]
	v_mfma_f32_16x16x32_bf16 v[50:53], v[170:173], v[204:207], v[50:53]
	v_mfma_f32_16x16x32_bf16 v[38:41], v[162:165], v[212:215], v[38:41]
	v_mfma_f32_16x16x32_bf16 v[34:37], v[170:173], v[212:215], v[34:37]
	v_mfma_f32_16x16x32_bf16 v[22:25], v[162:165], v[220:223], v[22:25]
	v_mfma_f32_16x16x32_bf16 v[18:21], v[170:173], v[220:223], v[18:21]
	v_mfma_f32_16x16x32_bf16 v[46:49], v[174:177], v[190:193], v[46:49]
	v_mfma_f32_16x16x32_bf16 v[42:45], v[182:185], v[190:193], v[42:45]
	v_mfma_f32_16x16x32_bf16 v[30:33], v[174:177], v[200:203], v[30:33]
	v_mfma_f32_16x16x32_bf16 v[26:29], v[182:185], v[200:203], v[26:29]
	v_mfma_f32_16x16x32_bf16 v[14:17], v[174:177], v[208:211], v[14:17]
	v_mfma_f32_16x16x32_bf16 v[10:13], v[182:185], v[208:211], v[10:13]
	v_mfma_f32_16x16x32_bf16 v[6:9], v[174:177], v[216:219], v[6:9]
	v_mfma_f32_16x16x32_bf16 v[2:5], v[182:185], v[216:219], v[2:5]
	v_mfma_f32_16x16x32_bf16 v[46:49], v[178:181], v[196:199], v[46:49]
	v_mfma_f32_16x16x32_bf16 v[42:45], v[186:189], v[196:199], v[42:45]
	v_mfma_f32_16x16x32_bf16 v[30:33], v[178:181], v[204:207], v[30:33]
	v_mfma_f32_16x16x32_bf16 v[26:29], v[186:189], v[204:207], v[26:29]
	v_mfma_f32_16x16x32_bf16 v[14:17], v[178:181], v[212:215], v[14:17]
	v_mfma_f32_16x16x32_bf16 v[10:13], v[186:189], v[212:215], v[10:13]
	v_mfma_f32_16x16x32_bf16 v[6:9], v[178:181], v[220:223], v[6:9]
	v_mfma_f32_16x16x32_bf16 v[2:5], v[186:189], v[220:223], v[2:5]
	s_setprio 0
	s_waitcnt vmcnt(8)
	s_barrier
	s_add_i32 s58, s58, 2
	s_add_u32 s26, s26, 0x100
	s_addc_u32 s27, s27, 0
	s_add_u32 s56, s56, 0x100
	s_addc_u32 s57, s57, 0
	s_cmp_gt_u32 s58, 61
	s_cbranch_scc0 .Lkt_L_3
	s_branch .Lkt_exit_3
.Lkt_T_3:
	ds_read_b128 v[158:161], v155
	ds_read_b128 v[162:165], v155 offset:1024
	ds_read_b128 v[166:169], v155 offset:2048
	ds_read_b128 v[170:173], v155 offset:3072
	ds_read_b128 v[174:177], v156
	ds_read_b128 v[178:181], v156 offset:1024
	ds_read_b128 v[182:185], v156 offset:2048
	ds_read_b128 v[186:189], v156 offset:3072
	s_add_u32 s28, s26, 0xfff00080
	s_addc_u32 s29, s27, -1
	s_cmp_eq_u32 s58, 60
	s_cselect_b32 s31, s21, s29
	s_cselect_b32 s30, s54, s28
	s_cselect_b32 s29, s19, s57
	s_cselect_b32 s28, s55, s56
	v_lshl_add_u64 v[224:225], s[26:27], 0, v[138:139]
	s_add_i32 m0, s17, 0xc000
	ds_read_b128 v[190:193], v157
	ds_read_b128 v[196:199], v157 offset:1024
	ds_read_b128 v[200:203], v157 offset:2048
	ds_read_b128 v[204:207], v157 offset:3072
	ds_read_b128 v[208:211], v157 offset:4096
	ds_read_b128 v[212:215], v157 offset:5120
	ds_read_b128 v[216:219], v157 offset:6144
	ds_read_b128 v[220:223], v157 offset:7168
	global_load_lds_dwordx4 v[224:225], off
	v_lshl_add_u64 v[224:225], s[26:27], 0, v[140:141]
	s_add_i32 m0, s17, 0xe000
	s_nop 0
	global_load_lds_dwordx4 v[224:225], off
	s_waitcnt vmcnt(8)
	s_waitcnt lgkmcnt(0)
	s_barrier
	s_setprio 1
	v_mfma_f32_16x16x32_bf16 v[126:129], v[158:161], v[190:193], v[126:129]
	v_mfma_f32_16x16x32_bf16 v[122:125], v[166:169], v[190:193], v[122:125]
	v_mfma_f32_16x16x32_bf16 v[118:121], v[158:161], v[200:203], v[118:121]
	v_mfma_f32_16x16x32_bf16 v[114:117], v[166:169], v[200:203], v[114:117]
	v_mfma_f32_16x16x32_bf16 v[102:105], v[158:161], v[208:211], v[102:105]
	v_mfma_f32_16x16x32_bf16 v[98:101], v[166:169], v[208:211], v[98:101]
	v_mfma_f32_16x16x32_bf16 v[86:89], v[158:161], v[216:219], v[86:89]
	v_mfma_f32_16x16x32_bf16 v[82:85], v[166:169], v[216:219], v[82:85]
	v_mfma_f32_16x16x32_bf16 v[126:129], v[162:165], v[196:199], v[126:129]
	v_mfma_f32_16x16x32_bf16 v[122:125], v[170:173], v[196:199], v[122:125]
	v_mfma_f32_16x16x32_bf16 v[118:121], v[162:165], v[204:207], v[118:121]
	v_mfma_f32_16x16x32_bf16 v[114:117], v[170:173], v[204:207], v[114:117]
	v_mfma_f32_16x16x32_bf16 v[102:105], v[162:165], v[212:215], v[102:105]
	v_mfma_f32_16x16x32_bf16 v[98:101], v[170:173], v[212:215], v[98:101]
	v_mfma_f32_16x16x32_bf16 v[86:89], v[162:165], v[220:223], v[86:89]
	v_mfma_f32_16x16x32_bf16 v[82:85], v[170:173], v[220:223], v[82:85]
	v_mfma_f32_16x16x32_bf16 v[110:113], v[174:177], v[190:193], v[110:113]
	v_mfma_f32_16x16x32_bf16 v[106:109], v[182:185], v[190:193], v[106:109]
	v_mfma_f32_16x16x32_bf16 v[94:97], v[174:177], v[200:203], v[94:97]
	v_mfma_f32_16x16x32_bf16 v[90:93], v[182:185], v[200:203], v[90:93]
	v_mfma_f32_16x16x32_bf16 v[78:81], v[174:177], v[208:211], v[78:81]
	v_mfma_f32_16x16x32_bf16 v[74:77], v[182:185], v[208:211], v[74:77]
	v_mfma_f32_16x16x32_bf16 v[70:73], v[174:177], v[216:219], v[70:73]
	v_mfma_f32_16x16x32_bf16 v[66:69], v[182:185], v[216:219], v[66:69]
	v_mfma_f32_16x16x32_bf16 v[110:113], v[178:181], v[196:199], v[110:113]
	v_mfma_f32_16x16x32_bf16 v[106:109], v[186:189], v[196:199], v[106:109]
	v_mfma_f32_16x16x32_bf16 v[94:97], v[178:181], v[204:207], v[94:97]
	v_mfma_f32_16x16x32_bf16 v[90:93], v[186:189], v[204:207], v[90:93]
	v_mfma_f32_16x16x32_bf16 v[78:81], v[178:181], v[212:215], v[78:81]
	v_mfma_f32_16x16x32_bf16 v[74:77], v[186:189], v[212:215], v[74:77]
	v_mfma_f32_16x16x32_bf16 v[70:73], v[178:181], v[220:223], v[70:73]
	v_mfma_f32_16x16x32_bf16 v[66:69], v[186:189], v[220:223], v[66:69]
	s_setprio 0
	s_barrier
	s_add_i32 s59, s50, s41
	v_lshl_add_u64 v[224:225], s[28:29], 0, v[134:135]
	s_mov_b32 m0, s59
	ds_read_b128 v[190:193], v157 offset:16384
	ds_read_b128 v[196:199], v157 offset:17408
	ds_read_b128 v[200:203], v157 offset:18432
	ds_read_b128 v[204:207], v157 offset:19456
	ds_read_b128 v[208:211], v157 offset:20480
	ds_read_b128 v[212:215], v157 offset:21504
	ds_read_b128 v[216:219], v157 offset:22528
	ds_read_b128 v[220:223], v157 offset:23552
	global_load_lds_dwordx4 v[224:225], off
	s_add_i32 m0, s59, 0x2000
	s_add_u32 s60, s28, 0x100000
	v_lshl_add_u64 v[226:227], s[28:29], 0, v[136:137]
	s_addc_u32 s61, s29, 0
	s_add_i32 s59, s51, s41
	global_load_lds_dwordx4 v[226:227], off
	v_lshl_add_u64 v[228:229], s[60:61], 0, v[134:135]
	s_mov_b32 m0, s59
	v_lshl_add_u64 v[230:231], s[30:31], 0, v[132:133]
	global_load_lds_dwordx4 v[228:229], off
	v_lshl_add_u64 v[228:229], s[60:61], 0, v[136:137]
	s_add_i32 m0, s59, 0x2000
	s_nop 0
	global_load_lds_dwordx4 v[228:229], off
	v_lshl_add_u64 v[228:229], s[30:31], 0, v[130:131]
	s_mov_b32 m0, s17
	s_nop 0
	global_load_lds_dwordx4 v[228:229], off
	s_mov_b32 m0, s42
	s_nop 0
	global_load_lds_dwordx4 v[230:231], off
	s_waitcnt vmcnt(8)
	s_waitcnt lgkmcnt(0)
	s_barrier
	s_setprio 1
	v_mfma_f32_16x16x32_bf16 v[62:65], v[158:161], v[190:193], v[62:65]
	v_mfma_f32_16x16x32_bf16 v[58:61], v[166:169], v[190:193], v[58:61]
	v_mfma_f32_16x16x32_bf16 v[54:57], v[158:161], v[200:203], v[54:57]
	v_mfma_f32_16x16x32_bf16 v[50:53], v[166:169], v[200:203], v[50:53]
	v_mfma_f32_16x16x32_bf16 v[38:41], v[158:161], v[208:211], v[38:41]
	v_mfma_f32_16x16x32_bf16 v[34:37], v[166:169], v[208:211], v[34:37]
	v_mfma_f32_16x16x32_bf16 v[22:25], v[158:161], v[216:219], v[22:25]
	v_mfma_f32_16x16x32_bf16 v[18:21], v[166:169], v[216:219], v[18:21]
	v_mfma_f32_16x16x32_bf16 v[62:65], v[162:165], v[196:199], v[62:65]
	v_mfma_f32_16x16x32_bf16 v[58:61], v[170:173], v[196:199], v[58:61]
	v_mfma_f32_16x16x32_bf16 v[54:57], v[162:165], v[204:207], v[54:57]
	v_mfma_f32_16x16x32_bf16 v[50:53], v[170:173], v[204:207], v[50:53]
	v_mfma_f32_16x16x32_bf16 v[38:41], v[162:165], v[212:215], v[38:41]
	v_mfma_f32_16x16x32_bf16 v[34:37], v[170:173], v[212:215], v[34:37]
	v_mfma_f32_16x16x32_bf16 v[22:25], v[162:165], v[220:223], v[22:25]
	v_mfma_f32_16x16x32_bf16 v[18:21], v[170:173], v[220:223], v[18:21]
	v_mfma_f32_16x16x32_bf16 v[46:49], v[174:177], v[190:193], v[46:49]
	v_mfma_f32_16x16x32_bf16 v[42:45], v[182:185], v[190:193], v[42:45]
	v_mfma_f32_16x16x32_bf16 v[30:33], v[174:177], v[200:203], v[30:33]
	v_mfma_f32_16x16x32_bf16 v[26:29], v[182:185], v[200:203], v[26:29]
	v_mfma_f32_16x16x32_bf16 v[14:17], v[174:177], v[208:211], v[14:17]
	v_mfma_f32_16x16x32_bf16 v[10:13], v[182:185], v[208:211], v[10:13]
	v_mfma_f32_16x16x32_bf16 v[6:9], v[174:177], v[216:219], v[6:9]
	v_mfma_f32_16x16x32_bf16 v[2:5], v[182:185], v[216:219], v[2:5]
	v_mfma_f32_16x16x32_bf16 v[46:49], v[178:181], v[196:199], v[46:49]
	v_mfma_f32_16x16x32_bf16 v[42:45], v[186:189], v[196:199], v[42:45]
	v_mfma_f32_16x16x32_bf16 v[30:33], v[178:181], v[204:207], v[30:33]
	v_mfma_f32_16x16x32_bf16 v[26:29], v[186:189], v[204:207], v[26:29]
	v_mfma_f32_16x16x32_bf16 v[14:17], v[178:181], v[212:215], v[14:17]
	v_mfma_f32_16x16x32_bf16 v[10:13], v[186:189], v[212:215], v[10:13]
	v_mfma_f32_16x16x32_bf16 v[6:9], v[178:181], v[220:223], v[6:9]
	v_mfma_f32_16x16x32_bf16 v[2:5], v[186:189], v[220:223], v[2:5]
	s_setprio 0
	s_barrier
	s_add_i32 s59, 0, 0x18000
	s_add_i32 s60, 0, 0x1c000
	v_add_u32_e32 v170, s59, v153
	v_add_u32_e32 v186, s60, v153
	ds_read_b128 v[158:161], v170
	ds_read_b128 v[162:165], v170 offset:1024
	ds_read_b128 v[166:169], v170 offset:2048
	ds_read_b128 v[170:173], v170 offset:3072
	ds_read_b128 v[174:177], v186
	ds_read_b128 v[178:181], v186 offset:1024
	ds_read_b128 v[182:185], v186 offset:2048
	ds_read_b128 v[186:189], v186 offset:3072
	s_add_u32 s30, s30, 0x100000
	s_addc_u32 s31, s31, 0
	s_mov_b32 m0, s43
	v_lshl_add_u64 v[232:233], s[30:31], 0, v[130:131]
	ds_read_b128 v[190:193], v157 offset:32768
	ds_read_b128 v[196:199], v157 offset:33792
	ds_read_b128 v[200:203], v157 offset:34816
	ds_read_b128 v[204:207], v157 offset:35840
	ds_read_b128 v[208:211], v157 offset:36864
	ds_read_b128 v[212:215], v157 offset:37888
	ds_read_b128 v[216:219], v157 offset:38912
	ds_read_b128 v[220:223], v157 offset:39936
	global_load_lds_dwordx4 v[232:233], off
	v_lshl_add_u64 v[232:233], s[30:31], 0, v[132:133]
	s_mov_b32 m0, s45
	s_nop 0
	global_load_lds_dwordx4 v[232:233], off
	s_waitcnt vmcnt(8)
	s_waitcnt lgkmcnt(0)
	s_barrier
	s_setprio 1
	v_mfma_f32_16x16x32_bf16 v[126:129], v[158:161], v[190:193], v[126:129]
	v_mfma_f32_16x16x32_bf16 v[122:125], v[166:169], v[190:193], v[122:125]
	v_mfma_f32_16x16x32_bf16 v[118:121], v[158:161], v[200:203], v[118:121]
	v_mfma_f32_16x16x32_bf16 v[114:117], v[166:169], v[200:203], v[114:117]
	v_mfma_f32_16x16x32_bf16 v[102:105], v[158:161], v[208:211], v[102:105]
	v_mfma_f32_16x16x32_bf16 v[98:101], v[166:169], v[208:211], v[98:101]
	v_mfma_f32_16x16x32_bf16 v[86:89], v[158:161], v[216:219], v[86:89]
	v_mfma_f32_16x16x32_bf16 v[82:85], v[166:169], v[216:219], v[82:85]
	v_mfma_f32_16x16x32_bf16 v[126:129], v[162:165], v[196:199], v[126:129]
	v_mfma_f32_16x16x32_bf16 v[122:125], v[170:173], v[196:199], v[122:125]
	v_mfma_f32_16x16x32_bf16 v[118:121], v[162:165], v[204:207], v[118:121]
	v_mfma_f32_16x16x32_bf16 v[114:117], v[170:173], v[204:207], v[114:117]
	v_mfma_f32_16x16x32_bf16 v[102:105], v[162:165], v[212:215], v[102:105]
	v_mfma_f32_16x16x32_bf16 v[98:101], v[170:173], v[212:215], v[98:101]
	v_mfma_f32_16x16x32_bf16 v[86:89], v[162:165], v[220:223], v[86:89]
	v_mfma_f32_16x16x32_bf16 v[82:85], v[170:173], v[220:223], v[82:85]
	v_mfma_f32_16x16x32_bf16 v[110:113], v[174:177], v[190:193], v[110:113]
	v_mfma_f32_16x16x32_bf16 v[106:109], v[182:185], v[190:193], v[106:109]
	v_mfma_f32_16x16x32_bf16 v[94:97], v[174:177], v[200:203], v[94:97]
	v_mfma_f32_16x16x32_bf16 v[90:93], v[182:185], v[200:203], v[90:93]
	v_mfma_f32_16x16x32_bf16 v[78:81], v[174:177], v[208:211], v[78:81]
	v_mfma_f32_16x16x32_bf16 v[74:77], v[182:185], v[208:211], v[74:77]
	v_mfma_f32_16x16x32_bf16 v[70:73], v[174:177], v[216:219], v[70:73]
	v_mfma_f32_16x16x32_bf16 v[66:69], v[182:185], v[216:219], v[66:69]
	v_mfma_f32_16x16x32_bf16 v[110:113], v[178:181], v[196:199], v[110:113]
	v_mfma_f32_16x16x32_bf16 v[106:109], v[186:189], v[196:199], v[106:109]
	v_mfma_f32_16x16x32_bf16 v[94:97], v[178:181], v[204:207], v[94:97]
	v_mfma_f32_16x16x32_bf16 v[90:93], v[186:189], v[204:207], v[90:93]
	v_mfma_f32_16x16x32_bf16 v[78:81], v[178:181], v[212:215], v[78:81]
	v_mfma_f32_16x16x32_bf16 v[74:77], v[186:189], v[212:215], v[74:77]
	v_mfma_f32_16x16x32_bf16 v[70:73], v[178:181], v[220:223], v[70:73]
	v_mfma_f32_16x16x32_bf16 v[66:69], v[186:189], v[220:223], v[66:69]
	s_setprio 0
	s_barrier
	s_add_i32 s30, s59, s41
	v_lshl_add_u64 v[224:225], v[224:225], 0, s[12:13]
	s_mov_b32 m0, s30
	ds_read_b128 v[190:193], v157 offset:49152
	ds_read_b128 v[196:199], v157 offset:50176
	ds_read_b128 v[200:203], v157 offset:51200
	ds_read_b128 v[204:207], v157 offset:52224
	ds_read_b128 v[208:211], v157 offset:53248
	ds_read_b128 v[212:215], v157 offset:54272
	ds_read_b128 v[216:219], v157 offset:55296
	ds_read_b128 v[220:223], v157 offset:56320
	global_load_lds_dwordx4 v[224:225], off
	s_add_i32 m0, s30, 0x2000
	s_add_u32 s28, s28, 0x100080
	v_lshl_add_u64 v[224:225], v[226:227], 0, s[12:13]
	s_addc_u32 s29, s29, 0
	s_add_i32 s30, s60, s41
	global_load_lds_dwordx4 v[224:225], off
	v_lshl_add_u64 v[224:225], s[28:29], 0, v[134:135]
	s_mov_b32 m0, s30
	s_nop 0
	global_load_lds_dwordx4 v[224:225], off
	v_lshl_add_u64 v[224:225], s[28:29], 0, v[136:137]
	s_add_i32 m0, s30, 0x2000
	s_nop 0
	global_load_lds_dwordx4 v[224:225], off
	v_lshl_add_u64 v[224:225], v[228:229], 0, s[12:13]
	s_mov_b32 m0, s47
	s_nop 0
	global_load_lds_dwordx4 v[224:225], off
	v_lshl_add_u64 v[224:225], v[230:231], 0, s[12:13]
	s_mov_b32 m0, s48
	s_nop 0
	global_load_lds_dwordx4 v[224:225], off
	s_nop 0
	s_waitcnt vmcnt(8)
	s_waitcnt lgkmcnt(0)
	s_barrier
	s_setprio 1
	v_mfma_f32_16x16x32_bf16 v[62:65], v[158:161], v[190:193], v[62:65]
	v_mfma_f32_16x16x32_bf16 v[58:61], v[166:169], v[190:193], v[58:61]
	v_mfma_f32_16x16x32_bf16 v[54:57], v[158:161], v[200:203], v[54:57]
	v_mfma_f32_16x16x32_bf16 v[50:53], v[166:169], v[200:203], v[50:53]
	v_mfma_f32_16x16x32_bf16 v[38:41], v[158:161], v[208:211], v[38:41]
	v_mfma_f32_16x16x32_bf16 v[34:37], v[166:169], v[208:211], v[34:37]
	v_mfma_f32_16x16x32_bf16 v[22:25], v[158:161], v[216:219], v[22:25]
	v_mfma_f32_16x16x32_bf16 v[18:21], v[166:169], v[216:219], v[18:21]
	v_mfma_f32_16x16x32_bf16 v[62:65], v[162:165], v[196:199], v[62:65]
	v_mfma_f32_16x16x32_bf16 v[58:61], v[170:173], v[196:199], v[58:61]
	v_mfma_f32_16x16x32_bf16 v[54:57], v[162:165], v[204:207], v[54:57]
	v_mfma_f32_16x16x32_bf16 v[50:53], v[170:173], v[204:207], v[50:53]
	v_mfma_f32_16x16x32_bf16 v[38:41], v[162:165], v[212:215], v[38:41]
	v_mfma_f32_16x16x32_bf16 v[34:37], v[170:173], v[212:215], v[34:37]
	v_mfma_f32_16x16x32_bf16 v[22:25], v[162:165], v[220:223], v[22:25]
	v_mfma_f32_16x16x32_bf16 v[18:21], v[170:173], v[220:223], v[18:21]
	v_mfma_f32_16x16x32_bf16 v[46:49], v[174:177], v[190:193], v[46:49]
	v_mfma_f32_16x16x32_bf16 v[42:45], v[182:185], v[190:193], v[42:45]
	v_mfma_f32_16x16x32_bf16 v[30:33], v[174:177], v[200:203], v[30:33]
	v_mfma_f32_16x16x32_bf16 v[26:29], v[182:185], v[200:203], v[26:29]
	v_mfma_f32_16x16x32_bf16 v[14:17], v[174:177], v[208:211], v[14:17]
	v_mfma_f32_16x16x32_bf16 v[10:13], v[182:185], v[208:211], v[10:13]
	v_mfma_f32_16x16x32_bf16 v[6:9], v[174:177], v[216:219], v[6:9]
	v_mfma_f32_16x16x32_bf16 v[2:5], v[182:185], v[216:219], v[2:5]
	v_mfma_f32_16x16x32_bf16 v[46:49], v[178:181], v[196:199], v[46:49]
	v_mfma_f32_16x16x32_bf16 v[42:45], v[186:189], v[196:199], v[42:45]
	v_mfma_f32_16x16x32_bf16 v[30:33], v[178:181], v[204:207], v[30:33]
	v_mfma_f32_16x16x32_bf16 v[26:29], v[186:189], v[204:207], v[26:29]
	v_mfma_f32_16x16x32_bf16 v[14:17], v[178:181], v[212:215], v[14:17]
	v_mfma_f32_16x16x32_bf16 v[10:13], v[186:189], v[212:215], v[10:13]
	v_mfma_f32_16x16x32_bf16 v[6:9], v[178:181], v[220:223], v[6:9]
	v_mfma_f32_16x16x32_bf16 v[2:5], v[186:189], v[220:223], v[2:5]
	s_setprio 0
	s_barrier
	s_add_i32 s58, s58, 2
	s_add_u32 s26, s26, 0x100
	s_addc_u32 s27, s27, 0
	s_add_u32 s56, s56, 0x100
	s_addc_u32 s57, s57, 0
	s_cmp_gt_u32 s58, 61
	s_cbranch_scc0 .Lkt_T_3
	s_nop 7

.Lkt_L_4:
	ds_read_b128 v[152:155], v144
	ds_read_b128 v[156:159], v144 offset:1024
	ds_read_b128 v[160:163], v144 offset:2048
	ds_read_b128 v[164:167], v144 offset:3072
	ds_read_b128 v[168:171], v145
	ds_read_b128 v[172:175], v145 offset:1024
	ds_read_b128 v[176:179], v145 offset:2048
	ds_read_b128 v[180:183], v145 offset:3072
	s_add_u32 s42, s40, 0xfff00080
	s_addc_u32 s43, s41, -1
	s_cmp_eq_u32 s70, 60
	s_cselect_b32 s47, s27, s43
	s_cselect_b32 s46, s66, s42
	s_cselect_b32 s43, s25, s69
	s_cselect_b32 s42, s67, s68
	v_lshl_add_u64 v[192:193], s[40:41], 0, v[134:135]
	s_add_i32 m0, s29, 0xc000
	ds_read_b128 v[184:187], v150
	ds_read_b128 v[188:191], v150 offset:1024
	ds_read_b128 v[196:199], v150 offset:2048
	ds_read_b128 v[200:203], v150 offset:3072
	ds_read_b128 v[204:207], v150 offset:4096
	ds_read_b128 v[208:211], v150 offset:5120
	ds_read_b128 v[212:215], v150 offset:6144
	ds_read_b128 v[216:219], v150 offset:7168
	global_load_lds_dwordx4 v[192:193], off
	v_lshl_add_u64 v[192:193], s[40:41], 0, v[136:137]
	s_add_i32 m0, s29, 0xe000
	s_nop 0
	global_load_lds_dwordx4 v[192:193], off
	s_waitcnt lgkmcnt(0)
	s_barrier
	s_nop 0
	s_setprio 1
	v_mfma_f32_16x16x32_bf16 v[126:129], v[152:155], v[184:187], v[126:129]
	v_mfma_f32_16x16x32_bf16 v[122:125], v[160:163], v[184:187], v[122:125]
	v_mfma_f32_16x16x32_bf16 v[118:121], v[152:155], v[196:199], v[118:121]
	v_mfma_f32_16x16x32_bf16 v[110:113], v[160:163], v[196:199], v[110:113]
	v_mfma_f32_16x16x32_bf16 v[102:105], v[152:155], v[204:207], v[102:105]
	v_mfma_f32_16x16x32_bf16 v[94:97], v[160:163], v[204:207], v[94:97]
	v_mfma_f32_16x16x32_bf16 v[86:89], v[152:155], v[212:215], v[86:89]
	v_mfma_f32_16x16x32_bf16 v[78:81], v[160:163], v[212:215], v[78:81]
	v_mfma_f32_16x16x32_bf16 v[126:129], v[156:159], v[188:191], v[126:129]
	v_mfma_f32_16x16x32_bf16 v[122:125], v[164:167], v[188:191], v[122:125]
	v_mfma_f32_16x16x32_bf16 v[118:121], v[156:159], v[200:203], v[118:121]
	v_mfma_f32_16x16x32_bf16 v[110:113], v[164:167], v[200:203], v[110:113]
	v_mfma_f32_16x16x32_bf16 v[102:105], v[156:159], v[208:211], v[102:105]
	v_mfma_f32_16x16x32_bf16 v[94:97], v[164:167], v[208:211], v[94:97]
	v_mfma_f32_16x16x32_bf16 v[86:89], v[156:159], v[216:219], v[86:89]
	v_mfma_f32_16x16x32_bf16 v[78:81], v[164:167], v[216:219], v[78:81]
	v_mfma_f32_16x16x32_bf16 v[114:117], v[168:171], v[184:187], v[114:117]
	v_mfma_f32_16x16x32_bf16 v[106:109], v[176:179], v[184:187], v[106:109]
	v_mfma_f32_16x16x32_bf16 v[98:101], v[168:171], v[196:199], v[98:101]
	v_mfma_f32_16x16x32_bf16 v[90:93], v[176:179], v[196:199], v[90:93]
	v_mfma_f32_16x16x32_bf16 v[82:85], v[168:171], v[204:207], v[82:85]
	v_mfma_f32_16x16x32_bf16 v[74:77], v[176:179], v[204:207], v[74:77]
	v_mfma_f32_16x16x32_bf16 v[70:73], v[168:171], v[212:215], v[70:73]
	v_mfma_f32_16x16x32_bf16 v[66:69], v[176:179], v[212:215], v[66:69]
	v_mfma_f32_16x16x32_bf16 v[114:117], v[172:175], v[188:191], v[114:117]
	v_mfma_f32_16x16x32_bf16 v[106:109], v[180:183], v[188:191], v[106:109]
	v_mfma_f32_16x16x32_bf16 v[98:101], v[172:175], v[200:203], v[98:101]
	v_mfma_f32_16x16x32_bf16 v[90:93], v[180:183], v[200:203], v[90:93]
	v_mfma_f32_16x16x32_bf16 v[82:85], v[172:175], v[208:211], v[82:85]
	v_mfma_f32_16x16x32_bf16 v[74:77], v[180:183], v[208:211], v[74:77]
	v_mfma_f32_16x16x32_bf16 v[70:73], v[172:175], v[216:219], v[70:73]
	v_mfma_f32_16x16x32_bf16 v[66:69], v[180:183], v[216:219], v[66:69]
	s_setprio 0
	s_waitcnt vmcnt(8)
	s_barrier
	s_add_i32 s71, s62, s54
	v_lshl_add_u64 v[192:193], s[42:43], 0, v[130:131]
	s_mov_b32 m0, s71
	ds_read_b128 v[184:187], v150 offset:16384
	ds_read_b128 v[188:191], v150 offset:17408
	ds_read_b128 v[196:199], v150 offset:18432
	ds_read_b128 v[200:203], v150 offset:19456
	ds_read_b128 v[204:207], v150 offset:20480
	ds_read_b128 v[208:211], v150 offset:21504
	ds_read_b128 v[212:215], v150 offset:22528
	ds_read_b128 v[216:219], v150 offset:23552
	global_load_lds_dwordx4 v[192:193], off
	s_add_i32 m0, s71, 0x2000
	s_add_u32 s72, s42, 0x100000
	v_lshl_add_u64 v[220:221], s[42:43], 0, v[132:133]
	s_addc_u32 s73, s43, 0
	s_add_i32 s71, s63, s54
	global_load_lds_dwordx4 v[220:221], off
	v_lshl_add_u64 v[222:223], s[72:73], 0, v[130:131]
	s_mov_b32 m0, s71
	v_lshl_add_u64 v[224:225], s[46:47], 0, v[132:133]
	global_load_lds_dwordx4 v[222:223], off
	v_lshl_add_u64 v[222:223], s[72:73], 0, v[132:133]
	s_add_i32 m0, s71, 0x2000
	s_nop 0
	global_load_lds_dwordx4 v[222:223], off
	v_lshl_add_u64 v[222:223], s[46:47], 0, v[130:131]
	s_mov_b32 m0, s29
	s_nop 0
	global_load_lds_dwordx4 v[222:223], off
	s_mov_b32 m0, s55
	s_nop 0
	global_load_lds_dwordx4 v[224:225], off
	s_waitcnt lgkmcnt(0)
	s_barrier
	s_setprio 1
	v_mfma_f32_16x16x32_bf16 v[62:65], v[152:155], v[184:187], v[62:65]
	v_mfma_f32_16x16x32_bf16 v[58:61], v[160:163], v[184:187], v[58:61]
	v_mfma_f32_16x16x32_bf16 v[54:57], v[152:155], v[196:199], v[54:57]
	v_mfma_f32_16x16x32_bf16 v[46:49], v[160:163], v[196:199], v[46:49]
	v_mfma_f32_16x16x32_bf16 v[38:41], v[152:155], v[204:207], v[38:41]
	v_mfma_f32_16x16x32_bf16 v[30:33], v[160:163], v[204:207], v[30:33]
	v_mfma_f32_16x16x32_bf16 v[22:25], v[152:155], v[212:215], v[22:25]
	v_mfma_f32_16x16x32_bf16 v[14:17], v[160:163], v[212:215], v[14:17]
	v_mfma_f32_16x16x32_bf16 v[62:65], v[156:159], v[188:191], v[62:65]
	v_mfma_f32_16x16x32_bf16 v[58:61], v[164:167], v[188:191], v[58:61]
	v_mfma_f32_16x16x32_bf16 v[54:57], v[156:159], v[200:203], v[54:57]
	v_mfma_f32_16x16x32_bf16 v[46:49], v[164:167], v[200:203], v[46:49]
	v_mfma_f32_16x16x32_bf16 v[38:41], v[156:159], v[208:211], v[38:41]
	v_mfma_f32_16x16x32_bf16 v[30:33], v[164:167], v[208:211], v[30:33]
	v_mfma_f32_16x16x32_bf16 v[22:25], v[156:159], v[216:219], v[22:25]
	v_mfma_f32_16x16x32_bf16 v[14:17], v[164:167], v[216:219], v[14:17]
	v_mfma_f32_16x16x32_bf16 v[50:53], v[168:171], v[184:187], v[50:53]
	v_mfma_f32_16x16x32_bf16 v[42:45], v[176:179], v[184:187], v[42:45]
	v_mfma_f32_16x16x32_bf16 v[34:37], v[168:171], v[196:199], v[34:37]
	v_mfma_f32_16x16x32_bf16 v[26:29], v[176:179], v[196:199], v[26:29]
	v_mfma_f32_16x16x32_bf16 v[18:21], v[168:171], v[204:207], v[18:21]
	v_mfma_f32_16x16x32_bf16 v[10:13], v[176:179], v[204:207], v[10:13]
	v_mfma_f32_16x16x32_bf16 v[6:9], v[168:171], v[212:215], v[6:9]
	v_mfma_f32_16x16x32_bf16 v[2:5], v[176:179], v[212:215], v[2:5]
	v_mfma_f32_16x16x32_bf16 v[50:53], v[172:175], v[188:191], v[50:53]
	v_mfma_f32_16x16x32_bf16 v[42:45], v[180:183], v[188:191], v[42:45]
	v_mfma_f32_16x16x32_bf16 v[34:37], v[172:175], v[200:203], v[34:37]
	v_mfma_f32_16x16x32_bf16 v[26:29], v[180:183], v[200:203], v[26:29]
	v_mfma_f32_16x16x32_bf16 v[18:21], v[172:175], v[208:211], v[18:21]
	v_mfma_f32_16x16x32_bf16 v[10:13], v[180:183], v[208:211], v[10:13]
	v_mfma_f32_16x16x32_bf16 v[6:9], v[172:175], v[216:219], v[6:9]
	v_mfma_f32_16x16x32_bf16 v[2:5], v[180:183], v[216:219], v[2:5]
	s_setprio 0
	s_waitcnt vmcnt(8)
	s_barrier
	s_add_i32 s71, 0, 0x18000
	v_add_u32_e32 v151, s71, v142
	s_add_i32 s72, 0, 0x1c000
	ds_read_b128 v[152:155], v151
	ds_read_b128 v[156:159], v151 offset:1024
	ds_read_b128 v[160:163], v151 offset:2048
	ds_read_b128 v[164:167], v151 offset:3072
	v_add_u32_e32 v151, s72, v142
	ds_read_b128 v[168:171], v151
	ds_read_b128 v[172:175], v151 offset:1024
	ds_read_b128 v[176:179], v151 offset:2048
	ds_read_b128 v[180:183], v151 offset:3072
	s_add_u32 s46, s46, 0x100000
	s_addc_u32 s47, s47, 0
	s_mov_b32 m0, s56
	v_lshl_add_u64 v[226:227], s[46:47], 0, v[130:131]
	ds_read_b128 v[184:187], v150 offset:32768
	ds_read_b128 v[188:191], v150 offset:33792
	ds_read_b128 v[196:199], v150 offset:34816
	ds_read_b128 v[200:203], v150 offset:35840
	ds_read_b128 v[204:207], v150 offset:36864
	ds_read_b128 v[208:211], v150 offset:37888
	ds_read_b128 v[212:215], v150 offset:38912
	ds_read_b128 v[216:219], v150 offset:39936
	global_load_lds_dwordx4 v[226:227], off
	v_lshl_add_u64 v[226:227], s[46:47], 0, v[132:133]
	s_mov_b32 m0, s57
	s_nop 0
	global_load_lds_dwordx4 v[226:227], off
	s_waitcnt lgkmcnt(0)
	s_barrier
	s_setprio 1
	v_mfma_f32_16x16x32_bf16 v[126:129], v[152:155], v[184:187], v[126:129]
	v_mfma_f32_16x16x32_bf16 v[122:125], v[160:163], v[184:187], v[122:125]
	v_mfma_f32_16x16x32_bf16 v[118:121], v[152:155], v[196:199], v[118:121]
	v_mfma_f32_16x16x32_bf16 v[110:113], v[160:163], v[196:199], v[110:113]
	v_mfma_f32_16x16x32_bf16 v[102:105], v[152:155], v[204:207], v[102:105]
	v_mfma_f32_16x16x32_bf16 v[94:97], v[160:163], v[204:207], v[94:97]
	v_mfma_f32_16x16x32_bf16 v[86:89], v[152:155], v[212:215], v[86:89]
	v_mfma_f32_16x16x32_bf16 v[78:81], v[160:163], v[212:215], v[78:81]
	v_mfma_f32_16x16x32_bf16 v[126:129], v[156:159], v[188:191], v[126:129]
	v_mfma_f32_16x16x32_bf16 v[122:125], v[164:167], v[188:191], v[122:125]
	v_mfma_f32_16x16x32_bf16 v[118:121], v[156:159], v[200:203], v[118:121]
	v_mfma_f32_16x16x32_bf16 v[110:113], v[164:167], v[200:203], v[110:113]
	v_mfma_f32_16x16x32_bf16 v[102:105], v[156:159], v[208:211], v[102:105]
	v_mfma_f32_16x16x32_bf16 v[94:97], v[164:167], v[208:211], v[94:97]
	v_mfma_f32_16x16x32_bf16 v[86:89], v[156:159], v[216:219], v[86:89]
	v_mfma_f32_16x16x32_bf16 v[78:81], v[164:167], v[216:219], v[78:81]
	v_mfma_f32_16x16x32_bf16 v[114:117], v[168:171], v[184:187], v[114:117]
	v_mfma_f32_16x16x32_bf16 v[106:109], v[176:179], v[184:187], v[106:109]
	v_mfma_f32_16x16x32_bf16 v[98:101], v[168:171], v[196:199], v[98:101]
	v_mfma_f32_16x16x32_bf16 v[90:93], v[176:179], v[196:199], v[90:93]
	v_mfma_f32_16x16x32_bf16 v[82:85], v[168:171], v[204:207], v[82:85]
	v_mfma_f32_16x16x32_bf16 v[74:77], v[176:179], v[204:207], v[74:77]
	v_mfma_f32_16x16x32_bf16 v[70:73], v[168:171], v[212:215], v[70:73]
	v_mfma_f32_16x16x32_bf16 v[66:69], v[176:179], v[212:215], v[66:69]
	v_mfma_f32_16x16x32_bf16 v[114:117], v[172:175], v[188:191], v[114:117]
	v_mfma_f32_16x16x32_bf16 v[106:109], v[180:183], v[188:191], v[106:109]
	v_mfma_f32_16x16x32_bf16 v[98:101], v[172:175], v[200:203], v[98:101]
	v_mfma_f32_16x16x32_bf16 v[90:93], v[180:183], v[200:203], v[90:93]
	v_mfma_f32_16x16x32_bf16 v[82:85], v[172:175], v[208:211], v[82:85]
	v_mfma_f32_16x16x32_bf16 v[74:77], v[180:183], v[208:211], v[74:77]
	v_mfma_f32_16x16x32_bf16 v[70:73], v[172:175], v[216:219], v[70:73]
	v_mfma_f32_16x16x32_bf16 v[66:69], v[180:183], v[216:219], v[66:69]
	s_setprio 0
	s_waitcnt vmcnt(8)
	s_barrier
	s_add_i32 s46, s71, s54
	v_lshl_add_u64 v[192:193], v[192:193], 0, s[10:11]
	s_mov_b32 m0, s46
	ds_read_b128 v[184:187], v150 offset:49152
	ds_read_b128 v[188:191], v150 offset:50176
	ds_read_b128 v[196:199], v150 offset:51200
	ds_read_b128 v[200:203], v150 offset:52224
	ds_read_b128 v[204:207], v150 offset:53248
	ds_read_b128 v[208:211], v150 offset:54272
	ds_read_b128 v[212:215], v150 offset:55296
	ds_read_b128 v[216:219], v150 offset:56320
	global_load_lds_dwordx4 v[192:193], off
	s_add_i32 m0, s46, 0x2000
	s_add_u32 s42, s42, 0x100080
	v_lshl_add_u64 v[192:193], v[220:221], 0, s[10:11]
	s_addc_u32 s43, s43, 0
	s_add_i32 s46, s72, s54
	global_load_lds_dwordx4 v[192:193], off
	v_lshl_add_u64 v[192:193], s[42:43], 0, v[130:131]
	s_mov_b32 m0, s46
	s_nop 0
	global_load_lds_dwordx4 v[192:193], off
	v_lshl_add_u64 v[192:193], s[42:43], 0, v[132:133]
	s_add_i32 m0, s46, 0x2000
	s_nop 0
	global_load_lds_dwordx4 v[192:193], off
	v_lshl_add_u64 v[192:193], v[222:223], 0, s[10:11]
	s_mov_b32 m0, s59
	s_nop 0
	global_load_lds_dwordx4 v[192:193], off
	v_lshl_add_u64 v[192:193], v[224:225], 0, s[10:11]
	s_mov_b32 m0, s60
	s_nop 0
	global_load_lds_dwordx4 v[192:193], off
	s_waitcnt lgkmcnt(0)
	s_barrier
	s_nop 0
	s_setprio 1
	v_mfma_f32_16x16x32_bf16 v[62:65], v[152:155], v[184:187], v[62:65]
	v_mfma_f32_16x16x32_bf16 v[58:61], v[160:163], v[184:187], v[58:61]
	v_mfma_f32_16x16x32_bf16 v[54:57], v[152:155], v[196:199], v[54:57]
	v_mfma_f32_16x16x32_bf16 v[46:49], v[160:163], v[196:199], v[46:49]
	v_mfma_f32_16x16x32_bf16 v[38:41], v[152:155], v[204:207], v[38:41]
	v_mfma_f32_16x16x32_bf16 v[30:33], v[160:163], v[204:207], v[30:33]
	v_mfma_f32_16x16x32_bf16 v[22:25], v[152:155], v[212:215], v[22:25]
	v_mfma_f32_16x16x32_bf16 v[14:17], v[160:163], v[212:215], v[14:17]
	v_mfma_f32_16x16x32_bf16 v[62:65], v[156:159], v[188:191], v[62:65]
	v_mfma_f32_16x16x32_bf16 v[58:61], v[164:167], v[188:191], v[58:61]
	v_mfma_f32_16x16x32_bf16 v[54:57], v[156:159], v[200:203], v[54:57]
	v_mfma_f32_16x16x32_bf16 v[46:49], v[164:167], v[200:203], v[46:49]
	v_mfma_f32_16x16x32_bf16 v[38:41], v[156:159], v[208:211], v[38:41]
	v_mfma_f32_16x16x32_bf16 v[30:33], v[164:167], v[208:211], v[30:33]
	v_mfma_f32_16x16x32_bf16 v[22:25], v[156:159], v[216:219], v[22:25]
	v_mfma_f32_16x16x32_bf16 v[14:17], v[164:167], v[216:219], v[14:17]
	v_mfma_f32_16x16x32_bf16 v[50:53], v[168:171], v[184:187], v[50:53]
	v_mfma_f32_16x16x32_bf16 v[42:45], v[176:179], v[184:187], v[42:45]
	v_mfma_f32_16x16x32_bf16 v[34:37], v[168:171], v[196:199], v[34:37]
	v_mfma_f32_16x16x32_bf16 v[26:29], v[176:179], v[196:199], v[26:29]
	v_mfma_f32_16x16x32_bf16 v[18:21], v[168:171], v[204:207], v[18:21]
	v_mfma_f32_16x16x32_bf16 v[10:13], v[176:179], v[204:207], v[10:13]
	v_mfma_f32_16x16x32_bf16 v[6:9], v[168:171], v[212:215], v[6:9]
	v_mfma_f32_16x16x32_bf16 v[2:5], v[176:179], v[212:215], v[2:5]
	v_mfma_f32_16x16x32_bf16 v[50:53], v[172:175], v[188:191], v[50:53]
	v_mfma_f32_16x16x32_bf16 v[42:45], v[180:183], v[188:191], v[42:45]
	v_mfma_f32_16x16x32_bf16 v[34:37], v[172:175], v[200:203], v[34:37]
	v_mfma_f32_16x16x32_bf16 v[26:29], v[180:183], v[200:203], v[26:29]
	v_mfma_f32_16x16x32_bf16 v[18:21], v[172:175], v[208:211], v[18:21]
	v_mfma_f32_16x16x32_bf16 v[10:13], v[180:183], v[208:211], v[10:13]
	v_mfma_f32_16x16x32_bf16 v[6:9], v[172:175], v[216:219], v[6:9]
	v_mfma_f32_16x16x32_bf16 v[2:5], v[180:183], v[216:219], v[2:5]
	s_setprio 0
	s_waitcnt vmcnt(8)
	s_barrier
	s_add_i32 s70, s70, 2
	s_add_u32 s40, s40, 0x100
	s_addc_u32 s41, s41, 0
	s_add_u32 s68, s68, 0x100
	s_addc_u32 s69, s69, 0
	s_cmp_gt_u32 s70, 61
	s_cbranch_scc0 .Lkt_L_4
	s_branch .Lkt_exit_4
.Lkt_T_4:
	ds_read_b128 v[152:155], v144
	ds_read_b128 v[156:159], v144 offset:1024
	ds_read_b128 v[160:163], v144 offset:2048
	ds_read_b128 v[164:167], v144 offset:3072
	ds_read_b128 v[168:171], v145
	ds_read_b128 v[172:175], v145 offset:1024
	ds_read_b128 v[176:179], v145 offset:2048
	ds_read_b128 v[180:183], v145 offset:3072
	s_add_u32 s42, s40, 0xfff00080
	s_addc_u32 s43, s41, -1
	s_cmp_eq_u32 s70, 60
	s_cselect_b32 s47, s27, s43
	s_cselect_b32 s46, s66, s42
	s_cselect_b32 s43, s25, s69
	s_cselect_b32 s42, s67, s68
	v_lshl_add_u64 v[192:193], s[40:41], 0, v[134:135]
	s_add_i32 m0, s29, 0xc000
	ds_read_b128 v[184:187], v150
	ds_read_b128 v[188:191], v150 offset:1024
	ds_read_b128 v[196:199], v150 offset:2048
	ds_read_b128 v[200:203], v150 offset:3072
	ds_read_b128 v[204:207], v150 offset:4096
	ds_read_b128 v[208:211], v150 offset:5120
	ds_read_b128 v[212:215], v150 offset:6144
	ds_read_b128 v[216:219], v150 offset:7168
	global_load_lds_dwordx4 v[192:193], off
	v_lshl_add_u64 v[192:193], s[40:41], 0, v[136:137]
	s_add_i32 m0, s29, 0xe000
	s_nop 0
	global_load_lds_dwordx4 v[192:193], off
	s_waitcnt vmcnt(8)
	s_waitcnt lgkmcnt(0)
	s_barrier
	s_setprio 1
	v_mfma_f32_16x16x32_bf16 v[126:129], v[152:155], v[184:187], v[126:129]
	v_mfma_f32_16x16x32_bf16 v[122:125], v[160:163], v[184:187], v[122:125]
	v_mfma_f32_16x16x32_bf16 v[118:121], v[152:155], v[196:199], v[118:121]
	v_mfma_f32_16x16x32_bf16 v[110:113], v[160:163], v[196:199], v[110:113]
	v_mfma_f32_16x16x32_bf16 v[102:105], v[152:155], v[204:207], v[102:105]
	v_mfma_f32_16x16x32_bf16 v[94:97], v[160:163], v[204:207], v[94:97]
	v_mfma_f32_16x16x32_bf16 v[86:89], v[152:155], v[212:215], v[86:89]
	v_mfma_f32_16x16x32_bf16 v[78:81], v[160:163], v[212:215], v[78:81]
	v_mfma_f32_16x16x32_bf16 v[126:129], v[156:159], v[188:191], v[126:129]
	v_mfma_f32_16x16x32_bf16 v[122:125], v[164:167], v[188:191], v[122:125]
	v_mfma_f32_16x16x32_bf16 v[118:121], v[156:159], v[200:203], v[118:121]
	v_mfma_f32_16x16x32_bf16 v[110:113], v[164:167], v[200:203], v[110:113]
	v_mfma_f32_16x16x32_bf16 v[102:105], v[156:159], v[208:211], v[102:105]
	v_mfma_f32_16x16x32_bf16 v[94:97], v[164:167], v[208:211], v[94:97]
	v_mfma_f32_16x16x32_bf16 v[86:89], v[156:159], v[216:219], v[86:89]
	v_mfma_f32_16x16x32_bf16 v[78:81], v[164:167], v[216:219], v[78:81]
	v_mfma_f32_16x16x32_bf16 v[114:117], v[168:171], v[184:187], v[114:117]
	v_mfma_f32_16x16x32_bf16 v[106:109], v[176:179], v[184:187], v[106:109]
	v_mfma_f32_16x16x32_bf16 v[98:101], v[168:171], v[196:199], v[98:101]
	v_mfma_f32_16x16x32_bf16 v[90:93], v[176:179], v[196:199], v[90:93]
	v_mfma_f32_16x16x32_bf16 v[82:85], v[168:171], v[204:207], v[82:85]
	v_mfma_f32_16x16x32_bf16 v[74:77], v[176:179], v[204:207], v[74:77]
	v_mfma_f32_16x16x32_bf16 v[70:73], v[168:171], v[212:215], v[70:73]
	v_mfma_f32_16x16x32_bf16 v[66:69], v[176:179], v[212:215], v[66:69]
	v_mfma_f32_16x16x32_bf16 v[114:117], v[172:175], v[188:191], v[114:117]
	v_mfma_f32_16x16x32_bf16 v[106:109], v[180:183], v[188:191], v[106:109]
	v_mfma_f32_16x16x32_bf16 v[98:101], v[172:175], v[200:203], v[98:101]
	v_mfma_f32_16x16x32_bf16 v[90:93], v[180:183], v[200:203], v[90:93]
	v_mfma_f32_16x16x32_bf16 v[82:85], v[172:175], v[208:211], v[82:85]
	v_mfma_f32_16x16x32_bf16 v[74:77], v[180:183], v[208:211], v[74:77]
	v_mfma_f32_16x16x32_bf16 v[70:73], v[172:175], v[216:219], v[70:73]
	v_mfma_f32_16x16x32_bf16 v[66:69], v[180:183], v[216:219], v[66:69]
	s_setprio 0
	s_barrier
	s_add_i32 s71, s62, s54
	v_lshl_add_u64 v[192:193], s[42:43], 0, v[130:131]
	s_mov_b32 m0, s71
	ds_read_b128 v[184:187], v150 offset:16384
	ds_read_b128 v[188:191], v150 offset:17408
	ds_read_b128 v[196:199], v150 offset:18432
	ds_read_b128 v[200:203], v150 offset:19456
	ds_read_b128 v[204:207], v150 offset:20480
	ds_read_b128 v[208:211], v150 offset:21504
	ds_read_b128 v[212:215], v150 offset:22528
	ds_read_b128 v[216:219], v150 offset:23552
	global_load_lds_dwordx4 v[192:193], off
	s_add_i32 m0, s71, 0x2000
	s_add_u32 s72, s42, 0x100000
	v_lshl_add_u64 v[220:221], s[42:43], 0, v[132:133]
	s_addc_u32 s73, s43, 0
	s_add_i32 s71, s63, s54
	global_load_lds_dwordx4 v[220:221], off
	v_lshl_add_u64 v[222:223], s[72:73], 0, v[130:131]
	s_mov_b32 m0, s71
	v_lshl_add_u64 v[224:225], s[46:47], 0, v[132:133]
	global_load_lds_dwordx4 v[222:223], off
	v_lshl_add_u64 v[222:223], s[72:73], 0, v[132:133]
	s_add_i32 m0, s71, 0x2000
	s_nop 0
	global_load_lds_dwordx4 v[222:223], off
	v_lshl_add_u64 v[222:223], s[46:47], 0, v[130:131]
	s_mov_b32 m0, s29
	s_nop 0
	global_load_lds_dwordx4 v[222:223], off
	s_mov_b32 m0, s55
	s_nop 0
	global_load_lds_dwordx4 v[224:225], off
	s_waitcnt vmcnt(8)
	s_waitcnt lgkmcnt(0)
	s_barrier
	s_setprio 1
	v_mfma_f32_16x16x32_bf16 v[62:65], v[152:155], v[184:187], v[62:65]
	v_mfma_f32_16x16x32_bf16 v[58:61], v[160:163], v[184:187], v[58:61]
	v_mfma_f32_16x16x32_bf16 v[54:57], v[152:155], v[196:199], v[54:57]
	v_mfma_f32_16x16x32_bf16 v[46:49], v[160:163], v[196:199], v[46:49]
	v_mfma_f32_16x16x32_bf16 v[38:41], v[152:155], v[204:207], v[38:41]
	v_mfma_f32_16x16x32_bf16 v[30:33], v[160:163], v[204:207], v[30:33]
	v_mfma_f32_16x16x32_bf16 v[22:25], v[152:155], v[212:215], v[22:25]
	v_mfma_f32_16x16x32_bf16 v[14:17], v[160:163], v[212:215], v[14:17]
	v_mfma_f32_16x16x32_bf16 v[62:65], v[156:159], v[188:191], v[62:65]
	v_mfma_f32_16x16x32_bf16 v[58:61], v[164:167], v[188:191], v[58:61]
	v_mfma_f32_16x16x32_bf16 v[54:57], v[156:159], v[200:203], v[54:57]
	v_mfma_f32_16x16x32_bf16 v[46:49], v[164:167], v[200:203], v[46:49]
	v_mfma_f32_16x16x32_bf16 v[38:41], v[156:159], v[208:211], v[38:41]
	v_mfma_f32_16x16x32_bf16 v[30:33], v[164:167], v[208:211], v[30:33]
	v_mfma_f32_16x16x32_bf16 v[22:25], v[156:159], v[216:219], v[22:25]
	v_mfma_f32_16x16x32_bf16 v[14:17], v[164:167], v[216:219], v[14:17]
	v_mfma_f32_16x16x32_bf16 v[50:53], v[168:171], v[184:187], v[50:53]
	v_mfma_f32_16x16x32_bf16 v[42:45], v[176:179], v[184:187], v[42:45]
	v_mfma_f32_16x16x32_bf16 v[34:37], v[168:171], v[196:199], v[34:37]
	v_mfma_f32_16x16x32_bf16 v[26:29], v[176:179], v[196:199], v[26:29]
	v_mfma_f32_16x16x32_bf16 v[18:21], v[168:171], v[204:207], v[18:21]
	v_mfma_f32_16x16x32_bf16 v[10:13], v[176:179], v[204:207], v[10:13]
	v_mfma_f32_16x16x32_bf16 v[6:9], v[168:171], v[212:215], v[6:9]
	v_mfma_f32_16x16x32_bf16 v[2:5], v[176:179], v[212:215], v[2:5]
	v_mfma_f32_16x16x32_bf16 v[50:53], v[172:175], v[188:191], v[50:53]
	v_mfma_f32_16x16x32_bf16 v[42:45], v[180:183], v[188:191], v[42:45]
	v_mfma_f32_16x16x32_bf16 v[34:37], v[172:175], v[200:203], v[34:37]
	v_mfma_f32_16x16x32_bf16 v[26:29], v[180:183], v[200:203], v[26:29]
	v_mfma_f32_16x16x32_bf16 v[18:21], v[172:175], v[208:211], v[18:21]
	v_mfma_f32_16x16x32_bf16 v[10:13], v[180:183], v[208:211], v[10:13]
	v_mfma_f32_16x16x32_bf16 v[6:9], v[172:175], v[216:219], v[6:9]
	v_mfma_f32_16x16x32_bf16 v[2:5], v[180:183], v[216:219], v[2:5]
	s_setprio 0
	s_barrier
	s_add_i32 s71, 0, 0x18000
	v_add_u32_e32 v151, s71, v142
	s_add_i32 s72, 0, 0x1c000
	ds_read_b128 v[152:155], v151
	ds_read_b128 v[156:159], v151 offset:1024
	ds_read_b128 v[160:163], v151 offset:2048
	ds_read_b128 v[164:167], v151 offset:3072
	v_add_u32_e32 v151, s72, v142
	ds_read_b128 v[168:171], v151
	ds_read_b128 v[172:175], v151 offset:1024
	ds_read_b128 v[176:179], v151 offset:2048
	ds_read_b128 v[180:183], v151 offset:3072
	s_add_u32 s46, s46, 0x100000
	s_addc_u32 s47, s47, 0
	s_mov_b32 m0, s56
	v_lshl_add_u64 v[226:227], s[46:47], 0, v[130:131]
	ds_read_b128 v[184:187], v150 offset:32768
	ds_read_b128 v[188:191], v150 offset:33792
	ds_read_b128 v[196:199], v150 offset:34816
	ds_read_b128 v[200:203], v150 offset:35840
	ds_read_b128 v[204:207], v150 offset:36864
	ds_read_b128 v[208:211], v150 offset:37888
	ds_read_b128 v[212:215], v150 offset:38912
	ds_read_b128 v[216:219], v150 offset:39936
	global_load_lds_dwordx4 v[226:227], off
	v_lshl_add_u64 v[226:227], s[46:47], 0, v[132:133]
	s_mov_b32 m0, s57
	s_nop 0
	global_load_lds_dwordx4 v[226:227], off
	s_waitcnt vmcnt(8)
	s_waitcnt lgkmcnt(0)
	s_barrier
	s_setprio 1
	v_mfma_f32_16x16x32_bf16 v[126:129], v[152:155], v[184:187], v[126:129]
	v_mfma_f32_16x16x32_bf16 v[122:125], v[160:163], v[184:187], v[122:125]
	v_mfma_f32_16x16x32_bf16 v[118:121], v[152:155], v[196:199], v[118:121]
	v_mfma_f32_16x16x32_bf16 v[110:113], v[160:163], v[196:199], v[110:113]
	v_mfma_f32_16x16x32_bf16 v[102:105], v[152:155], v[204:207], v[102:105]
	v_mfma_f32_16x16x32_bf16 v[94:97], v[160:163], v[204:207], v[94:97]
	v_mfma_f32_16x16x32_bf16 v[86:89], v[152:155], v[212:215], v[86:89]
	v_mfma_f32_16x16x32_bf16 v[78:81], v[160:163], v[212:215], v[78:81]
	v_mfma_f32_16x16x32_bf16 v[126:129], v[156:159], v[188:191], v[126:129]
	v_mfma_f32_16x16x32_bf16 v[122:125], v[164:167], v[188:191], v[122:125]
	v_mfma_f32_16x16x32_bf16 v[118:121], v[156:159], v[200:203], v[118:121]
	v_mfma_f32_16x16x32_bf16 v[110:113], v[164:167], v[200:203], v[110:113]
	v_mfma_f32_16x16x32_bf16 v[102:105], v[156:159], v[208:211], v[102:105]
	v_mfma_f32_16x16x32_bf16 v[94:97], v[164:167], v[208:211], v[94:97]
	v_mfma_f32_16x16x32_bf16 v[86:89], v[156:159], v[216:219], v[86:89]
	v_mfma_f32_16x16x32_bf16 v[78:81], v[164:167], v[216:219], v[78:81]
	v_mfma_f32_16x16x32_bf16 v[114:117], v[168:171], v[184:187], v[114:117]
	v_mfma_f32_16x16x32_bf16 v[106:109], v[176:179], v[184:187], v[106:109]
	v_mfma_f32_16x16x32_bf16 v[98:101], v[168:171], v[196:199], v[98:101]
	v_mfma_f32_16x16x32_bf16 v[90:93], v[176:179], v[196:199], v[90:93]
	v_mfma_f32_16x16x32_bf16 v[82:85], v[168:171], v[204:207], v[82:85]
	v_mfma_f32_16x16x32_bf16 v[74:77], v[176:179], v[204:207], v[74:77]
	v_mfma_f32_16x16x32_bf16 v[70:73], v[168:171], v[212:215], v[70:73]
	v_mfma_f32_16x16x32_bf16 v[66:69], v[176:179], v[212:215], v[66:69]
	v_mfma_f32_16x16x32_bf16 v[114:117], v[172:175], v[188:191], v[114:117]
	v_mfma_f32_16x16x32_bf16 v[106:109], v[180:183], v[188:191], v[106:109]
	v_mfma_f32_16x16x32_bf16 v[98:101], v[172:175], v[200:203], v[98:101]
	v_mfma_f32_16x16x32_bf16 v[90:93], v[180:183], v[200:203], v[90:93]
	v_mfma_f32_16x16x32_bf16 v[82:85], v[172:175], v[208:211], v[82:85]
	v_mfma_f32_16x16x32_bf16 v[74:77], v[180:183], v[208:211], v[74:77]
	v_mfma_f32_16x16x32_bf16 v[70:73], v[172:175], v[216:219], v[70:73]
	v_mfma_f32_16x16x32_bf16 v[66:69], v[180:183], v[216:219], v[66:69]
	s_setprio 0
	s_barrier
	s_add_i32 s46, s71, s54
	v_lshl_add_u64 v[192:193], v[192:193], 0, s[10:11]
	s_mov_b32 m0, s46
	ds_read_b128 v[184:187], v150 offset:49152
	ds_read_b128 v[188:191], v150 offset:50176
	ds_read_b128 v[196:199], v150 offset:51200
	ds_read_b128 v[200:203], v150 offset:52224
	ds_read_b128 v[204:207], v150 offset:53248
	ds_read_b128 v[208:211], v150 offset:54272
	ds_read_b128 v[212:215], v150 offset:55296
	ds_read_b128 v[216:219], v150 offset:56320
	global_load_lds_dwordx4 v[192:193], off
	s_add_i32 m0, s46, 0x2000
	s_add_u32 s42, s42, 0x100080
	v_lshl_add_u64 v[192:193], v[220:221], 0, s[10:11]
	s_addc_u32 s43, s43, 0
	s_add_i32 s46, s72, s54
	global_load_lds_dwordx4 v[192:193], off
	v_lshl_add_u64 v[192:193], s[42:43], 0, v[130:131]
	s_mov_b32 m0, s46
	s_nop 0
	global_load_lds_dwordx4 v[192:193], off
	v_lshl_add_u64 v[192:193], s[42:43], 0, v[132:133]
	s_add_i32 m0, s46, 0x2000
	s_nop 0
	global_load_lds_dwordx4 v[192:193], off
	v_lshl_add_u64 v[192:193], v[222:223], 0, s[10:11]
	s_mov_b32 m0, s59
	s_nop 0
	global_load_lds_dwordx4 v[192:193], off
	v_lshl_add_u64 v[192:193], v[224:225], 0, s[10:11]
	s_mov_b32 m0, s60
	s_nop 0
	global_load_lds_dwordx4 v[192:193], off
	s_nop 0
	s_waitcnt vmcnt(8)
	s_waitcnt lgkmcnt(0)
	s_barrier
	s_setprio 1
	v_mfma_f32_16x16x32_bf16 v[62:65], v[152:155], v[184:187], v[62:65]
	v_mfma_f32_16x16x32_bf16 v[58:61], v[160:163], v[184:187], v[58:61]
	v_mfma_f32_16x16x32_bf16 v[54:57], v[152:155], v[196:199], v[54:57]
	v_mfma_f32_16x16x32_bf16 v[46:49], v[160:163], v[196:199], v[46:49]
	v_mfma_f32_16x16x32_bf16 v[38:41], v[152:155], v[204:207], v[38:41]
	v_mfma_f32_16x16x32_bf16 v[30:33], v[160:163], v[204:207], v[30:33]
	v_mfma_f32_16x16x32_bf16 v[22:25], v[152:155], v[212:215], v[22:25]
	v_mfma_f32_16x16x32_bf16 v[14:17], v[160:163], v[212:215], v[14:17]
	v_mfma_f32_16x16x32_bf16 v[62:65], v[156:159], v[188:191], v[62:65]
	v_mfma_f32_16x16x32_bf16 v[58:61], v[164:167], v[188:191], v[58:61]
	v_mfma_f32_16x16x32_bf16 v[54:57], v[156:159], v[200:203], v[54:57]
	v_mfma_f32_16x16x32_bf16 v[46:49], v[164:167], v[200:203], v[46:49]
	v_mfma_f32_16x16x32_bf16 v[38:41], v[156:159], v[208:211], v[38:41]
	v_mfma_f32_16x16x32_bf16 v[30:33], v[164:167], v[208:211], v[30:33]
	v_mfma_f32_16x16x32_bf16 v[22:25], v[156:159], v[216:219], v[22:25]
	v_mfma_f32_16x16x32_bf16 v[14:17], v[164:167], v[216:219], v[14:17]
	v_mfma_f32_16x16x32_bf16 v[50:53], v[168:171], v[184:187], v[50:53]
	v_mfma_f32_16x16x32_bf16 v[42:45], v[176:179], v[184:187], v[42:45]
	v_mfma_f32_16x16x32_bf16 v[34:37], v[168:171], v[196:199], v[34:37]
	v_mfma_f32_16x16x32_bf16 v[26:29], v[176:179], v[196:199], v[26:29]
	v_mfma_f32_16x16x32_bf16 v[18:21], v[168:171], v[204:207], v[18:21]
	v_mfma_f32_16x16x32_bf16 v[10:13], v[176:179], v[204:207], v[10:13]
	v_mfma_f32_16x16x32_bf16 v[6:9], v[168:171], v[212:215], v[6:9]
	v_mfma_f32_16x16x32_bf16 v[2:5], v[176:179], v[212:215], v[2:5]
	v_mfma_f32_16x16x32_bf16 v[50:53], v[172:175], v[188:191], v[50:53]
	v_mfma_f32_16x16x32_bf16 v[42:45], v[180:183], v[188:191], v[42:45]
	v_mfma_f32_16x16x32_bf16 v[34:37], v[172:175], v[200:203], v[34:37]
	v_mfma_f32_16x16x32_bf16 v[26:29], v[180:183], v[200:203], v[26:29]
	v_mfma_f32_16x16x32_bf16 v[18:21], v[172:175], v[208:211], v[18:21]
	v_mfma_f32_16x16x32_bf16 v[10:13], v[180:183], v[208:211], v[10:13]
	v_mfma_f32_16x16x32_bf16 v[6:9], v[172:175], v[216:219], v[6:9]
	v_mfma_f32_16x16x32_bf16 v[2:5], v[180:183], v[216:219], v[2:5]
	s_setprio 0
	s_barrier
	s_add_i32 s70, s70, 2
	s_add_u32 s40, s40, 0x100
	s_addc_u32 s41, s41, 0
	s_add_u32 s68, s68, 0x100
	s_addc_u32 s69, s69, 0
	s_cmp_gt_u32 s70, 61
	s_cbranch_scc0 .Lkt_T_4
	s_nop 7

.Lkt_L_5:
	ds_read_b128 v[144:147], v139
	ds_read_b128 v[148:151], v139 offset:1024
	ds_read_b128 v[152:155], v139 offset:2048
	ds_read_b128 v[156:159], v139 offset:3072
	ds_read_b128 v[160:163], v140
	ds_read_b128 v[164:167], v140 offset:1024
	ds_read_b128 v[168:171], v140 offset:2048
	ds_read_b128 v[172:175], v140 offset:3072
	s_add_u32 s42, s40, 0xfff00080
	s_addc_u32 s43, s41, -1
	s_cmp_eq_u32 s67, 60
	s_cselect_b32 s47, s27, s43
	s_cselect_b32 s46, s63, s42
	s_cselect_b32 s43, s25, s66
	s_cselect_b32 s42, s64, s65
	v_lshl_add_u64 v[192:193], s[40:41], 0, v[134:135]
	s_add_i32 m0, s29, 0xc000
	ds_read_b128 v[176:179], v142
	ds_read_b128 v[180:183], v142 offset:1024
	ds_read_b128 v[184:187], v142 offset:2048
	ds_read_b128 v[188:191], v142 offset:3072
	ds_read_b128 v[196:199], v142 offset:4096
	ds_read_b128 v[200:203], v142 offset:5120
	ds_read_b128 v[204:207], v142 offset:6144
	ds_read_b128 v[208:211], v142 offset:7168
	global_load_lds_dwordx4 v[192:193], off
	v_lshl_add_u64 v[192:193], s[40:41], 0, v[136:137]
	s_add_i32 m0, s29, 0xe000
	s_nop 0
	global_load_lds_dwordx4 v[192:193], off
	s_waitcnt lgkmcnt(0)
	s_barrier
	s_nop 0
	s_setprio 1
	v_mfma_f32_16x16x32_bf16 v[126:129], v[144:147], v[176:179], v[126:129]
	v_mfma_f32_16x16x32_bf16 v[122:125], v[152:155], v[176:179], v[122:125]
	v_mfma_f32_16x16x32_bf16 v[118:121], v[144:147], v[184:187], v[118:121]
	v_mfma_f32_16x16x32_bf16 v[110:113], v[152:155], v[184:187], v[110:113]
	v_mfma_f32_16x16x32_bf16 v[102:105], v[144:147], v[196:199], v[102:105]
	v_mfma_f32_16x16x32_bf16 v[94:97], v[152:155], v[196:199], v[94:97]
	v_mfma_f32_16x16x32_bf16 v[86:89], v[144:147], v[204:207], v[86:89]
	v_mfma_f32_16x16x32_bf16 v[78:81], v[152:155], v[204:207], v[78:81]
	v_mfma_f32_16x16x32_bf16 v[126:129], v[148:151], v[180:183], v[126:129]
	v_mfma_f32_16x16x32_bf16 v[122:125], v[156:159], v[180:183], v[122:125]
	v_mfma_f32_16x16x32_bf16 v[118:121], v[148:151], v[188:191], v[118:121]
	v_mfma_f32_16x16x32_bf16 v[110:113], v[156:159], v[188:191], v[110:113]
	v_mfma_f32_16x16x32_bf16 v[102:105], v[148:151], v[200:203], v[102:105]
	v_mfma_f32_16x16x32_bf16 v[94:97], v[156:159], v[200:203], v[94:97]
	v_mfma_f32_16x16x32_bf16 v[86:89], v[148:151], v[208:211], v[86:89]
	v_mfma_f32_16x16x32_bf16 v[78:81], v[156:159], v[208:211], v[78:81]
	v_mfma_f32_16x16x32_bf16 v[114:117], v[160:163], v[176:179], v[114:117]
	v_mfma_f32_16x16x32_bf16 v[106:109], v[168:171], v[176:179], v[106:109]
	v_mfma_f32_16x16x32_bf16 v[98:101], v[160:163], v[184:187], v[98:101]
	v_mfma_f32_16x16x32_bf16 v[90:93], v[168:171], v[184:187], v[90:93]
	v_mfma_f32_16x16x32_bf16 v[82:85], v[160:163], v[196:199], v[82:85]
	v_mfma_f32_16x16x32_bf16 v[74:77], v[168:171], v[196:199], v[74:77]
	v_mfma_f32_16x16x32_bf16 v[70:73], v[160:163], v[204:207], v[70:73]
	v_mfma_f32_16x16x32_bf16 v[66:69], v[168:171], v[204:207], v[66:69]
	v_mfma_f32_16x16x32_bf16 v[114:117], v[164:167], v[180:183], v[114:117]
	v_mfma_f32_16x16x32_bf16 v[106:109], v[172:175], v[180:183], v[106:109]
	v_mfma_f32_16x16x32_bf16 v[98:101], v[164:167], v[188:191], v[98:101]
	v_mfma_f32_16x16x32_bf16 v[90:93], v[172:175], v[188:191], v[90:93]
	v_mfma_f32_16x16x32_bf16 v[82:85], v[164:167], v[200:203], v[82:85]
	v_mfma_f32_16x16x32_bf16 v[74:77], v[172:175], v[200:203], v[74:77]
	v_mfma_f32_16x16x32_bf16 v[70:73], v[164:167], v[208:211], v[70:73]
	v_mfma_f32_16x16x32_bf16 v[66:69], v[172:175], v[208:211], v[66:69]
	s_setprio 0
	s_waitcnt vmcnt(8)
	s_barrier
	s_add_i32 s68, s59, s51
	v_lshl_add_u64 v[192:193], s[42:43], 0, v[130:131]
	s_mov_b32 m0, s68
	ds_read_b128 v[176:179], v142 offset:16384
	ds_read_b128 v[180:183], v142 offset:17408
	ds_read_b128 v[184:187], v142 offset:18432
	ds_read_b128 v[188:191], v142 offset:19456
	ds_read_b128 v[196:199], v142 offset:20480
	ds_read_b128 v[200:203], v142 offset:21504
	ds_read_b128 v[204:207], v142 offset:22528
	ds_read_b128 v[208:211], v142 offset:23552
	global_load_lds_dwordx4 v[192:193], off
	s_add_i32 m0, s68, 0x2000
	s_add_u32 s68, s42, 0x100000
	v_lshl_add_u64 v[212:213], s[42:43], 0, v[132:133]
	s_addc_u32 s69, s43, 0
	s_add_i32 s70, s60, s51
	global_load_lds_dwordx4 v[212:213], off
	v_lshl_add_u64 v[214:215], s[68:69], 0, v[130:131]
	s_mov_b32 m0, s70
	v_lshl_add_u64 v[216:217], s[46:47], 0, v[132:133]
	global_load_lds_dwordx4 v[214:215], off
	v_lshl_add_u64 v[214:215], s[68:69], 0, v[132:133]
	s_add_i32 m0, s70, 0x2000
	s_nop 0
	global_load_lds_dwordx4 v[214:215], off
	v_lshl_add_u64 v[214:215], s[46:47], 0, v[130:131]
	s_mov_b32 m0, s29
	s_nop 0
	global_load_lds_dwordx4 v[214:215], off
	s_mov_b32 m0, s52
	s_nop 0
	global_load_lds_dwordx4 v[216:217], off
	s_waitcnt lgkmcnt(0)
	s_barrier
	s_setprio 1
	v_mfma_f32_16x16x32_bf16 v[62:65], v[144:147], v[176:179], v[62:65]
	v_mfma_f32_16x16x32_bf16 v[58:61], v[152:155], v[176:179], v[58:61]
	v_mfma_f32_16x16x32_bf16 v[54:57], v[144:147], v[184:187], v[54:57]
	v_mfma_f32_16x16x32_bf16 v[46:49], v[152:155], v[184:187], v[46:49]
	v_mfma_f32_16x16x32_bf16 v[38:41], v[144:147], v[196:199], v[38:41]
	v_mfma_f32_16x16x32_bf16 v[30:33], v[152:155], v[196:199], v[30:33]
	v_mfma_f32_16x16x32_bf16 v[22:25], v[144:147], v[204:207], v[22:25]
	v_mfma_f32_16x16x32_bf16 v[14:17], v[152:155], v[204:207], v[14:17]
	v_mfma_f32_16x16x32_bf16 v[62:65], v[148:151], v[180:183], v[62:65]
	v_mfma_f32_16x16x32_bf16 v[58:61], v[156:159], v[180:183], v[58:61]
	v_mfma_f32_16x16x32_bf16 v[54:57], v[148:151], v[188:191], v[54:57]
	v_mfma_f32_16x16x32_bf16 v[46:49], v[156:159], v[188:191], v[46:49]
	v_mfma_f32_16x16x32_bf16 v[38:41], v[148:151], v[200:203], v[38:41]
	v_mfma_f32_16x16x32_bf16 v[30:33], v[156:159], v[200:203], v[30:33]
	v_mfma_f32_16x16x32_bf16 v[22:25], v[148:151], v[208:211], v[22:25]
	v_mfma_f32_16x16x32_bf16 v[14:17], v[156:159], v[208:211], v[14:17]
	v_mfma_f32_16x16x32_bf16 v[50:53], v[160:163], v[176:179], v[50:53]
	v_mfma_f32_16x16x32_bf16 v[42:45], v[168:171], v[176:179], v[42:45]
	v_mfma_f32_16x16x32_bf16 v[34:37], v[160:163], v[184:187], v[34:37]
	v_mfma_f32_16x16x32_bf16 v[26:29], v[168:171], v[184:187], v[26:29]
	v_mfma_f32_16x16x32_bf16 v[18:21], v[160:163], v[196:199], v[18:21]
	v_mfma_f32_16x16x32_bf16 v[10:13], v[168:171], v[196:199], v[10:13]
	v_mfma_f32_16x16x32_bf16 v[6:9], v[160:163], v[204:207], v[6:9]
	v_mfma_f32_16x16x32_bf16 v[2:5], v[168:171], v[204:207], v[2:5]
	v_mfma_f32_16x16x32_bf16 v[50:53], v[164:167], v[180:183], v[50:53]
	v_mfma_f32_16x16x32_bf16 v[42:45], v[172:175], v[180:183], v[42:45]
	v_mfma_f32_16x16x32_bf16 v[34:37], v[164:167], v[188:191], v[34:37]
	v_mfma_f32_16x16x32_bf16 v[26:29], v[172:175], v[188:191], v[26:29]
	v_mfma_f32_16x16x32_bf16 v[18:21], v[164:167], v[200:203], v[18:21]
	v_mfma_f32_16x16x32_bf16 v[10:13], v[172:175], v[200:203], v[10:13]
	v_mfma_f32_16x16x32_bf16 v[6:9], v[164:167], v[208:211], v[6:9]
	v_mfma_f32_16x16x32_bf16 v[2:5], v[172:175], v[208:211], v[2:5]
	s_setprio 0
	s_waitcnt vmcnt(8)
	s_barrier
	s_add_i32 s68, 0, 0x18000
	v_add_u32_e32 v143, s68, v1
	s_add_i32 s69, 0, 0x1c000
	ds_read_b128 v[144:147], v143
	ds_read_b128 v[148:151], v143 offset:1024
	ds_read_b128 v[152:155], v143 offset:2048
	ds_read_b128 v[156:159], v143 offset:3072
	v_add_u32_e32 v143, s69, v1
	ds_read_b128 v[160:163], v143
	ds_read_b128 v[164:167], v143 offset:1024
	ds_read_b128 v[168:171], v143 offset:2048
	ds_read_b128 v[172:175], v143 offset:3072
	s_add_u32 s46, s46, 0x100000
	s_addc_u32 s47, s47, 0
	s_mov_b32 m0, s53
	v_lshl_add_u64 v[218:219], s[46:47], 0, v[130:131]
	ds_read_b128 v[176:179], v142 offset:32768
	ds_read_b128 v[180:183], v142 offset:33792
	ds_read_b128 v[184:187], v142 offset:34816
	ds_read_b128 v[188:191], v142 offset:35840
	ds_read_b128 v[196:199], v142 offset:36864
	ds_read_b128 v[200:203], v142 offset:37888
	ds_read_b128 v[204:207], v142 offset:38912
	ds_read_b128 v[208:211], v142 offset:39936
	global_load_lds_dwordx4 v[218:219], off
	v_lshl_add_u64 v[218:219], s[46:47], 0, v[132:133]
	s_mov_b32 m0, s54
	s_nop 0
	global_load_lds_dwordx4 v[218:219], off
	s_waitcnt lgkmcnt(0)
	s_barrier
	s_setprio 1
	v_mfma_f32_16x16x32_bf16 v[126:129], v[144:147], v[176:179], v[126:129]
	v_mfma_f32_16x16x32_bf16 v[122:125], v[152:155], v[176:179], v[122:125]
	v_mfma_f32_16x16x32_bf16 v[118:121], v[144:147], v[184:187], v[118:121]
	v_mfma_f32_16x16x32_bf16 v[110:113], v[152:155], v[184:187], v[110:113]
	v_mfma_f32_16x16x32_bf16 v[102:105], v[144:147], v[196:199], v[102:105]
	v_mfma_f32_16x16x32_bf16 v[94:97], v[152:155], v[196:199], v[94:97]
	v_mfma_f32_16x16x32_bf16 v[86:89], v[144:147], v[204:207], v[86:89]
	v_mfma_f32_16x16x32_bf16 v[78:81], v[152:155], v[204:207], v[78:81]
	v_mfma_f32_16x16x32_bf16 v[126:129], v[148:151], v[180:183], v[126:129]
	v_mfma_f32_16x16x32_bf16 v[122:125], v[156:159], v[180:183], v[122:125]
	v_mfma_f32_16x16x32_bf16 v[118:121], v[148:151], v[188:191], v[118:121]
	v_mfma_f32_16x16x32_bf16 v[110:113], v[156:159], v[188:191], v[110:113]
	v_mfma_f32_16x16x32_bf16 v[102:105], v[148:151], v[200:203], v[102:105]
	v_mfma_f32_16x16x32_bf16 v[94:97], v[156:159], v[200:203], v[94:97]
	v_mfma_f32_16x16x32_bf16 v[86:89], v[148:151], v[208:211], v[86:89]
	v_mfma_f32_16x16x32_bf16 v[78:81], v[156:159], v[208:211], v[78:81]
	v_mfma_f32_16x16x32_bf16 v[114:117], v[160:163], v[176:179], v[114:117]
	v_mfma_f32_16x16x32_bf16 v[106:109], v[168:171], v[176:179], v[106:109]
	v_mfma_f32_16x16x32_bf16 v[98:101], v[160:163], v[184:187], v[98:101]
	v_mfma_f32_16x16x32_bf16 v[90:93], v[168:171], v[184:187], v[90:93]
	v_mfma_f32_16x16x32_bf16 v[82:85], v[160:163], v[196:199], v[82:85]
	v_mfma_f32_16x16x32_bf16 v[74:77], v[168:171], v[196:199], v[74:77]
	v_mfma_f32_16x16x32_bf16 v[70:73], v[160:163], v[204:207], v[70:73]
	v_mfma_f32_16x16x32_bf16 v[66:69], v[168:171], v[204:207], v[66:69]
	v_mfma_f32_16x16x32_bf16 v[114:117], v[164:167], v[180:183], v[114:117]
	v_mfma_f32_16x16x32_bf16 v[106:109], v[172:175], v[180:183], v[106:109]
	v_mfma_f32_16x16x32_bf16 v[98:101], v[164:167], v[188:191], v[98:101]
	v_mfma_f32_16x16x32_bf16 v[90:93], v[172:175], v[188:191], v[90:93]
	v_mfma_f32_16x16x32_bf16 v[82:85], v[164:167], v[200:203], v[82:85]
	v_mfma_f32_16x16x32_bf16 v[74:77], v[172:175], v[200:203], v[74:77]
	v_mfma_f32_16x16x32_bf16 v[70:73], v[164:167], v[208:211], v[70:73]
	v_mfma_f32_16x16x32_bf16 v[66:69], v[172:175], v[208:211], v[66:69]
	s_setprio 0
	s_waitcnt vmcnt(8)
	s_barrier
	s_add_i32 s46, s68, s51
	v_lshl_add_u64 v[192:193], v[192:193], 0, s[10:11]
	s_mov_b32 m0, s46
	ds_read_b128 v[176:179], v142 offset:49152
	ds_read_b128 v[180:183], v142 offset:50176
	ds_read_b128 v[184:187], v142 offset:51200
	ds_read_b128 v[188:191], v142 offset:52224
	ds_read_b128 v[196:199], v142 offset:53248
	ds_read_b128 v[200:203], v142 offset:54272
	ds_read_b128 v[204:207], v142 offset:55296
	ds_read_b128 v[208:211], v142 offset:56320
	global_load_lds_dwordx4 v[192:193], off
	s_add_i32 m0, s46, 0x2000
	s_add_u32 s42, s42, 0x100080
	v_lshl_add_u64 v[192:193], v[212:213], 0, s[10:11]
	s_addc_u32 s43, s43, 0
	s_add_i32 s46, s69, s51
	global_load_lds_dwordx4 v[192:193], off
	v_lshl_add_u64 v[192:193], s[42:43], 0, v[130:131]
	s_mov_b32 m0, s46
	s_nop 0
	global_load_lds_dwordx4 v[192:193], off
	v_lshl_add_u64 v[192:193], s[42:43], 0, v[132:133]
	s_add_i32 m0, s46, 0x2000
	s_nop 0
	global_load_lds_dwordx4 v[192:193], off
	v_lshl_add_u64 v[192:193], v[214:215], 0, s[10:11]
	s_mov_b32 m0, s56
	s_nop 0
	global_load_lds_dwordx4 v[192:193], off
	v_lshl_add_u64 v[192:193], v[216:217], 0, s[10:11]
	s_mov_b32 m0, s57
	s_nop 0
	global_load_lds_dwordx4 v[192:193], off
	s_waitcnt lgkmcnt(0)
	s_barrier
	s_nop 0
	s_setprio 1
	v_mfma_f32_16x16x32_bf16 v[62:65], v[144:147], v[176:179], v[62:65]
	v_mfma_f32_16x16x32_bf16 v[58:61], v[152:155], v[176:179], v[58:61]
	v_mfma_f32_16x16x32_bf16 v[54:57], v[144:147], v[184:187], v[54:57]
	v_mfma_f32_16x16x32_bf16 v[46:49], v[152:155], v[184:187], v[46:49]
	v_mfma_f32_16x16x32_bf16 v[38:41], v[144:147], v[196:199], v[38:41]
	v_mfma_f32_16x16x32_bf16 v[30:33], v[152:155], v[196:199], v[30:33]
	v_mfma_f32_16x16x32_bf16 v[22:25], v[144:147], v[204:207], v[22:25]
	v_mfma_f32_16x16x32_bf16 v[14:17], v[152:155], v[204:207], v[14:17]
	v_mfma_f32_16x16x32_bf16 v[62:65], v[148:151], v[180:183], v[62:65]
	v_mfma_f32_16x16x32_bf16 v[58:61], v[156:159], v[180:183], v[58:61]
	v_mfma_f32_16x16x32_bf16 v[54:57], v[148:151], v[188:191], v[54:57]
	v_mfma_f32_16x16x32_bf16 v[46:49], v[156:159], v[188:191], v[46:49]
	v_mfma_f32_16x16x32_bf16 v[38:41], v[148:151], v[200:203], v[38:41]
	v_mfma_f32_16x16x32_bf16 v[30:33], v[156:159], v[200:203], v[30:33]
	v_mfma_f32_16x16x32_bf16 v[22:25], v[148:151], v[208:211], v[22:25]
	v_mfma_f32_16x16x32_bf16 v[14:17], v[156:159], v[208:211], v[14:17]
	v_mfma_f32_16x16x32_bf16 v[50:53], v[160:163], v[176:179], v[50:53]
	v_mfma_f32_16x16x32_bf16 v[42:45], v[168:171], v[176:179], v[42:45]
	v_mfma_f32_16x16x32_bf16 v[34:37], v[160:163], v[184:187], v[34:37]
	v_mfma_f32_16x16x32_bf16 v[26:29], v[168:171], v[184:187], v[26:29]
	v_mfma_f32_16x16x32_bf16 v[18:21], v[160:163], v[196:199], v[18:21]
	v_mfma_f32_16x16x32_bf16 v[10:13], v[168:171], v[196:199], v[10:13]
	v_mfma_f32_16x16x32_bf16 v[6:9], v[160:163], v[204:207], v[6:9]
	v_mfma_f32_16x16x32_bf16 v[2:5], v[168:171], v[204:207], v[2:5]
	v_mfma_f32_16x16x32_bf16 v[50:53], v[164:167], v[180:183], v[50:53]
	v_mfma_f32_16x16x32_bf16 v[42:45], v[172:175], v[180:183], v[42:45]
	v_mfma_f32_16x16x32_bf16 v[34:37], v[164:167], v[188:191], v[34:37]
	v_mfma_f32_16x16x32_bf16 v[26:29], v[172:175], v[188:191], v[26:29]
	v_mfma_f32_16x16x32_bf16 v[18:21], v[164:167], v[200:203], v[18:21]
	v_mfma_f32_16x16x32_bf16 v[10:13], v[172:175], v[200:203], v[10:13]
	v_mfma_f32_16x16x32_bf16 v[6:9], v[164:167], v[208:211], v[6:9]
	v_mfma_f32_16x16x32_bf16 v[2:5], v[172:175], v[208:211], v[2:5]
	s_setprio 0
	s_waitcnt vmcnt(8)
	s_barrier
	s_add_i32 s67, s67, 2
	s_add_u32 s40, s40, 0x100
	s_addc_u32 s41, s41, 0
	s_add_u32 s65, s65, 0x100
	s_addc_u32 s66, s66, 0
	s_cmp_gt_u32 s67, 61
	s_cbranch_scc0 .Lkt_L_5
	s_branch .Lkt_exit_5
.Lkt_T_5:
	ds_read_b128 v[144:147], v139
	ds_read_b128 v[148:151], v139 offset:1024
	ds_read_b128 v[152:155], v139 offset:2048
	ds_read_b128 v[156:159], v139 offset:3072
	ds_read_b128 v[160:163], v140
	ds_read_b128 v[164:167], v140 offset:1024
	ds_read_b128 v[168:171], v140 offset:2048
	ds_read_b128 v[172:175], v140 offset:3072
	s_add_u32 s42, s40, 0xfff00080
	s_addc_u32 s43, s41, -1
	s_cmp_eq_u32 s67, 60
	s_cselect_b32 s47, s27, s43
	s_cselect_b32 s46, s63, s42
	s_cselect_b32 s43, s25, s66
	s_cselect_b32 s42, s64, s65
	v_lshl_add_u64 v[192:193], s[40:41], 0, v[134:135]
	s_add_i32 m0, s29, 0xc000
	ds_read_b128 v[176:179], v142
	ds_read_b128 v[180:183], v142 offset:1024
	ds_read_b128 v[184:187], v142 offset:2048
	ds_read_b128 v[188:191], v142 offset:3072
	ds_read_b128 v[196:199], v142 offset:4096
	ds_read_b128 v[200:203], v142 offset:5120
	ds_read_b128 v[204:207], v142 offset:6144
	ds_read_b128 v[208:211], v142 offset:7168
	global_load_lds_dwordx4 v[192:193], off
	v_lshl_add_u64 v[192:193], s[40:41], 0, v[136:137]
	s_add_i32 m0, s29, 0xe000
	s_nop 0
	global_load_lds_dwordx4 v[192:193], off
	s_waitcnt vmcnt(8)
	s_waitcnt lgkmcnt(0)
	s_barrier
	s_setprio 1
	v_mfma_f32_16x16x32_bf16 v[126:129], v[144:147], v[176:179], v[126:129]
	v_mfma_f32_16x16x32_bf16 v[122:125], v[152:155], v[176:179], v[122:125]
	v_mfma_f32_16x16x32_bf16 v[118:121], v[144:147], v[184:187], v[118:121]
	v_mfma_f32_16x16x32_bf16 v[110:113], v[152:155], v[184:187], v[110:113]
	v_mfma_f32_16x16x32_bf16 v[102:105], v[144:147], v[196:199], v[102:105]
	v_mfma_f32_16x16x32_bf16 v[94:97], v[152:155], v[196:199], v[94:97]
	v_mfma_f32_16x16x32_bf16 v[86:89], v[144:147], v[204:207], v[86:89]
	v_mfma_f32_16x16x32_bf16 v[78:81], v[152:155], v[204:207], v[78:81]
	v_mfma_f32_16x16x32_bf16 v[126:129], v[148:151], v[180:183], v[126:129]
	v_mfma_f32_16x16x32_bf16 v[122:125], v[156:159], v[180:183], v[122:125]
	v_mfma_f32_16x16x32_bf16 v[118:121], v[148:151], v[188:191], v[118:121]
	v_mfma_f32_16x16x32_bf16 v[110:113], v[156:159], v[188:191], v[110:113]
	v_mfma_f32_16x16x32_bf16 v[102:105], v[148:151], v[200:203], v[102:105]
	v_mfma_f32_16x16x32_bf16 v[94:97], v[156:159], v[200:203], v[94:97]
	v_mfma_f32_16x16x32_bf16 v[86:89], v[148:151], v[208:211], v[86:89]
	v_mfma_f32_16x16x32_bf16 v[78:81], v[156:159], v[208:211], v[78:81]
	v_mfma_f32_16x16x32_bf16 v[114:117], v[160:163], v[176:179], v[114:117]
	v_mfma_f32_16x16x32_bf16 v[106:109], v[168:171], v[176:179], v[106:109]
	v_mfma_f32_16x16x32_bf16 v[98:101], v[160:163], v[184:187], v[98:101]
	v_mfma_f32_16x16x32_bf16 v[90:93], v[168:171], v[184:187], v[90:93]
	v_mfma_f32_16x16x32_bf16 v[82:85], v[160:163], v[196:199], v[82:85]
	v_mfma_f32_16x16x32_bf16 v[74:77], v[168:171], v[196:199], v[74:77]
	v_mfma_f32_16x16x32_bf16 v[70:73], v[160:163], v[204:207], v[70:73]
	v_mfma_f32_16x16x32_bf16 v[66:69], v[168:171], v[204:207], v[66:69]
	v_mfma_f32_16x16x32_bf16 v[114:117], v[164:167], v[180:183], v[114:117]
	v_mfma_f32_16x16x32_bf16 v[106:109], v[172:175], v[180:183], v[106:109]
	v_mfma_f32_16x16x32_bf16 v[98:101], v[164:167], v[188:191], v[98:101]
	v_mfma_f32_16x16x32_bf16 v[90:93], v[172:175], v[188:191], v[90:93]
	v_mfma_f32_16x16x32_bf16 v[82:85], v[164:167], v[200:203], v[82:85]
	v_mfma_f32_16x16x32_bf16 v[74:77], v[172:175], v[200:203], v[74:77]
	v_mfma_f32_16x16x32_bf16 v[70:73], v[164:167], v[208:211], v[70:73]
	v_mfma_f32_16x16x32_bf16 v[66:69], v[172:175], v[208:211], v[66:69]
	s_setprio 0
	s_barrier
	s_add_i32 s68, s59, s51
	v_lshl_add_u64 v[192:193], s[42:43], 0, v[130:131]
	s_mov_b32 m0, s68
	ds_read_b128 v[176:179], v142 offset:16384
	ds_read_b128 v[180:183], v142 offset:17408
	ds_read_b128 v[184:187], v142 offset:18432
	ds_read_b128 v[188:191], v142 offset:19456
	ds_read_b128 v[196:199], v142 offset:20480
	ds_read_b128 v[200:203], v142 offset:21504
	ds_read_b128 v[204:207], v142 offset:22528
	ds_read_b128 v[208:211], v142 offset:23552
	global_load_lds_dwordx4 v[192:193], off
	s_add_i32 m0, s68, 0x2000
	s_add_u32 s68, s42, 0x100000
	v_lshl_add_u64 v[212:213], s[42:43], 0, v[132:133]
	s_addc_u32 s69, s43, 0
	s_add_i32 s70, s60, s51
	global_load_lds_dwordx4 v[212:213], off
	v_lshl_add_u64 v[214:215], s[68:69], 0, v[130:131]
	s_mov_b32 m0, s70
	v_lshl_add_u64 v[216:217], s[46:47], 0, v[132:133]
	global_load_lds_dwordx4 v[214:215], off
	v_lshl_add_u64 v[214:215], s[68:69], 0, v[132:133]
	s_add_i32 m0, s70, 0x2000
	s_nop 0
	global_load_lds_dwordx4 v[214:215], off
	v_lshl_add_u64 v[214:215], s[46:47], 0, v[130:131]
	s_mov_b32 m0, s29
	s_nop 0
	global_load_lds_dwordx4 v[214:215], off
	s_mov_b32 m0, s52
	s_nop 0
	global_load_lds_dwordx4 v[216:217], off
	s_waitcnt vmcnt(8)
	s_waitcnt lgkmcnt(0)
	s_barrier
	s_setprio 1
	v_mfma_f32_16x16x32_bf16 v[62:65], v[144:147], v[176:179], v[62:65]
	v_mfma_f32_16x16x32_bf16 v[58:61], v[152:155], v[176:179], v[58:61]
	v_mfma_f32_16x16x32_bf16 v[54:57], v[144:147], v[184:187], v[54:57]
	v_mfma_f32_16x16x32_bf16 v[46:49], v[152:155], v[184:187], v[46:49]
	v_mfma_f32_16x16x32_bf16 v[38:41], v[144:147], v[196:199], v[38:41]
	v_mfma_f32_16x16x32_bf16 v[30:33], v[152:155], v[196:199], v[30:33]
	v_mfma_f32_16x16x32_bf16 v[22:25], v[144:147], v[204:207], v[22:25]
	v_mfma_f32_16x16x32_bf16 v[14:17], v[152:155], v[204:207], v[14:17]
	v_mfma_f32_16x16x32_bf16 v[62:65], v[148:151], v[180:183], v[62:65]
	v_mfma_f32_16x16x32_bf16 v[58:61], v[156:159], v[180:183], v[58:61]
	v_mfma_f32_16x16x32_bf16 v[54:57], v[148:151], v[188:191], v[54:57]
	v_mfma_f32_16x16x32_bf16 v[46:49], v[156:159], v[188:191], v[46:49]
	v_mfma_f32_16x16x32_bf16 v[38:41], v[148:151], v[200:203], v[38:41]
	v_mfma_f32_16x16x32_bf16 v[30:33], v[156:159], v[200:203], v[30:33]
	v_mfma_f32_16x16x32_bf16 v[22:25], v[148:151], v[208:211], v[22:25]
	v_mfma_f32_16x16x32_bf16 v[14:17], v[156:159], v[208:211], v[14:17]
	v_mfma_f32_16x16x32_bf16 v[50:53], v[160:163], v[176:179], v[50:53]
	v_mfma_f32_16x16x32_bf16 v[42:45], v[168:171], v[176:179], v[42:45]
	v_mfma_f32_16x16x32_bf16 v[34:37], v[160:163], v[184:187], v[34:37]
	v_mfma_f32_16x16x32_bf16 v[26:29], v[168:171], v[184:187], v[26:29]
	v_mfma_f32_16x16x32_bf16 v[18:21], v[160:163], v[196:199], v[18:21]
	v_mfma_f32_16x16x32_bf16 v[10:13], v[168:171], v[196:199], v[10:13]
	v_mfma_f32_16x16x32_bf16 v[6:9], v[160:163], v[204:207], v[6:9]
	v_mfma_f32_16x16x32_bf16 v[2:5], v[168:171], v[204:207], v[2:5]
	v_mfma_f32_16x16x32_bf16 v[50:53], v[164:167], v[180:183], v[50:53]
	v_mfma_f32_16x16x32_bf16 v[42:45], v[172:175], v[180:183], v[42:45]
	v_mfma_f32_16x16x32_bf16 v[34:37], v[164:167], v[188:191], v[34:37]
	v_mfma_f32_16x16x32_bf16 v[26:29], v[172:175], v[188:191], v[26:29]
	v_mfma_f32_16x16x32_bf16 v[18:21], v[164:167], v[200:203], v[18:21]
	v_mfma_f32_16x16x32_bf16 v[10:13], v[172:175], v[200:203], v[10:13]
	v_mfma_f32_16x16x32_bf16 v[6:9], v[164:167], v[208:211], v[6:9]
	v_mfma_f32_16x16x32_bf16 v[2:5], v[172:175], v[208:211], v[2:5]
	s_setprio 0
	s_barrier
	s_add_i32 s68, 0, 0x18000
	v_add_u32_e32 v143, s68, v1
	s_add_i32 s69, 0, 0x1c000
	ds_read_b128 v[144:147], v143
	ds_read_b128 v[148:151], v143 offset:1024
	ds_read_b128 v[152:155], v143 offset:2048
	ds_read_b128 v[156:159], v143 offset:3072
	v_add_u32_e32 v143, s69, v1
	ds_read_b128 v[160:163], v143
	ds_read_b128 v[164:167], v143 offset:1024
	ds_read_b128 v[168:171], v143 offset:2048
	ds_read_b128 v[172:175], v143 offset:3072
	s_add_u32 s46, s46, 0x100000
	s_addc_u32 s47, s47, 0
	s_mov_b32 m0, s53
	v_lshl_add_u64 v[218:219], s[46:47], 0, v[130:131]
	ds_read_b128 v[176:179], v142 offset:32768
	ds_read_b128 v[180:183], v142 offset:33792
	ds_read_b128 v[184:187], v142 offset:34816
	ds_read_b128 v[188:191], v142 offset:35840
	ds_read_b128 v[196:199], v142 offset:36864
	ds_read_b128 v[200:203], v142 offset:37888
	ds_read_b128 v[204:207], v142 offset:38912
	ds_read_b128 v[208:211], v142 offset:39936
	global_load_lds_dwordx4 v[218:219], off
	v_lshl_add_u64 v[218:219], s[46:47], 0, v[132:133]
	s_mov_b32 m0, s54
	s_nop 0
	global_load_lds_dwordx4 v[218:219], off
	s_waitcnt vmcnt(8)
	s_waitcnt lgkmcnt(0)
	s_barrier
	s_setprio 1
	v_mfma_f32_16x16x32_bf16 v[126:129], v[144:147], v[176:179], v[126:129]
	v_mfma_f32_16x16x32_bf16 v[122:125], v[152:155], v[176:179], v[122:125]
	v_mfma_f32_16x16x32_bf16 v[118:121], v[144:147], v[184:187], v[118:121]
	v_mfma_f32_16x16x32_bf16 v[110:113], v[152:155], v[184:187], v[110:113]
	v_mfma_f32_16x16x32_bf16 v[102:105], v[144:147], v[196:199], v[102:105]
	v_mfma_f32_16x16x32_bf16 v[94:97], v[152:155], v[196:199], v[94:97]
	v_mfma_f32_16x16x32_bf16 v[86:89], v[144:147], v[204:207], v[86:89]
	v_mfma_f32_16x16x32_bf16 v[78:81], v[152:155], v[204:207], v[78:81]
	v_mfma_f32_16x16x32_bf16 v[126:129], v[148:151], v[180:183], v[126:129]
	v_mfma_f32_16x16x32_bf16 v[122:125], v[156:159], v[180:183], v[122:125]
	v_mfma_f32_16x16x32_bf16 v[118:121], v[148:151], v[188:191], v[118:121]
	v_mfma_f32_16x16x32_bf16 v[110:113], v[156:159], v[188:191], v[110:113]
	v_mfma_f32_16x16x32_bf16 v[102:105], v[148:151], v[200:203], v[102:105]
	v_mfma_f32_16x16x32_bf16 v[94:97], v[156:159], v[200:203], v[94:97]
	v_mfma_f32_16x16x32_bf16 v[86:89], v[148:151], v[208:211], v[86:89]
	v_mfma_f32_16x16x32_bf16 v[78:81], v[156:159], v[208:211], v[78:81]
	v_mfma_f32_16x16x32_bf16 v[114:117], v[160:163], v[176:179], v[114:117]
	v_mfma_f32_16x16x32_bf16 v[106:109], v[168:171], v[176:179], v[106:109]
	v_mfma_f32_16x16x32_bf16 v[98:101], v[160:163], v[184:187], v[98:101]
	v_mfma_f32_16x16x32_bf16 v[90:93], v[168:171], v[184:187], v[90:93]
	v_mfma_f32_16x16x32_bf16 v[82:85], v[160:163], v[196:199], v[82:85]
	v_mfma_f32_16x16x32_bf16 v[74:77], v[168:171], v[196:199], v[74:77]
	v_mfma_f32_16x16x32_bf16 v[70:73], v[160:163], v[204:207], v[70:73]
	v_mfma_f32_16x16x32_bf16 v[66:69], v[168:171], v[204:207], v[66:69]
	v_mfma_f32_16x16x32_bf16 v[114:117], v[164:167], v[180:183], v[114:117]
	v_mfma_f32_16x16x32_bf16 v[106:109], v[172:175], v[180:183], v[106:109]
	v_mfma_f32_16x16x32_bf16 v[98:101], v[164:167], v[188:191], v[98:101]
	v_mfma_f32_16x16x32_bf16 v[90:93], v[172:175], v[188:191], v[90:93]
	v_mfma_f32_16x16x32_bf16 v[82:85], v[164:167], v[200:203], v[82:85]
	v_mfma_f32_16x16x32_bf16 v[74:77], v[172:175], v[200:203], v[74:77]
	v_mfma_f32_16x16x32_bf16 v[70:73], v[164:167], v[208:211], v[70:73]
	v_mfma_f32_16x16x32_bf16 v[66:69], v[172:175], v[208:211], v[66:69]
	s_setprio 0
	s_barrier
	s_add_i32 s46, s68, s51
	v_lshl_add_u64 v[192:193], v[192:193], 0, s[10:11]
	s_mov_b32 m0, s46
	ds_read_b128 v[176:179], v142 offset:49152
	ds_read_b128 v[180:183], v142 offset:50176
	ds_read_b128 v[184:187], v142 offset:51200
	ds_read_b128 v[188:191], v142 offset:52224
	ds_read_b128 v[196:199], v142 offset:53248
	ds_read_b128 v[200:203], v142 offset:54272
	ds_read_b128 v[204:207], v142 offset:55296
	ds_read_b128 v[208:211], v142 offset:56320
	global_load_lds_dwordx4 v[192:193], off
	s_add_i32 m0, s46, 0x2000
	s_add_u32 s42, s42, 0x100080
	v_lshl_add_u64 v[192:193], v[212:213], 0, s[10:11]
	s_addc_u32 s43, s43, 0
	s_add_i32 s46, s69, s51
	global_load_lds_dwordx4 v[192:193], off
	v_lshl_add_u64 v[192:193], s[42:43], 0, v[130:131]
	s_mov_b32 m0, s46
	s_nop 0
	global_load_lds_dwordx4 v[192:193], off
	v_lshl_add_u64 v[192:193], s[42:43], 0, v[132:133]
	s_add_i32 m0, s46, 0x2000
	s_nop 0
	global_load_lds_dwordx4 v[192:193], off
	v_lshl_add_u64 v[192:193], v[214:215], 0, s[10:11]
	s_mov_b32 m0, s56
	s_nop 0
	global_load_lds_dwordx4 v[192:193], off
	v_lshl_add_u64 v[192:193], v[216:217], 0, s[10:11]
	s_mov_b32 m0, s57
	s_nop 0
	global_load_lds_dwordx4 v[192:193], off
	s_nop 0
	s_waitcnt vmcnt(8)
	s_waitcnt lgkmcnt(0)
	s_barrier
	s_setprio 1
	v_mfma_f32_16x16x32_bf16 v[62:65], v[144:147], v[176:179], v[62:65]
	v_mfma_f32_16x16x32_bf16 v[58:61], v[152:155], v[176:179], v[58:61]
	v_mfma_f32_16x16x32_bf16 v[54:57], v[144:147], v[184:187], v[54:57]
	v_mfma_f32_16x16x32_bf16 v[46:49], v[152:155], v[184:187], v[46:49]
	v_mfma_f32_16x16x32_bf16 v[38:41], v[144:147], v[196:199], v[38:41]
	v_mfma_f32_16x16x32_bf16 v[30:33], v[152:155], v[196:199], v[30:33]
	v_mfma_f32_16x16x32_bf16 v[22:25], v[144:147], v[204:207], v[22:25]
	v_mfma_f32_16x16x32_bf16 v[14:17], v[152:155], v[204:207], v[14:17]
	v_mfma_f32_16x16x32_bf16 v[62:65], v[148:151], v[180:183], v[62:65]
	v_mfma_f32_16x16x32_bf16 v[58:61], v[156:159], v[180:183], v[58:61]
	v_mfma_f32_16x16x32_bf16 v[54:57], v[148:151], v[188:191], v[54:57]
	v_mfma_f32_16x16x32_bf16 v[46:49], v[156:159], v[188:191], v[46:49]
	v_mfma_f32_16x16x32_bf16 v[38:41], v[148:151], v[200:203], v[38:41]
	v_mfma_f32_16x16x32_bf16 v[30:33], v[156:159], v[200:203], v[30:33]
	v_mfma_f32_16x16x32_bf16 v[22:25], v[148:151], v[208:211], v[22:25]
	v_mfma_f32_16x16x32_bf16 v[14:17], v[156:159], v[208:211], v[14:17]
	v_mfma_f32_16x16x32_bf16 v[50:53], v[160:163], v[176:179], v[50:53]
	v_mfma_f32_16x16x32_bf16 v[42:45], v[168:171], v[176:179], v[42:45]
	v_mfma_f32_16x16x32_bf16 v[34:37], v[160:163], v[184:187], v[34:37]
	v_mfma_f32_16x16x32_bf16 v[26:29], v[168:171], v[184:187], v[26:29]
	v_mfma_f32_16x16x32_bf16 v[18:21], v[160:163], v[196:199], v[18:21]
	v_mfma_f32_16x16x32_bf16 v[10:13], v[168:171], v[196:199], v[10:13]
	v_mfma_f32_16x16x32_bf16 v[6:9], v[160:163], v[204:207], v[6:9]
	v_mfma_f32_16x16x32_bf16 v[2:5], v[168:171], v[204:207], v[2:5]
	v_mfma_f32_16x16x32_bf16 v[50:53], v[164:167], v[180:183], v[50:53]
	v_mfma_f32_16x16x32_bf16 v[42:45], v[172:175], v[180:183], v[42:45]
	v_mfma_f32_16x16x32_bf16 v[34:37], v[164:167], v[188:191], v[34:37]
	v_mfma_f32_16x16x32_bf16 v[26:29], v[172:175], v[188:191], v[26:29]
	v_mfma_f32_16x16x32_bf16 v[18:21], v[164:167], v[200:203], v[18:21]
	v_mfma_f32_16x16x32_bf16 v[10:13], v[172:175], v[200:203], v[10:13]
	v_mfma_f32_16x16x32_bf16 v[6:9], v[164:167], v[208:211], v[6:9]
	v_mfma_f32_16x16x32_bf16 v[2:5], v[172:175], v[208:211], v[2:5]
	s_setprio 0
	s_barrier
	s_add_i32 s67, s67, 2
	s_add_u32 s40, s40, 0x100
	s_addc_u32 s41, s41, 0
	s_add_u32 s65, s65, 0x100
	s_addc_u32 s66, s66, 0
	s_cmp_gt_u32 s67, 61
	s_cbranch_scc0 .Lkt_T_5
	s_nop 7

.Lkt_L_6:
	ds_read_b128 v[146:149], v152
	ds_read_b128 v[156:159], v152 offset:1024
	ds_read_b128 v[160:163], v152 offset:2048
	ds_read_b128 v[164:167], v152 offset:3072
	ds_read_b128 v[168:171], v153
	ds_read_b128 v[172:175], v153 offset:1024
	ds_read_b128 v[176:179], v153 offset:2048
	ds_read_b128 v[180:183], v153 offset:3072
	s_add_u32 s30, s28, 0xfff80080
	s_addc_u32 s31, s29, -1
	s_cmp_eq_u32 s57, 28
	s_cselect_b32 s35, s21, s31
	s_cselect_b32 s34, s53, s30
	s_cselect_b32 s31, s19, s56
	s_cselect_b32 s30, s54, s55
	v_lshl_add_u64 v[192:193], s[28:29], 0, v[138:139]
	s_add_i32 m0, s27, 0xc000
	ds_read_b128 v[184:187], v154
	ds_read_b128 v[188:191], v154 offset:1024
	ds_read_b128 v[196:199], v154 offset:2048
	ds_read_b128 v[200:203], v154 offset:3072
	ds_read_b128 v[206:209], v154 offset:4096
	ds_read_b128 v[210:213], v154 offset:5120
	ds_read_b128 v[214:217], v154 offset:6144
	ds_read_b128 v[218:221], v154 offset:7168
	global_load_lds_dwordx4 v[192:193], off
	v_lshl_add_u64 v[192:193], s[28:29], 0, v[140:141]
	s_add_i32 m0, s27, 0xe000
	s_nop 0
	global_load_lds_dwordx4 v[192:193], off
	s_waitcnt lgkmcnt(0)
	s_barrier
	s_nop 0
	s_setprio 1
	v_mfma_f32_16x16x32_bf16 v[126:129], v[146:149], v[184:187], v[126:129]
	v_mfma_f32_16x16x32_bf16 v[122:125], v[160:163], v[184:187], v[122:125]
	v_mfma_f32_16x16x32_bf16 v[110:113], v[146:149], v[196:199], v[110:113]
	v_mfma_f32_16x16x32_bf16 v[106:109], v[160:163], v[196:199], v[106:109]
	v_mfma_f32_16x16x32_bf16 v[98:101], v[146:149], v[206:209], v[98:101]
	v_mfma_f32_16x16x32_bf16 v[90:93], v[160:163], v[206:209], v[90:93]
	v_mfma_f32_16x16x32_bf16 v[78:81], v[146:149], v[214:217], v[78:81]
	v_mfma_f32_16x16x32_bf16 v[74:77], v[160:163], v[214:217], v[74:77]
	v_mfma_f32_16x16x32_bf16 v[126:129], v[156:159], v[188:191], v[126:129]
	v_mfma_f32_16x16x32_bf16 v[122:125], v[164:167], v[188:191], v[122:125]
	v_mfma_f32_16x16x32_bf16 v[110:113], v[156:159], v[200:203], v[110:113]
	v_mfma_f32_16x16x32_bf16 v[106:109], v[164:167], v[200:203], v[106:109]
	v_mfma_f32_16x16x32_bf16 v[98:101], v[156:159], v[210:213], v[98:101]
	v_mfma_f32_16x16x32_bf16 v[90:93], v[164:167], v[210:213], v[90:93]
	v_mfma_f32_16x16x32_bf16 v[78:81], v[156:159], v[218:221], v[78:81]
	v_mfma_f32_16x16x32_bf16 v[74:77], v[164:167], v[218:221], v[74:77]
	v_mfma_f32_16x16x32_bf16 v[118:121], v[168:171], v[184:187], v[118:121]
	v_mfma_f32_16x16x32_bf16 v[114:117], v[176:179], v[184:187], v[114:117]
	v_mfma_f32_16x16x32_bf16 v[102:105], v[168:171], v[196:199], v[102:105]
	v_mfma_f32_16x16x32_bf16 v[94:97], v[176:179], v[196:199], v[94:97]
	v_mfma_f32_16x16x32_bf16 v[86:89], v[168:171], v[206:209], v[86:89]
	v_mfma_f32_16x16x32_bf16 v[82:85], v[176:179], v[206:209], v[82:85]
	v_mfma_f32_16x16x32_bf16 v[70:73], v[168:171], v[214:217], v[70:73]
	v_mfma_f32_16x16x32_bf16 v[66:69], v[176:179], v[214:217], v[66:69]
	v_mfma_f32_16x16x32_bf16 v[118:121], v[172:175], v[188:191], v[118:121]
	v_mfma_f32_16x16x32_bf16 v[114:117], v[180:183], v[188:191], v[114:117]
	v_mfma_f32_16x16x32_bf16 v[102:105], v[172:175], v[200:203], v[102:105]
	v_mfma_f32_16x16x32_bf16 v[94:97], v[180:183], v[200:203], v[94:97]
	v_mfma_f32_16x16x32_bf16 v[86:89], v[172:175], v[210:213], v[86:89]
	v_mfma_f32_16x16x32_bf16 v[82:85], v[180:183], v[210:213], v[82:85]
	v_mfma_f32_16x16x32_bf16 v[70:73], v[172:175], v[218:221], v[70:73]
	v_mfma_f32_16x16x32_bf16 v[66:69], v[180:183], v[218:221], v[66:69]
	s_setprio 0
	s_waitcnt vmcnt(8)
	s_barrier
	s_add_i32 s58, s50, s40
	v_lshl_add_u64 v[192:193], s[30:31], 0, v[134:135]
	s_mov_b32 m0, s58
	ds_read_b128 v[184:187], v154 offset:16384
	ds_read_b128 v[188:191], v154 offset:17408
	ds_read_b128 v[196:199], v154 offset:18432
	ds_read_b128 v[200:203], v154 offset:19456
	ds_read_b128 v[206:209], v154 offset:20480
	ds_read_b128 v[210:213], v154 offset:21504
	ds_read_b128 v[214:217], v154 offset:22528
	ds_read_b128 v[218:221], v154 offset:23552
	global_load_lds_dwordx4 v[192:193], off
	s_add_i32 m0, s58, 0x2000
	s_add_u32 s58, s30, 0x80000
	v_lshl_add_u64 v[222:223], s[30:31], 0, v[130:131]
	s_addc_u32 s59, s31, 0
	s_add_i32 s60, s51, s40
	global_load_lds_dwordx4 v[222:223], off
	v_lshl_add_u64 v[224:225], s[58:59], 0, v[134:135]
	s_mov_b32 m0, s60
	v_lshl_add_u64 v[226:227], s[34:35], 0, v[132:133]
	global_load_lds_dwordx4 v[224:225], off
	v_lshl_add_u64 v[224:225], s[58:59], 0, v[130:131]
	s_add_i32 m0, s60, 0x2000
	s_nop 0
	global_load_lds_dwordx4 v[224:225], off
	v_lshl_add_u64 v[224:225], s[34:35], 0, v[136:137]
	s_mov_b32 m0, s27
	s_nop 0
	global_load_lds_dwordx4 v[224:225], off
	s_mov_b32 m0, s42
	s_nop 0
	global_load_lds_dwordx4 v[226:227], off
	s_waitcnt lgkmcnt(0)
	s_barrier
	s_setprio 1
	v_mfma_f32_16x16x32_bf16 v[62:65], v[146:149], v[184:187], v[62:65]
	v_mfma_f32_16x16x32_bf16 v[58:61], v[160:163], v[184:187], v[58:61]
	v_mfma_f32_16x16x32_bf16 v[46:49], v[146:149], v[196:199], v[46:49]
	v_mfma_f32_16x16x32_bf16 v[42:45], v[160:163], v[196:199], v[42:45]
	v_mfma_f32_16x16x32_bf16 v[30:33], v[146:149], v[206:209], v[30:33]
	v_mfma_f32_16x16x32_bf16 v[26:29], v[160:163], v[206:209], v[26:29]
	v_mfma_f32_16x16x32_bf16 v[14:17], v[146:149], v[214:217], v[14:17]
	v_mfma_f32_16x16x32_bf16 v[10:13], v[160:163], v[214:217], v[10:13]
	v_mfma_f32_16x16x32_bf16 v[62:65], v[156:159], v[188:191], v[62:65]
	v_mfma_f32_16x16x32_bf16 v[58:61], v[164:167], v[188:191], v[58:61]
	v_mfma_f32_16x16x32_bf16 v[46:49], v[156:159], v[200:203], v[46:49]
	v_mfma_f32_16x16x32_bf16 v[42:45], v[164:167], v[200:203], v[42:45]
	v_mfma_f32_16x16x32_bf16 v[30:33], v[156:159], v[210:213], v[30:33]
	v_mfma_f32_16x16x32_bf16 v[26:29], v[164:167], v[210:213], v[26:29]
	v_mfma_f32_16x16x32_bf16 v[14:17], v[156:159], v[218:221], v[14:17]
	v_mfma_f32_16x16x32_bf16 v[10:13], v[164:167], v[218:221], v[10:13]
	v_mfma_f32_16x16x32_bf16 v[54:57], v[168:171], v[184:187], v[54:57]
	v_mfma_f32_16x16x32_bf16 v[50:53], v[176:179], v[184:187], v[50:53]
	v_mfma_f32_16x16x32_bf16 v[38:41], v[168:171], v[196:199], v[38:41]
	v_mfma_f32_16x16x32_bf16 v[34:37], v[176:179], v[196:199], v[34:37]
	v_mfma_f32_16x16x32_bf16 v[22:25], v[168:171], v[206:209], v[22:25]
	v_mfma_f32_16x16x32_bf16 v[18:21], v[176:179], v[206:209], v[18:21]
	v_mfma_f32_16x16x32_bf16 v[6:9], v[168:171], v[214:217], v[6:9]
	v_mfma_f32_16x16x32_bf16 v[2:5], v[176:179], v[214:217], v[2:5]
	v_mfma_f32_16x16x32_bf16 v[54:57], v[172:175], v[188:191], v[54:57]
	v_mfma_f32_16x16x32_bf16 v[50:53], v[180:183], v[188:191], v[50:53]
	v_mfma_f32_16x16x32_bf16 v[38:41], v[172:175], v[200:203], v[38:41]
	v_mfma_f32_16x16x32_bf16 v[34:37], v[180:183], v[200:203], v[34:37]
	v_mfma_f32_16x16x32_bf16 v[22:25], v[172:175], v[210:213], v[22:25]
	v_mfma_f32_16x16x32_bf16 v[18:21], v[180:183], v[210:213], v[18:21]
	v_mfma_f32_16x16x32_bf16 v[6:9], v[172:175], v[218:221], v[6:9]
	v_mfma_f32_16x16x32_bf16 v[2:5], v[180:183], v[218:221], v[2:5]
	s_setprio 0
	s_waitcnt vmcnt(8)
	s_barrier
	s_add_i32 s58, 0, 0x18000
	v_add_u32_e32 v155, s58, v150
	s_add_i32 s59, 0, 0x1c000
	ds_read_b128 v[146:149], v155
	ds_read_b128 v[156:159], v155 offset:1024
	ds_read_b128 v[160:163], v155 offset:2048
	ds_read_b128 v[164:167], v155 offset:3072
	v_add_u32_e32 v155, s59, v150
	ds_read_b128 v[168:171], v155
	ds_read_b128 v[172:175], v155 offset:1024
	ds_read_b128 v[176:179], v155 offset:2048
	ds_read_b128 v[180:183], v155 offset:3072
	s_add_u32 s34, s34, 0x80000
	s_addc_u32 s35, s35, 0
	s_mov_b32 m0, s43
	v_lshl_add_u64 v[228:229], s[34:35], 0, v[136:137]
	ds_read_b128 v[184:187], v154 offset:32768
	ds_read_b128 v[188:191], v154 offset:33792
	ds_read_b128 v[196:199], v154 offset:34816
	ds_read_b128 v[200:203], v154 offset:35840
	ds_read_b128 v[206:209], v154 offset:36864
	ds_read_b128 v[210:213], v154 offset:37888
	ds_read_b128 v[214:217], v154 offset:38912
	ds_read_b128 v[218:221], v154 offset:39936
	global_load_lds_dwordx4 v[228:229], off
	v_lshl_add_u64 v[228:229], s[34:35], 0, v[132:133]
	s_mov_b32 m0, s45
	s_nop 0
	global_load_lds_dwordx4 v[228:229], off
	s_waitcnt lgkmcnt(0)
	s_barrier
	s_setprio 1
	v_mfma_f32_16x16x32_bf16 v[126:129], v[146:149], v[184:187], v[126:129]
	v_mfma_f32_16x16x32_bf16 v[122:125], v[160:163], v[184:187], v[122:125]
	v_mfma_f32_16x16x32_bf16 v[110:113], v[146:149], v[196:199], v[110:113]
	v_mfma_f32_16x16x32_bf16 v[106:109], v[160:163], v[196:199], v[106:109]
	v_mfma_f32_16x16x32_bf16 v[98:101], v[146:149], v[206:209], v[98:101]
	v_mfma_f32_16x16x32_bf16 v[90:93], v[160:163], v[206:209], v[90:93]
	v_mfma_f32_16x16x32_bf16 v[78:81], v[146:149], v[214:217], v[78:81]
	v_mfma_f32_16x16x32_bf16 v[74:77], v[160:163], v[214:217], v[74:77]
	v_mfma_f32_16x16x32_bf16 v[126:129], v[156:159], v[188:191], v[126:129]
	v_mfma_f32_16x16x32_bf16 v[122:125], v[164:167], v[188:191], v[122:125]
	v_mfma_f32_16x16x32_bf16 v[110:113], v[156:159], v[200:203], v[110:113]
	v_mfma_f32_16x16x32_bf16 v[106:109], v[164:167], v[200:203], v[106:109]
	v_mfma_f32_16x16x32_bf16 v[98:101], v[156:159], v[210:213], v[98:101]
	v_mfma_f32_16x16x32_bf16 v[90:93], v[164:167], v[210:213], v[90:93]
	v_mfma_f32_16x16x32_bf16 v[78:81], v[156:159], v[218:221], v[78:81]
	v_mfma_f32_16x16x32_bf16 v[74:77], v[164:167], v[218:221], v[74:77]
	v_mfma_f32_16x16x32_bf16 v[118:121], v[168:171], v[184:187], v[118:121]
	v_mfma_f32_16x16x32_bf16 v[114:117], v[176:179], v[184:187], v[114:117]
	v_mfma_f32_16x16x32_bf16 v[102:105], v[168:171], v[196:199], v[102:105]
	v_mfma_f32_16x16x32_bf16 v[94:97], v[176:179], v[196:199], v[94:97]
	v_mfma_f32_16x16x32_bf16 v[86:89], v[168:171], v[206:209], v[86:89]
	v_mfma_f32_16x16x32_bf16 v[82:85], v[176:179], v[206:209], v[82:85]
	v_mfma_f32_16x16x32_bf16 v[70:73], v[168:171], v[214:217], v[70:73]
	v_mfma_f32_16x16x32_bf16 v[66:69], v[176:179], v[214:217], v[66:69]
	v_mfma_f32_16x16x32_bf16 v[118:121], v[172:175], v[188:191], v[118:121]
	v_mfma_f32_16x16x32_bf16 v[114:117], v[180:183], v[188:191], v[114:117]
	v_mfma_f32_16x16x32_bf16 v[102:105], v[172:175], v[200:203], v[102:105]
	v_mfma_f32_16x16x32_bf16 v[94:97], v[180:183], v[200:203], v[94:97]
	v_mfma_f32_16x16x32_bf16 v[86:89], v[172:175], v[210:213], v[86:89]
	v_mfma_f32_16x16x32_bf16 v[82:85], v[180:183], v[210:213], v[82:85]
	v_mfma_f32_16x16x32_bf16 v[70:73], v[172:175], v[218:221], v[70:73]
	v_mfma_f32_16x16x32_bf16 v[66:69], v[180:183], v[218:221], v[66:69]
	s_setprio 0
	s_waitcnt vmcnt(8)
	s_barrier
	s_add_i32 s34, s58, s40
	v_lshl_add_u64 v[192:193], v[192:193], 0, s[14:15]
	s_mov_b32 m0, s34
	ds_read_b128 v[184:187], v154 offset:49152
	ds_read_b128 v[188:191], v154 offset:50176
	ds_read_b128 v[196:199], v154 offset:51200
	ds_read_b128 v[200:203], v154 offset:52224
	ds_read_b128 v[206:209], v154 offset:53248
	ds_read_b128 v[210:213], v154 offset:54272
	ds_read_b128 v[214:217], v154 offset:55296
	ds_read_b128 v[218:221], v154 offset:56320
	global_load_lds_dwordx4 v[192:193], off
	s_add_i32 m0, s34, 0x2000
	s_add_u32 s30, s30, 0x80080
	v_lshl_add_u64 v[192:193], v[222:223], 0, s[14:15]
	s_addc_u32 s31, s31, 0
	s_add_i32 s34, s59, s40
	global_load_lds_dwordx4 v[192:193], off
	v_lshl_add_u64 v[192:193], s[30:31], 0, v[134:135]
	s_mov_b32 m0, s34
	s_nop 0
	global_load_lds_dwordx4 v[192:193], off
	v_lshl_add_u64 v[192:193], s[30:31], 0, v[130:131]
	s_add_i32 m0, s34, 0x2000
	s_nop 0
	global_load_lds_dwordx4 v[192:193], off
	v_lshl_add_u64 v[192:193], v[224:225], 0, s[14:15]
	s_mov_b32 m0, s47
	s_nop 0
	global_load_lds_dwordx4 v[192:193], off
	v_lshl_add_u64 v[192:193], v[226:227], 0, s[14:15]
	s_mov_b32 m0, s48
	s_nop 0
	global_load_lds_dwordx4 v[192:193], off
	s_waitcnt lgkmcnt(0)
	s_barrier
	s_nop 0
	s_setprio 1
	v_mfma_f32_16x16x32_bf16 v[62:65], v[146:149], v[184:187], v[62:65]
	v_mfma_f32_16x16x32_bf16 v[58:61], v[160:163], v[184:187], v[58:61]
	v_mfma_f32_16x16x32_bf16 v[46:49], v[146:149], v[196:199], v[46:49]
	v_mfma_f32_16x16x32_bf16 v[42:45], v[160:163], v[196:199], v[42:45]
	v_mfma_f32_16x16x32_bf16 v[30:33], v[146:149], v[206:209], v[30:33]
	v_mfma_f32_16x16x32_bf16 v[26:29], v[160:163], v[206:209], v[26:29]
	v_mfma_f32_16x16x32_bf16 v[14:17], v[146:149], v[214:217], v[14:17]
	v_mfma_f32_16x16x32_bf16 v[10:13], v[160:163], v[214:217], v[10:13]
	v_mfma_f32_16x16x32_bf16 v[62:65], v[156:159], v[188:191], v[62:65]
	v_mfma_f32_16x16x32_bf16 v[58:61], v[164:167], v[188:191], v[58:61]
	v_mfma_f32_16x16x32_bf16 v[46:49], v[156:159], v[200:203], v[46:49]
	v_mfma_f32_16x16x32_bf16 v[42:45], v[164:167], v[200:203], v[42:45]
	v_mfma_f32_16x16x32_bf16 v[30:33], v[156:159], v[210:213], v[30:33]
	v_mfma_f32_16x16x32_bf16 v[26:29], v[164:167], v[210:213], v[26:29]
	v_mfma_f32_16x16x32_bf16 v[14:17], v[156:159], v[218:221], v[14:17]
	v_mfma_f32_16x16x32_bf16 v[10:13], v[164:167], v[218:221], v[10:13]
	v_mfma_f32_16x16x32_bf16 v[54:57], v[168:171], v[184:187], v[54:57]
	v_mfma_f32_16x16x32_bf16 v[50:53], v[176:179], v[184:187], v[50:53]
	v_mfma_f32_16x16x32_bf16 v[38:41], v[168:171], v[196:199], v[38:41]
	v_mfma_f32_16x16x32_bf16 v[34:37], v[176:179], v[196:199], v[34:37]
	v_mfma_f32_16x16x32_bf16 v[22:25], v[168:171], v[206:209], v[22:25]
	v_mfma_f32_16x16x32_bf16 v[18:21], v[176:179], v[206:209], v[18:21]
	v_mfma_f32_16x16x32_bf16 v[6:9], v[168:171], v[214:217], v[6:9]
	v_mfma_f32_16x16x32_bf16 v[2:5], v[176:179], v[214:217], v[2:5]
	v_mfma_f32_16x16x32_bf16 v[54:57], v[172:175], v[188:191], v[54:57]
	v_mfma_f32_16x16x32_bf16 v[50:53], v[180:183], v[188:191], v[50:53]
	v_mfma_f32_16x16x32_bf16 v[38:41], v[172:175], v[200:203], v[38:41]
	v_mfma_f32_16x16x32_bf16 v[34:37], v[180:183], v[200:203], v[34:37]
	v_mfma_f32_16x16x32_bf16 v[22:25], v[172:175], v[210:213], v[22:25]
	v_mfma_f32_16x16x32_bf16 v[18:21], v[180:183], v[210:213], v[18:21]
	v_mfma_f32_16x16x32_bf16 v[6:9], v[172:175], v[218:221], v[6:9]
	v_mfma_f32_16x16x32_bf16 v[2:5], v[180:183], v[218:221], v[2:5]
	s_setprio 0
	s_waitcnt vmcnt(8)
	s_barrier
	s_add_i32 s57, s57, 2
	s_add_u32 s28, s28, 0x100
	s_addc_u32 s29, s29, 0
	s_add_u32 s55, s55, 0x100
	s_addc_u32 s56, s56, 0
	s_cmp_gt_u32 s57, 29
	s_cbranch_scc0 .Lkt_L_6
	s_branch .Lkt_exit_6
.Lkt_T_6:
	ds_read_b128 v[146:149], v152
	ds_read_b128 v[156:159], v152 offset:1024
	ds_read_b128 v[160:163], v152 offset:2048
	ds_read_b128 v[164:167], v152 offset:3072
	ds_read_b128 v[168:171], v153
	ds_read_b128 v[172:175], v153 offset:1024
	ds_read_b128 v[176:179], v153 offset:2048
	ds_read_b128 v[180:183], v153 offset:3072
	s_add_u32 s30, s28, 0xfff80080
	s_addc_u32 s31, s29, -1
	s_cmp_eq_u32 s57, 28
	s_cselect_b32 s35, s21, s31
	s_cselect_b32 s34, s53, s30
	s_cselect_b32 s31, s19, s56
	s_cselect_b32 s30, s54, s55
	v_lshl_add_u64 v[192:193], s[28:29], 0, v[138:139]
	s_add_i32 m0, s27, 0xc000
	ds_read_b128 v[184:187], v154
	ds_read_b128 v[188:191], v154 offset:1024
	ds_read_b128 v[196:199], v154 offset:2048
	ds_read_b128 v[200:203], v154 offset:3072
	ds_read_b128 v[206:209], v154 offset:4096
	ds_read_b128 v[210:213], v154 offset:5120
	ds_read_b128 v[214:217], v154 offset:6144
	ds_read_b128 v[218:221], v154 offset:7168
	global_load_lds_dwordx4 v[192:193], off
	v_lshl_add_u64 v[192:193], s[28:29], 0, v[140:141]
	s_add_i32 m0, s27, 0xe000
	s_nop 0
	global_load_lds_dwordx4 v[192:193], off
	s_waitcnt vmcnt(8)
	s_waitcnt lgkmcnt(0)
	s_barrier
	s_setprio 1
	v_mfma_f32_16x16x32_bf16 v[126:129], v[146:149], v[184:187], v[126:129]
	v_mfma_f32_16x16x32_bf16 v[122:125], v[160:163], v[184:187], v[122:125]
	v_mfma_f32_16x16x32_bf16 v[110:113], v[146:149], v[196:199], v[110:113]
	v_mfma_f32_16x16x32_bf16 v[106:109], v[160:163], v[196:199], v[106:109]
	v_mfma_f32_16x16x32_bf16 v[98:101], v[146:149], v[206:209], v[98:101]
	v_mfma_f32_16x16x32_bf16 v[90:93], v[160:163], v[206:209], v[90:93]
	v_mfma_f32_16x16x32_bf16 v[78:81], v[146:149], v[214:217], v[78:81]
	v_mfma_f32_16x16x32_bf16 v[74:77], v[160:163], v[214:217], v[74:77]
	v_mfma_f32_16x16x32_bf16 v[126:129], v[156:159], v[188:191], v[126:129]
	v_mfma_f32_16x16x32_bf16 v[122:125], v[164:167], v[188:191], v[122:125]
	v_mfma_f32_16x16x32_bf16 v[110:113], v[156:159], v[200:203], v[110:113]
	v_mfma_f32_16x16x32_bf16 v[106:109], v[164:167], v[200:203], v[106:109]
	v_mfma_f32_16x16x32_bf16 v[98:101], v[156:159], v[210:213], v[98:101]
	v_mfma_f32_16x16x32_bf16 v[90:93], v[164:167], v[210:213], v[90:93]
	v_mfma_f32_16x16x32_bf16 v[78:81], v[156:159], v[218:221], v[78:81]
	v_mfma_f32_16x16x32_bf16 v[74:77], v[164:167], v[218:221], v[74:77]
	v_mfma_f32_16x16x32_bf16 v[118:121], v[168:171], v[184:187], v[118:121]
	v_mfma_f32_16x16x32_bf16 v[114:117], v[176:179], v[184:187], v[114:117]
	v_mfma_f32_16x16x32_bf16 v[102:105], v[168:171], v[196:199], v[102:105]
	v_mfma_f32_16x16x32_bf16 v[94:97], v[176:179], v[196:199], v[94:97]
	v_mfma_f32_16x16x32_bf16 v[86:89], v[168:171], v[206:209], v[86:89]
	v_mfma_f32_16x16x32_bf16 v[82:85], v[176:179], v[206:209], v[82:85]
	v_mfma_f32_16x16x32_bf16 v[70:73], v[168:171], v[214:217], v[70:73]
	v_mfma_f32_16x16x32_bf16 v[66:69], v[176:179], v[214:217], v[66:69]
	v_mfma_f32_16x16x32_bf16 v[118:121], v[172:175], v[188:191], v[118:121]
	v_mfma_f32_16x16x32_bf16 v[114:117], v[180:183], v[188:191], v[114:117]
	v_mfma_f32_16x16x32_bf16 v[102:105], v[172:175], v[200:203], v[102:105]
	v_mfma_f32_16x16x32_bf16 v[94:97], v[180:183], v[200:203], v[94:97]
	v_mfma_f32_16x16x32_bf16 v[86:89], v[172:175], v[210:213], v[86:89]
	v_mfma_f32_16x16x32_bf16 v[82:85], v[180:183], v[210:213], v[82:85]
	v_mfma_f32_16x16x32_bf16 v[70:73], v[172:175], v[218:221], v[70:73]
	v_mfma_f32_16x16x32_bf16 v[66:69], v[180:183], v[218:221], v[66:69]
	s_setprio 0
	s_barrier
	s_add_i32 s58, s50, s40
	v_lshl_add_u64 v[192:193], s[30:31], 0, v[134:135]
	s_mov_b32 m0, s58
	ds_read_b128 v[184:187], v154 offset:16384
	ds_read_b128 v[188:191], v154 offset:17408
	ds_read_b128 v[196:199], v154 offset:18432
	ds_read_b128 v[200:203], v154 offset:19456
	ds_read_b128 v[206:209], v154 offset:20480
	ds_read_b128 v[210:213], v154 offset:21504
	ds_read_b128 v[214:217], v154 offset:22528
	ds_read_b128 v[218:221], v154 offset:23552
	global_load_lds_dwordx4 v[192:193], off
	s_add_i32 m0, s58, 0x2000
	s_add_u32 s58, s30, 0x80000
	v_lshl_add_u64 v[222:223], s[30:31], 0, v[130:131]
	s_addc_u32 s59, s31, 0
	s_add_i32 s60, s51, s40
	global_load_lds_dwordx4 v[222:223], off
	v_lshl_add_u64 v[224:225], s[58:59], 0, v[134:135]
	s_mov_b32 m0, s60
	v_lshl_add_u64 v[226:227], s[34:35], 0, v[132:133]
	global_load_lds_dwordx4 v[224:225], off
	v_lshl_add_u64 v[224:225], s[58:59], 0, v[130:131]
	s_add_i32 m0, s60, 0x2000
	s_nop 0
	global_load_lds_dwordx4 v[224:225], off
	v_lshl_add_u64 v[224:225], s[34:35], 0, v[136:137]
	s_mov_b32 m0, s27
	s_nop 0
	global_load_lds_dwordx4 v[224:225], off
	s_mov_b32 m0, s42
	s_nop 0
	global_load_lds_dwordx4 v[226:227], off
	s_waitcnt vmcnt(8)
	s_waitcnt lgkmcnt(0)
	s_barrier
	s_setprio 1
	v_mfma_f32_16x16x32_bf16 v[62:65], v[146:149], v[184:187], v[62:65]
	v_mfma_f32_16x16x32_bf16 v[58:61], v[160:163], v[184:187], v[58:61]
	v_mfma_f32_16x16x32_bf16 v[46:49], v[146:149], v[196:199], v[46:49]
	v_mfma_f32_16x16x32_bf16 v[42:45], v[160:163], v[196:199], v[42:45]
	v_mfma_f32_16x16x32_bf16 v[30:33], v[146:149], v[206:209], v[30:33]
	v_mfma_f32_16x16x32_bf16 v[26:29], v[160:163], v[206:209], v[26:29]
	v_mfma_f32_16x16x32_bf16 v[14:17], v[146:149], v[214:217], v[14:17]
	v_mfma_f32_16x16x32_bf16 v[10:13], v[160:163], v[214:217], v[10:13]
	v_mfma_f32_16x16x32_bf16 v[62:65], v[156:159], v[188:191], v[62:65]
	v_mfma_f32_16x16x32_bf16 v[58:61], v[164:167], v[188:191], v[58:61]
	v_mfma_f32_16x16x32_bf16 v[46:49], v[156:159], v[200:203], v[46:49]
	v_mfma_f32_16x16x32_bf16 v[42:45], v[164:167], v[200:203], v[42:45]
	v_mfma_f32_16x16x32_bf16 v[30:33], v[156:159], v[210:213], v[30:33]
	v_mfma_f32_16x16x32_bf16 v[26:29], v[164:167], v[210:213], v[26:29]
	v_mfma_f32_16x16x32_bf16 v[14:17], v[156:159], v[218:221], v[14:17]
	v_mfma_f32_16x16x32_bf16 v[10:13], v[164:167], v[218:221], v[10:13]
	v_mfma_f32_16x16x32_bf16 v[54:57], v[168:171], v[184:187], v[54:57]
	v_mfma_f32_16x16x32_bf16 v[50:53], v[176:179], v[184:187], v[50:53]
	v_mfma_f32_16x16x32_bf16 v[38:41], v[168:171], v[196:199], v[38:41]
	v_mfma_f32_16x16x32_bf16 v[34:37], v[176:179], v[196:199], v[34:37]
	v_mfma_f32_16x16x32_bf16 v[22:25], v[168:171], v[206:209], v[22:25]
	v_mfma_f32_16x16x32_bf16 v[18:21], v[176:179], v[206:209], v[18:21]
	v_mfma_f32_16x16x32_bf16 v[6:9], v[168:171], v[214:217], v[6:9]
	v_mfma_f32_16x16x32_bf16 v[2:5], v[176:179], v[214:217], v[2:5]
	v_mfma_f32_16x16x32_bf16 v[54:57], v[172:175], v[188:191], v[54:57]
	v_mfma_f32_16x16x32_bf16 v[50:53], v[180:183], v[188:191], v[50:53]
	v_mfma_f32_16x16x32_bf16 v[38:41], v[172:175], v[200:203], v[38:41]
	v_mfma_f32_16x16x32_bf16 v[34:37], v[180:183], v[200:203], v[34:37]
	v_mfma_f32_16x16x32_bf16 v[22:25], v[172:175], v[210:213], v[22:25]
	v_mfma_f32_16x16x32_bf16 v[18:21], v[180:183], v[210:213], v[18:21]
	v_mfma_f32_16x16x32_bf16 v[6:9], v[172:175], v[218:221], v[6:9]
	v_mfma_f32_16x16x32_bf16 v[2:5], v[180:183], v[218:221], v[2:5]
	s_setprio 0
	s_barrier
	s_add_i32 s58, 0, 0x18000
	v_add_u32_e32 v155, s58, v150
	s_add_i32 s59, 0, 0x1c000
	ds_read_b128 v[146:149], v155
	ds_read_b128 v[156:159], v155 offset:1024
	ds_read_b128 v[160:163], v155 offset:2048
	ds_read_b128 v[164:167], v155 offset:3072
	v_add_u32_e32 v155, s59, v150
	ds_read_b128 v[168:171], v155
	ds_read_b128 v[172:175], v155 offset:1024
	ds_read_b128 v[176:179], v155 offset:2048
	ds_read_b128 v[180:183], v155 offset:3072
	s_add_u32 s34, s34, 0x80000
	s_addc_u32 s35, s35, 0
	s_mov_b32 m0, s43
	v_lshl_add_u64 v[228:229], s[34:35], 0, v[136:137]
	ds_read_b128 v[184:187], v154 offset:32768
	ds_read_b128 v[188:191], v154 offset:33792
	ds_read_b128 v[196:199], v154 offset:34816
	ds_read_b128 v[200:203], v154 offset:35840
	ds_read_b128 v[206:209], v154 offset:36864
	ds_read_b128 v[210:213], v154 offset:37888
	ds_read_b128 v[214:217], v154 offset:38912
	ds_read_b128 v[218:221], v154 offset:39936
	global_load_lds_dwordx4 v[228:229], off
	v_lshl_add_u64 v[228:229], s[34:35], 0, v[132:133]
	s_mov_b32 m0, s45
	s_nop 0
	global_load_lds_dwordx4 v[228:229], off
	s_waitcnt vmcnt(8)
	s_waitcnt lgkmcnt(0)
	s_barrier
	s_setprio 1
	v_mfma_f32_16x16x32_bf16 v[126:129], v[146:149], v[184:187], v[126:129]
	v_mfma_f32_16x16x32_bf16 v[122:125], v[160:163], v[184:187], v[122:125]
	v_mfma_f32_16x16x32_bf16 v[110:113], v[146:149], v[196:199], v[110:113]
	v_mfma_f32_16x16x32_bf16 v[106:109], v[160:163], v[196:199], v[106:109]
	v_mfma_f32_16x16x32_bf16 v[98:101], v[146:149], v[206:209], v[98:101]
	v_mfma_f32_16x16x32_bf16 v[90:93], v[160:163], v[206:209], v[90:93]
	v_mfma_f32_16x16x32_bf16 v[78:81], v[146:149], v[214:217], v[78:81]
	v_mfma_f32_16x16x32_bf16 v[74:77], v[160:163], v[214:217], v[74:77]
	v_mfma_f32_16x16x32_bf16 v[126:129], v[156:159], v[188:191], v[126:129]
	v_mfma_f32_16x16x32_bf16 v[122:125], v[164:167], v[188:191], v[122:125]
	v_mfma_f32_16x16x32_bf16 v[110:113], v[156:159], v[200:203], v[110:113]
	v_mfma_f32_16x16x32_bf16 v[106:109], v[164:167], v[200:203], v[106:109]
	v_mfma_f32_16x16x32_bf16 v[98:101], v[156:159], v[210:213], v[98:101]
	v_mfma_f32_16x16x32_bf16 v[90:93], v[164:167], v[210:213], v[90:93]
	v_mfma_f32_16x16x32_bf16 v[78:81], v[156:159], v[218:221], v[78:81]
	v_mfma_f32_16x16x32_bf16 v[74:77], v[164:167], v[218:221], v[74:77]
	v_mfma_f32_16x16x32_bf16 v[118:121], v[168:171], v[184:187], v[118:121]
	v_mfma_f32_16x16x32_bf16 v[114:117], v[176:179], v[184:187], v[114:117]
	v_mfma_f32_16x16x32_bf16 v[102:105], v[168:171], v[196:199], v[102:105]
	v_mfma_f32_16x16x32_bf16 v[94:97], v[176:179], v[196:199], v[94:97]
	v_mfma_f32_16x16x32_bf16 v[86:89], v[168:171], v[206:209], v[86:89]
	v_mfma_f32_16x16x32_bf16 v[82:85], v[176:179], v[206:209], v[82:85]
	v_mfma_f32_16x16x32_bf16 v[70:73], v[168:171], v[214:217], v[70:73]
	v_mfma_f32_16x16x32_bf16 v[66:69], v[176:179], v[214:217], v[66:69]
	v_mfma_f32_16x16x32_bf16 v[118:121], v[172:175], v[188:191], v[118:121]
	v_mfma_f32_16x16x32_bf16 v[114:117], v[180:183], v[188:191], v[114:117]
	v_mfma_f32_16x16x32_bf16 v[102:105], v[172:175], v[200:203], v[102:105]
	v_mfma_f32_16x16x32_bf16 v[94:97], v[180:183], v[200:203], v[94:97]
	v_mfma_f32_16x16x32_bf16 v[86:89], v[172:175], v[210:213], v[86:89]
	v_mfma_f32_16x16x32_bf16 v[82:85], v[180:183], v[210:213], v[82:85]
	v_mfma_f32_16x16x32_bf16 v[70:73], v[172:175], v[218:221], v[70:73]
	v_mfma_f32_16x16x32_bf16 v[66:69], v[180:183], v[218:221], v[66:69]
	s_setprio 0
	s_barrier
	s_add_i32 s34, s58, s40
	v_lshl_add_u64 v[192:193], v[192:193], 0, s[14:15]
	s_mov_b32 m0, s34
	ds_read_b128 v[184:187], v154 offset:49152
	ds_read_b128 v[188:191], v154 offset:50176
	ds_read_b128 v[196:199], v154 offset:51200
	ds_read_b128 v[200:203], v154 offset:52224
	ds_read_b128 v[206:209], v154 offset:53248
	ds_read_b128 v[210:213], v154 offset:54272
	ds_read_b128 v[214:217], v154 offset:55296
	ds_read_b128 v[218:221], v154 offset:56320
	global_load_lds_dwordx4 v[192:193], off
	s_add_i32 m0, s34, 0x2000
	s_add_u32 s30, s30, 0x80080
	v_lshl_add_u64 v[192:193], v[222:223], 0, s[14:15]
	s_addc_u32 s31, s31, 0
	s_add_i32 s34, s59, s40
	global_load_lds_dwordx4 v[192:193], off
	v_lshl_add_u64 v[192:193], s[30:31], 0, v[134:135]
	s_mov_b32 m0, s34
	s_nop 0
	global_load_lds_dwordx4 v[192:193], off
	v_lshl_add_u64 v[192:193], s[30:31], 0, v[130:131]
	s_add_i32 m0, s34, 0x2000
	s_nop 0
	global_load_lds_dwordx4 v[192:193], off
	v_lshl_add_u64 v[192:193], v[224:225], 0, s[14:15]
	s_mov_b32 m0, s47
	s_nop 0
	global_load_lds_dwordx4 v[192:193], off
	v_lshl_add_u64 v[192:193], v[226:227], 0, s[14:15]
	s_mov_b32 m0, s48
	s_nop 0
	global_load_lds_dwordx4 v[192:193], off
	s_nop 0
	s_waitcnt vmcnt(8)
	s_waitcnt lgkmcnt(0)
	s_barrier
	s_setprio 1
	v_mfma_f32_16x16x32_bf16 v[62:65], v[146:149], v[184:187], v[62:65]
	v_mfma_f32_16x16x32_bf16 v[58:61], v[160:163], v[184:187], v[58:61]
	v_mfma_f32_16x16x32_bf16 v[46:49], v[146:149], v[196:199], v[46:49]
	v_mfma_f32_16x16x32_bf16 v[42:45], v[160:163], v[196:199], v[42:45]
	v_mfma_f32_16x16x32_bf16 v[30:33], v[146:149], v[206:209], v[30:33]
	v_mfma_f32_16x16x32_bf16 v[26:29], v[160:163], v[206:209], v[26:29]
	v_mfma_f32_16x16x32_bf16 v[14:17], v[146:149], v[214:217], v[14:17]
	v_mfma_f32_16x16x32_bf16 v[10:13], v[160:163], v[214:217], v[10:13]
	v_mfma_f32_16x16x32_bf16 v[62:65], v[156:159], v[188:191], v[62:65]
	v_mfma_f32_16x16x32_bf16 v[58:61], v[164:167], v[188:191], v[58:61]
	v_mfma_f32_16x16x32_bf16 v[46:49], v[156:159], v[200:203], v[46:49]
	v_mfma_f32_16x16x32_bf16 v[42:45], v[164:167], v[200:203], v[42:45]
	v_mfma_f32_16x16x32_bf16 v[30:33], v[156:159], v[210:213], v[30:33]
	v_mfma_f32_16x16x32_bf16 v[26:29], v[164:167], v[210:213], v[26:29]
	v_mfma_f32_16x16x32_bf16 v[14:17], v[156:159], v[218:221], v[14:17]
	v_mfma_f32_16x16x32_bf16 v[10:13], v[164:167], v[218:221], v[10:13]
	v_mfma_f32_16x16x32_bf16 v[54:57], v[168:171], v[184:187], v[54:57]
	v_mfma_f32_16x16x32_bf16 v[50:53], v[176:179], v[184:187], v[50:53]
	v_mfma_f32_16x16x32_bf16 v[38:41], v[168:171], v[196:199], v[38:41]
	v_mfma_f32_16x16x32_bf16 v[34:37], v[176:179], v[196:199], v[34:37]
	v_mfma_f32_16x16x32_bf16 v[22:25], v[168:171], v[206:209], v[22:25]
	v_mfma_f32_16x16x32_bf16 v[18:21], v[176:179], v[206:209], v[18:21]
	v_mfma_f32_16x16x32_bf16 v[6:9], v[168:171], v[214:217], v[6:9]
	v_mfma_f32_16x16x32_bf16 v[2:5], v[176:179], v[214:217], v[2:5]
	v_mfma_f32_16x16x32_bf16 v[54:57], v[172:175], v[188:191], v[54:57]
	v_mfma_f32_16x16x32_bf16 v[50:53], v[180:183], v[188:191], v[50:53]
	v_mfma_f32_16x16x32_bf16 v[38:41], v[172:175], v[200:203], v[38:41]
	v_mfma_f32_16x16x32_bf16 v[34:37], v[180:183], v[200:203], v[34:37]
	v_mfma_f32_16x16x32_bf16 v[22:25], v[172:175], v[210:213], v[22:25]
	v_mfma_f32_16x16x32_bf16 v[18:21], v[180:183], v[210:213], v[18:21]
	v_mfma_f32_16x16x32_bf16 v[6:9], v[172:175], v[218:221], v[6:9]
	v_mfma_f32_16x16x32_bf16 v[2:5], v[180:183], v[218:221], v[2:5]
	s_setprio 0
	s_barrier
	s_add_i32 s57, s57, 2
	s_add_u32 s28, s28, 0x100
	s_addc_u32 s29, s29, 0
	s_add_u32 s55, s55, 0x100
	s_addc_u32 s56, s56, 0
	s_cmp_gt_u32 s57, 29
	s_cbranch_scc0 .Lkt_T_6
	s_nop 7
.Lkt_exit_6:
	s_and_b64 vcc, exec, s[16:17]
	s_cbranch_vccz .LBB0_970
	s_barrier

.Lkt_L_7:
	ds_read_b128 v[150:153], v158
	ds_read_b128 v[162:165], v158 offset:1024
	ds_read_b128 v[166:169], v158 offset:2048
	ds_read_b128 v[170:173], v158 offset:3072
	ds_read_b128 v[174:177], v159
	ds_read_b128 v[178:181], v159 offset:1024
	ds_read_b128 v[182:185], v159 offset:2048
	ds_read_b128 v[186:189], v159 offset:3072
	s_add_i32 s84, s48, 2
	s_add_u32 s49, s62, 0xfff00080
	s_addc_u32 s64, s63, -1
	s_cmp_eq_u32 s51, s48
	s_cselect_b32 s48, s56, s53
	s_cselect_b32 s65, s9, s64
	s_cselect_b32 s64, s8, s49
	s_cselect_b32 s49, s57, s55
	v_lshl_add_u64 v[154:155], s[62:63], 0, v[138:139]
	s_add_i32 m0, s59, 0xc000
	ds_read_b128 v[190:193], v160
	ds_read_b128 v[196:199], v160 offset:1024
	ds_read_b128 v[200:203], v160 offset:2048
	ds_read_b128 v[206:209], v160 offset:3072
	ds_read_b128 v[210:213], v160 offset:4096
	ds_read_b128 v[214:217], v160 offset:5120
	ds_read_b128 v[218:221], v160 offset:6144
	ds_read_b128 v[222:225], v160 offset:7168
	global_load_lds_dwordx4 v[154:155], off
	v_lshl_add_u64 v[154:155], s[62:63], 0, v[140:141]
	s_add_i32 m0, s59, 0xe000
	s_nop 0
	global_load_lds_dwordx4 v[154:155], off
	s_waitcnt lgkmcnt(0)
	s_barrier
	s_nop 0
	s_setprio 1
	v_mfma_f32_16x16x32_bf16 v[126:129], v[150:153], v[190:193], v[126:129]
	v_mfma_f32_16x16x32_bf16 v[122:125], v[166:169], v[190:193], v[122:125]
	v_mfma_f32_16x16x32_bf16 v[110:113], v[150:153], v[200:203], v[110:113]
	v_mfma_f32_16x16x32_bf16 v[106:109], v[166:169], v[200:203], v[106:109]
	v_mfma_f32_16x16x32_bf16 v[94:97], v[150:153], v[210:213], v[94:97]
	v_mfma_f32_16x16x32_bf16 v[90:93], v[166:169], v[210:213], v[90:93]
	v_mfma_f32_16x16x32_bf16 v[78:81], v[150:153], v[218:221], v[78:81]
	v_mfma_f32_16x16x32_bf16 v[74:77], v[166:169], v[218:221], v[74:77]
	v_mfma_f32_16x16x32_bf16 v[126:129], v[162:165], v[196:199], v[126:129]
	v_mfma_f32_16x16x32_bf16 v[122:125], v[170:173], v[196:199], v[122:125]
	v_mfma_f32_16x16x32_bf16 v[110:113], v[162:165], v[206:209], v[110:113]
	v_mfma_f32_16x16x32_bf16 v[106:109], v[170:173], v[206:209], v[106:109]
	v_mfma_f32_16x16x32_bf16 v[94:97], v[162:165], v[214:217], v[94:97]
	v_mfma_f32_16x16x32_bf16 v[90:93], v[170:173], v[214:217], v[90:93]
	v_mfma_f32_16x16x32_bf16 v[78:81], v[162:165], v[222:225], v[78:81]
	v_mfma_f32_16x16x32_bf16 v[74:77], v[170:173], v[222:225], v[74:77]
	v_mfma_f32_16x16x32_bf16 v[118:121], v[174:177], v[190:193], v[118:121]
	v_mfma_f32_16x16x32_bf16 v[114:117], v[182:185], v[190:193], v[114:117]
	v_mfma_f32_16x16x32_bf16 v[102:105], v[174:177], v[200:203], v[102:105]
	v_mfma_f32_16x16x32_bf16 v[98:101], v[182:185], v[200:203], v[98:101]
	v_mfma_f32_16x16x32_bf16 v[86:89], v[174:177], v[210:213], v[86:89]
	v_mfma_f32_16x16x32_bf16 v[82:85], v[182:185], v[210:213], v[82:85]
	v_mfma_f32_16x16x32_bf16 v[70:73], v[174:177], v[218:221], v[70:73]
	v_mfma_f32_16x16x32_bf16 v[66:69], v[182:185], v[218:221], v[66:69]
	v_mfma_f32_16x16x32_bf16 v[118:121], v[178:181], v[196:199], v[118:121]
	v_mfma_f32_16x16x32_bf16 v[114:117], v[186:189], v[196:199], v[114:117]
	v_mfma_f32_16x16x32_bf16 v[102:105], v[178:181], v[206:209], v[102:105]
	v_mfma_f32_16x16x32_bf16 v[98:101], v[186:189], v[206:209], v[98:101]
	v_mfma_f32_16x16x32_bf16 v[86:89], v[178:181], v[214:217], v[86:89]
	v_mfma_f32_16x16x32_bf16 v[82:85], v[186:189], v[214:217], v[82:85]
	v_mfma_f32_16x16x32_bf16 v[70:73], v[178:181], v[222:225], v[70:73]
	v_mfma_f32_16x16x32_bf16 v[66:69], v[186:189], v[222:225], v[66:69]
	s_setprio 0
	s_waitcnt vmcnt(8)
	s_barrier
	s_add_i32 s85, s75, s66
	v_lshl_add_u64 v[154:155], s[48:49], 0, v[132:133]
	s_mov_b32 m0, s85
	ds_read_b128 v[190:193], v160 offset:16384
	ds_read_b128 v[196:199], v160 offset:17408
	ds_read_b128 v[200:203], v160 offset:18432
	ds_read_b128 v[206:209], v160 offset:19456
	ds_read_b128 v[210:213], v160 offset:20480
	ds_read_b128 v[214:217], v160 offset:21504
	ds_read_b128 v[218:221], v160 offset:22528
	ds_read_b128 v[222:225], v160 offset:23552
	global_load_lds_dwordx4 v[154:155], off
	s_add_i32 m0, s85, 0x2000
	s_add_u32 s86, s48, 0x100000
	v_lshl_add_u64 v[226:227], s[48:49], 0, v[136:137]
	s_addc_u32 s87, s49, 0
	s_add_i32 s85, s76, s66
	global_load_lds_dwordx4 v[226:227], off
	v_lshl_add_u64 v[228:229], s[86:87], 0, v[132:133]
	s_mov_b32 m0, s85
	v_lshl_add_u64 v[230:231], s[64:65], 0, v[134:135]
	global_load_lds_dwordx4 v[228:229], off
	v_lshl_add_u64 v[228:229], s[86:87], 0, v[136:137]
	s_add_i32 m0, s85, 0x2000
	s_nop 0
	global_load_lds_dwordx4 v[228:229], off
	v_lshl_add_u64 v[228:229], s[64:65], 0, v[130:131]
	s_mov_b32 m0, s59
	s_nop 0
	global_load_lds_dwordx4 v[228:229], off
	s_mov_b32 m0, s61
	s_nop 0
	global_load_lds_dwordx4 v[230:231], off
	s_waitcnt lgkmcnt(0)
	s_barrier
	s_setprio 1
	v_mfma_f32_16x16x32_bf16 v[62:65], v[150:153], v[190:193], v[62:65]
	v_mfma_f32_16x16x32_bf16 v[58:61], v[166:169], v[190:193], v[58:61]
	v_mfma_f32_16x16x32_bf16 v[46:49], v[150:153], v[200:203], v[46:49]
	v_mfma_f32_16x16x32_bf16 v[42:45], v[166:169], v[200:203], v[42:45]
	v_mfma_f32_16x16x32_bf16 v[30:33], v[150:153], v[210:213], v[30:33]
	v_mfma_f32_16x16x32_bf16 v[26:29], v[166:169], v[210:213], v[26:29]
	v_mfma_f32_16x16x32_bf16 v[14:17], v[150:153], v[218:221], v[14:17]
	v_mfma_f32_16x16x32_bf16 v[10:13], v[166:169], v[218:221], v[10:13]
	v_mfma_f32_16x16x32_bf16 v[62:65], v[162:165], v[196:199], v[62:65]
	v_mfma_f32_16x16x32_bf16 v[58:61], v[170:173], v[196:199], v[58:61]
	v_mfma_f32_16x16x32_bf16 v[46:49], v[162:165], v[206:209], v[46:49]
	v_mfma_f32_16x16x32_bf16 v[42:45], v[170:173], v[206:209], v[42:45]
	v_mfma_f32_16x16x32_bf16 v[30:33], v[162:165], v[214:217], v[30:33]
	v_mfma_f32_16x16x32_bf16 v[26:29], v[170:173], v[214:217], v[26:29]
	v_mfma_f32_16x16x32_bf16 v[14:17], v[162:165], v[222:225], v[14:17]
	v_mfma_f32_16x16x32_bf16 v[10:13], v[170:173], v[222:225], v[10:13]
	v_mfma_f32_16x16x32_bf16 v[54:57], v[174:177], v[190:193], v[54:57]
	v_mfma_f32_16x16x32_bf16 v[50:53], v[182:185], v[190:193], v[50:53]
	v_mfma_f32_16x16x32_bf16 v[38:41], v[174:177], v[200:203], v[38:41]
	v_mfma_f32_16x16x32_bf16 v[34:37], v[182:185], v[200:203], v[34:37]
	v_mfma_f32_16x16x32_bf16 v[22:25], v[174:177], v[210:213], v[22:25]
	v_mfma_f32_16x16x32_bf16 v[18:21], v[182:185], v[210:213], v[18:21]
	v_mfma_f32_16x16x32_bf16 v[6:9], v[174:177], v[218:221], v[6:9]
	v_mfma_f32_16x16x32_bf16 v[2:5], v[182:185], v[218:221], v[2:5]
	v_mfma_f32_16x16x32_bf16 v[54:57], v[178:181], v[196:199], v[54:57]
	v_mfma_f32_16x16x32_bf16 v[50:53], v[186:189], v[196:199], v[50:53]
	v_mfma_f32_16x16x32_bf16 v[38:41], v[178:181], v[206:209], v[38:41]
	v_mfma_f32_16x16x32_bf16 v[34:37], v[186:189], v[206:209], v[34:37]
	v_mfma_f32_16x16x32_bf16 v[22:25], v[178:181], v[214:217], v[22:25]
	v_mfma_f32_16x16x32_bf16 v[18:21], v[186:189], v[214:217], v[18:21]
	v_mfma_f32_16x16x32_bf16 v[6:9], v[178:181], v[222:225], v[6:9]
	v_mfma_f32_16x16x32_bf16 v[2:5], v[186:189], v[222:225], v[2:5]
	s_setprio 0
	s_waitcnt vmcnt(8)
	s_barrier
	s_add_i32 s85, 0, 0x18000
	v_add_u32_e32 v161, s85, v156
	s_add_i32 s86, 0, 0x1c000
	ds_read_b128 v[150:153], v161
	ds_read_b128 v[162:165], v161 offset:1024
	ds_read_b128 v[166:169], v161 offset:2048
	ds_read_b128 v[170:173], v161 offset:3072
	v_add_u32_e32 v161, s86, v156
	ds_read_b128 v[174:177], v161
	ds_read_b128 v[178:181], v161 offset:1024
	ds_read_b128 v[182:185], v161 offset:2048
	ds_read_b128 v[186:189], v161 offset:3072
	s_add_u32 s64, s64, 0x100000
	s_addc_u32 s65, s65, 0
	s_mov_b32 m0, s67
	v_lshl_add_u64 v[232:233], s[64:65], 0, v[130:131]
	ds_read_b128 v[190:193], v160 offset:32768
	ds_read_b128 v[196:199], v160 offset:33792
	ds_read_b128 v[200:203], v160 offset:34816
	ds_read_b128 v[206:209], v160 offset:35840
	ds_read_b128 v[210:213], v160 offset:36864
	ds_read_b128 v[214:217], v160 offset:37888
	ds_read_b128 v[218:221], v160 offset:38912
	ds_read_b128 v[222:225], v160 offset:39936
	global_load_lds_dwordx4 v[232:233], off
	v_lshl_add_u64 v[232:233], s[64:65], 0, v[134:135]
	s_mov_b32 m0, s68
	s_nop 0
	global_load_lds_dwordx4 v[232:233], off
	s_waitcnt lgkmcnt(0)
	s_barrier
	s_setprio 1
	v_mfma_f32_16x16x32_bf16 v[126:129], v[150:153], v[190:193], v[126:129]
	v_mfma_f32_16x16x32_bf16 v[122:125], v[166:169], v[190:193], v[122:125]
	v_mfma_f32_16x16x32_bf16 v[110:113], v[150:153], v[200:203], v[110:113]
	v_mfma_f32_16x16x32_bf16 v[106:109], v[166:169], v[200:203], v[106:109]
	v_mfma_f32_16x16x32_bf16 v[94:97], v[150:153], v[210:213], v[94:97]
	v_mfma_f32_16x16x32_bf16 v[90:93], v[166:169], v[210:213], v[90:93]
	v_mfma_f32_16x16x32_bf16 v[78:81], v[150:153], v[218:221], v[78:81]
	v_mfma_f32_16x16x32_bf16 v[74:77], v[166:169], v[218:221], v[74:77]
	v_mfma_f32_16x16x32_bf16 v[126:129], v[162:165], v[196:199], v[126:129]
	v_mfma_f32_16x16x32_bf16 v[122:125], v[170:173], v[196:199], v[122:125]
	v_mfma_f32_16x16x32_bf16 v[110:113], v[162:165], v[206:209], v[110:113]
	v_mfma_f32_16x16x32_bf16 v[106:109], v[170:173], v[206:209], v[106:109]
	v_mfma_f32_16x16x32_bf16 v[94:97], v[162:165], v[214:217], v[94:97]
	v_mfma_f32_16x16x32_bf16 v[90:93], v[170:173], v[214:217], v[90:93]
	v_mfma_f32_16x16x32_bf16 v[78:81], v[162:165], v[222:225], v[78:81]
	v_mfma_f32_16x16x32_bf16 v[74:77], v[170:173], v[222:225], v[74:77]
	v_mfma_f32_16x16x32_bf16 v[118:121], v[174:177], v[190:193], v[118:121]
	v_mfma_f32_16x16x32_bf16 v[114:117], v[182:185], v[190:193], v[114:117]
	v_mfma_f32_16x16x32_bf16 v[102:105], v[174:177], v[200:203], v[102:105]
	v_mfma_f32_16x16x32_bf16 v[98:101], v[182:185], v[200:203], v[98:101]
	v_mfma_f32_16x16x32_bf16 v[86:89], v[174:177], v[210:213], v[86:89]
	v_mfma_f32_16x16x32_bf16 v[82:85], v[182:185], v[210:213], v[82:85]
	v_mfma_f32_16x16x32_bf16 v[70:73], v[174:177], v[218:221], v[70:73]
	v_mfma_f32_16x16x32_bf16 v[66:69], v[182:185], v[218:221], v[66:69]
	v_mfma_f32_16x16x32_bf16 v[118:121], v[178:181], v[196:199], v[118:121]
	v_mfma_f32_16x16x32_bf16 v[114:117], v[186:189], v[196:199], v[114:117]
	v_mfma_f32_16x16x32_bf16 v[102:105], v[178:181], v[206:209], v[102:105]
	v_mfma_f32_16x16x32_bf16 v[98:101], v[186:189], v[206:209], v[98:101]
	v_mfma_f32_16x16x32_bf16 v[86:89], v[178:181], v[214:217], v[86:89]
	v_mfma_f32_16x16x32_bf16 v[82:85], v[186:189], v[214:217], v[82:85]
	v_mfma_f32_16x16x32_bf16 v[70:73], v[178:181], v[222:225], v[70:73]
	v_mfma_f32_16x16x32_bf16 v[66:69], v[186:189], v[222:225], v[66:69]
	s_setprio 0
	s_waitcnt vmcnt(8)
	s_barrier
	s_add_i32 s64, s85, s66
	v_lshl_add_u64 v[154:155], v[154:155], 0, s[20:21]
	s_mov_b32 m0, s64
	ds_read_b128 v[190:193], v160 offset:49152
	ds_read_b128 v[196:199], v160 offset:50176
	ds_read_b128 v[200:203], v160 offset:51200
	ds_read_b128 v[206:209], v160 offset:52224
	ds_read_b128 v[210:213], v160 offset:53248
	ds_read_b128 v[214:217], v160 offset:54272
	ds_read_b128 v[218:221], v160 offset:55296
	ds_read_b128 v[222:225], v160 offset:56320
	global_load_lds_dwordx4 v[154:155], off
	s_add_i32 m0, s64, 0x2000
	s_add_u32 s48, s48, 0x100080
	v_lshl_add_u64 v[154:155], v[226:227], 0, s[20:21]
	s_addc_u32 s49, s49, 0
	s_add_i32 s64, s86, s66
	global_load_lds_dwordx4 v[154:155], off
	v_lshl_add_u64 v[154:155], s[48:49], 0, v[132:133]
	s_mov_b32 m0, s64
	s_nop 0
	global_load_lds_dwordx4 v[154:155], off
	v_lshl_add_u64 v[154:155], s[48:49], 0, v[136:137]
	s_add_i32 m0, s64, 0x2000
	s_nop 0
	global_load_lds_dwordx4 v[154:155], off
	v_lshl_add_u64 v[154:155], v[228:229], 0, s[20:21]
	s_mov_b32 m0, s72
	s_nop 0
	global_load_lds_dwordx4 v[154:155], off
	v_lshl_add_u64 v[154:155], v[230:231], 0, s[20:21]
	s_mov_b32 m0, s73
	s_nop 0
	global_load_lds_dwordx4 v[154:155], off
	s_waitcnt lgkmcnt(0)
	s_barrier
	s_nop 0
	s_setprio 1
	v_mfma_f32_16x16x32_bf16 v[62:65], v[150:153], v[190:193], v[62:65]
	v_mfma_f32_16x16x32_bf16 v[58:61], v[166:169], v[190:193], v[58:61]
	v_mfma_f32_16x16x32_bf16 v[46:49], v[150:153], v[200:203], v[46:49]
	v_mfma_f32_16x16x32_bf16 v[42:45], v[166:169], v[200:203], v[42:45]
	v_mfma_f32_16x16x32_bf16 v[30:33], v[150:153], v[210:213], v[30:33]
	v_mfma_f32_16x16x32_bf16 v[26:29], v[166:169], v[210:213], v[26:29]
	v_mfma_f32_16x16x32_bf16 v[14:17], v[150:153], v[218:221], v[14:17]
	v_mfma_f32_16x16x32_bf16 v[10:13], v[166:169], v[218:221], v[10:13]
	v_mfma_f32_16x16x32_bf16 v[62:65], v[162:165], v[196:199], v[62:65]
	v_mfma_f32_16x16x32_bf16 v[58:61], v[170:173], v[196:199], v[58:61]
	v_mfma_f32_16x16x32_bf16 v[46:49], v[162:165], v[206:209], v[46:49]
	v_mfma_f32_16x16x32_bf16 v[42:45], v[170:173], v[206:209], v[42:45]
	v_mfma_f32_16x16x32_bf16 v[30:33], v[162:165], v[214:217], v[30:33]
	v_mfma_f32_16x16x32_bf16 v[26:29], v[170:173], v[214:217], v[26:29]
	v_mfma_f32_16x16x32_bf16 v[14:17], v[162:165], v[222:225], v[14:17]
	v_mfma_f32_16x16x32_bf16 v[10:13], v[170:173], v[222:225], v[10:13]
	v_mfma_f32_16x16x32_bf16 v[54:57], v[174:177], v[190:193], v[54:57]
	v_mfma_f32_16x16x32_bf16 v[50:53], v[182:185], v[190:193], v[50:53]
	v_mfma_f32_16x16x32_bf16 v[38:41], v[174:177], v[200:203], v[38:41]
	v_mfma_f32_16x16x32_bf16 v[34:37], v[182:185], v[200:203], v[34:37]
	v_mfma_f32_16x16x32_bf16 v[22:25], v[174:177], v[210:213], v[22:25]
	v_mfma_f32_16x16x32_bf16 v[18:21], v[182:185], v[210:213], v[18:21]
	v_mfma_f32_16x16x32_bf16 v[6:9], v[174:177], v[218:221], v[6:9]
	v_mfma_f32_16x16x32_bf16 v[2:5], v[182:185], v[218:221], v[2:5]
	v_mfma_f32_16x16x32_bf16 v[54:57], v[178:181], v[196:199], v[54:57]
	v_mfma_f32_16x16x32_bf16 v[50:53], v[186:189], v[196:199], v[50:53]
	v_mfma_f32_16x16x32_bf16 v[38:41], v[178:181], v[206:209], v[38:41]
	v_mfma_f32_16x16x32_bf16 v[34:37], v[186:189], v[206:209], v[34:37]
	v_mfma_f32_16x16x32_bf16 v[22:25], v[178:181], v[214:217], v[22:25]
	v_mfma_f32_16x16x32_bf16 v[18:21], v[186:189], v[214:217], v[18:21]
	v_mfma_f32_16x16x32_bf16 v[6:9], v[178:181], v[222:225], v[6:9]
	v_mfma_f32_16x16x32_bf16 v[2:5], v[186:189], v[222:225], v[2:5]
	s_setprio 0
	s_waitcnt vmcnt(8)
	s_barrier
	s_add_u32 s62, s62, 0x100
	s_addc_u32 s63, s63, 0
	s_add_u32 s53, s53, 0x100
	s_addc_u32 s55, s55, 0
	s_cmp_ge_i32 s84, s83
	s_mov_b32 s48, s84
	s_cbranch_scc0 .Lkt_L_7
	s_branch .Lkt_exit_7
.Lkt_T_7:
	ds_read_b128 v[150:153], v158
	ds_read_b128 v[162:165], v158 offset:1024
	ds_read_b128 v[166:169], v158 offset:2048
	ds_read_b128 v[170:173], v158 offset:3072
	ds_read_b128 v[174:177], v159
	ds_read_b128 v[178:181], v159 offset:1024
	ds_read_b128 v[182:185], v159 offset:2048
	ds_read_b128 v[186:189], v159 offset:3072
	s_add_i32 s84, s48, 2
	s_add_u32 s49, s62, 0xfff00080
	s_addc_u32 s64, s63, -1
	s_cmp_eq_u32 s51, s48
	s_cselect_b32 s48, s56, s53
	s_cselect_b32 s65, s9, s64
	s_cselect_b32 s64, s8, s49
	s_cselect_b32 s49, s57, s55
	v_lshl_add_u64 v[154:155], s[62:63], 0, v[138:139]
	s_add_i32 m0, s59, 0xc000
	ds_read_b128 v[190:193], v160
	ds_read_b128 v[196:199], v160 offset:1024
	ds_read_b128 v[200:203], v160 offset:2048
	ds_read_b128 v[206:209], v160 offset:3072
	ds_read_b128 v[210:213], v160 offset:4096
	ds_read_b128 v[214:217], v160 offset:5120
	ds_read_b128 v[218:221], v160 offset:6144
	ds_read_b128 v[222:225], v160 offset:7168
	global_load_lds_dwordx4 v[154:155], off
	v_lshl_add_u64 v[154:155], s[62:63], 0, v[140:141]
	s_add_i32 m0, s59, 0xe000
	s_nop 0
	global_load_lds_dwordx4 v[154:155], off
	s_nop 0
	s_waitcnt vmcnt(8)
	s_waitcnt lgkmcnt(0)
	s_barrier
	s_setprio 1
	v_mfma_f32_16x16x32_bf16 v[126:129], v[150:153], v[190:193], v[126:129]
	v_mfma_f32_16x16x32_bf16 v[122:125], v[166:169], v[190:193], v[122:125]
	v_mfma_f32_16x16x32_bf16 v[110:113], v[150:153], v[200:203], v[110:113]
	v_mfma_f32_16x16x32_bf16 v[106:109], v[166:169], v[200:203], v[106:109]
	v_mfma_f32_16x16x32_bf16 v[94:97], v[150:153], v[210:213], v[94:97]
	v_mfma_f32_16x16x32_bf16 v[90:93], v[166:169], v[210:213], v[90:93]
	v_mfma_f32_16x16x32_bf16 v[78:81], v[150:153], v[218:221], v[78:81]
	v_mfma_f32_16x16x32_bf16 v[74:77], v[166:169], v[218:221], v[74:77]
	v_mfma_f32_16x16x32_bf16 v[126:129], v[162:165], v[196:199], v[126:129]
	v_mfma_f32_16x16x32_bf16 v[122:125], v[170:173], v[196:199], v[122:125]
	v_mfma_f32_16x16x32_bf16 v[110:113], v[162:165], v[206:209], v[110:113]
	v_mfma_f32_16x16x32_bf16 v[106:109], v[170:173], v[206:209], v[106:109]
	v_mfma_f32_16x16x32_bf16 v[94:97], v[162:165], v[214:217], v[94:97]
	v_mfma_f32_16x16x32_bf16 v[90:93], v[170:173], v[214:217], v[90:93]
	v_mfma_f32_16x16x32_bf16 v[78:81], v[162:165], v[222:225], v[78:81]
	v_mfma_f32_16x16x32_bf16 v[74:77], v[170:173], v[222:225], v[74:77]
	v_mfma_f32_16x16x32_bf16 v[118:121], v[174:177], v[190:193], v[118:121]
	v_mfma_f32_16x16x32_bf16 v[114:117], v[182:185], v[190:193], v[114:117]
	v_mfma_f32_16x16x32_bf16 v[102:105], v[174:177], v[200:203], v[102:105]
	v_mfma_f32_16x16x32_bf16 v[98:101], v[182:185], v[200:203], v[98:101]
	v_mfma_f32_16x16x32_bf16 v[86:89], v[174:177], v[210:213], v[86:89]
	v_mfma_f32_16x16x32_bf16 v[82:85], v[182:185], v[210:213], v[82:85]
	v_mfma_f32_16x16x32_bf16 v[70:73], v[174:177], v[218:221], v[70:73]
	v_mfma_f32_16x16x32_bf16 v[66:69], v[182:185], v[218:221], v[66:69]
	v_mfma_f32_16x16x32_bf16 v[118:121], v[178:181], v[196:199], v[118:121]
	v_mfma_f32_16x16x32_bf16 v[114:117], v[186:189], v[196:199], v[114:117]
	v_mfma_f32_16x16x32_bf16 v[102:105], v[178:181], v[206:209], v[102:105]
	v_mfma_f32_16x16x32_bf16 v[98:101], v[186:189], v[206:209], v[98:101]
	v_mfma_f32_16x16x32_bf16 v[86:89], v[178:181], v[214:217], v[86:89]
	v_mfma_f32_16x16x32_bf16 v[82:85], v[186:189], v[214:217], v[82:85]
	v_mfma_f32_16x16x32_bf16 v[70:73], v[178:181], v[222:225], v[70:73]
	v_mfma_f32_16x16x32_bf16 v[66:69], v[186:189], v[222:225], v[66:69]
	s_setprio 0
	s_barrier
	s_add_i32 s85, s75, s66
	v_lshl_add_u64 v[154:155], s[48:49], 0, v[132:133]
	s_mov_b32 m0, s85
	ds_read_b128 v[190:193], v160 offset:16384
	ds_read_b128 v[196:199], v160 offset:17408
	ds_read_b128 v[200:203], v160 offset:18432
	ds_read_b128 v[206:209], v160 offset:19456
	ds_read_b128 v[210:213], v160 offset:20480
	ds_read_b128 v[214:217], v160 offset:21504
	ds_read_b128 v[218:221], v160 offset:22528
	ds_read_b128 v[222:225], v160 offset:23552
	global_load_lds_dwordx4 v[154:155], off
	s_add_i32 m0, s85, 0x2000
	s_add_u32 s86, s48, 0x100000
	v_lshl_add_u64 v[226:227], s[48:49], 0, v[136:137]
	s_addc_u32 s87, s49, 0
	s_add_i32 s85, s76, s66
	global_load_lds_dwordx4 v[226:227], off
	v_lshl_add_u64 v[228:229], s[86:87], 0, v[132:133]
	s_mov_b32 m0, s85
	v_lshl_add_u64 v[230:231], s[64:65], 0, v[134:135]
	global_load_lds_dwordx4 v[228:229], off
	v_lshl_add_u64 v[228:229], s[86:87], 0, v[136:137]
	s_add_i32 m0, s85, 0x2000
	s_nop 0
	global_load_lds_dwordx4 v[228:229], off
	v_lshl_add_u64 v[228:229], s[64:65], 0, v[130:131]
	s_mov_b32 m0, s59
	s_nop 0
	global_load_lds_dwordx4 v[228:229], off
	s_mov_b32 m0, s61
	s_nop 0
	global_load_lds_dwordx4 v[230:231], off
	s_waitcnt vmcnt(8)
	s_waitcnt lgkmcnt(0)
	s_barrier
	s_setprio 1
	v_mfma_f32_16x16x32_bf16 v[62:65], v[150:153], v[190:193], v[62:65]
	v_mfma_f32_16x16x32_bf16 v[58:61], v[166:169], v[190:193], v[58:61]
	v_mfma_f32_16x16x32_bf16 v[46:49], v[150:153], v[200:203], v[46:49]
	v_mfma_f32_16x16x32_bf16 v[42:45], v[166:169], v[200:203], v[42:45]
	v_mfma_f32_16x16x32_bf16 v[30:33], v[150:153], v[210:213], v[30:33]
	v_mfma_f32_16x16x32_bf16 v[26:29], v[166:169], v[210:213], v[26:29]
	v_mfma_f32_16x16x32_bf16 v[14:17], v[150:153], v[218:221], v[14:17]
	v_mfma_f32_16x16x32_bf16 v[10:13], v[166:169], v[218:221], v[10:13]
	v_mfma_f32_16x16x32_bf16 v[62:65], v[162:165], v[196:199], v[62:65]
	v_mfma_f32_16x16x32_bf16 v[58:61], v[170:173], v[196:199], v[58:61]
	v_mfma_f32_16x16x32_bf16 v[46:49], v[162:165], v[206:209], v[46:49]
	v_mfma_f32_16x16x32_bf16 v[42:45], v[170:173], v[206:209], v[42:45]
	v_mfma_f32_16x16x32_bf16 v[30:33], v[162:165], v[214:217], v[30:33]
	v_mfma_f32_16x16x32_bf16 v[26:29], v[170:173], v[214:217], v[26:29]
	v_mfma_f32_16x16x32_bf16 v[14:17], v[162:165], v[222:225], v[14:17]
	v_mfma_f32_16x16x32_bf16 v[10:13], v[170:173], v[222:225], v[10:13]
	v_mfma_f32_16x16x32_bf16 v[54:57], v[174:177], v[190:193], v[54:57]
	v_mfma_f32_16x16x32_bf16 v[50:53], v[182:185], v[190:193], v[50:53]
	v_mfma_f32_16x16x32_bf16 v[38:41], v[174:177], v[200:203], v[38:41]
	v_mfma_f32_16x16x32_bf16 v[34:37], v[182:185], v[200:203], v[34:37]
	v_mfma_f32_16x16x32_bf16 v[22:25], v[174:177], v[210:213], v[22:25]
	v_mfma_f32_16x16x32_bf16 v[18:21], v[182:185], v[210:213], v[18:21]
	v_mfma_f32_16x16x32_bf16 v[6:9], v[174:177], v[218:221], v[6:9]
	v_mfma_f32_16x16x32_bf16 v[2:5], v[182:185], v[218:221], v[2:5]
	v_mfma_f32_16x16x32_bf16 v[54:57], v[178:181], v[196:199], v[54:57]
	v_mfma_f32_16x16x32_bf16 v[50:53], v[186:189], v[196:199], v[50:53]
	v_mfma_f32_16x16x32_bf16 v[38:41], v[178:181], v[206:209], v[38:41]
	v_mfma_f32_16x16x32_bf16 v[34:37], v[186:189], v[206:209], v[34:37]
	v_mfma_f32_16x16x32_bf16 v[22:25], v[178:181], v[214:217], v[22:25]
	v_mfma_f32_16x16x32_bf16 v[18:21], v[186:189], v[214:217], v[18:21]
	v_mfma_f32_16x16x32_bf16 v[6:9], v[178:181], v[222:225], v[6:9]
	v_mfma_f32_16x16x32_bf16 v[2:5], v[186:189], v[222:225], v[2:5]
	s_setprio 0
	s_barrier
	s_add_i32 s85, 0, 0x18000
	v_add_u32_e32 v161, s85, v156
	s_add_i32 s86, 0, 0x1c000
	ds_read_b128 v[150:153], v161
	ds_read_b128 v[162:165], v161 offset:1024
	ds_read_b128 v[166:169], v161 offset:2048
	ds_read_b128 v[170:173], v161 offset:3072
	v_add_u32_e32 v161, s86, v156
	ds_read_b128 v[174:177], v161
	ds_read_b128 v[178:181], v161 offset:1024
	ds_read_b128 v[182:185], v161 offset:2048
	ds_read_b128 v[186:189], v161 offset:3072
	s_add_u32 s64, s64, 0x100000
	s_addc_u32 s65, s65, 0
	s_mov_b32 m0, s67
	v_lshl_add_u64 v[232:233], s[64:65], 0, v[130:131]
	ds_read_b128 v[190:193], v160 offset:32768
	ds_read_b128 v[196:199], v160 offset:33792
	ds_read_b128 v[200:203], v160 offset:34816
	ds_read_b128 v[206:209], v160 offset:35840
	ds_read_b128 v[210:213], v160 offset:36864
	ds_read_b128 v[214:217], v160 offset:37888
	ds_read_b128 v[218:221], v160 offset:38912
	ds_read_b128 v[222:225], v160 offset:39936
	global_load_lds_dwordx4 v[232:233], off
	v_lshl_add_u64 v[232:233], s[64:65], 0, v[134:135]
	s_mov_b32 m0, s68
	s_nop 0
	global_load_lds_dwordx4 v[232:233], off
	s_waitcnt vmcnt(8)
	s_waitcnt lgkmcnt(0)
	s_barrier
	s_setprio 1
	v_mfma_f32_16x16x32_bf16 v[126:129], v[150:153], v[190:193], v[126:129]
	v_mfma_f32_16x16x32_bf16 v[122:125], v[166:169], v[190:193], v[122:125]
	v_mfma_f32_16x16x32_bf16 v[110:113], v[150:153], v[200:203], v[110:113]
	v_mfma_f32_16x16x32_bf16 v[106:109], v[166:169], v[200:203], v[106:109]
	v_mfma_f32_16x16x32_bf16 v[94:97], v[150:153], v[210:213], v[94:97]
	v_mfma_f32_16x16x32_bf16 v[90:93], v[166:169], v[210:213], v[90:93]
	v_mfma_f32_16x16x32_bf16 v[78:81], v[150:153], v[218:221], v[78:81]
	v_mfma_f32_16x16x32_bf16 v[74:77], v[166:169], v[218:221], v[74:77]
	v_mfma_f32_16x16x32_bf16 v[126:129], v[162:165], v[196:199], v[126:129]
	v_mfma_f32_16x16x32_bf16 v[122:125], v[170:173], v[196:199], v[122:125]
	v_mfma_f32_16x16x32_bf16 v[110:113], v[162:165], v[206:209], v[110:113]
	v_mfma_f32_16x16x32_bf16 v[106:109], v[170:173], v[206:209], v[106:109]
	v_mfma_f32_16x16x32_bf16 v[94:97], v[162:165], v[214:217], v[94:97]
	v_mfma_f32_16x16x32_bf16 v[90:93], v[170:173], v[214:217], v[90:93]
	v_mfma_f32_16x16x32_bf16 v[78:81], v[162:165], v[222:225], v[78:81]
	v_mfma_f32_16x16x32_bf16 v[74:77], v[170:173], v[222:225], v[74:77]
	v_mfma_f32_16x16x32_bf16 v[118:121], v[174:177], v[190:193], v[118:121]
	v_mfma_f32_16x16x32_bf16 v[114:117], v[182:185], v[190:193], v[114:117]
	v_mfma_f32_16x16x32_bf16 v[102:105], v[174:177], v[200:203], v[102:105]
	v_mfma_f32_16x16x32_bf16 v[98:101], v[182:185], v[200:203], v[98:101]
	v_mfma_f32_16x16x32_bf16 v[86:89], v[174:177], v[210:213], v[86:89]
	v_mfma_f32_16x16x32_bf16 v[82:85], v[182:185], v[210:213], v[82:85]
	v_mfma_f32_16x16x32_bf16 v[70:73], v[174:177], v[218:221], v[70:73]
	v_mfma_f32_16x16x32_bf16 v[66:69], v[182:185], v[218:221], v[66:69]
	v_mfma_f32_16x16x32_bf16 v[118:121], v[178:181], v[196:199], v[118:121]
	v_mfma_f32_16x16x32_bf16 v[114:117], v[186:189], v[196:199], v[114:117]
	v_mfma_f32_16x16x32_bf16 v[102:105], v[178:181], v[206:209], v[102:105]
	v_mfma_f32_16x16x32_bf16 v[98:101], v[186:189], v[206:209], v[98:101]
	v_mfma_f32_16x16x32_bf16 v[86:89], v[178:181], v[214:217], v[86:89]
	v_mfma_f32_16x16x32_bf16 v[82:85], v[186:189], v[214:217], v[82:85]
	v_mfma_f32_16x16x32_bf16 v[70:73], v[178:181], v[222:225], v[70:73]
	v_mfma_f32_16x16x32_bf16 v[66:69], v[186:189], v[222:225], v[66:69]
	s_setprio 0
	s_barrier
	s_add_i32 s64, s85, s66
	v_lshl_add_u64 v[154:155], v[154:155], 0, s[20:21]
	s_mov_b32 m0, s64
	ds_read_b128 v[190:193], v160 offset:49152
	ds_read_b128 v[196:199], v160 offset:50176
	ds_read_b128 v[200:203], v160 offset:51200
	ds_read_b128 v[206:209], v160 offset:52224
	ds_read_b128 v[210:213], v160 offset:53248
	ds_read_b128 v[214:217], v160 offset:54272
	ds_read_b128 v[218:221], v160 offset:55296
	ds_read_b128 v[222:225], v160 offset:56320
	global_load_lds_dwordx4 v[154:155], off
	s_add_i32 m0, s64, 0x2000
	s_add_u32 s48, s48, 0x100080
	v_lshl_add_u64 v[154:155], v[226:227], 0, s[20:21]
	s_addc_u32 s49, s49, 0
	s_add_i32 s64, s86, s66
	global_load_lds_dwordx4 v[154:155], off
	v_lshl_add_u64 v[154:155], s[48:49], 0, v[132:133]
	s_mov_b32 m0, s64
	s_nop 0
	global_load_lds_dwordx4 v[154:155], off
	v_lshl_add_u64 v[154:155], s[48:49], 0, v[136:137]
	s_add_i32 m0, s64, 0x2000
	s_nop 0
	global_load_lds_dwordx4 v[154:155], off
	v_lshl_add_u64 v[154:155], v[228:229], 0, s[20:21]
	s_mov_b32 m0, s72
	s_nop 0
	global_load_lds_dwordx4 v[154:155], off
	v_lshl_add_u64 v[154:155], v[230:231], 0, s[20:21]
	s_mov_b32 m0, s73
	s_nop 0
	global_load_lds_dwordx4 v[154:155], off
	s_nop 0
	s_waitcnt vmcnt(8)
	s_waitcnt lgkmcnt(0)
	s_barrier
	s_setprio 1
	v_mfma_f32_16x16x32_bf16 v[62:65], v[150:153], v[190:193], v[62:65]
	v_mfma_f32_16x16x32_bf16 v[58:61], v[166:169], v[190:193], v[58:61]
	v_mfma_f32_16x16x32_bf16 v[46:49], v[150:153], v[200:203], v[46:49]
	v_mfma_f32_16x16x32_bf16 v[42:45], v[166:169], v[200:203], v[42:45]
	v_mfma_f32_16x16x32_bf16 v[30:33], v[150:153], v[210:213], v[30:33]
	v_mfma_f32_16x16x32_bf16 v[26:29], v[166:169], v[210:213], v[26:29]
	v_mfma_f32_16x16x32_bf16 v[14:17], v[150:153], v[218:221], v[14:17]
	v_mfma_f32_16x16x32_bf16 v[10:13], v[166:169], v[218:221], v[10:13]
	v_mfma_f32_16x16x32_bf16 v[62:65], v[162:165], v[196:199], v[62:65]
	v_mfma_f32_16x16x32_bf16 v[58:61], v[170:173], v[196:199], v[58:61]
	v_mfma_f32_16x16x32_bf16 v[46:49], v[162:165], v[206:209], v[46:49]
	v_mfma_f32_16x16x32_bf16 v[42:45], v[170:173], v[206:209], v[42:45]
	v_mfma_f32_16x16x32_bf16 v[30:33], v[162:165], v[214:217], v[30:33]
	v_mfma_f32_16x16x32_bf16 v[26:29], v[170:173], v[214:217], v[26:29]
	v_mfma_f32_16x16x32_bf16 v[14:17], v[162:165], v[222:225], v[14:17]
	v_mfma_f32_16x16x32_bf16 v[10:13], v[170:173], v[222:225], v[10:13]
	v_mfma_f32_16x16x32_bf16 v[54:57], v[174:177], v[190:193], v[54:57]
	v_mfma_f32_16x16x32_bf16 v[50:53], v[182:185], v[190:193], v[50:53]
	v_mfma_f32_16x16x32_bf16 v[38:41], v[174:177], v[200:203], v[38:41]
	v_mfma_f32_16x16x32_bf16 v[34:37], v[182:185], v[200:203], v[34:37]
	v_mfma_f32_16x16x32_bf16 v[22:25], v[174:177], v[210:213], v[22:25]
	v_mfma_f32_16x16x32_bf16 v[18:21], v[182:185], v[210:213], v[18:21]
	v_mfma_f32_16x16x32_bf16 v[6:9], v[174:177], v[218:221], v[6:9]
	v_mfma_f32_16x16x32_bf16 v[2:5], v[182:185], v[218:221], v[2:5]
	v_mfma_f32_16x16x32_bf16 v[54:57], v[178:181], v[196:199], v[54:57]
	v_mfma_f32_16x16x32_bf16 v[50:53], v[186:189], v[196:199], v[50:53]
	v_mfma_f32_16x16x32_bf16 v[38:41], v[178:181], v[206:209], v[38:41]
	v_mfma_f32_16x16x32_bf16 v[34:37], v[186:189], v[206:209], v[34:37]
	v_mfma_f32_16x16x32_bf16 v[22:25], v[178:181], v[214:217], v[22:25]
	v_mfma_f32_16x16x32_bf16 v[18:21], v[186:189], v[214:217], v[18:21]
	v_mfma_f32_16x16x32_bf16 v[6:9], v[178:181], v[222:225], v[6:9]
	v_mfma_f32_16x16x32_bf16 v[2:5], v[186:189], v[222:225], v[2:5]
	s_setprio 0
	s_barrier
	s_add_u32 s62, s62, 0x100
	s_addc_u32 s63, s63, 0
	s_add_u32 s53, s53, 0x100
	s_addc_u32 s55, s55, 0
	s_cmp_ge_i32 s84, s83
	s_mov_b32 s48, s84
	s_cbranch_scc0 .Lkt_T_7
	s_nop 7
.Lkt_exit_7:
	s_and_b64 vcc, exec, s[22:23]
	s_cbranch_vccz .LBB0_1060
	s_barrier

.Lkt_L_8:
	ds_read_b128 v[162:165], v141
	ds_read_b128 v[166:169], v141 offset:1024
	ds_read_b128 v[170:173], v141 offset:2048
	ds_read_b128 v[174:177], v141 offset:3072
	ds_read_b128 v[178:181], v145
	ds_read_b128 v[182:185], v145 offset:1024
	ds_read_b128 v[186:189], v145 offset:2048
	ds_read_b128 v[190:193], v145 offset:3072
	s_add_i32 s65, s34, 2
	s_add_u32 s35, s30, 0xfff00080
	s_addc_u32 s40, s31, -1
	s_cmp_eq_u32 s62, s34
	s_cselect_b32 s34, s61, s63
	s_cselect_b32 s41, s21, s40
	s_cselect_b32 s40, s25, s35
	s_cselect_b32 s35, s23, s64
	v_lshl_add_u64 v[158:159], s[30:31], 0, v[148:149]
	s_add_i32 m0, s8, 0xc000
	ds_read_b128 v[196:199], v160
	ds_read_b128 v[200:203], v160 offset:1024
	ds_read_b128 v[206:209], v160 offset:2048
	ds_read_b128 v[210:213], v160 offset:3072
	ds_read_b128 v[214:217], v160 offset:4096
	ds_read_b128 v[218:221], v160 offset:5120
	ds_read_b128 v[222:225], v160 offset:6144
	ds_read_b128 v[226:229], v160 offset:7168
	global_load_lds_dwordx4 v[158:159], off
	v_lshl_add_u64 v[158:159], s[30:31], 0, v[150:151]
	s_add_i32 m0, s8, 0xe000
	s_nop 0
	global_load_lds_dwordx4 v[158:159], off
	s_waitcnt lgkmcnt(0)
	s_barrier
	s_nop 0
	s_setprio 1
	v_mfma_f32_16x16x32_bf16 v[126:129], v[162:165], v[196:199], v[126:129]
	v_mfma_f32_16x16x32_bf16 v[122:125], v[170:173], v[196:199], v[122:125]
	v_mfma_f32_16x16x32_bf16 v[118:121], v[162:165], v[206:209], v[118:121]
	v_mfma_f32_16x16x32_bf16 v[114:117], v[170:173], v[206:209], v[114:117]
	v_mfma_f32_16x16x32_bf16 v[102:105], v[162:165], v[214:217], v[102:105]
	v_mfma_f32_16x16x32_bf16 v[98:101], v[170:173], v[214:217], v[98:101]
	v_mfma_f32_16x16x32_bf16 v[42:45], v[162:165], v[222:225], v[42:45]
	v_mfma_f32_16x16x32_bf16 v[34:37], v[170:173], v[222:225], v[34:37]
	v_mfma_f32_16x16x32_bf16 v[126:129], v[166:169], v[200:203], v[126:129]
	v_mfma_f32_16x16x32_bf16 v[122:125], v[174:177], v[200:203], v[122:125]
	v_mfma_f32_16x16x32_bf16 v[118:121], v[166:169], v[210:213], v[118:121]
	v_mfma_f32_16x16x32_bf16 v[114:117], v[174:177], v[210:213], v[114:117]
	v_mfma_f32_16x16x32_bf16 v[102:105], v[166:169], v[218:221], v[102:105]
	v_mfma_f32_16x16x32_bf16 v[98:101], v[174:177], v[218:221], v[98:101]
	v_mfma_f32_16x16x32_bf16 v[42:45], v[166:169], v[226:229], v[42:45]
	v_mfma_f32_16x16x32_bf16 v[34:37], v[174:177], v[226:229], v[34:37]
	v_mfma_f32_16x16x32_bf16 v[110:113], v[178:181], v[196:199], v[110:113]
	v_mfma_f32_16x16x32_bf16 v[106:109], v[186:189], v[196:199], v[106:109]
	v_mfma_f32_16x16x32_bf16 v[94:97], v[178:181], v[206:209], v[94:97]
	v_mfma_f32_16x16x32_bf16 v[90:93], v[186:189], v[206:209], v[90:93]
	v_mfma_f32_16x16x32_bf16 v[86:89], v[178:181], v[214:217], v[86:89]
	v_mfma_f32_16x16x32_bf16 v[82:85], v[186:189], v[214:217], v[82:85]
	v_mfma_f32_16x16x32_bf16 v[30:33], v[178:181], v[222:225], v[30:33]
	v_mfma_f32_16x16x32_bf16 v[26:29], v[186:189], v[222:225], v[26:29]
	v_mfma_f32_16x16x32_bf16 v[110:113], v[182:185], v[200:203], v[110:113]
	v_mfma_f32_16x16x32_bf16 v[106:109], v[190:193], v[200:203], v[106:109]
	v_mfma_f32_16x16x32_bf16 v[94:97], v[182:185], v[210:213], v[94:97]
	v_mfma_f32_16x16x32_bf16 v[90:93], v[190:193], v[210:213], v[90:93]
	v_mfma_f32_16x16x32_bf16 v[86:89], v[182:185], v[218:221], v[86:89]
	v_mfma_f32_16x16x32_bf16 v[82:85], v[190:193], v[218:221], v[82:85]
	v_mfma_f32_16x16x32_bf16 v[30:33], v[182:185], v[226:229], v[30:33]
	v_mfma_f32_16x16x32_bf16 v[26:29], v[190:193], v[226:229], v[26:29]
	s_setprio 0
	s_waitcnt vmcnt(8)
	s_barrier
	s_add_i32 s66, s56, s42
	v_lshl_add_u64 v[158:159], s[34:35], 0, v[134:135]
	s_mov_b32 m0, s66
	ds_read_b128 v[196:199], v160 offset:16384
	ds_read_b128 v[200:203], v160 offset:17408
	ds_read_b128 v[206:209], v160 offset:18432
	ds_read_b128 v[210:213], v160 offset:19456
	ds_read_b128 v[214:217], v160 offset:20480
	ds_read_b128 v[218:221], v160 offset:21504
	ds_read_b128 v[222:225], v160 offset:22528
	ds_read_b128 v[226:229], v160 offset:23552
	global_load_lds_dwordx4 v[158:159], off
	s_add_i32 m0, s66, 0x2000
	s_add_u32 s66, s34, 0x100000
	v_lshl_add_u64 v[230:231], s[34:35], 0, v[132:133]
	s_addc_u32 s67, s35, 0
	s_add_i32 s68, s57, s42
	global_load_lds_dwordx4 v[230:231], off
	v_lshl_add_u64 v[232:233], s[66:67], 0, v[134:135]
	s_mov_b32 m0, s68
	v_lshl_add_u64 v[234:235], s[40:41], 0, v[132:133]
	global_load_lds_dwordx4 v[232:233], off
	v_lshl_add_u64 v[232:233], s[66:67], 0, v[132:133]
	s_add_i32 m0, s68, 0x2000
	s_nop 0
	global_load_lds_dwordx4 v[232:233], off
	v_lshl_add_u64 v[232:233], s[40:41], 0, v[134:135]
	s_mov_b32 m0, s8
	s_nop 0
	global_load_lds_dwordx4 v[232:233], off
	s_mov_b32 m0, s15
	s_nop 0
	global_load_lds_dwordx4 v[234:235], off
	s_waitcnt lgkmcnt(0)
	s_barrier
	s_setprio 1
	v_mfma_f32_16x16x32_bf16 v[78:81], v[162:165], v[196:199], v[78:81]
	v_mfma_f32_16x16x32_bf16 v[74:77], v[170:173], v[196:199], v[74:77]
	v_mfma_f32_16x16x32_bf16 v[70:73], v[162:165], v[206:209], v[70:73]
	v_mfma_f32_16x16x32_bf16 v[66:69], v[170:173], v[206:209], v[66:69]
	v_mfma_f32_16x16x32_bf16 v[54:57], v[162:165], v[214:217], v[54:57]
	v_mfma_f32_16x16x32_bf16 v[50:53], v[170:173], v[214:217], v[50:53]
	v_mfma_f32_16x16x32_bf16 v[14:17], v[162:165], v[222:225], v[14:17]
	v_mfma_f32_16x16x32_bf16 v[10:13], v[170:173], v[222:225], v[10:13]
	v_mfma_f32_16x16x32_bf16 v[78:81], v[166:169], v[200:203], v[78:81]
	v_mfma_f32_16x16x32_bf16 v[74:77], v[174:177], v[200:203], v[74:77]
	v_mfma_f32_16x16x32_bf16 v[70:73], v[166:169], v[210:213], v[70:73]
	v_mfma_f32_16x16x32_bf16 v[66:69], v[174:177], v[210:213], v[66:69]
	v_mfma_f32_16x16x32_bf16 v[54:57], v[166:169], v[218:221], v[54:57]
	v_mfma_f32_16x16x32_bf16 v[50:53], v[174:177], v[218:221], v[50:53]
	v_mfma_f32_16x16x32_bf16 v[14:17], v[166:169], v[226:229], v[14:17]
	v_mfma_f32_16x16x32_bf16 v[10:13], v[174:177], v[226:229], v[10:13]
	v_mfma_f32_16x16x32_bf16 v[62:65], v[178:181], v[196:199], v[62:65]
	v_mfma_f32_16x16x32_bf16 v[58:61], v[186:189], v[196:199], v[58:61]
	v_mfma_f32_16x16x32_bf16 v[46:49], v[178:181], v[206:209], v[46:49]
	v_mfma_f32_16x16x32_bf16 v[38:41], v[186:189], v[206:209], v[38:41]
	v_mfma_f32_16x16x32_bf16 v[22:25], v[178:181], v[214:217], v[22:25]
	v_mfma_f32_16x16x32_bf16 v[18:21], v[186:189], v[214:217], v[18:21]
	v_mfma_f32_16x16x32_bf16 v[6:9], v[178:181], v[222:225], v[6:9]
	v_mfma_f32_16x16x32_bf16 v[2:5], v[186:189], v[222:225], v[2:5]
	v_mfma_f32_16x16x32_bf16 v[62:65], v[182:185], v[200:203], v[62:65]
	v_mfma_f32_16x16x32_bf16 v[58:61], v[190:193], v[200:203], v[58:61]
	v_mfma_f32_16x16x32_bf16 v[46:49], v[182:185], v[210:213], v[46:49]
	v_mfma_f32_16x16x32_bf16 v[38:41], v[190:193], v[210:213], v[38:41]
	v_mfma_f32_16x16x32_bf16 v[22:25], v[182:185], v[218:221], v[22:25]
	v_mfma_f32_16x16x32_bf16 v[18:21], v[190:193], v[218:221], v[18:21]
	v_mfma_f32_16x16x32_bf16 v[6:9], v[182:185], v[226:229], v[6:9]
	v_mfma_f32_16x16x32_bf16 v[2:5], v[190:193], v[226:229], v[2:5]
	s_setprio 0
	s_waitcnt vmcnt(8)
	s_barrier
	s_add_i32 s66, 0, 0x18000
	v_add_u32_e32 v161, s66, v1
	s_add_i32 s67, 0, 0x1c000
	ds_read_b128 v[162:165], v161
	ds_read_b128 v[166:169], v161 offset:1024
	ds_read_b128 v[170:173], v161 offset:2048
	ds_read_b128 v[174:177], v161 offset:3072
	v_add_u32_e32 v161, s67, v1
	ds_read_b128 v[178:181], v161
	ds_read_b128 v[182:185], v161 offset:1024
	ds_read_b128 v[186:189], v161 offset:2048
	ds_read_b128 v[190:193], v161 offset:3072
	s_add_u32 s40, s40, 0x100000
	s_addc_u32 s41, s41, 0
	s_mov_b32 m0, s46
	v_lshl_add_u64 v[236:237], s[40:41], 0, v[134:135]
	ds_read_b128 v[196:199], v160 offset:32768
	ds_read_b128 v[200:203], v160 offset:33792
	ds_read_b128 v[206:209], v160 offset:34816
	ds_read_b128 v[210:213], v160 offset:35840
	ds_read_b128 v[214:217], v160 offset:36864
	ds_read_b128 v[218:221], v160 offset:37888
	ds_read_b128 v[222:225], v160 offset:38912
	ds_read_b128 v[226:229], v160 offset:39936
	global_load_lds_dwordx4 v[236:237], off
	v_lshl_add_u64 v[236:237], s[40:41], 0, v[132:133]
	s_mov_b32 m0, s47
	s_nop 0
	global_load_lds_dwordx4 v[236:237], off
	s_waitcnt lgkmcnt(0)
	s_barrier
	s_setprio 1
	v_mfma_f32_16x16x32_bf16 v[126:129], v[162:165], v[196:199], v[126:129]
	v_mfma_f32_16x16x32_bf16 v[122:125], v[170:173], v[196:199], v[122:125]
	v_mfma_f32_16x16x32_bf16 v[118:121], v[162:165], v[206:209], v[118:121]
	v_mfma_f32_16x16x32_bf16 v[114:117], v[170:173], v[206:209], v[114:117]
	v_mfma_f32_16x16x32_bf16 v[102:105], v[162:165], v[214:217], v[102:105]
	v_mfma_f32_16x16x32_bf16 v[98:101], v[170:173], v[214:217], v[98:101]
	v_mfma_f32_16x16x32_bf16 v[42:45], v[162:165], v[222:225], v[42:45]
	v_mfma_f32_16x16x32_bf16 v[34:37], v[170:173], v[222:225], v[34:37]
	v_mfma_f32_16x16x32_bf16 v[126:129], v[166:169], v[200:203], v[126:129]
	v_mfma_f32_16x16x32_bf16 v[122:125], v[174:177], v[200:203], v[122:125]
	v_mfma_f32_16x16x32_bf16 v[118:121], v[166:169], v[210:213], v[118:121]
	v_mfma_f32_16x16x32_bf16 v[114:117], v[174:177], v[210:213], v[114:117]
	v_mfma_f32_16x16x32_bf16 v[102:105], v[166:169], v[218:221], v[102:105]
	v_mfma_f32_16x16x32_bf16 v[98:101], v[174:177], v[218:221], v[98:101]
	v_mfma_f32_16x16x32_bf16 v[42:45], v[166:169], v[226:229], v[42:45]
	v_mfma_f32_16x16x32_bf16 v[34:37], v[174:177], v[226:229], v[34:37]
	v_mfma_f32_16x16x32_bf16 v[110:113], v[178:181], v[196:199], v[110:113]
	v_mfma_f32_16x16x32_bf16 v[106:109], v[186:189], v[196:199], v[106:109]
	v_mfma_f32_16x16x32_bf16 v[94:97], v[178:181], v[206:209], v[94:97]
	v_mfma_f32_16x16x32_bf16 v[90:93], v[186:189], v[206:209], v[90:93]
	v_mfma_f32_16x16x32_bf16 v[86:89], v[178:181], v[214:217], v[86:89]
	v_mfma_f32_16x16x32_bf16 v[82:85], v[186:189], v[214:217], v[82:85]
	v_mfma_f32_16x16x32_bf16 v[30:33], v[178:181], v[222:225], v[30:33]
	v_mfma_f32_16x16x32_bf16 v[26:29], v[186:189], v[222:225], v[26:29]
	v_mfma_f32_16x16x32_bf16 v[110:113], v[182:185], v[200:203], v[110:113]
	v_mfma_f32_16x16x32_bf16 v[106:109], v[190:193], v[200:203], v[106:109]
	v_mfma_f32_16x16x32_bf16 v[94:97], v[182:185], v[210:213], v[94:97]
	v_mfma_f32_16x16x32_bf16 v[90:93], v[190:193], v[210:213], v[90:93]
	v_mfma_f32_16x16x32_bf16 v[86:89], v[182:185], v[218:221], v[86:89]
	v_mfma_f32_16x16x32_bf16 v[82:85], v[190:193], v[218:221], v[82:85]
	v_mfma_f32_16x16x32_bf16 v[30:33], v[182:185], v[226:229], v[30:33]
	v_mfma_f32_16x16x32_bf16 v[26:29], v[190:193], v[226:229], v[26:29]
	s_setprio 0
	s_waitcnt vmcnt(8)
	s_barrier
	s_add_i32 s40, s66, s42
	v_lshl_add_u64 v[158:159], v[158:159], 0, s[12:13]
	s_mov_b32 m0, s40
	ds_read_b128 v[196:199], v160 offset:49152
	ds_read_b128 v[200:203], v160 offset:50176
	ds_read_b128 v[206:209], v160 offset:51200
	ds_read_b128 v[210:213], v160 offset:52224
	ds_read_b128 v[214:217], v160 offset:53248
	ds_read_b128 v[218:221], v160 offset:54272
	ds_read_b128 v[222:225], v160 offset:55296
	ds_read_b128 v[226:229], v160 offset:56320
	global_load_lds_dwordx4 v[158:159], off
	s_add_i32 m0, s40, 0x2000
	s_add_u32 s34, s34, 0x100080
	v_lshl_add_u64 v[158:159], v[230:231], 0, s[12:13]
	s_addc_u32 s35, s35, 0
	s_add_i32 s40, s67, s42
	global_load_lds_dwordx4 v[158:159], off
	v_lshl_add_u64 v[158:159], s[34:35], 0, v[134:135]
	s_mov_b32 m0, s40
	s_nop 0
	global_load_lds_dwordx4 v[158:159], off
	v_lshl_add_u64 v[158:159], s[34:35], 0, v[132:133]
	s_add_i32 m0, s40, 0x2000
	s_nop 0
	global_load_lds_dwordx4 v[158:159], off
	v_lshl_add_u64 v[158:159], v[232:233], 0, s[12:13]
	s_mov_b32 m0, s52
	s_nop 0
	global_load_lds_dwordx4 v[158:159], off
	v_lshl_add_u64 v[158:159], v[234:235], 0, s[12:13]
	s_mov_b32 m0, s53
	s_nop 0
	global_load_lds_dwordx4 v[158:159], off
	s_waitcnt lgkmcnt(0)
	s_barrier
	s_nop 0
	s_setprio 1
	v_mfma_f32_16x16x32_bf16 v[78:81], v[162:165], v[196:199], v[78:81]
	v_mfma_f32_16x16x32_bf16 v[74:77], v[170:173], v[196:199], v[74:77]
	v_mfma_f32_16x16x32_bf16 v[70:73], v[162:165], v[206:209], v[70:73]
	v_mfma_f32_16x16x32_bf16 v[66:69], v[170:173], v[206:209], v[66:69]
	v_mfma_f32_16x16x32_bf16 v[54:57], v[162:165], v[214:217], v[54:57]
	v_mfma_f32_16x16x32_bf16 v[50:53], v[170:173], v[214:217], v[50:53]
	v_mfma_f32_16x16x32_bf16 v[14:17], v[162:165], v[222:225], v[14:17]
	v_mfma_f32_16x16x32_bf16 v[10:13], v[170:173], v[222:225], v[10:13]
	v_mfma_f32_16x16x32_bf16 v[78:81], v[166:169], v[200:203], v[78:81]
	v_mfma_f32_16x16x32_bf16 v[74:77], v[174:177], v[200:203], v[74:77]
	v_mfma_f32_16x16x32_bf16 v[70:73], v[166:169], v[210:213], v[70:73]
	v_mfma_f32_16x16x32_bf16 v[66:69], v[174:177], v[210:213], v[66:69]
	v_mfma_f32_16x16x32_bf16 v[54:57], v[166:169], v[218:221], v[54:57]
	v_mfma_f32_16x16x32_bf16 v[50:53], v[174:177], v[218:221], v[50:53]
	v_mfma_f32_16x16x32_bf16 v[14:17], v[166:169], v[226:229], v[14:17]
	v_mfma_f32_16x16x32_bf16 v[10:13], v[174:177], v[226:229], v[10:13]
	v_mfma_f32_16x16x32_bf16 v[62:65], v[178:181], v[196:199], v[62:65]
	v_mfma_f32_16x16x32_bf16 v[58:61], v[186:189], v[196:199], v[58:61]
	v_mfma_f32_16x16x32_bf16 v[46:49], v[178:181], v[206:209], v[46:49]
	v_mfma_f32_16x16x32_bf16 v[38:41], v[186:189], v[206:209], v[38:41]
	v_mfma_f32_16x16x32_bf16 v[22:25], v[178:181], v[214:217], v[22:25]
	v_mfma_f32_16x16x32_bf16 v[18:21], v[186:189], v[214:217], v[18:21]
	v_mfma_f32_16x16x32_bf16 v[6:9], v[178:181], v[222:225], v[6:9]
	v_mfma_f32_16x16x32_bf16 v[2:5], v[186:189], v[222:225], v[2:5]
	v_mfma_f32_16x16x32_bf16 v[62:65], v[182:185], v[200:203], v[62:65]
	v_mfma_f32_16x16x32_bf16 v[58:61], v[190:193], v[200:203], v[58:61]
	v_mfma_f32_16x16x32_bf16 v[46:49], v[182:185], v[210:213], v[46:49]
	v_mfma_f32_16x16x32_bf16 v[38:41], v[190:193], v[210:213], v[38:41]
	v_mfma_f32_16x16x32_bf16 v[22:25], v[182:185], v[218:221], v[22:25]
	v_mfma_f32_16x16x32_bf16 v[18:21], v[190:193], v[218:221], v[18:21]
	v_mfma_f32_16x16x32_bf16 v[6:9], v[182:185], v[226:229], v[6:9]
	v_mfma_f32_16x16x32_bf16 v[2:5], v[190:193], v[226:229], v[2:5]
	s_setprio 0
	s_waitcnt vmcnt(8)
	s_barrier
	s_add_u32 s30, s30, 0x100
	s_addc_u32 s31, s31, 0
	s_add_u32 s63, s63, 0x100
	s_addc_u32 s64, s64, 0
	s_cmp_ge_i32 s65, s60
	s_mov_b32 s34, s65
	s_cbranch_scc0 .Lkt_L_8
	s_branch .Lkt_exit_8
.Lkt_T_8:
	ds_read_b128 v[162:165], v141
	ds_read_b128 v[166:169], v141 offset:1024
	ds_read_b128 v[170:173], v141 offset:2048
	ds_read_b128 v[174:177], v141 offset:3072
	ds_read_b128 v[178:181], v145
	ds_read_b128 v[182:185], v145 offset:1024
	ds_read_b128 v[186:189], v145 offset:2048
	ds_read_b128 v[190:193], v145 offset:3072
	s_add_i32 s65, s34, 2
	s_add_u32 s35, s30, 0xfff00080
	s_addc_u32 s40, s31, -1
	s_cmp_eq_u32 s62, s34
	s_cselect_b32 s34, s61, s63
	s_cselect_b32 s41, s21, s40
	s_cselect_b32 s40, s25, s35
	s_cselect_b32 s35, s23, s64
	v_lshl_add_u64 v[158:159], s[30:31], 0, v[148:149]
	s_add_i32 m0, s8, 0xc000
	ds_read_b128 v[196:199], v160
	ds_read_b128 v[200:203], v160 offset:1024
	ds_read_b128 v[206:209], v160 offset:2048
	ds_read_b128 v[210:213], v160 offset:3072
	ds_read_b128 v[214:217], v160 offset:4096
	ds_read_b128 v[218:221], v160 offset:5120
	ds_read_b128 v[222:225], v160 offset:6144
	ds_read_b128 v[226:229], v160 offset:7168
	global_load_lds_dwordx4 v[158:159], off
	v_lshl_add_u64 v[158:159], s[30:31], 0, v[150:151]
	s_add_i32 m0, s8, 0xe000
	s_nop 0
	global_load_lds_dwordx4 v[158:159], off
	s_nop 0
	s_waitcnt vmcnt(8)
	s_waitcnt lgkmcnt(0)
	s_barrier
	s_setprio 1
	v_mfma_f32_16x16x32_bf16 v[126:129], v[162:165], v[196:199], v[126:129]
	v_mfma_f32_16x16x32_bf16 v[122:125], v[170:173], v[196:199], v[122:125]
	v_mfma_f32_16x16x32_bf16 v[118:121], v[162:165], v[206:209], v[118:121]
	v_mfma_f32_16x16x32_bf16 v[114:117], v[170:173], v[206:209], v[114:117]
	v_mfma_f32_16x16x32_bf16 v[102:105], v[162:165], v[214:217], v[102:105]
	v_mfma_f32_16x16x32_bf16 v[98:101], v[170:173], v[214:217], v[98:101]
	v_mfma_f32_16x16x32_bf16 v[42:45], v[162:165], v[222:225], v[42:45]
	v_mfma_f32_16x16x32_bf16 v[34:37], v[170:173], v[222:225], v[34:37]
	v_mfma_f32_16x16x32_bf16 v[126:129], v[166:169], v[200:203], v[126:129]
	v_mfma_f32_16x16x32_bf16 v[122:125], v[174:177], v[200:203], v[122:125]
	v_mfma_f32_16x16x32_bf16 v[118:121], v[166:169], v[210:213], v[118:121]
	v_mfma_f32_16x16x32_bf16 v[114:117], v[174:177], v[210:213], v[114:117]
	v_mfma_f32_16x16x32_bf16 v[102:105], v[166:169], v[218:221], v[102:105]
	v_mfma_f32_16x16x32_bf16 v[98:101], v[174:177], v[218:221], v[98:101]
	v_mfma_f32_16x16x32_bf16 v[42:45], v[166:169], v[226:229], v[42:45]
	v_mfma_f32_16x16x32_bf16 v[34:37], v[174:177], v[226:229], v[34:37]
	v_mfma_f32_16x16x32_bf16 v[110:113], v[178:181], v[196:199], v[110:113]
	v_mfma_f32_16x16x32_bf16 v[106:109], v[186:189], v[196:199], v[106:109]
	v_mfma_f32_16x16x32_bf16 v[94:97], v[178:181], v[206:209], v[94:97]
	v_mfma_f32_16x16x32_bf16 v[90:93], v[186:189], v[206:209], v[90:93]
	v_mfma_f32_16x16x32_bf16 v[86:89], v[178:181], v[214:217], v[86:89]
	v_mfma_f32_16x16x32_bf16 v[82:85], v[186:189], v[214:217], v[82:85]
	v_mfma_f32_16x16x32_bf16 v[30:33], v[178:181], v[222:225], v[30:33]
	v_mfma_f32_16x16x32_bf16 v[26:29], v[186:189], v[222:225], v[26:29]
	v_mfma_f32_16x16x32_bf16 v[110:113], v[182:185], v[200:203], v[110:113]
	v_mfma_f32_16x16x32_bf16 v[106:109], v[190:193], v[200:203], v[106:109]
	v_mfma_f32_16x16x32_bf16 v[94:97], v[182:185], v[210:213], v[94:97]
	v_mfma_f32_16x16x32_bf16 v[90:93], v[190:193], v[210:213], v[90:93]
	v_mfma_f32_16x16x32_bf16 v[86:89], v[182:185], v[218:221], v[86:89]
	v_mfma_f32_16x16x32_bf16 v[82:85], v[190:193], v[218:221], v[82:85]
	v_mfma_f32_16x16x32_bf16 v[30:33], v[182:185], v[226:229], v[30:33]
	v_mfma_f32_16x16x32_bf16 v[26:29], v[190:193], v[226:229], v[26:29]
	s_setprio 0
	s_barrier
	s_add_i32 s66, s56, s42
	v_lshl_add_u64 v[158:159], s[34:35], 0, v[134:135]
	s_mov_b32 m0, s66
	ds_read_b128 v[196:199], v160 offset:16384
	ds_read_b128 v[200:203], v160 offset:17408
	ds_read_b128 v[206:209], v160 offset:18432
	ds_read_b128 v[210:213], v160 offset:19456
	ds_read_b128 v[214:217], v160 offset:20480
	ds_read_b128 v[218:221], v160 offset:21504
	ds_read_b128 v[222:225], v160 offset:22528
	ds_read_b128 v[226:229], v160 offset:23552
	global_load_lds_dwordx4 v[158:159], off
	s_add_i32 m0, s66, 0x2000
	s_add_u32 s66, s34, 0x100000
	v_lshl_add_u64 v[230:231], s[34:35], 0, v[132:133]
	s_addc_u32 s67, s35, 0
	s_add_i32 s68, s57, s42
	global_load_lds_dwordx4 v[230:231], off
	v_lshl_add_u64 v[232:233], s[66:67], 0, v[134:135]
	s_mov_b32 m0, s68
	v_lshl_add_u64 v[234:235], s[40:41], 0, v[132:133]
	global_load_lds_dwordx4 v[232:233], off
	v_lshl_add_u64 v[232:233], s[66:67], 0, v[132:133]
	s_add_i32 m0, s68, 0x2000
	s_nop 0
	global_load_lds_dwordx4 v[232:233], off
	v_lshl_add_u64 v[232:233], s[40:41], 0, v[134:135]
	s_mov_b32 m0, s8
	s_nop 0
	global_load_lds_dwordx4 v[232:233], off
	s_mov_b32 m0, s15
	s_nop 0
	global_load_lds_dwordx4 v[234:235], off
	s_waitcnt vmcnt(8)
	s_waitcnt lgkmcnt(0)
	s_barrier
	s_setprio 1
	v_mfma_f32_16x16x32_bf16 v[78:81], v[162:165], v[196:199], v[78:81]
	v_mfma_f32_16x16x32_bf16 v[74:77], v[170:173], v[196:199], v[74:77]
	v_mfma_f32_16x16x32_bf16 v[70:73], v[162:165], v[206:209], v[70:73]
	v_mfma_f32_16x16x32_bf16 v[66:69], v[170:173], v[206:209], v[66:69]
	v_mfma_f32_16x16x32_bf16 v[54:57], v[162:165], v[214:217], v[54:57]
	v_mfma_f32_16x16x32_bf16 v[50:53], v[170:173], v[214:217], v[50:53]
	v_mfma_f32_16x16x32_bf16 v[14:17], v[162:165], v[222:225], v[14:17]
	v_mfma_f32_16x16x32_bf16 v[10:13], v[170:173], v[222:225], v[10:13]
	v_mfma_f32_16x16x32_bf16 v[78:81], v[166:169], v[200:203], v[78:81]
	v_mfma_f32_16x16x32_bf16 v[74:77], v[174:177], v[200:203], v[74:77]
	v_mfma_f32_16x16x32_bf16 v[70:73], v[166:169], v[210:213], v[70:73]
	v_mfma_f32_16x16x32_bf16 v[66:69], v[174:177], v[210:213], v[66:69]
	v_mfma_f32_16x16x32_bf16 v[54:57], v[166:169], v[218:221], v[54:57]
	v_mfma_f32_16x16x32_bf16 v[50:53], v[174:177], v[218:221], v[50:53]
	v_mfma_f32_16x16x32_bf16 v[14:17], v[166:169], v[226:229], v[14:17]
	v_mfma_f32_16x16x32_bf16 v[10:13], v[174:177], v[226:229], v[10:13]
	v_mfma_f32_16x16x32_bf16 v[62:65], v[178:181], v[196:199], v[62:65]
	v_mfma_f32_16x16x32_bf16 v[58:61], v[186:189], v[196:199], v[58:61]
	v_mfma_f32_16x16x32_bf16 v[46:49], v[178:181], v[206:209], v[46:49]
	v_mfma_f32_16x16x32_bf16 v[38:41], v[186:189], v[206:209], v[38:41]
	v_mfma_f32_16x16x32_bf16 v[22:25], v[178:181], v[214:217], v[22:25]
	v_mfma_f32_16x16x32_bf16 v[18:21], v[186:189], v[214:217], v[18:21]
	v_mfma_f32_16x16x32_bf16 v[6:9], v[178:181], v[222:225], v[6:9]
	v_mfma_f32_16x16x32_bf16 v[2:5], v[186:189], v[222:225], v[2:5]
	v_mfma_f32_16x16x32_bf16 v[62:65], v[182:185], v[200:203], v[62:65]
	v_mfma_f32_16x16x32_bf16 v[58:61], v[190:193], v[200:203], v[58:61]
	v_mfma_f32_16x16x32_bf16 v[46:49], v[182:185], v[210:213], v[46:49]
	v_mfma_f32_16x16x32_bf16 v[38:41], v[190:193], v[210:213], v[38:41]
	v_mfma_f32_16x16x32_bf16 v[22:25], v[182:185], v[218:221], v[22:25]
	v_mfma_f32_16x16x32_bf16 v[18:21], v[190:193], v[218:221], v[18:21]
	v_mfma_f32_16x16x32_bf16 v[6:9], v[182:185], v[226:229], v[6:9]
	v_mfma_f32_16x16x32_bf16 v[2:5], v[190:193], v[226:229], v[2:5]
	s_setprio 0
	s_barrier
	s_add_i32 s66, 0, 0x18000
	v_add_u32_e32 v161, s66, v1
	s_add_i32 s67, 0, 0x1c000
	ds_read_b128 v[162:165], v161
	ds_read_b128 v[166:169], v161 offset:1024
	ds_read_b128 v[170:173], v161 offset:2048
	ds_read_b128 v[174:177], v161 offset:3072
	v_add_u32_e32 v161, s67, v1
	ds_read_b128 v[178:181], v161
	ds_read_b128 v[182:185], v161 offset:1024
	ds_read_b128 v[186:189], v161 offset:2048
	ds_read_b128 v[190:193], v161 offset:3072
	s_add_u32 s40, s40, 0x100000
	s_addc_u32 s41, s41, 0
	s_mov_b32 m0, s46
	v_lshl_add_u64 v[236:237], s[40:41], 0, v[134:135]
	ds_read_b128 v[196:199], v160 offset:32768
	ds_read_b128 v[200:203], v160 offset:33792
	ds_read_b128 v[206:209], v160 offset:34816
	ds_read_b128 v[210:213], v160 offset:35840
	ds_read_b128 v[214:217], v160 offset:36864
	ds_read_b128 v[218:221], v160 offset:37888
	ds_read_b128 v[222:225], v160 offset:38912
	ds_read_b128 v[226:229], v160 offset:39936
	global_load_lds_dwordx4 v[236:237], off
	v_lshl_add_u64 v[236:237], s[40:41], 0, v[132:133]
	s_mov_b32 m0, s47
	s_nop 0
	global_load_lds_dwordx4 v[236:237], off
	s_waitcnt vmcnt(8)
	s_waitcnt lgkmcnt(0)
	s_barrier
	s_setprio 1
	v_mfma_f32_16x16x32_bf16 v[126:129], v[162:165], v[196:199], v[126:129]
	v_mfma_f32_16x16x32_bf16 v[122:125], v[170:173], v[196:199], v[122:125]
	v_mfma_f32_16x16x32_bf16 v[118:121], v[162:165], v[206:209], v[118:121]
	v_mfma_f32_16x16x32_bf16 v[114:117], v[170:173], v[206:209], v[114:117]
	v_mfma_f32_16x16x32_bf16 v[102:105], v[162:165], v[214:217], v[102:105]
	v_mfma_f32_16x16x32_bf16 v[98:101], v[170:173], v[214:217], v[98:101]
	v_mfma_f32_16x16x32_bf16 v[42:45], v[162:165], v[222:225], v[42:45]
	v_mfma_f32_16x16x32_bf16 v[34:37], v[170:173], v[222:225], v[34:37]
	v_mfma_f32_16x16x32_bf16 v[126:129], v[166:169], v[200:203], v[126:129]
	v_mfma_f32_16x16x32_bf16 v[122:125], v[174:177], v[200:203], v[122:125]
	v_mfma_f32_16x16x32_bf16 v[118:121], v[166:169], v[210:213], v[118:121]
	v_mfma_f32_16x16x32_bf16 v[114:117], v[174:177], v[210:213], v[114:117]
	v_mfma_f32_16x16x32_bf16 v[102:105], v[166:169], v[218:221], v[102:105]
	v_mfma_f32_16x16x32_bf16 v[98:101], v[174:177], v[218:221], v[98:101]
	v_mfma_f32_16x16x32_bf16 v[42:45], v[166:169], v[226:229], v[42:45]
	v_mfma_f32_16x16x32_bf16 v[34:37], v[174:177], v[226:229], v[34:37]
	v_mfma_f32_16x16x32_bf16 v[110:113], v[178:181], v[196:199], v[110:113]
	v_mfma_f32_16x16x32_bf16 v[106:109], v[186:189], v[196:199], v[106:109]
	v_mfma_f32_16x16x32_bf16 v[94:97], v[178:181], v[206:209], v[94:97]
	v_mfma_f32_16x16x32_bf16 v[90:93], v[186:189], v[206:209], v[90:93]
	v_mfma_f32_16x16x32_bf16 v[86:89], v[178:181], v[214:217], v[86:89]
	v_mfma_f32_16x16x32_bf16 v[82:85], v[186:189], v[214:217], v[82:85]
	v_mfma_f32_16x16x32_bf16 v[30:33], v[178:181], v[222:225], v[30:33]
	v_mfma_f32_16x16x32_bf16 v[26:29], v[186:189], v[222:225], v[26:29]
	v_mfma_f32_16x16x32_bf16 v[110:113], v[182:185], v[200:203], v[110:113]
	v_mfma_f32_16x16x32_bf16 v[106:109], v[190:193], v[200:203], v[106:109]
	v_mfma_f32_16x16x32_bf16 v[94:97], v[182:185], v[210:213], v[94:97]
	v_mfma_f32_16x16x32_bf16 v[90:93], v[190:193], v[210:213], v[90:93]
	v_mfma_f32_16x16x32_bf16 v[86:89], v[182:185], v[218:221], v[86:89]
	v_mfma_f32_16x16x32_bf16 v[82:85], v[190:193], v[218:221], v[82:85]
	v_mfma_f32_16x16x32_bf16 v[30:33], v[182:185], v[226:229], v[30:33]
	v_mfma_f32_16x16x32_bf16 v[26:29], v[190:193], v[226:229], v[26:29]
	s_setprio 0
	s_barrier
	s_add_i32 s40, s66, s42
	v_lshl_add_u64 v[158:159], v[158:159], 0, s[12:13]
	s_mov_b32 m0, s40
	ds_read_b128 v[196:199], v160 offset:49152
	ds_read_b128 v[200:203], v160 offset:50176
	ds_read_b128 v[206:209], v160 offset:51200
	ds_read_b128 v[210:213], v160 offset:52224
	ds_read_b128 v[214:217], v160 offset:53248
	ds_read_b128 v[218:221], v160 offset:54272
	ds_read_b128 v[222:225], v160 offset:55296
	ds_read_b128 v[226:229], v160 offset:56320
	global_load_lds_dwordx4 v[158:159], off
	s_add_i32 m0, s40, 0x2000
	s_add_u32 s34, s34, 0x100080
	v_lshl_add_u64 v[158:159], v[230:231], 0, s[12:13]
	s_addc_u32 s35, s35, 0
	s_add_i32 s40, s67, s42
	global_load_lds_dwordx4 v[158:159], off
	v_lshl_add_u64 v[158:159], s[34:35], 0, v[134:135]
	s_mov_b32 m0, s40
	s_nop 0
	global_load_lds_dwordx4 v[158:159], off
	v_lshl_add_u64 v[158:159], s[34:35], 0, v[132:133]
	s_add_i32 m0, s40, 0x2000
	s_nop 0
	global_load_lds_dwordx4 v[158:159], off
	v_lshl_add_u64 v[158:159], v[232:233], 0, s[12:13]
	s_mov_b32 m0, s52
	s_nop 0
	global_load_lds_dwordx4 v[158:159], off
	v_lshl_add_u64 v[158:159], v[234:235], 0, s[12:13]
	s_mov_b32 m0, s53
	s_nop 0
	global_load_lds_dwordx4 v[158:159], off
	s_nop 0
	s_waitcnt vmcnt(8)
	s_waitcnt lgkmcnt(0)
	s_barrier
	s_setprio 1
	v_mfma_f32_16x16x32_bf16 v[78:81], v[162:165], v[196:199], v[78:81]
	v_mfma_f32_16x16x32_bf16 v[74:77], v[170:173], v[196:199], v[74:77]
	v_mfma_f32_16x16x32_bf16 v[70:73], v[162:165], v[206:209], v[70:73]
	v_mfma_f32_16x16x32_bf16 v[66:69], v[170:173], v[206:209], v[66:69]
	v_mfma_f32_16x16x32_bf16 v[54:57], v[162:165], v[214:217], v[54:57]
	v_mfma_f32_16x16x32_bf16 v[50:53], v[170:173], v[214:217], v[50:53]
	v_mfma_f32_16x16x32_bf16 v[14:17], v[162:165], v[222:225], v[14:17]
	v_mfma_f32_16x16x32_bf16 v[10:13], v[170:173], v[222:225], v[10:13]
	v_mfma_f32_16x16x32_bf16 v[78:81], v[166:169], v[200:203], v[78:81]
	v_mfma_f32_16x16x32_bf16 v[74:77], v[174:177], v[200:203], v[74:77]
	v_mfma_f32_16x16x32_bf16 v[70:73], v[166:169], v[210:213], v[70:73]
	v_mfma_f32_16x16x32_bf16 v[66:69], v[174:177], v[210:213], v[66:69]
	v_mfma_f32_16x16x32_bf16 v[54:57], v[166:169], v[218:221], v[54:57]
	v_mfma_f32_16x16x32_bf16 v[50:53], v[174:177], v[218:221], v[50:53]
	v_mfma_f32_16x16x32_bf16 v[14:17], v[166:169], v[226:229], v[14:17]
	v_mfma_f32_16x16x32_bf16 v[10:13], v[174:177], v[226:229], v[10:13]
	v_mfma_f32_16x16x32_bf16 v[62:65], v[178:181], v[196:199], v[62:65]
	v_mfma_f32_16x16x32_bf16 v[58:61], v[186:189], v[196:199], v[58:61]
	v_mfma_f32_16x16x32_bf16 v[46:49], v[178:181], v[206:209], v[46:49]
	v_mfma_f32_16x16x32_bf16 v[38:41], v[186:189], v[206:209], v[38:41]
	v_mfma_f32_16x16x32_bf16 v[22:25], v[178:181], v[214:217], v[22:25]
	v_mfma_f32_16x16x32_bf16 v[18:21], v[186:189], v[214:217], v[18:21]
	v_mfma_f32_16x16x32_bf16 v[6:9], v[178:181], v[222:225], v[6:9]
	v_mfma_f32_16x16x32_bf16 v[2:5], v[186:189], v[222:225], v[2:5]
	v_mfma_f32_16x16x32_bf16 v[62:65], v[182:185], v[200:203], v[62:65]
	v_mfma_f32_16x16x32_bf16 v[58:61], v[190:193], v[200:203], v[58:61]
	v_mfma_f32_16x16x32_bf16 v[46:49], v[182:185], v[210:213], v[46:49]
	v_mfma_f32_16x16x32_bf16 v[38:41], v[190:193], v[210:213], v[38:41]
	v_mfma_f32_16x16x32_bf16 v[22:25], v[182:185], v[218:221], v[22:25]
	v_mfma_f32_16x16x32_bf16 v[18:21], v[190:193], v[218:221], v[18:21]
	v_mfma_f32_16x16x32_bf16 v[6:9], v[182:185], v[226:229], v[6:9]
	v_mfma_f32_16x16x32_bf16 v[2:5], v[190:193], v[226:229], v[2:5]
	s_setprio 0
	s_barrier
	s_add_u32 s30, s30, 0x100
	s_addc_u32 s31, s31, 0
	s_add_u32 s63, s63, 0x100
	s_addc_u32 s64, s64, 0
	s_cmp_ge_i32 s65, s60
	s_mov_b32 s34, s65
	s_cbranch_scc0 .Lkt_T_8
	s_nop 7
.Lkt_exit_8:
	s_and_b64 vcc, exec, s[18:19]
	s_cbranch_vccz .LBB0_1200
	s_barrier

.Lkt_L_9:
	ds_read_b128 v[152:155], v159
	ds_read_b128 v[162:165], v159 offset:1024
	ds_read_b128 v[166:169], v159 offset:2048
	ds_read_b128 v[170:173], v159 offset:3072
	ds_read_b128 v[174:177], v160
	ds_read_b128 v[178:181], v160 offset:1024
	ds_read_b128 v[182:185], v160 offset:2048
	ds_read_b128 v[186:189], v160 offset:3072
	s_add_i32 s82, s48, 2
	s_add_u32 s49, s60, 0xfffe0080
	s_addc_u32 s62, s61, -1
	s_cmp_eq_u32 s47, s48
	s_cselect_b32 s48, s54, s51
	s_cselect_b32 s63, s9, s62
	s_cselect_b32 s62, s8, s49
	s_cselect_b32 s49, s55, s53
	v_lshl_add_u64 v[156:157], s[60:61], 0, v[140:141]
	s_add_i32 m0, s57, 0xc000
	ds_read_b128 v[190:193], v161
	ds_read_b128 v[196:199], v161 offset:1024
	ds_read_b128 v[200:203], v161 offset:2048
	ds_read_b128 v[206:209], v161 offset:3072
	ds_read_b128 v[210:213], v161 offset:4096
	ds_read_b128 v[214:217], v161 offset:5120
	ds_read_b128 v[218:221], v161 offset:6144
	ds_read_b128 v[222:225], v161 offset:7168
	global_load_lds_dwordx4 v[156:157], off
	v_lshl_add_u64 v[156:157], s[60:61], 0, v[142:143]
	s_add_i32 m0, s57, 0xe000
	s_nop 0
	global_load_lds_dwordx4 v[156:157], off
	s_waitcnt lgkmcnt(0)
	s_barrier
	s_nop 0
	s_setprio 1
	v_mfma_f32_16x16x32_bf16 v[126:129], v[152:155], v[190:193], v[126:129]
	v_mfma_f32_16x16x32_bf16 v[122:125], v[166:169], v[190:193], v[122:125]
	v_mfma_f32_16x16x32_bf16 v[110:113], v[152:155], v[200:203], v[110:113]
	v_mfma_f32_16x16x32_bf16 v[106:109], v[166:169], v[200:203], v[106:109]
	v_mfma_f32_16x16x32_bf16 v[94:97], v[152:155], v[210:213], v[94:97]
	v_mfma_f32_16x16x32_bf16 v[90:93], v[166:169], v[210:213], v[90:93]
	v_mfma_f32_16x16x32_bf16 v[78:81], v[152:155], v[218:221], v[78:81]
	v_mfma_f32_16x16x32_bf16 v[74:77], v[166:169], v[218:221], v[74:77]
	v_mfma_f32_16x16x32_bf16 v[126:129], v[162:165], v[196:199], v[126:129]
	v_mfma_f32_16x16x32_bf16 v[122:125], v[170:173], v[196:199], v[122:125]
	v_mfma_f32_16x16x32_bf16 v[110:113], v[162:165], v[206:209], v[110:113]
	v_mfma_f32_16x16x32_bf16 v[106:109], v[170:173], v[206:209], v[106:109]
	v_mfma_f32_16x16x32_bf16 v[94:97], v[162:165], v[214:217], v[94:97]
	v_mfma_f32_16x16x32_bf16 v[90:93], v[170:173], v[214:217], v[90:93]
	v_mfma_f32_16x16x32_bf16 v[78:81], v[162:165], v[222:225], v[78:81]
	v_mfma_f32_16x16x32_bf16 v[74:77], v[170:173], v[222:225], v[74:77]
	v_mfma_f32_16x16x32_bf16 v[118:121], v[174:177], v[190:193], v[118:121]
	v_mfma_f32_16x16x32_bf16 v[114:117], v[182:185], v[190:193], v[114:117]
	v_mfma_f32_16x16x32_bf16 v[102:105], v[174:177], v[200:203], v[102:105]
	v_mfma_f32_16x16x32_bf16 v[98:101], v[182:185], v[200:203], v[98:101]
	v_mfma_f32_16x16x32_bf16 v[86:89], v[174:177], v[210:213], v[86:89]
	v_mfma_f32_16x16x32_bf16 v[82:85], v[182:185], v[210:213], v[82:85]
	v_mfma_f32_16x16x32_bf16 v[70:73], v[174:177], v[218:221], v[70:73]
	v_mfma_f32_16x16x32_bf16 v[66:69], v[182:185], v[218:221], v[66:69]
	v_mfma_f32_16x16x32_bf16 v[118:121], v[178:181], v[196:199], v[118:121]
	v_mfma_f32_16x16x32_bf16 v[114:117], v[186:189], v[196:199], v[114:117]
	v_mfma_f32_16x16x32_bf16 v[102:105], v[178:181], v[206:209], v[102:105]
	v_mfma_f32_16x16x32_bf16 v[98:101], v[186:189], v[206:209], v[98:101]
	v_mfma_f32_16x16x32_bf16 v[86:89], v[178:181], v[214:217], v[86:89]
	v_mfma_f32_16x16x32_bf16 v[82:85], v[186:189], v[214:217], v[82:85]
	v_mfma_f32_16x16x32_bf16 v[70:73], v[178:181], v[222:225], v[70:73]
	v_mfma_f32_16x16x32_bf16 v[66:69], v[186:189], v[222:225], v[66:69]
	s_setprio 0
	s_waitcnt vmcnt(8)
	s_barrier
	s_add_i32 s83, s73, s64
	v_lshl_add_u64 v[156:157], s[48:49], 0, v[134:135]
	s_mov_b32 m0, s83
	ds_read_b128 v[190:193], v161 offset:16384
	ds_read_b128 v[196:199], v161 offset:17408
	ds_read_b128 v[200:203], v161 offset:18432
	ds_read_b128 v[206:209], v161 offset:19456
	ds_read_b128 v[210:213], v161 offset:20480
	ds_read_b128 v[214:217], v161 offset:21504
	ds_read_b128 v[218:221], v161 offset:22528
	ds_read_b128 v[222:225], v161 offset:23552
	global_load_lds_dwordx4 v[156:157], off
	s_add_i32 m0, s83, 0x2000
	s_add_u32 s84, s48, 0x20000
	v_lshl_add_u64 v[226:227], s[48:49], 0, v[138:139]
	s_addc_u32 s85, s49, 0
	s_add_i32 s83, s74, s64
	global_load_lds_dwordx4 v[226:227], off
	v_lshl_add_u64 v[228:229], s[84:85], 0, v[134:135]
	s_mov_b32 m0, s83
	v_lshl_add_u64 v[230:231], s[62:63], 0, v[136:137]
	global_load_lds_dwordx4 v[228:229], off
	v_lshl_add_u64 v[228:229], s[84:85], 0, v[138:139]
	s_add_i32 m0, s83, 0x2000
	s_nop 0
	global_load_lds_dwordx4 v[228:229], off
	v_lshl_add_u64 v[228:229], s[62:63], 0, v[132:133]
	s_mov_b32 m0, s57
	s_nop 0
	global_load_lds_dwordx4 v[228:229], off
	s_mov_b32 m0, s59
	s_nop 0
	global_load_lds_dwordx4 v[230:231], off
	s_waitcnt lgkmcnt(0)
	s_barrier
	s_setprio 1
	v_mfma_f32_16x16x32_bf16 v[62:65], v[152:155], v[190:193], v[62:65]
	v_mfma_f32_16x16x32_bf16 v[58:61], v[166:169], v[190:193], v[58:61]
	v_mfma_f32_16x16x32_bf16 v[46:49], v[152:155], v[200:203], v[46:49]
	v_mfma_f32_16x16x32_bf16 v[42:45], v[166:169], v[200:203], v[42:45]
	v_mfma_f32_16x16x32_bf16 v[30:33], v[152:155], v[210:213], v[30:33]
	v_mfma_f32_16x16x32_bf16 v[26:29], v[166:169], v[210:213], v[26:29]
	v_mfma_f32_16x16x32_bf16 v[14:17], v[152:155], v[218:221], v[14:17]
	v_mfma_f32_16x16x32_bf16 v[10:13], v[166:169], v[218:221], v[10:13]
	v_mfma_f32_16x16x32_bf16 v[62:65], v[162:165], v[196:199], v[62:65]
	v_mfma_f32_16x16x32_bf16 v[58:61], v[170:173], v[196:199], v[58:61]
	v_mfma_f32_16x16x32_bf16 v[46:49], v[162:165], v[206:209], v[46:49]
	v_mfma_f32_16x16x32_bf16 v[42:45], v[170:173], v[206:209], v[42:45]
	v_mfma_f32_16x16x32_bf16 v[30:33], v[162:165], v[214:217], v[30:33]
	v_mfma_f32_16x16x32_bf16 v[26:29], v[170:173], v[214:217], v[26:29]
	v_mfma_f32_16x16x32_bf16 v[14:17], v[162:165], v[222:225], v[14:17]
	v_mfma_f32_16x16x32_bf16 v[10:13], v[170:173], v[222:225], v[10:13]
	v_mfma_f32_16x16x32_bf16 v[54:57], v[174:177], v[190:193], v[54:57]
	v_mfma_f32_16x16x32_bf16 v[50:53], v[182:185], v[190:193], v[50:53]
	v_mfma_f32_16x16x32_bf16 v[38:41], v[174:177], v[200:203], v[38:41]
	v_mfma_f32_16x16x32_bf16 v[34:37], v[182:185], v[200:203], v[34:37]
	v_mfma_f32_16x16x32_bf16 v[22:25], v[174:177], v[210:213], v[22:25]
	v_mfma_f32_16x16x32_bf16 v[18:21], v[182:185], v[210:213], v[18:21]
	v_mfma_f32_16x16x32_bf16 v[6:9], v[174:177], v[218:221], v[6:9]
	v_mfma_f32_16x16x32_bf16 v[2:5], v[182:185], v[218:221], v[2:5]
	v_mfma_f32_16x16x32_bf16 v[54:57], v[178:181], v[196:199], v[54:57]
	v_mfma_f32_16x16x32_bf16 v[50:53], v[186:189], v[196:199], v[50:53]
	v_mfma_f32_16x16x32_bf16 v[38:41], v[178:181], v[206:209], v[38:41]
	v_mfma_f32_16x16x32_bf16 v[34:37], v[186:189], v[206:209], v[34:37]
	v_mfma_f32_16x16x32_bf16 v[22:25], v[178:181], v[214:217], v[22:25]
	v_mfma_f32_16x16x32_bf16 v[18:21], v[186:189], v[214:217], v[18:21]
	v_mfma_f32_16x16x32_bf16 v[6:9], v[178:181], v[222:225], v[6:9]
	v_mfma_f32_16x16x32_bf16 v[2:5], v[186:189], v[222:225], v[2:5]
	s_setprio 0
	s_waitcnt vmcnt(8)
	s_barrier
	s_add_i32 s83, 0, 0x18000
	s_add_i32 s84, 0, 0x1c000
	v_add_u32_e32 v170, s83, v131
	v_add_u32_e32 v186, s84, v131
	ds_read_b128 v[152:155], v170
	ds_read_b128 v[162:165], v170 offset:1024
	ds_read_b128 v[166:169], v170 offset:2048
	ds_read_b128 v[170:173], v170 offset:3072
	ds_read_b128 v[174:177], v186
	ds_read_b128 v[178:181], v186 offset:1024
	ds_read_b128 v[182:185], v186 offset:2048
	ds_read_b128 v[186:189], v186 offset:3072
	s_add_u32 s62, s62, 0x20000
	s_addc_u32 s63, s63, 0
	s_mov_b32 m0, s65
	v_lshl_add_u64 v[232:233], s[62:63], 0, v[132:133]
	ds_read_b128 v[190:193], v161 offset:32768
	ds_read_b128 v[196:199], v161 offset:33792
	ds_read_b128 v[200:203], v161 offset:34816
	ds_read_b128 v[206:209], v161 offset:35840
	ds_read_b128 v[210:213], v161 offset:36864
	ds_read_b128 v[214:217], v161 offset:37888
	ds_read_b128 v[218:221], v161 offset:38912
	ds_read_b128 v[222:225], v161 offset:39936
	global_load_lds_dwordx4 v[232:233], off
	v_lshl_add_u64 v[232:233], s[62:63], 0, v[136:137]
	s_mov_b32 m0, s66
	s_nop 0
	global_load_lds_dwordx4 v[232:233], off
	s_waitcnt lgkmcnt(0)
	s_barrier
	s_setprio 1
	v_mfma_f32_16x16x32_bf16 v[126:129], v[152:155], v[190:193], v[126:129]
	v_mfma_f32_16x16x32_bf16 v[122:125], v[166:169], v[190:193], v[122:125]
	v_mfma_f32_16x16x32_bf16 v[110:113], v[152:155], v[200:203], v[110:113]
	v_mfma_f32_16x16x32_bf16 v[106:109], v[166:169], v[200:203], v[106:109]
	v_mfma_f32_16x16x32_bf16 v[94:97], v[152:155], v[210:213], v[94:97]
	v_mfma_f32_16x16x32_bf16 v[90:93], v[166:169], v[210:213], v[90:93]
	v_mfma_f32_16x16x32_bf16 v[78:81], v[152:155], v[218:221], v[78:81]
	v_mfma_f32_16x16x32_bf16 v[74:77], v[166:169], v[218:221], v[74:77]
	v_mfma_f32_16x16x32_bf16 v[126:129], v[162:165], v[196:199], v[126:129]
	v_mfma_f32_16x16x32_bf16 v[122:125], v[170:173], v[196:199], v[122:125]
	v_mfma_f32_16x16x32_bf16 v[110:113], v[162:165], v[206:209], v[110:113]
	v_mfma_f32_16x16x32_bf16 v[106:109], v[170:173], v[206:209], v[106:109]
	v_mfma_f32_16x16x32_bf16 v[94:97], v[162:165], v[214:217], v[94:97]
	v_mfma_f32_16x16x32_bf16 v[90:93], v[170:173], v[214:217], v[90:93]
	v_mfma_f32_16x16x32_bf16 v[78:81], v[162:165], v[222:225], v[78:81]
	v_mfma_f32_16x16x32_bf16 v[74:77], v[170:173], v[222:225], v[74:77]
	v_mfma_f32_16x16x32_bf16 v[118:121], v[174:177], v[190:193], v[118:121]
	v_mfma_f32_16x16x32_bf16 v[114:117], v[182:185], v[190:193], v[114:117]
	v_mfma_f32_16x16x32_bf16 v[102:105], v[174:177], v[200:203], v[102:105]
	v_mfma_f32_16x16x32_bf16 v[98:101], v[182:185], v[200:203], v[98:101]
	v_mfma_f32_16x16x32_bf16 v[86:89], v[174:177], v[210:213], v[86:89]
	v_mfma_f32_16x16x32_bf16 v[82:85], v[182:185], v[210:213], v[82:85]
	v_mfma_f32_16x16x32_bf16 v[70:73], v[174:177], v[218:221], v[70:73]
	v_mfma_f32_16x16x32_bf16 v[66:69], v[182:185], v[218:221], v[66:69]
	v_mfma_f32_16x16x32_bf16 v[118:121], v[178:181], v[196:199], v[118:121]
	v_mfma_f32_16x16x32_bf16 v[114:117], v[186:189], v[196:199], v[114:117]
	v_mfma_f32_16x16x32_bf16 v[102:105], v[178:181], v[206:209], v[102:105]
	v_mfma_f32_16x16x32_bf16 v[98:101], v[186:189], v[206:209], v[98:101]
	v_mfma_f32_16x16x32_bf16 v[86:89], v[178:181], v[214:217], v[86:89]
	v_mfma_f32_16x16x32_bf16 v[82:85], v[186:189], v[214:217], v[82:85]
	v_mfma_f32_16x16x32_bf16 v[70:73], v[178:181], v[222:225], v[70:73]
	v_mfma_f32_16x16x32_bf16 v[66:69], v[186:189], v[222:225], v[66:69]
	s_setprio 0
	s_waitcnt vmcnt(8)
	s_barrier
	s_add_i32 s62, s83, s64
	v_lshl_add_u64 v[156:157], v[156:157], 0, s[18:19]
	s_mov_b32 m0, s62
	ds_read_b128 v[190:193], v161 offset:49152
	ds_read_b128 v[196:199], v161 offset:50176
	ds_read_b128 v[200:203], v161 offset:51200
	ds_read_b128 v[206:209], v161 offset:52224
	ds_read_b128 v[210:213], v161 offset:53248
	ds_read_b128 v[214:217], v161 offset:54272
	ds_read_b128 v[218:221], v161 offset:55296
	ds_read_b128 v[222:225], v161 offset:56320
	global_load_lds_dwordx4 v[156:157], off
	s_add_i32 m0, s62, 0x2000
	s_add_u32 s48, s48, 0x20080
	v_lshl_add_u64 v[156:157], v[226:227], 0, s[18:19]
	s_addc_u32 s49, s49, 0
	s_add_i32 s62, s84, s64
	global_load_lds_dwordx4 v[156:157], off
	v_lshl_add_u64 v[156:157], s[48:49], 0, v[134:135]
	s_mov_b32 m0, s62
	s_nop 0
	global_load_lds_dwordx4 v[156:157], off
	v_lshl_add_u64 v[156:157], s[48:49], 0, v[138:139]
	s_add_i32 m0, s62, 0x2000
	s_nop 0
	global_load_lds_dwordx4 v[156:157], off
	v_lshl_add_u64 v[156:157], v[228:229], 0, s[18:19]
	s_mov_b32 m0, s70
	s_nop 0
	global_load_lds_dwordx4 v[156:157], off
	v_lshl_add_u64 v[156:157], v[230:231], 0, s[18:19]
	s_mov_b32 m0, s71
	s_nop 0
	global_load_lds_dwordx4 v[156:157], off
	s_waitcnt lgkmcnt(0)
	s_barrier
	s_nop 0
	s_setprio 1
	v_mfma_f32_16x16x32_bf16 v[62:65], v[152:155], v[190:193], v[62:65]
	v_mfma_f32_16x16x32_bf16 v[58:61], v[166:169], v[190:193], v[58:61]
	v_mfma_f32_16x16x32_bf16 v[46:49], v[152:155], v[200:203], v[46:49]
	v_mfma_f32_16x16x32_bf16 v[42:45], v[166:169], v[200:203], v[42:45]
	v_mfma_f32_16x16x32_bf16 v[30:33], v[152:155], v[210:213], v[30:33]
	v_mfma_f32_16x16x32_bf16 v[26:29], v[166:169], v[210:213], v[26:29]
	v_mfma_f32_16x16x32_bf16 v[14:17], v[152:155], v[218:221], v[14:17]
	v_mfma_f32_16x16x32_bf16 v[10:13], v[166:169], v[218:221], v[10:13]
	v_mfma_f32_16x16x32_bf16 v[62:65], v[162:165], v[196:199], v[62:65]
	v_mfma_f32_16x16x32_bf16 v[58:61], v[170:173], v[196:199], v[58:61]
	v_mfma_f32_16x16x32_bf16 v[46:49], v[162:165], v[206:209], v[46:49]
	v_mfma_f32_16x16x32_bf16 v[42:45], v[170:173], v[206:209], v[42:45]
	v_mfma_f32_16x16x32_bf16 v[30:33], v[162:165], v[214:217], v[30:33]
	v_mfma_f32_16x16x32_bf16 v[26:29], v[170:173], v[214:217], v[26:29]
	v_mfma_f32_16x16x32_bf16 v[14:17], v[162:165], v[222:225], v[14:17]
	v_mfma_f32_16x16x32_bf16 v[10:13], v[170:173], v[222:225], v[10:13]
	v_mfma_f32_16x16x32_bf16 v[54:57], v[174:177], v[190:193], v[54:57]
	v_mfma_f32_16x16x32_bf16 v[50:53], v[182:185], v[190:193], v[50:53]
	v_mfma_f32_16x16x32_bf16 v[38:41], v[174:177], v[200:203], v[38:41]
	v_mfma_f32_16x16x32_bf16 v[34:37], v[182:185], v[200:203], v[34:37]
	v_mfma_f32_16x16x32_bf16 v[22:25], v[174:177], v[210:213], v[22:25]
	v_mfma_f32_16x16x32_bf16 v[18:21], v[182:185], v[210:213], v[18:21]
	v_mfma_f32_16x16x32_bf16 v[6:9], v[174:177], v[218:221], v[6:9]
	v_mfma_f32_16x16x32_bf16 v[2:5], v[182:185], v[218:221], v[2:5]
	v_mfma_f32_16x16x32_bf16 v[54:57], v[178:181], v[196:199], v[54:57]
	v_mfma_f32_16x16x32_bf16 v[50:53], v[186:189], v[196:199], v[50:53]
	v_mfma_f32_16x16x32_bf16 v[38:41], v[178:181], v[206:209], v[38:41]
	v_mfma_f32_16x16x32_bf16 v[34:37], v[186:189], v[206:209], v[34:37]
	v_mfma_f32_16x16x32_bf16 v[22:25], v[178:181], v[214:217], v[22:25]
	v_mfma_f32_16x16x32_bf16 v[18:21], v[186:189], v[214:217], v[18:21]
	v_mfma_f32_16x16x32_bf16 v[6:9], v[178:181], v[222:225], v[6:9]
	v_mfma_f32_16x16x32_bf16 v[2:5], v[186:189], v[222:225], v[2:5]
	s_setprio 0
	s_waitcnt vmcnt(8)
	s_barrier
	s_add_u32 s60, s60, 0x100
	s_addc_u32 s61, s61, 0
	s_add_u32 s51, s51, 0x100
	s_addc_u32 s53, s53, 0
	s_cmp_ge_i32 s82, s81
	s_mov_b32 s48, s82
	s_cbranch_scc0 .Lkt_L_9
	s_branch .Lkt_exit_9
.Lkt_T_9:
	ds_read_b128 v[152:155], v159
	ds_read_b128 v[162:165], v159 offset:1024
	ds_read_b128 v[166:169], v159 offset:2048
	ds_read_b128 v[170:173], v159 offset:3072
	ds_read_b128 v[174:177], v160
	ds_read_b128 v[178:181], v160 offset:1024
	ds_read_b128 v[182:185], v160 offset:2048
	ds_read_b128 v[186:189], v160 offset:3072
	s_add_i32 s82, s48, 2
	s_add_u32 s49, s60, 0xfffe0080
	s_addc_u32 s62, s61, -1
	s_cmp_eq_u32 s47, s48
	s_cselect_b32 s48, s54, s51
	s_cselect_b32 s63, s9, s62
	s_cselect_b32 s62, s8, s49
	s_cselect_b32 s49, s55, s53
	v_lshl_add_u64 v[156:157], s[60:61], 0, v[140:141]
	s_add_i32 m0, s57, 0xc000
	ds_read_b128 v[190:193], v161
	ds_read_b128 v[196:199], v161 offset:1024
	ds_read_b128 v[200:203], v161 offset:2048
	ds_read_b128 v[206:209], v161 offset:3072
	ds_read_b128 v[210:213], v161 offset:4096
	ds_read_b128 v[214:217], v161 offset:5120
	ds_read_b128 v[218:221], v161 offset:6144
	ds_read_b128 v[222:225], v161 offset:7168
	global_load_lds_dwordx4 v[156:157], off
	v_lshl_add_u64 v[156:157], s[60:61], 0, v[142:143]
	s_add_i32 m0, s57, 0xe000
	s_nop 0
	global_load_lds_dwordx4 v[156:157], off
	s_nop 0
	s_waitcnt vmcnt(8)
	s_waitcnt lgkmcnt(0)
	s_barrier
	s_setprio 1
	v_mfma_f32_16x16x32_bf16 v[126:129], v[152:155], v[190:193], v[126:129]
	v_mfma_f32_16x16x32_bf16 v[122:125], v[166:169], v[190:193], v[122:125]
	v_mfma_f32_16x16x32_bf16 v[110:113], v[152:155], v[200:203], v[110:113]
	v_mfma_f32_16x16x32_bf16 v[106:109], v[166:169], v[200:203], v[106:109]
	v_mfma_f32_16x16x32_bf16 v[94:97], v[152:155], v[210:213], v[94:97]
	v_mfma_f32_16x16x32_bf16 v[90:93], v[166:169], v[210:213], v[90:93]
	v_mfma_f32_16x16x32_bf16 v[78:81], v[152:155], v[218:221], v[78:81]
	v_mfma_f32_16x16x32_bf16 v[74:77], v[166:169], v[218:221], v[74:77]
	v_mfma_f32_16x16x32_bf16 v[126:129], v[162:165], v[196:199], v[126:129]
	v_mfma_f32_16x16x32_bf16 v[122:125], v[170:173], v[196:199], v[122:125]
	v_mfma_f32_16x16x32_bf16 v[110:113], v[162:165], v[206:209], v[110:113]
	v_mfma_f32_16x16x32_bf16 v[106:109], v[170:173], v[206:209], v[106:109]
	v_mfma_f32_16x16x32_bf16 v[94:97], v[162:165], v[214:217], v[94:97]
	v_mfma_f32_16x16x32_bf16 v[90:93], v[170:173], v[214:217], v[90:93]
	v_mfma_f32_16x16x32_bf16 v[78:81], v[162:165], v[222:225], v[78:81]
	v_mfma_f32_16x16x32_bf16 v[74:77], v[170:173], v[222:225], v[74:77]
	v_mfma_f32_16x16x32_bf16 v[118:121], v[174:177], v[190:193], v[118:121]
	v_mfma_f32_16x16x32_bf16 v[114:117], v[182:185], v[190:193], v[114:117]
	v_mfma_f32_16x16x32_bf16 v[102:105], v[174:177], v[200:203], v[102:105]
	v_mfma_f32_16x16x32_bf16 v[98:101], v[182:185], v[200:203], v[98:101]
	v_mfma_f32_16x16x32_bf16 v[86:89], v[174:177], v[210:213], v[86:89]
	v_mfma_f32_16x16x32_bf16 v[82:85], v[182:185], v[210:213], v[82:85]
	v_mfma_f32_16x16x32_bf16 v[70:73], v[174:177], v[218:221], v[70:73]
	v_mfma_f32_16x16x32_bf16 v[66:69], v[182:185], v[218:221], v[66:69]
	v_mfma_f32_16x16x32_bf16 v[118:121], v[178:181], v[196:199], v[118:121]
	v_mfma_f32_16x16x32_bf16 v[114:117], v[186:189], v[196:199], v[114:117]
	v_mfma_f32_16x16x32_bf16 v[102:105], v[178:181], v[206:209], v[102:105]
	v_mfma_f32_16x16x32_bf16 v[98:101], v[186:189], v[206:209], v[98:101]
	v_mfma_f32_16x16x32_bf16 v[86:89], v[178:181], v[214:217], v[86:89]
	v_mfma_f32_16x16x32_bf16 v[82:85], v[186:189], v[214:217], v[82:85]
	v_mfma_f32_16x16x32_bf16 v[70:73], v[178:181], v[222:225], v[70:73]
	v_mfma_f32_16x16x32_bf16 v[66:69], v[186:189], v[222:225], v[66:69]
	s_setprio 0
	s_barrier
	s_add_i32 s83, s73, s64
	v_lshl_add_u64 v[156:157], s[48:49], 0, v[134:135]
	s_mov_b32 m0, s83
	ds_read_b128 v[190:193], v161 offset:16384
	ds_read_b128 v[196:199], v161 offset:17408
	ds_read_b128 v[200:203], v161 offset:18432
	ds_read_b128 v[206:209], v161 offset:19456
	ds_read_b128 v[210:213], v161 offset:20480
	ds_read_b128 v[214:217], v161 offset:21504
	ds_read_b128 v[218:221], v161 offset:22528
	ds_read_b128 v[222:225], v161 offset:23552
	global_load_lds_dwordx4 v[156:157], off
	s_add_i32 m0, s83, 0x2000
	s_add_u32 s84, s48, 0x20000
	v_lshl_add_u64 v[226:227], s[48:49], 0, v[138:139]
	s_addc_u32 s85, s49, 0
	s_add_i32 s83, s74, s64
	global_load_lds_dwordx4 v[226:227], off
	v_lshl_add_u64 v[228:229], s[84:85], 0, v[134:135]
	s_mov_b32 m0, s83
	v_lshl_add_u64 v[230:231], s[62:63], 0, v[136:137]
	global_load_lds_dwordx4 v[228:229], off
	v_lshl_add_u64 v[228:229], s[84:85], 0, v[138:139]
	s_add_i32 m0, s83, 0x2000
	s_nop 0
	global_load_lds_dwordx4 v[228:229], off
	v_lshl_add_u64 v[228:229], s[62:63], 0, v[132:133]
	s_mov_b32 m0, s57
	s_nop 0
	global_load_lds_dwordx4 v[228:229], off
	s_mov_b32 m0, s59
	s_nop 0
	global_load_lds_dwordx4 v[230:231], off
	s_waitcnt vmcnt(8)
	s_waitcnt lgkmcnt(0)
	s_barrier
	s_setprio 1
	v_mfma_f32_16x16x32_bf16 v[62:65], v[152:155], v[190:193], v[62:65]
	v_mfma_f32_16x16x32_bf16 v[58:61], v[166:169], v[190:193], v[58:61]
	v_mfma_f32_16x16x32_bf16 v[46:49], v[152:155], v[200:203], v[46:49]
	v_mfma_f32_16x16x32_bf16 v[42:45], v[166:169], v[200:203], v[42:45]
	v_mfma_f32_16x16x32_bf16 v[30:33], v[152:155], v[210:213], v[30:33]
	v_mfma_f32_16x16x32_bf16 v[26:29], v[166:169], v[210:213], v[26:29]
	v_mfma_f32_16x16x32_bf16 v[14:17], v[152:155], v[218:221], v[14:17]
	v_mfma_f32_16x16x32_bf16 v[10:13], v[166:169], v[218:221], v[10:13]
	v_mfma_f32_16x16x32_bf16 v[62:65], v[162:165], v[196:199], v[62:65]
	v_mfma_f32_16x16x32_bf16 v[58:61], v[170:173], v[196:199], v[58:61]
	v_mfma_f32_16x16x32_bf16 v[46:49], v[162:165], v[206:209], v[46:49]
	v_mfma_f32_16x16x32_bf16 v[42:45], v[170:173], v[206:209], v[42:45]
	v_mfma_f32_16x16x32_bf16 v[30:33], v[162:165], v[214:217], v[30:33]
	v_mfma_f32_16x16x32_bf16 v[26:29], v[170:173], v[214:217], v[26:29]
	v_mfma_f32_16x16x32_bf16 v[14:17], v[162:165], v[222:225], v[14:17]
	v_mfma_f32_16x16x32_bf16 v[10:13], v[170:173], v[222:225], v[10:13]
	v_mfma_f32_16x16x32_bf16 v[54:57], v[174:177], v[190:193], v[54:57]
	v_mfma_f32_16x16x32_bf16 v[50:53], v[182:185], v[190:193], v[50:53]
	v_mfma_f32_16x16x32_bf16 v[38:41], v[174:177], v[200:203], v[38:41]
	v_mfma_f32_16x16x32_bf16 v[34:37], v[182:185], v[200:203], v[34:37]
	v_mfma_f32_16x16x32_bf16 v[22:25], v[174:177], v[210:213], v[22:25]
	v_mfma_f32_16x16x32_bf16 v[18:21], v[182:185], v[210:213], v[18:21]
	v_mfma_f32_16x16x32_bf16 v[6:9], v[174:177], v[218:221], v[6:9]
	v_mfma_f32_16x16x32_bf16 v[2:5], v[182:185], v[218:221], v[2:5]
	v_mfma_f32_16x16x32_bf16 v[54:57], v[178:181], v[196:199], v[54:57]
	v_mfma_f32_16x16x32_bf16 v[50:53], v[186:189], v[196:199], v[50:53]
	v_mfma_f32_16x16x32_bf16 v[38:41], v[178:181], v[206:209], v[38:41]
	v_mfma_f32_16x16x32_bf16 v[34:37], v[186:189], v[206:209], v[34:37]
	v_mfma_f32_16x16x32_bf16 v[22:25], v[178:181], v[214:217], v[22:25]
	v_mfma_f32_16x16x32_bf16 v[18:21], v[186:189], v[214:217], v[18:21]
	v_mfma_f32_16x16x32_bf16 v[6:9], v[178:181], v[222:225], v[6:9]
	v_mfma_f32_16x16x32_bf16 v[2:5], v[186:189], v[222:225], v[2:5]
	s_setprio 0
	s_barrier
	s_add_i32 s83, 0, 0x18000
	s_add_i32 s84, 0, 0x1c000
	v_add_u32_e32 v170, s83, v131
	v_add_u32_e32 v186, s84, v131
	ds_read_b128 v[152:155], v170
	ds_read_b128 v[162:165], v170 offset:1024
	ds_read_b128 v[166:169], v170 offset:2048
	ds_read_b128 v[170:173], v170 offset:3072
	ds_read_b128 v[174:177], v186
	ds_read_b128 v[178:181], v186 offset:1024
	ds_read_b128 v[182:185], v186 offset:2048
	ds_read_b128 v[186:189], v186 offset:3072
	s_add_u32 s62, s62, 0x20000
	s_addc_u32 s63, s63, 0
	s_mov_b32 m0, s65
	v_lshl_add_u64 v[232:233], s[62:63], 0, v[132:133]
	ds_read_b128 v[190:193], v161 offset:32768
	ds_read_b128 v[196:199], v161 offset:33792
	ds_read_b128 v[200:203], v161 offset:34816
	ds_read_b128 v[206:209], v161 offset:35840
	ds_read_b128 v[210:213], v161 offset:36864
	ds_read_b128 v[214:217], v161 offset:37888
	ds_read_b128 v[218:221], v161 offset:38912
	ds_read_b128 v[222:225], v161 offset:39936
	global_load_lds_dwordx4 v[232:233], off
	v_lshl_add_u64 v[232:233], s[62:63], 0, v[136:137]
	s_mov_b32 m0, s66
	s_nop 0
	global_load_lds_dwordx4 v[232:233], off
	s_waitcnt vmcnt(8)
	s_waitcnt lgkmcnt(0)
	s_barrier
	s_setprio 1
	v_mfma_f32_16x16x32_bf16 v[126:129], v[152:155], v[190:193], v[126:129]
	v_mfma_f32_16x16x32_bf16 v[122:125], v[166:169], v[190:193], v[122:125]
	v_mfma_f32_16x16x32_bf16 v[110:113], v[152:155], v[200:203], v[110:113]
	v_mfma_f32_16x16x32_bf16 v[106:109], v[166:169], v[200:203], v[106:109]
	v_mfma_f32_16x16x32_bf16 v[94:97], v[152:155], v[210:213], v[94:97]
	v_mfma_f32_16x16x32_bf16 v[90:93], v[166:169], v[210:213], v[90:93]
	v_mfma_f32_16x16x32_bf16 v[78:81], v[152:155], v[218:221], v[78:81]
	v_mfma_f32_16x16x32_bf16 v[74:77], v[166:169], v[218:221], v[74:77]
	v_mfma_f32_16x16x32_bf16 v[126:129], v[162:165], v[196:199], v[126:129]
	v_mfma_f32_16x16x32_bf16 v[122:125], v[170:173], v[196:199], v[122:125]
	v_mfma_f32_16x16x32_bf16 v[110:113], v[162:165], v[206:209], v[110:113]
	v_mfma_f32_16x16x32_bf16 v[106:109], v[170:173], v[206:209], v[106:109]
	v_mfma_f32_16x16x32_bf16 v[94:97], v[162:165], v[214:217], v[94:97]
	v_mfma_f32_16x16x32_bf16 v[90:93], v[170:173], v[214:217], v[90:93]
	v_mfma_f32_16x16x32_bf16 v[78:81], v[162:165], v[222:225], v[78:81]
	v_mfma_f32_16x16x32_bf16 v[74:77], v[170:173], v[222:225], v[74:77]
	v_mfma_f32_16x16x32_bf16 v[118:121], v[174:177], v[190:193], v[118:121]
	v_mfma_f32_16x16x32_bf16 v[114:117], v[182:185], v[190:193], v[114:117]
	v_mfma_f32_16x16x32_bf16 v[102:105], v[174:177], v[200:203], v[102:105]
	v_mfma_f32_16x16x32_bf16 v[98:101], v[182:185], v[200:203], v[98:101]
	v_mfma_f32_16x16x32_bf16 v[86:89], v[174:177], v[210:213], v[86:89]
	v_mfma_f32_16x16x32_bf16 v[82:85], v[182:185], v[210:213], v[82:85]
	v_mfma_f32_16x16x32_bf16 v[70:73], v[174:177], v[218:221], v[70:73]
	v_mfma_f32_16x16x32_bf16 v[66:69], v[182:185], v[218:221], v[66:69]
	v_mfma_f32_16x16x32_bf16 v[118:121], v[178:181], v[196:199], v[118:121]
	v_mfma_f32_16x16x32_bf16 v[114:117], v[186:189], v[196:199], v[114:117]
	v_mfma_f32_16x16x32_bf16 v[102:105], v[178:181], v[206:209], v[102:105]
	v_mfma_f32_16x16x32_bf16 v[98:101], v[186:189], v[206:209], v[98:101]
	v_mfma_f32_16x16x32_bf16 v[86:89], v[178:181], v[214:217], v[86:89]
	v_mfma_f32_16x16x32_bf16 v[82:85], v[186:189], v[214:217], v[82:85]
	v_mfma_f32_16x16x32_bf16 v[70:73], v[178:181], v[222:225], v[70:73]
	v_mfma_f32_16x16x32_bf16 v[66:69], v[186:189], v[222:225], v[66:69]
	s_setprio 0
	s_barrier
	s_add_i32 s62, s83, s64
	v_lshl_add_u64 v[156:157], v[156:157], 0, s[18:19]
	s_mov_b32 m0, s62
	ds_read_b128 v[190:193], v161 offset:49152
	ds_read_b128 v[196:199], v161 offset:50176
	ds_read_b128 v[200:203], v161 offset:51200
	ds_read_b128 v[206:209], v161 offset:52224
	ds_read_b128 v[210:213], v161 offset:53248
	ds_read_b128 v[214:217], v161 offset:54272
	ds_read_b128 v[218:221], v161 offset:55296
	ds_read_b128 v[222:225], v161 offset:56320
	global_load_lds_dwordx4 v[156:157], off
	s_add_i32 m0, s62, 0x2000
	s_add_u32 s48, s48, 0x20080
	v_lshl_add_u64 v[156:157], v[226:227], 0, s[18:19]
	s_addc_u32 s49, s49, 0
	s_add_i32 s62, s84, s64
	global_load_lds_dwordx4 v[156:157], off
	v_lshl_add_u64 v[156:157], s[48:49], 0, v[134:135]
	s_mov_b32 m0, s62
	s_nop 0
	global_load_lds_dwordx4 v[156:157], off
	v_lshl_add_u64 v[156:157], s[48:49], 0, v[138:139]
	s_add_i32 m0, s62, 0x2000
	s_nop 0
	global_load_lds_dwordx4 v[156:157], off
	v_lshl_add_u64 v[156:157], v[228:229], 0, s[18:19]
	s_mov_b32 m0, s70
	s_nop 0
	global_load_lds_dwordx4 v[156:157], off
	v_lshl_add_u64 v[156:157], v[230:231], 0, s[18:19]
	s_mov_b32 m0, s71
	s_nop 0
	global_load_lds_dwordx4 v[156:157], off
	s_nop 0
	s_waitcnt vmcnt(8)
	s_waitcnt lgkmcnt(0)
	s_barrier
	s_setprio 1
	v_mfma_f32_16x16x32_bf16 v[62:65], v[152:155], v[190:193], v[62:65]
	v_mfma_f32_16x16x32_bf16 v[58:61], v[166:169], v[190:193], v[58:61]
	v_mfma_f32_16x16x32_bf16 v[46:49], v[152:155], v[200:203], v[46:49]
	v_mfma_f32_16x16x32_bf16 v[42:45], v[166:169], v[200:203], v[42:45]
	v_mfma_f32_16x16x32_bf16 v[30:33], v[152:155], v[210:213], v[30:33]
	v_mfma_f32_16x16x32_bf16 v[26:29], v[166:169], v[210:213], v[26:29]
	v_mfma_f32_16x16x32_bf16 v[14:17], v[152:155], v[218:221], v[14:17]
	v_mfma_f32_16x16x32_bf16 v[10:13], v[166:169], v[218:221], v[10:13]
	v_mfma_f32_16x16x32_bf16 v[62:65], v[162:165], v[196:199], v[62:65]
	v_mfma_f32_16x16x32_bf16 v[58:61], v[170:173], v[196:199], v[58:61]
	v_mfma_f32_16x16x32_bf16 v[46:49], v[162:165], v[206:209], v[46:49]
	v_mfma_f32_16x16x32_bf16 v[42:45], v[170:173], v[206:209], v[42:45]
	v_mfma_f32_16x16x32_bf16 v[30:33], v[162:165], v[214:217], v[30:33]
	v_mfma_f32_16x16x32_bf16 v[26:29], v[170:173], v[214:217], v[26:29]
	v_mfma_f32_16x16x32_bf16 v[14:17], v[162:165], v[222:225], v[14:17]
	v_mfma_f32_16x16x32_bf16 v[10:13], v[170:173], v[222:225], v[10:13]
	v_mfma_f32_16x16x32_bf16 v[54:57], v[174:177], v[190:193], v[54:57]
	v_mfma_f32_16x16x32_bf16 v[50:53], v[182:185], v[190:193], v[50:53]
	v_mfma_f32_16x16x32_bf16 v[38:41], v[174:177], v[200:203], v[38:41]
	v_mfma_f32_16x16x32_bf16 v[34:37], v[182:185], v[200:203], v[34:37]
	v_mfma_f32_16x16x32_bf16 v[22:25], v[174:177], v[210:213], v[22:25]
	v_mfma_f32_16x16x32_bf16 v[18:21], v[182:185], v[210:213], v[18:21]
	v_mfma_f32_16x16x32_bf16 v[6:9], v[174:177], v[218:221], v[6:9]
	v_mfma_f32_16x16x32_bf16 v[2:5], v[182:185], v[218:221], v[2:5]
	v_mfma_f32_16x16x32_bf16 v[54:57], v[178:181], v[196:199], v[54:57]
	v_mfma_f32_16x16x32_bf16 v[50:53], v[186:189], v[196:199], v[50:53]
	v_mfma_f32_16x16x32_bf16 v[38:41], v[178:181], v[206:209], v[38:41]
	v_mfma_f32_16x16x32_bf16 v[34:37], v[186:189], v[206:209], v[34:37]
	v_mfma_f32_16x16x32_bf16 v[22:25], v[178:181], v[214:217], v[22:25]
	v_mfma_f32_16x16x32_bf16 v[18:21], v[186:189], v[214:217], v[18:21]
	v_mfma_f32_16x16x32_bf16 v[6:9], v[178:181], v[222:225], v[6:9]
	v_mfma_f32_16x16x32_bf16 v[2:5], v[186:189], v[222:225], v[2:5]
	s_setprio 0
	s_barrier
	s_add_u32 s60, s60, 0x100
	s_addc_u32 s61, s61, 0
	s_add_u32 s51, s51, 0x100
	s_addc_u32 s53, s53, 0
	s_cmp_ge_i32 s82, s81
	s_mov_b32 s48, s82
	s_cbranch_scc0 .Lkt_T_9
	s_nop 7
.Lkt_exit_9:
	s_and_b64 vcc, exec, s[20:21]
	s_cbranch_vccz .LBB0_1394
	s_barrier

.Lkt_L_10:
	ds_read_b128 v[156:159], v161
	ds_read_b128 v[164:167], v161 offset:1024
	ds_read_b128 v[168:171], v161 offset:2048
	ds_read_b128 v[172:175], v161 offset:3072
	ds_read_b128 v[176:179], v162
	ds_read_b128 v[180:183], v162 offset:1024
	ds_read_b128 v[184:187], v162 offset:2048
	ds_read_b128 v[188:191], v162 offset:3072
	s_add_i32 s76, s48, 2
	s_add_u32 s49, s46, 0xfff00080
	s_addc_u32 s50, s47, -1
	s_cmp_eq_u32 s73, s48
	s_cselect_b32 s48, s29, s74
	s_cselect_b32 s51, s9, s50
	s_cselect_b32 s50, s27, s49
	s_cselect_b32 s49, s25, s75
	v_lshl_add_u64 v[192:193], s[46:47], 0, v[148:149]
	s_add_i32 m0, s43, 0xc000
	ds_read_b128 v[196:199], v163
	ds_read_b128 v[200:203], v163 offset:1024
	ds_read_b128 v[206:209], v163 offset:2048
	ds_read_b128 v[210:213], v163 offset:3072
	ds_read_b128 v[214:217], v163 offset:4096
	ds_read_b128 v[218:221], v163 offset:5120
	ds_read_b128 v[222:225], v163 offset:6144
	ds_read_b128 v[226:229], v163 offset:7168
	global_load_lds_dwordx4 v[192:193], off
	v_lshl_add_u64 v[192:193], s[46:47], 0, v[150:151]
	s_add_i32 m0, s43, 0xe000
	s_nop 0
	global_load_lds_dwordx4 v[192:193], off
	s_waitcnt lgkmcnt(0)
	s_barrier
	s_nop 0
	s_setprio 1
	v_mfma_f32_16x16x32_bf16 v[78:81], v[156:159], v[196:199], v[78:81]
	v_mfma_f32_16x16x32_bf16 v[74:77], v[168:171], v[196:199], v[74:77]
	v_mfma_f32_16x16x32_bf16 v[70:73], v[156:159], v[206:209], v[70:73]
	v_mfma_f32_16x16x32_bf16 v[62:65], v[168:171], v[206:209], v[62:65]
	v_mfma_f32_16x16x32_bf16 v[58:61], v[156:159], v[214:217], v[58:61]
	v_mfma_f32_16x16x32_bf16 v[54:57], v[168:171], v[214:217], v[54:57]
	v_mfma_f32_16x16x32_bf16 v[46:49], v[156:159], v[222:225], v[46:49]
	v_mfma_f32_16x16x32_bf16 v[38:41], v[168:171], v[222:225], v[38:41]
	v_mfma_f32_16x16x32_bf16 v[78:81], v[164:167], v[200:203], v[78:81]
	v_mfma_f32_16x16x32_bf16 v[74:77], v[172:175], v[200:203], v[74:77]
	v_mfma_f32_16x16x32_bf16 v[70:73], v[164:167], v[210:213], v[70:73]
	v_mfma_f32_16x16x32_bf16 v[62:65], v[172:175], v[210:213], v[62:65]
	v_mfma_f32_16x16x32_bf16 v[58:61], v[164:167], v[218:221], v[58:61]
	v_mfma_f32_16x16x32_bf16 v[54:57], v[172:175], v[218:221], v[54:57]
	v_mfma_f32_16x16x32_bf16 v[46:49], v[164:167], v[226:229], v[46:49]
	v_mfma_f32_16x16x32_bf16 v[38:41], v[172:175], v[226:229], v[38:41]
	v_mfma_f32_16x16x32_bf16 v[50:53], v[176:179], v[196:199], v[50:53]
	v_mfma_f32_16x16x32_bf16 v[42:45], v[184:187], v[196:199], v[42:45]
	v_mfma_f32_16x16x32_bf16 v[34:37], v[176:179], v[206:209], v[34:37]
	v_mfma_f32_16x16x32_bf16 v[26:29], v[184:187], v[206:209], v[26:29]
	v_mfma_f32_16x16x32_bf16 v[18:21], v[176:179], v[214:217], v[18:21]
	v_mfma_f32_16x16x32_bf16 v[14:17], v[184:187], v[214:217], v[14:17]
	v_mfma_f32_16x16x32_bf16 v[10:13], v[176:179], v[222:225], v[10:13]
	v_mfma_f32_16x16x32_bf16 v[6:9], v[184:187], v[222:225], v[6:9]
	v_mfma_f32_16x16x32_bf16 v[50:53], v[180:183], v[200:203], v[50:53]
	v_mfma_f32_16x16x32_bf16 v[42:45], v[188:191], v[200:203], v[42:45]
	v_mfma_f32_16x16x32_bf16 v[34:37], v[180:183], v[210:213], v[34:37]
	v_mfma_f32_16x16x32_bf16 v[26:29], v[188:191], v[210:213], v[26:29]
	v_mfma_f32_16x16x32_bf16 v[18:21], v[180:183], v[218:221], v[18:21]
	v_mfma_f32_16x16x32_bf16 v[14:17], v[188:191], v[218:221], v[14:17]
	v_mfma_f32_16x16x32_bf16 v[10:13], v[180:183], v[226:229], v[10:13]
	v_mfma_f32_16x16x32_bf16 v[6:9], v[188:191], v[226:229], v[6:9]
	s_setprio 0
	s_waitcnt vmcnt(8)
	s_barrier
	s_add_i32 s77, s66, s53
	v_lshl_add_u64 v[192:193], s[48:49], 0, v[134:135]
	s_mov_b32 m0, s77
	ds_read_b128 v[196:199], v163 offset:16384
	ds_read_b128 v[200:203], v163 offset:17408
	ds_read_b128 v[206:209], v163 offset:18432
	ds_read_b128 v[210:213], v163 offset:19456
	ds_read_b128 v[214:217], v163 offset:20480
	ds_read_b128 v[218:221], v163 offset:21504
	ds_read_b128 v[222:225], v163 offset:22528
	ds_read_b128 v[226:229], v163 offset:23552
	global_load_lds_dwordx4 v[192:193], off
	s_add_i32 m0, s77, 0x2000
	s_add_u32 s78, s48, 0x100000
	v_lshl_add_u64 v[230:231], s[48:49], 0, v[138:139]
	s_addc_u32 s79, s49, 0
	s_add_i32 s77, s67, s53
	global_load_lds_dwordx4 v[230:231], off
	v_lshl_add_u64 v[232:233], s[78:79], 0, v[134:135]
	s_mov_b32 m0, s77
	v_lshl_add_u64 v[234:235], s[50:51], 0, v[136:137]
	global_load_lds_dwordx4 v[232:233], off
	v_lshl_add_u64 v[232:233], s[78:79], 0, v[138:139]
	s_add_i32 m0, s77, 0x2000
	s_nop 0
	global_load_lds_dwordx4 v[232:233], off
	v_lshl_add_u64 v[232:233], s[50:51], 0, v[132:133]
	s_mov_b32 m0, s43
	s_nop 0
	global_load_lds_dwordx4 v[232:233], off
	s_mov_b32 m0, s54
	s_nop 0
	global_load_lds_dwordx4 v[234:235], off
	s_waitcnt lgkmcnt(0)
	s_barrier
	s_setprio 1
	v_mfma_f32_16x16x32_bf16 v[126:129], v[156:159], v[196:199], v[126:129]
	v_mfma_f32_16x16x32_bf16 v[118:121], v[168:171], v[196:199], v[118:121]
	v_mfma_f32_16x16x32_bf16 v[110:113], v[156:159], v[206:209], v[110:113]
	v_mfma_f32_16x16x32_bf16 v[102:105], v[168:171], v[206:209], v[102:105]
	v_mfma_f32_16x16x32_bf16 v[94:97], v[156:159], v[214:217], v[94:97]
	v_mfma_f32_16x16x32_bf16 v[86:89], v[168:171], v[214:217], v[86:89]
	v_mfma_f32_16x16x32_bf16 v[66:69], v[156:159], v[222:225], v[66:69]
	v_mfma_f32_16x16x32_bf16 v[22:25], v[168:171], v[222:225], v[22:25]
	v_mfma_f32_16x16x32_bf16 v[126:129], v[164:167], v[200:203], v[126:129]
	v_mfma_f32_16x16x32_bf16 v[118:121], v[172:175], v[200:203], v[118:121]
	v_mfma_f32_16x16x32_bf16 v[110:113], v[164:167], v[210:213], v[110:113]
	v_mfma_f32_16x16x32_bf16 v[102:105], v[172:175], v[210:213], v[102:105]
	v_mfma_f32_16x16x32_bf16 v[94:97], v[164:167], v[218:221], v[94:97]
	v_mfma_f32_16x16x32_bf16 v[86:89], v[172:175], v[218:221], v[86:89]
	v_mfma_f32_16x16x32_bf16 v[66:69], v[164:167], v[226:229], v[66:69]
	v_mfma_f32_16x16x32_bf16 v[22:25], v[172:175], v[226:229], v[22:25]
	v_mfma_f32_16x16x32_bf16 v[122:125], v[176:179], v[196:199], v[122:125]
	v_mfma_f32_16x16x32_bf16 v[114:117], v[184:187], v[196:199], v[114:117]
	v_mfma_f32_16x16x32_bf16 v[106:109], v[176:179], v[206:209], v[106:109]
	v_mfma_f32_16x16x32_bf16 v[98:101], v[184:187], v[206:209], v[98:101]
	v_mfma_f32_16x16x32_bf16 v[90:93], v[176:179], v[214:217], v[90:93]
	v_mfma_f32_16x16x32_bf16 v[82:85], v[184:187], v[214:217], v[82:85]
	v_mfma_f32_16x16x32_bf16 v[30:33], v[176:179], v[222:225], v[30:33]
	v_mfma_f32_16x16x32_bf16 v[2:5], v[184:187], v[222:225], v[2:5]
	v_mfma_f32_16x16x32_bf16 v[122:125], v[180:183], v[200:203], v[122:125]
	v_mfma_f32_16x16x32_bf16 v[114:117], v[188:191], v[200:203], v[114:117]
	v_mfma_f32_16x16x32_bf16 v[106:109], v[180:183], v[210:213], v[106:109]
	v_mfma_f32_16x16x32_bf16 v[98:101], v[188:191], v[210:213], v[98:101]
	v_mfma_f32_16x16x32_bf16 v[90:93], v[180:183], v[218:221], v[90:93]
	v_mfma_f32_16x16x32_bf16 v[82:85], v[188:191], v[218:221], v[82:85]
	v_mfma_f32_16x16x32_bf16 v[30:33], v[180:183], v[226:229], v[30:33]
	v_mfma_f32_16x16x32_bf16 v[2:5], v[188:191], v[226:229], v[2:5]
	s_setprio 0
	s_waitcnt vmcnt(8)
	s_barrier
	s_add_i32 s77, 0, 0x18000
	s_add_i32 s78, 0, 0x1c000
	v_add_u32_e32 v172, s77, v131
	v_add_u32_e32 v188, s78, v131
	ds_read_b128 v[156:159], v172
	ds_read_b128 v[164:167], v172 offset:1024
	ds_read_b128 v[168:171], v172 offset:2048
	ds_read_b128 v[172:175], v172 offset:3072
	ds_read_b128 v[176:179], v188
	ds_read_b128 v[180:183], v188 offset:1024
	ds_read_b128 v[184:187], v188 offset:2048
	ds_read_b128 v[188:191], v188 offset:3072
	s_add_u32 s50, s50, 0x100000
	s_addc_u32 s51, s51, 0
	s_mov_b32 m0, s55
	v_lshl_add_u64 v[236:237], s[50:51], 0, v[132:133]
	ds_read_b128 v[196:199], v163 offset:32768
	ds_read_b128 v[200:203], v163 offset:33792
	ds_read_b128 v[206:209], v163 offset:34816
	ds_read_b128 v[210:213], v163 offset:35840
	ds_read_b128 v[214:217], v163 offset:36864
	ds_read_b128 v[218:221], v163 offset:37888
	ds_read_b128 v[222:225], v163 offset:38912
	ds_read_b128 v[226:229], v163 offset:39936
	global_load_lds_dwordx4 v[236:237], off
	v_lshl_add_u64 v[236:237], s[50:51], 0, v[136:137]
	s_mov_b32 m0, s56
	s_nop 0
	global_load_lds_dwordx4 v[236:237], off
	s_waitcnt lgkmcnt(0)
	s_barrier
	s_setprio 1
	v_mfma_f32_16x16x32_bf16 v[78:81], v[156:159], v[196:199], v[78:81]
	v_mfma_f32_16x16x32_bf16 v[74:77], v[168:171], v[196:199], v[74:77]
	v_mfma_f32_16x16x32_bf16 v[70:73], v[156:159], v[206:209], v[70:73]
	v_mfma_f32_16x16x32_bf16 v[62:65], v[168:171], v[206:209], v[62:65]
	v_mfma_f32_16x16x32_bf16 v[58:61], v[156:159], v[214:217], v[58:61]
	v_mfma_f32_16x16x32_bf16 v[54:57], v[168:171], v[214:217], v[54:57]
	v_mfma_f32_16x16x32_bf16 v[46:49], v[156:159], v[222:225], v[46:49]
	v_mfma_f32_16x16x32_bf16 v[38:41], v[168:171], v[222:225], v[38:41]
	v_mfma_f32_16x16x32_bf16 v[78:81], v[164:167], v[200:203], v[78:81]
	v_mfma_f32_16x16x32_bf16 v[74:77], v[172:175], v[200:203], v[74:77]
	v_mfma_f32_16x16x32_bf16 v[70:73], v[164:167], v[210:213], v[70:73]
	v_mfma_f32_16x16x32_bf16 v[62:65], v[172:175], v[210:213], v[62:65]
	v_mfma_f32_16x16x32_bf16 v[58:61], v[164:167], v[218:221], v[58:61]
	v_mfma_f32_16x16x32_bf16 v[54:57], v[172:175], v[218:221], v[54:57]
	v_mfma_f32_16x16x32_bf16 v[46:49], v[164:167], v[226:229], v[46:49]
	v_mfma_f32_16x16x32_bf16 v[38:41], v[172:175], v[226:229], v[38:41]
	v_mfma_f32_16x16x32_bf16 v[50:53], v[176:179], v[196:199], v[50:53]
	v_mfma_f32_16x16x32_bf16 v[42:45], v[184:187], v[196:199], v[42:45]
	v_mfma_f32_16x16x32_bf16 v[34:37], v[176:179], v[206:209], v[34:37]
	v_mfma_f32_16x16x32_bf16 v[26:29], v[184:187], v[206:209], v[26:29]
	v_mfma_f32_16x16x32_bf16 v[18:21], v[176:179], v[214:217], v[18:21]
	v_mfma_f32_16x16x32_bf16 v[14:17], v[184:187], v[214:217], v[14:17]
	v_mfma_f32_16x16x32_bf16 v[10:13], v[176:179], v[222:225], v[10:13]
	v_mfma_f32_16x16x32_bf16 v[6:9], v[184:187], v[222:225], v[6:9]
	v_mfma_f32_16x16x32_bf16 v[50:53], v[180:183], v[200:203], v[50:53]
	v_mfma_f32_16x16x32_bf16 v[42:45], v[188:191], v[200:203], v[42:45]
	v_mfma_f32_16x16x32_bf16 v[34:37], v[180:183], v[210:213], v[34:37]
	v_mfma_f32_16x16x32_bf16 v[26:29], v[188:191], v[210:213], v[26:29]
	v_mfma_f32_16x16x32_bf16 v[18:21], v[180:183], v[218:221], v[18:21]
	v_mfma_f32_16x16x32_bf16 v[14:17], v[188:191], v[218:221], v[14:17]
	v_mfma_f32_16x16x32_bf16 v[10:13], v[180:183], v[226:229], v[10:13]
	v_mfma_f32_16x16x32_bf16 v[6:9], v[188:191], v[226:229], v[6:9]
	s_setprio 0
	s_waitcnt vmcnt(8)
	s_barrier
	s_add_i32 s50, s77, s53
	v_lshl_add_u64 v[192:193], v[192:193], 0, s[14:15]
	s_mov_b32 m0, s50
	ds_read_b128 v[196:199], v163 offset:49152
	ds_read_b128 v[200:203], v163 offset:50176
	ds_read_b128 v[206:209], v163 offset:51200
	ds_read_b128 v[210:213], v163 offset:52224
	ds_read_b128 v[214:217], v163 offset:53248
	ds_read_b128 v[218:221], v163 offset:54272
	ds_read_b128 v[222:225], v163 offset:55296
	ds_read_b128 v[226:229], v163 offset:56320
	global_load_lds_dwordx4 v[192:193], off
	s_add_i32 m0, s50, 0x2000
	s_add_u32 s48, s48, 0x100080
	v_lshl_add_u64 v[192:193], v[230:231], 0, s[14:15]
	s_addc_u32 s49, s49, 0
	s_add_i32 s50, s78, s53
	global_load_lds_dwordx4 v[192:193], off
	v_lshl_add_u64 v[192:193], s[48:49], 0, v[134:135]
	s_mov_b32 m0, s50
	s_nop 0
	global_load_lds_dwordx4 v[192:193], off
	v_lshl_add_u64 v[192:193], s[48:49], 0, v[138:139]
	s_add_i32 m0, s50, 0x2000
	s_nop 0
	global_load_lds_dwordx4 v[192:193], off
	v_lshl_add_u64 v[192:193], v[232:233], 0, s[14:15]
	s_mov_b32 m0, s59
	s_nop 0
	global_load_lds_dwordx4 v[192:193], off
	v_lshl_add_u64 v[192:193], v[234:235], 0, s[14:15]
	s_mov_b32 m0, s60
	s_nop 0
	global_load_lds_dwordx4 v[192:193], off
	s_waitcnt lgkmcnt(0)
	s_barrier
	s_nop 0
	s_setprio 1
	v_mfma_f32_16x16x32_bf16 v[126:129], v[156:159], v[196:199], v[126:129]
	v_mfma_f32_16x16x32_bf16 v[118:121], v[168:171], v[196:199], v[118:121]
	v_mfma_f32_16x16x32_bf16 v[110:113], v[156:159], v[206:209], v[110:113]
	v_mfma_f32_16x16x32_bf16 v[102:105], v[168:171], v[206:209], v[102:105]
	v_mfma_f32_16x16x32_bf16 v[94:97], v[156:159], v[214:217], v[94:97]
	v_mfma_f32_16x16x32_bf16 v[86:89], v[168:171], v[214:217], v[86:89]
	v_mfma_f32_16x16x32_bf16 v[66:69], v[156:159], v[222:225], v[66:69]
	v_mfma_f32_16x16x32_bf16 v[22:25], v[168:171], v[222:225], v[22:25]
	v_mfma_f32_16x16x32_bf16 v[126:129], v[164:167], v[200:203], v[126:129]
	v_mfma_f32_16x16x32_bf16 v[118:121], v[172:175], v[200:203], v[118:121]
	v_mfma_f32_16x16x32_bf16 v[110:113], v[164:167], v[210:213], v[110:113]
	v_mfma_f32_16x16x32_bf16 v[102:105], v[172:175], v[210:213], v[102:105]
	v_mfma_f32_16x16x32_bf16 v[94:97], v[164:167], v[218:221], v[94:97]
	v_mfma_f32_16x16x32_bf16 v[86:89], v[172:175], v[218:221], v[86:89]
	v_mfma_f32_16x16x32_bf16 v[66:69], v[164:167], v[226:229], v[66:69]
	v_mfma_f32_16x16x32_bf16 v[22:25], v[172:175], v[226:229], v[22:25]
	v_mfma_f32_16x16x32_bf16 v[122:125], v[176:179], v[196:199], v[122:125]
	v_mfma_f32_16x16x32_bf16 v[114:117], v[184:187], v[196:199], v[114:117]
	v_mfma_f32_16x16x32_bf16 v[106:109], v[176:179], v[206:209], v[106:109]
	v_mfma_f32_16x16x32_bf16 v[98:101], v[184:187], v[206:209], v[98:101]
	v_mfma_f32_16x16x32_bf16 v[90:93], v[176:179], v[214:217], v[90:93]
	v_mfma_f32_16x16x32_bf16 v[82:85], v[184:187], v[214:217], v[82:85]
	v_mfma_f32_16x16x32_bf16 v[30:33], v[176:179], v[222:225], v[30:33]
	v_mfma_f32_16x16x32_bf16 v[2:5], v[184:187], v[222:225], v[2:5]
	v_mfma_f32_16x16x32_bf16 v[122:125], v[180:183], v[200:203], v[122:125]
	v_mfma_f32_16x16x32_bf16 v[114:117], v[188:191], v[200:203], v[114:117]
	v_mfma_f32_16x16x32_bf16 v[106:109], v[180:183], v[210:213], v[106:109]
	v_mfma_f32_16x16x32_bf16 v[98:101], v[188:191], v[210:213], v[98:101]
	v_mfma_f32_16x16x32_bf16 v[90:93], v[180:183], v[218:221], v[90:93]
	v_mfma_f32_16x16x32_bf16 v[82:85], v[188:191], v[218:221], v[82:85]
	v_mfma_f32_16x16x32_bf16 v[30:33], v[180:183], v[226:229], v[30:33]
	v_mfma_f32_16x16x32_bf16 v[2:5], v[188:191], v[226:229], v[2:5]
	s_setprio 0
	s_waitcnt vmcnt(8)
	s_barrier
	s_add_u32 s46, s46, 0x100
	s_addc_u32 s47, s47, 0
	s_add_u32 s74, s74, 0x100
	s_addc_u32 s75, s75, 0
	s_cmp_ge_i32 s76, s72
	s_mov_b32 s48, s76
	s_cbranch_scc0 .Lkt_L_10
	s_branch .Lkt_exit_10
.Lkt_T_10:
	ds_read_b128 v[156:159], v161
	ds_read_b128 v[164:167], v161 offset:1024
	ds_read_b128 v[168:171], v161 offset:2048
	ds_read_b128 v[172:175], v161 offset:3072
	ds_read_b128 v[176:179], v162
	ds_read_b128 v[180:183], v162 offset:1024
	ds_read_b128 v[184:187], v162 offset:2048
	ds_read_b128 v[188:191], v162 offset:3072
	s_add_i32 s76, s48, 2
	s_add_u32 s49, s46, 0xfff00080
	s_addc_u32 s50, s47, -1
	s_cmp_eq_u32 s73, s48
	s_cselect_b32 s48, s29, s74
	s_cselect_b32 s51, s9, s50
	s_cselect_b32 s50, s27, s49
	s_cselect_b32 s49, s25, s75
	v_lshl_add_u64 v[192:193], s[46:47], 0, v[148:149]
	s_add_i32 m0, s43, 0xc000
	ds_read_b128 v[196:199], v163
	ds_read_b128 v[200:203], v163 offset:1024
	ds_read_b128 v[206:209], v163 offset:2048
	ds_read_b128 v[210:213], v163 offset:3072
	ds_read_b128 v[214:217], v163 offset:4096
	ds_read_b128 v[218:221], v163 offset:5120
	ds_read_b128 v[222:225], v163 offset:6144
	ds_read_b128 v[226:229], v163 offset:7168
	global_load_lds_dwordx4 v[192:193], off
	v_lshl_add_u64 v[192:193], s[46:47], 0, v[150:151]
	s_add_i32 m0, s43, 0xe000
	s_nop 0
	global_load_lds_dwordx4 v[192:193], off
	s_nop 0
	s_waitcnt vmcnt(8)
	s_waitcnt lgkmcnt(0)
	s_barrier
	s_setprio 1
	v_mfma_f32_16x16x32_bf16 v[78:81], v[156:159], v[196:199], v[78:81]
	v_mfma_f32_16x16x32_bf16 v[74:77], v[168:171], v[196:199], v[74:77]
	v_mfma_f32_16x16x32_bf16 v[70:73], v[156:159], v[206:209], v[70:73]
	v_mfma_f32_16x16x32_bf16 v[62:65], v[168:171], v[206:209], v[62:65]
	v_mfma_f32_16x16x32_bf16 v[58:61], v[156:159], v[214:217], v[58:61]
	v_mfma_f32_16x16x32_bf16 v[54:57], v[168:171], v[214:217], v[54:57]
	v_mfma_f32_16x16x32_bf16 v[46:49], v[156:159], v[222:225], v[46:49]
	v_mfma_f32_16x16x32_bf16 v[38:41], v[168:171], v[222:225], v[38:41]
	v_mfma_f32_16x16x32_bf16 v[78:81], v[164:167], v[200:203], v[78:81]
	v_mfma_f32_16x16x32_bf16 v[74:77], v[172:175], v[200:203], v[74:77]
	v_mfma_f32_16x16x32_bf16 v[70:73], v[164:167], v[210:213], v[70:73]
	v_mfma_f32_16x16x32_bf16 v[62:65], v[172:175], v[210:213], v[62:65]
	v_mfma_f32_16x16x32_bf16 v[58:61], v[164:167], v[218:221], v[58:61]
	v_mfma_f32_16x16x32_bf16 v[54:57], v[172:175], v[218:221], v[54:57]
	v_mfma_f32_16x16x32_bf16 v[46:49], v[164:167], v[226:229], v[46:49]
	v_mfma_f32_16x16x32_bf16 v[38:41], v[172:175], v[226:229], v[38:41]
	v_mfma_f32_16x16x32_bf16 v[50:53], v[176:179], v[196:199], v[50:53]
	v_mfma_f32_16x16x32_bf16 v[42:45], v[184:187], v[196:199], v[42:45]
	v_mfma_f32_16x16x32_bf16 v[34:37], v[176:179], v[206:209], v[34:37]
	v_mfma_f32_16x16x32_bf16 v[26:29], v[184:187], v[206:209], v[26:29]
	v_mfma_f32_16x16x32_bf16 v[18:21], v[176:179], v[214:217], v[18:21]
	v_mfma_f32_16x16x32_bf16 v[14:17], v[184:187], v[214:217], v[14:17]
	v_mfma_f32_16x16x32_bf16 v[10:13], v[176:179], v[222:225], v[10:13]
	v_mfma_f32_16x16x32_bf16 v[6:9], v[184:187], v[222:225], v[6:9]
	v_mfma_f32_16x16x32_bf16 v[50:53], v[180:183], v[200:203], v[50:53]
	v_mfma_f32_16x16x32_bf16 v[42:45], v[188:191], v[200:203], v[42:45]
	v_mfma_f32_16x16x32_bf16 v[34:37], v[180:183], v[210:213], v[34:37]
	v_mfma_f32_16x16x32_bf16 v[26:29], v[188:191], v[210:213], v[26:29]
	v_mfma_f32_16x16x32_bf16 v[18:21], v[180:183], v[218:221], v[18:21]
	v_mfma_f32_16x16x32_bf16 v[14:17], v[188:191], v[218:221], v[14:17]
	v_mfma_f32_16x16x32_bf16 v[10:13], v[180:183], v[226:229], v[10:13]
	v_mfma_f32_16x16x32_bf16 v[6:9], v[188:191], v[226:229], v[6:9]
	s_setprio 0
	s_barrier
	s_add_i32 s77, s66, s53
	v_lshl_add_u64 v[192:193], s[48:49], 0, v[134:135]
	s_mov_b32 m0, s77
	ds_read_b128 v[196:199], v163 offset:16384
	ds_read_b128 v[200:203], v163 offset:17408
	ds_read_b128 v[206:209], v163 offset:18432
	ds_read_b128 v[210:213], v163 offset:19456
	ds_read_b128 v[214:217], v163 offset:20480
	ds_read_b128 v[218:221], v163 offset:21504
	ds_read_b128 v[222:225], v163 offset:22528
	ds_read_b128 v[226:229], v163 offset:23552
	global_load_lds_dwordx4 v[192:193], off
	s_add_i32 m0, s77, 0x2000
	s_add_u32 s78, s48, 0x100000
	v_lshl_add_u64 v[230:231], s[48:49], 0, v[138:139]
	s_addc_u32 s79, s49, 0
	s_add_i32 s77, s67, s53
	global_load_lds_dwordx4 v[230:231], off
	v_lshl_add_u64 v[232:233], s[78:79], 0, v[134:135]
	s_mov_b32 m0, s77
	v_lshl_add_u64 v[234:235], s[50:51], 0, v[136:137]
	global_load_lds_dwordx4 v[232:233], off
	v_lshl_add_u64 v[232:233], s[78:79], 0, v[138:139]
	s_add_i32 m0, s77, 0x2000
	s_nop 0
	global_load_lds_dwordx4 v[232:233], off
	v_lshl_add_u64 v[232:233], s[50:51], 0, v[132:133]
	s_mov_b32 m0, s43
	s_nop 0
	global_load_lds_dwordx4 v[232:233], off
	s_mov_b32 m0, s54
	s_nop 0
	global_load_lds_dwordx4 v[234:235], off
	s_waitcnt vmcnt(8)
	s_waitcnt lgkmcnt(0)
	s_barrier
	s_setprio 1
	v_mfma_f32_16x16x32_bf16 v[126:129], v[156:159], v[196:199], v[126:129]
	v_mfma_f32_16x16x32_bf16 v[118:121], v[168:171], v[196:199], v[118:121]
	v_mfma_f32_16x16x32_bf16 v[110:113], v[156:159], v[206:209], v[110:113]
	v_mfma_f32_16x16x32_bf16 v[102:105], v[168:171], v[206:209], v[102:105]
	v_mfma_f32_16x16x32_bf16 v[94:97], v[156:159], v[214:217], v[94:97]
	v_mfma_f32_16x16x32_bf16 v[86:89], v[168:171], v[214:217], v[86:89]
	v_mfma_f32_16x16x32_bf16 v[66:69], v[156:159], v[222:225], v[66:69]
	v_mfma_f32_16x16x32_bf16 v[22:25], v[168:171], v[222:225], v[22:25]
	v_mfma_f32_16x16x32_bf16 v[126:129], v[164:167], v[200:203], v[126:129]
	v_mfma_f32_16x16x32_bf16 v[118:121], v[172:175], v[200:203], v[118:121]
	v_mfma_f32_16x16x32_bf16 v[110:113], v[164:167], v[210:213], v[110:113]
	v_mfma_f32_16x16x32_bf16 v[102:105], v[172:175], v[210:213], v[102:105]
	v_mfma_f32_16x16x32_bf16 v[94:97], v[164:167], v[218:221], v[94:97]
	v_mfma_f32_16x16x32_bf16 v[86:89], v[172:175], v[218:221], v[86:89]
	v_mfma_f32_16x16x32_bf16 v[66:69], v[164:167], v[226:229], v[66:69]
	v_mfma_f32_16x16x32_bf16 v[22:25], v[172:175], v[226:229], v[22:25]
	v_mfma_f32_16x16x32_bf16 v[122:125], v[176:179], v[196:199], v[122:125]
	v_mfma_f32_16x16x32_bf16 v[114:117], v[184:187], v[196:199], v[114:117]
	v_mfma_f32_16x16x32_bf16 v[106:109], v[176:179], v[206:209], v[106:109]
	v_mfma_f32_16x16x32_bf16 v[98:101], v[184:187], v[206:209], v[98:101]
	v_mfma_f32_16x16x32_bf16 v[90:93], v[176:179], v[214:217], v[90:93]
	v_mfma_f32_16x16x32_bf16 v[82:85], v[184:187], v[214:217], v[82:85]
	v_mfma_f32_16x16x32_bf16 v[30:33], v[176:179], v[222:225], v[30:33]
	v_mfma_f32_16x16x32_bf16 v[2:5], v[184:187], v[222:225], v[2:5]
	v_mfma_f32_16x16x32_bf16 v[122:125], v[180:183], v[200:203], v[122:125]
	v_mfma_f32_16x16x32_bf16 v[114:117], v[188:191], v[200:203], v[114:117]
	v_mfma_f32_16x16x32_bf16 v[106:109], v[180:183], v[210:213], v[106:109]
	v_mfma_f32_16x16x32_bf16 v[98:101], v[188:191], v[210:213], v[98:101]
	v_mfma_f32_16x16x32_bf16 v[90:93], v[180:183], v[218:221], v[90:93]
	v_mfma_f32_16x16x32_bf16 v[82:85], v[188:191], v[218:221], v[82:85]
	v_mfma_f32_16x16x32_bf16 v[30:33], v[180:183], v[226:229], v[30:33]
	v_mfma_f32_16x16x32_bf16 v[2:5], v[188:191], v[226:229], v[2:5]
	s_setprio 0
	s_barrier
	s_add_i32 s77, 0, 0x18000
	s_add_i32 s78, 0, 0x1c000
	v_add_u32_e32 v172, s77, v131
	v_add_u32_e32 v188, s78, v131
	ds_read_b128 v[156:159], v172
	ds_read_b128 v[164:167], v172 offset:1024
	ds_read_b128 v[168:171], v172 offset:2048
	ds_read_b128 v[172:175], v172 offset:3072
	ds_read_b128 v[176:179], v188
	ds_read_b128 v[180:183], v188 offset:1024
	ds_read_b128 v[184:187], v188 offset:2048
	ds_read_b128 v[188:191], v188 offset:3072
	s_add_u32 s50, s50, 0x100000
	s_addc_u32 s51, s51, 0
	s_mov_b32 m0, s55
	v_lshl_add_u64 v[236:237], s[50:51], 0, v[132:133]
	ds_read_b128 v[196:199], v163 offset:32768
	ds_read_b128 v[200:203], v163 offset:33792
	ds_read_b128 v[206:209], v163 offset:34816
	ds_read_b128 v[210:213], v163 offset:35840
	ds_read_b128 v[214:217], v163 offset:36864
	ds_read_b128 v[218:221], v163 offset:37888
	ds_read_b128 v[222:225], v163 offset:38912
	ds_read_b128 v[226:229], v163 offset:39936
	global_load_lds_dwordx4 v[236:237], off
	v_lshl_add_u64 v[236:237], s[50:51], 0, v[136:137]
	s_mov_b32 m0, s56
	s_nop 0
	global_load_lds_dwordx4 v[236:237], off
	s_waitcnt vmcnt(8)
	s_waitcnt lgkmcnt(0)
	s_barrier
	s_setprio 1
	v_mfma_f32_16x16x32_bf16 v[78:81], v[156:159], v[196:199], v[78:81]
	v_mfma_f32_16x16x32_bf16 v[74:77], v[168:171], v[196:199], v[74:77]
	v_mfma_f32_16x16x32_bf16 v[70:73], v[156:159], v[206:209], v[70:73]
	v_mfma_f32_16x16x32_bf16 v[62:65], v[168:171], v[206:209], v[62:65]
	v_mfma_f32_16x16x32_bf16 v[58:61], v[156:159], v[214:217], v[58:61]
	v_mfma_f32_16x16x32_bf16 v[54:57], v[168:171], v[214:217], v[54:57]
	v_mfma_f32_16x16x32_bf16 v[46:49], v[156:159], v[222:225], v[46:49]
	v_mfma_f32_16x16x32_bf16 v[38:41], v[168:171], v[222:225], v[38:41]
	v_mfma_f32_16x16x32_bf16 v[78:81], v[164:167], v[200:203], v[78:81]
	v_mfma_f32_16x16x32_bf16 v[74:77], v[172:175], v[200:203], v[74:77]
	v_mfma_f32_16x16x32_bf16 v[70:73], v[164:167], v[210:213], v[70:73]
	v_mfma_f32_16x16x32_bf16 v[62:65], v[172:175], v[210:213], v[62:65]
	v_mfma_f32_16x16x32_bf16 v[58:61], v[164:167], v[218:221], v[58:61]
	v_mfma_f32_16x16x32_bf16 v[54:57], v[172:175], v[218:221], v[54:57]
	v_mfma_f32_16x16x32_bf16 v[46:49], v[164:167], v[226:229], v[46:49]
	v_mfma_f32_16x16x32_bf16 v[38:41], v[172:175], v[226:229], v[38:41]
	v_mfma_f32_16x16x32_bf16 v[50:53], v[176:179], v[196:199], v[50:53]
	v_mfma_f32_16x16x32_bf16 v[42:45], v[184:187], v[196:199], v[42:45]
	v_mfma_f32_16x16x32_bf16 v[34:37], v[176:179], v[206:209], v[34:37]
	v_mfma_f32_16x16x32_bf16 v[26:29], v[184:187], v[206:209], v[26:29]
	v_mfma_f32_16x16x32_bf16 v[18:21], v[176:179], v[214:217], v[18:21]
	v_mfma_f32_16x16x32_bf16 v[14:17], v[184:187], v[214:217], v[14:17]
	v_mfma_f32_16x16x32_bf16 v[10:13], v[176:179], v[222:225], v[10:13]
	v_mfma_f32_16x16x32_bf16 v[6:9], v[184:187], v[222:225], v[6:9]
	v_mfma_f32_16x16x32_bf16 v[50:53], v[180:183], v[200:203], v[50:53]
	v_mfma_f32_16x16x32_bf16 v[42:45], v[188:191], v[200:203], v[42:45]
	v_mfma_f32_16x16x32_bf16 v[34:37], v[180:183], v[210:213], v[34:37]
	v_mfma_f32_16x16x32_bf16 v[26:29], v[188:191], v[210:213], v[26:29]
	v_mfma_f32_16x16x32_bf16 v[18:21], v[180:183], v[218:221], v[18:21]
	v_mfma_f32_16x16x32_bf16 v[14:17], v[188:191], v[218:221], v[14:17]
	v_mfma_f32_16x16x32_bf16 v[10:13], v[180:183], v[226:229], v[10:13]
	v_mfma_f32_16x16x32_bf16 v[6:9], v[188:191], v[226:229], v[6:9]
	s_setprio 0
	s_barrier
	s_add_i32 s50, s77, s53
	v_lshl_add_u64 v[192:193], v[192:193], 0, s[14:15]
	s_mov_b32 m0, s50
	ds_read_b128 v[196:199], v163 offset:49152
	ds_read_b128 v[200:203], v163 offset:50176
	ds_read_b128 v[206:209], v163 offset:51200
	ds_read_b128 v[210:213], v163 offset:52224
	ds_read_b128 v[214:217], v163 offset:53248
	ds_read_b128 v[218:221], v163 offset:54272
	ds_read_b128 v[222:225], v163 offset:55296
	ds_read_b128 v[226:229], v163 offset:56320
	global_load_lds_dwordx4 v[192:193], off
	s_add_i32 m0, s50, 0x2000
	s_add_u32 s48, s48, 0x100080
	v_lshl_add_u64 v[192:193], v[230:231], 0, s[14:15]
	s_addc_u32 s49, s49, 0
	s_add_i32 s50, s78, s53
	global_load_lds_dwordx4 v[192:193], off
	v_lshl_add_u64 v[192:193], s[48:49], 0, v[134:135]
	s_mov_b32 m0, s50
	s_nop 0
	global_load_lds_dwordx4 v[192:193], off
	v_lshl_add_u64 v[192:193], s[48:49], 0, v[138:139]
	s_add_i32 m0, s50, 0x2000
	s_nop 0
	global_load_lds_dwordx4 v[192:193], off
	v_lshl_add_u64 v[192:193], v[232:233], 0, s[14:15]
	s_mov_b32 m0, s59
	s_nop 0
	global_load_lds_dwordx4 v[192:193], off
	v_lshl_add_u64 v[192:193], v[234:235], 0, s[14:15]
	s_mov_b32 m0, s60
	s_nop 0
	global_load_lds_dwordx4 v[192:193], off
	s_nop 0
	s_waitcnt vmcnt(8)
	s_waitcnt lgkmcnt(0)
	s_barrier
	s_setprio 1
	v_mfma_f32_16x16x32_bf16 v[126:129], v[156:159], v[196:199], v[126:129]
	v_mfma_f32_16x16x32_bf16 v[118:121], v[168:171], v[196:199], v[118:121]
	v_mfma_f32_16x16x32_bf16 v[110:113], v[156:159], v[206:209], v[110:113]
	v_mfma_f32_16x16x32_bf16 v[102:105], v[168:171], v[206:209], v[102:105]
	v_mfma_f32_16x16x32_bf16 v[94:97], v[156:159], v[214:217], v[94:97]
	v_mfma_f32_16x16x32_bf16 v[86:89], v[168:171], v[214:217], v[86:89]
	v_mfma_f32_16x16x32_bf16 v[66:69], v[156:159], v[222:225], v[66:69]
	v_mfma_f32_16x16x32_bf16 v[22:25], v[168:171], v[222:225], v[22:25]
	v_mfma_f32_16x16x32_bf16 v[126:129], v[164:167], v[200:203], v[126:129]
	v_mfma_f32_16x16x32_bf16 v[118:121], v[172:175], v[200:203], v[118:121]
	v_mfma_f32_16x16x32_bf16 v[110:113], v[164:167], v[210:213], v[110:113]
	v_mfma_f32_16x16x32_bf16 v[102:105], v[172:175], v[210:213], v[102:105]
	v_mfma_f32_16x16x32_bf16 v[94:97], v[164:167], v[218:221], v[94:97]
	v_mfma_f32_16x16x32_bf16 v[86:89], v[172:175], v[218:221], v[86:89]
	v_mfma_f32_16x16x32_bf16 v[66:69], v[164:167], v[226:229], v[66:69]
	v_mfma_f32_16x16x32_bf16 v[22:25], v[172:175], v[226:229], v[22:25]
	v_mfma_f32_16x16x32_bf16 v[122:125], v[176:179], v[196:199], v[122:125]
	v_mfma_f32_16x16x32_bf16 v[114:117], v[184:187], v[196:199], v[114:117]
	v_mfma_f32_16x16x32_bf16 v[106:109], v[176:179], v[206:209], v[106:109]
	v_mfma_f32_16x16x32_bf16 v[98:101], v[184:187], v[206:209], v[98:101]
	v_mfma_f32_16x16x32_bf16 v[90:93], v[176:179], v[214:217], v[90:93]
	v_mfma_f32_16x16x32_bf16 v[82:85], v[184:187], v[214:217], v[82:85]
	v_mfma_f32_16x16x32_bf16 v[30:33], v[176:179], v[222:225], v[30:33]
	v_mfma_f32_16x16x32_bf16 v[2:5], v[184:187], v[222:225], v[2:5]
	v_mfma_f32_16x16x32_bf16 v[122:125], v[180:183], v[200:203], v[122:125]
	v_mfma_f32_16x16x32_bf16 v[114:117], v[188:191], v[200:203], v[114:117]
	v_mfma_f32_16x16x32_bf16 v[106:109], v[180:183], v[210:213], v[106:109]
	v_mfma_f32_16x16x32_bf16 v[98:101], v[188:191], v[210:213], v[98:101]
	v_mfma_f32_16x16x32_bf16 v[90:93], v[180:183], v[218:221], v[90:93]
	v_mfma_f32_16x16x32_bf16 v[82:85], v[188:191], v[218:221], v[82:85]
	v_mfma_f32_16x16x32_bf16 v[30:33], v[180:183], v[226:229], v[30:33]
	v_mfma_f32_16x16x32_bf16 v[2:5], v[188:191], v[226:229], v[2:5]
	s_setprio 0
	s_barrier
	s_add_u32 s46, s46, 0x100
	s_addc_u32 s47, s47, 0
	s_add_u32 s74, s74, 0x100
	s_addc_u32 s75, s75, 0
	s_cmp_ge_i32 s76, s72
	s_mov_b32 s48, s76
	s_cbranch_scc0 .Lkt_T_10
	s_nop 7
.Lkt_exit_10:
	s_and_b64 vcc, exec, s[16:17]
	s_cbranch_vccz .LBB0_1558
	s_barrier
	s_cmp_lt_i32 s52, 0
	s_mov_b64 s[46:47], -1
	s_cbranch_scc1 .LBB0_1559

.Lkt_L_11:
	ds_read_b128 v[152:155], v160
	ds_read_b128 v[164:167], v160 offset:1024
	ds_read_b128 v[168:171], v160 offset:2048
	ds_read_b128 v[172:175], v160 offset:3072
	ds_read_b128 v[176:179], v161
	ds_read_b128 v[180:183], v161 offset:1024
	ds_read_b128 v[184:187], v161 offset:2048
	ds_read_b128 v[188:191], v161 offset:3072
	s_add_i32 s82, s48, 2
	s_add_u32 s49, s52, 0xffd50080
	s_addc_u32 s54, s53, -1
	s_cmp_eq_u32 s47, s48
	s_cselect_b32 s48, s50, s80
	s_cselect_b32 s55, s9, s54
	s_cselect_b32 s54, s8, s49
	s_cselect_b32 s49, s51, s81
	v_lshl_add_u64 v[156:157], s[52:53], 0, v[140:141]
	s_add_i32 m0, s57, 0xc000
	ds_read_b128 v[196:199], v162
	ds_read_b128 v[200:203], v162 offset:1024
	ds_read_b128 v[206:209], v162 offset:2048
	ds_read_b128 v[210:213], v162 offset:3072
	ds_read_b128 v[214:217], v162 offset:4096
	ds_read_b128 v[218:221], v162 offset:5120
	ds_read_b128 v[222:225], v162 offset:6144
	ds_read_b128 v[226:229], v162 offset:7168
	global_load_lds_dwordx4 v[156:157], off
	v_lshl_add_u64 v[156:157], s[52:53], 0, v[142:143]
	s_add_i32 m0, s57, 0xe000
	s_nop 0
	global_load_lds_dwordx4 v[156:157], off
	s_waitcnt lgkmcnt(0)
	s_barrier
	s_setprio 1
	v_mfma_f32_16x16x32_bf16 v[126:129], v[152:155], v[196:199], v[126:129]
	v_mfma_f32_16x16x32_bf16 v[122:125], v[168:171], v[196:199], v[122:125]
	v_mfma_f32_16x16x32_bf16 v[110:113], v[152:155], v[206:209], v[110:113]
	v_mfma_f32_16x16x32_bf16 v[106:109], v[168:171], v[206:209], v[106:109]
	v_mfma_f32_16x16x32_bf16 v[94:97], v[152:155], v[214:217], v[94:97]
	v_mfma_f32_16x16x32_bf16 v[90:93], v[168:171], v[214:217], v[90:93]
	v_mfma_f32_16x16x32_bf16 v[78:81], v[152:155], v[222:225], v[78:81]
	v_mfma_f32_16x16x32_bf16 v[74:77], v[168:171], v[222:225], v[74:77]
	v_mfma_f32_16x16x32_bf16 v[126:129], v[164:167], v[200:203], v[126:129]
	v_mfma_f32_16x16x32_bf16 v[122:125], v[172:175], v[200:203], v[122:125]
	v_mfma_f32_16x16x32_bf16 v[110:113], v[164:167], v[210:213], v[110:113]
	v_mfma_f32_16x16x32_bf16 v[106:109], v[172:175], v[210:213], v[106:109]
	v_mfma_f32_16x16x32_bf16 v[94:97], v[164:167], v[218:221], v[94:97]
	v_mfma_f32_16x16x32_bf16 v[90:93], v[172:175], v[218:221], v[90:93]
	v_mfma_f32_16x16x32_bf16 v[78:81], v[164:167], v[226:229], v[78:81]
	v_mfma_f32_16x16x32_bf16 v[74:77], v[172:175], v[226:229], v[74:77]
	v_mfma_f32_16x16x32_bf16 v[118:121], v[176:179], v[196:199], v[118:121]
	v_mfma_f32_16x16x32_bf16 v[114:117], v[184:187], v[196:199], v[114:117]
	v_mfma_f32_16x16x32_bf16 v[102:105], v[176:179], v[206:209], v[102:105]
	v_mfma_f32_16x16x32_bf16 v[98:101], v[184:187], v[206:209], v[98:101]
	v_mfma_f32_16x16x32_bf16 v[86:89], v[176:179], v[214:217], v[86:89]
	v_mfma_f32_16x16x32_bf16 v[82:85], v[184:187], v[214:217], v[82:85]
	v_mfma_f32_16x16x32_bf16 v[70:73], v[176:179], v[222:225], v[70:73]
	v_mfma_f32_16x16x32_bf16 v[66:69], v[184:187], v[222:225], v[66:69]
	v_mfma_f32_16x16x32_bf16 v[118:121], v[180:183], v[200:203], v[118:121]
	v_mfma_f32_16x16x32_bf16 v[114:117], v[188:191], v[200:203], v[114:117]
	v_mfma_f32_16x16x32_bf16 v[102:105], v[180:183], v[210:213], v[102:105]
	v_mfma_f32_16x16x32_bf16 v[98:101], v[188:191], v[210:213], v[98:101]
	v_mfma_f32_16x16x32_bf16 v[86:89], v[180:183], v[218:221], v[86:89]
	v_mfma_f32_16x16x32_bf16 v[82:85], v[188:191], v[218:221], v[82:85]
	v_mfma_f32_16x16x32_bf16 v[70:73], v[180:183], v[226:229], v[70:73]
	v_mfma_f32_16x16x32_bf16 v[66:69], v[188:191], v[226:229], v[66:69]
	s_setprio 0
	s_waitcnt vmcnt(8)
	s_barrier
	s_add_i32 s83, s67, s56
	v_lshl_add_u64 v[156:157], s[48:49], 0, v[134:135]
	s_mov_b32 m0, s83
	ds_read_b128 v[196:199], v162 offset:16384
	ds_read_b128 v[200:203], v162 offset:17408
	ds_read_b128 v[206:209], v162 offset:18432
	ds_read_b128 v[210:213], v162 offset:19456
	ds_read_b128 v[214:217], v162 offset:20480
	ds_read_b128 v[218:221], v162 offset:21504
	ds_read_b128 v[222:225], v162 offset:22528
	ds_read_b128 v[226:229], v162 offset:23552
	global_load_lds_dwordx4 v[156:157], off
	s_add_i32 m0, s83, 0x2000
	s_add_u32 s84, s48, 0x2b0000
	v_lshl_add_u64 v[192:193], s[48:49], 0, v[138:139]
	s_addc_u32 s85, s49, 0
	s_add_i32 s83, s68, s56
	global_load_lds_dwordx4 v[192:193], off
	v_lshl_add_u64 v[230:231], s[84:85], 0, v[134:135]
	s_mov_b32 m0, s83
	v_lshl_add_u64 v[232:233], s[54:55], 0, v[136:137]
	global_load_lds_dwordx4 v[230:231], off
	v_lshl_add_u64 v[230:231], s[84:85], 0, v[138:139]
	s_add_i32 m0, s83, 0x2000
	s_nop 0
	global_load_lds_dwordx4 v[230:231], off
	v_lshl_add_u64 v[230:231], s[54:55], 0, v[132:133]
	s_mov_b32 m0, s57
	s_nop 0
	global_load_lds_dwordx4 v[230:231], off
	s_mov_b32 m0, s58
	s_nop 0
	global_load_lds_dwordx4 v[232:233], off
	s_waitcnt lgkmcnt(0)
	s_barrier
	s_setprio 1
	v_mfma_f32_16x16x32_bf16 v[62:65], v[152:155], v[196:199], v[62:65]
	v_mfma_f32_16x16x32_bf16 v[58:61], v[168:171], v[196:199], v[58:61]
	v_mfma_f32_16x16x32_bf16 v[46:49], v[152:155], v[206:209], v[46:49]
	v_mfma_f32_16x16x32_bf16 v[42:45], v[168:171], v[206:209], v[42:45]
	v_mfma_f32_16x16x32_bf16 v[30:33], v[152:155], v[214:217], v[30:33]
	v_mfma_f32_16x16x32_bf16 v[26:29], v[168:171], v[214:217], v[26:29]
	v_mfma_f32_16x16x32_bf16 v[14:17], v[152:155], v[222:225], v[14:17]
	v_mfma_f32_16x16x32_bf16 v[10:13], v[168:171], v[222:225], v[10:13]
	v_mfma_f32_16x16x32_bf16 v[62:65], v[164:167], v[200:203], v[62:65]
	v_mfma_f32_16x16x32_bf16 v[58:61], v[172:175], v[200:203], v[58:61]
	v_mfma_f32_16x16x32_bf16 v[46:49], v[164:167], v[210:213], v[46:49]
	v_mfma_f32_16x16x32_bf16 v[42:45], v[172:175], v[210:213], v[42:45]
	v_mfma_f32_16x16x32_bf16 v[30:33], v[164:167], v[218:221], v[30:33]
	v_mfma_f32_16x16x32_bf16 v[26:29], v[172:175], v[218:221], v[26:29]
	v_mfma_f32_16x16x32_bf16 v[14:17], v[164:167], v[226:229], v[14:17]
	v_mfma_f32_16x16x32_bf16 v[10:13], v[172:175], v[226:229], v[10:13]
	v_mfma_f32_16x16x32_bf16 v[54:57], v[176:179], v[196:199], v[54:57]
	v_mfma_f32_16x16x32_bf16 v[50:53], v[184:187], v[196:199], v[50:53]
	v_mfma_f32_16x16x32_bf16 v[38:41], v[176:179], v[206:209], v[38:41]
	v_mfma_f32_16x16x32_bf16 v[34:37], v[184:187], v[206:209], v[34:37]
	v_mfma_f32_16x16x32_bf16 v[22:25], v[176:179], v[214:217], v[22:25]
	v_mfma_f32_16x16x32_bf16 v[18:21], v[184:187], v[214:217], v[18:21]
	v_mfma_f32_16x16x32_bf16 v[6:9], v[176:179], v[222:225], v[6:9]
	v_mfma_f32_16x16x32_bf16 v[2:5], v[184:187], v[222:225], v[2:5]
	v_mfma_f32_16x16x32_bf16 v[54:57], v[180:183], v[200:203], v[54:57]
	v_mfma_f32_16x16x32_bf16 v[50:53], v[188:191], v[200:203], v[50:53]
	v_mfma_f32_16x16x32_bf16 v[38:41], v[180:183], v[210:213], v[38:41]
	v_mfma_f32_16x16x32_bf16 v[34:37], v[188:191], v[210:213], v[34:37]
	v_mfma_f32_16x16x32_bf16 v[22:25], v[180:183], v[218:221], v[22:25]
	v_mfma_f32_16x16x32_bf16 v[18:21], v[188:191], v[218:221], v[18:21]
	v_mfma_f32_16x16x32_bf16 v[6:9], v[180:183], v[226:229], v[6:9]
	v_mfma_f32_16x16x32_bf16 v[2:5], v[188:191], v[226:229], v[2:5]
	s_setprio 0
	s_waitcnt vmcnt(8)
	s_barrier
	s_add_i32 s83, 0, 0x18000
	v_add_u32_e32 v163, s83, v158
	s_add_i32 s84, 0, 0x1c000
	ds_read_b128 v[152:155], v163
	ds_read_b128 v[164:167], v163 offset:1024
	ds_read_b128 v[168:171], v163 offset:2048
	ds_read_b128 v[172:175], v163 offset:3072
	v_add_u32_e32 v163, s84, v158
	ds_read_b128 v[176:179], v163
	ds_read_b128 v[180:183], v163 offset:1024
	ds_read_b128 v[184:187], v163 offset:2048
	ds_read_b128 v[188:191], v163 offset:3072
	s_add_u32 s54, s54, 0x2b0000
	s_addc_u32 s55, s55, 0
	s_mov_b32 m0, s59
	v_lshl_add_u64 v[234:235], s[54:55], 0, v[132:133]
	ds_read_b128 v[196:199], v162 offset:32768
	ds_read_b128 v[200:203], v162 offset:33792
	ds_read_b128 v[206:209], v162 offset:34816
	ds_read_b128 v[210:213], v162 offset:35840
	ds_read_b128 v[214:217], v162 offset:36864
	ds_read_b128 v[218:221], v162 offset:37888
	ds_read_b128 v[222:225], v162 offset:38912
	ds_read_b128 v[226:229], v162 offset:39936
	global_load_lds_dwordx4 v[234:235], off
	v_lshl_add_u64 v[234:235], s[54:55], 0, v[136:137]
	s_mov_b32 m0, s60
	s_nop 0
	global_load_lds_dwordx4 v[234:235], off
	s_waitcnt lgkmcnt(0)
	s_barrier
	s_setprio 1
	v_mfma_f32_16x16x32_bf16 v[126:129], v[152:155], v[196:199], v[126:129]
	v_mfma_f32_16x16x32_bf16 v[122:125], v[168:171], v[196:199], v[122:125]
	v_mfma_f32_16x16x32_bf16 v[110:113], v[152:155], v[206:209], v[110:113]
	v_mfma_f32_16x16x32_bf16 v[106:109], v[168:171], v[206:209], v[106:109]
	v_mfma_f32_16x16x32_bf16 v[94:97], v[152:155], v[214:217], v[94:97]
	v_mfma_f32_16x16x32_bf16 v[90:93], v[168:171], v[214:217], v[90:93]
	v_mfma_f32_16x16x32_bf16 v[78:81], v[152:155], v[222:225], v[78:81]
	v_mfma_f32_16x16x32_bf16 v[74:77], v[168:171], v[222:225], v[74:77]
	v_mfma_f32_16x16x32_bf16 v[126:129], v[164:167], v[200:203], v[126:129]
	v_mfma_f32_16x16x32_bf16 v[122:125], v[172:175], v[200:203], v[122:125]
	v_mfma_f32_16x16x32_bf16 v[110:113], v[164:167], v[210:213], v[110:113]
	v_mfma_f32_16x16x32_bf16 v[106:109], v[172:175], v[210:213], v[106:109]
	v_mfma_f32_16x16x32_bf16 v[94:97], v[164:167], v[218:221], v[94:97]
	v_mfma_f32_16x16x32_bf16 v[90:93], v[172:175], v[218:221], v[90:93]
	v_mfma_f32_16x16x32_bf16 v[78:81], v[164:167], v[226:229], v[78:81]
	v_mfma_f32_16x16x32_bf16 v[74:77], v[172:175], v[226:229], v[74:77]
	v_mfma_f32_16x16x32_bf16 v[118:121], v[176:179], v[196:199], v[118:121]
	v_mfma_f32_16x16x32_bf16 v[114:117], v[184:187], v[196:199], v[114:117]
	v_mfma_f32_16x16x32_bf16 v[102:105], v[176:179], v[206:209], v[102:105]
	v_mfma_f32_16x16x32_bf16 v[98:101], v[184:187], v[206:209], v[98:101]
	v_mfma_f32_16x16x32_bf16 v[86:89], v[176:179], v[214:217], v[86:89]
	v_mfma_f32_16x16x32_bf16 v[82:85], v[184:187], v[214:217], v[82:85]
	v_mfma_f32_16x16x32_bf16 v[70:73], v[176:179], v[222:225], v[70:73]
	v_mfma_f32_16x16x32_bf16 v[66:69], v[184:187], v[222:225], v[66:69]
	v_mfma_f32_16x16x32_bf16 v[118:121], v[180:183], v[200:203], v[118:121]
	v_mfma_f32_16x16x32_bf16 v[114:117], v[188:191], v[200:203], v[114:117]
	v_mfma_f32_16x16x32_bf16 v[102:105], v[180:183], v[210:213], v[102:105]
	v_mfma_f32_16x16x32_bf16 v[98:101], v[188:191], v[210:213], v[98:101]
	v_mfma_f32_16x16x32_bf16 v[86:89], v[180:183], v[218:221], v[86:89]
	v_mfma_f32_16x16x32_bf16 v[82:85], v[188:191], v[218:221], v[82:85]
	v_mfma_f32_16x16x32_bf16 v[70:73], v[180:183], v[226:229], v[70:73]
	v_mfma_f32_16x16x32_bf16 v[66:69], v[188:191], v[226:229], v[66:69]
	s_setprio 0
	s_waitcnt vmcnt(8)
	s_barrier
	s_add_i32 s54, s83, s56
	v_lshl_add_u64 v[156:157], v[156:157], 0, s[18:19]
	s_mov_b32 m0, s54
	ds_read_b128 v[196:199], v162 offset:49152
	ds_read_b128 v[200:203], v162 offset:50176
	ds_read_b128 v[206:209], v162 offset:51200
	ds_read_b128 v[210:213], v162 offset:52224
	ds_read_b128 v[214:217], v162 offset:53248
	ds_read_b128 v[218:221], v162 offset:54272
	ds_read_b128 v[222:225], v162 offset:55296
	ds_read_b128 v[226:229], v162 offset:56320
	global_load_lds_dwordx4 v[156:157], off
	s_add_i32 m0, s54, 0x2000
	s_add_u32 s48, s48, 0x2b0080
	v_lshl_add_u64 v[156:157], v[192:193], 0, s[18:19]
	s_addc_u32 s49, s49, 0
	s_add_i32 s54, s84, s56
	global_load_lds_dwordx4 v[156:157], off
	v_lshl_add_u64 v[156:157], s[48:49], 0, v[134:135]
	s_mov_b32 m0, s54
	s_nop 0
	global_load_lds_dwordx4 v[156:157], off
	v_lshl_add_u64 v[156:157], s[48:49], 0, v[138:139]
	s_add_i32 m0, s54, 0x2000
	s_nop 0
	global_load_lds_dwordx4 v[156:157], off
	v_lshl_add_u64 v[156:157], v[230:231], 0, s[18:19]
	s_mov_b32 m0, s64
	s_nop 0
	global_load_lds_dwordx4 v[156:157], off
	v_lshl_add_u64 v[156:157], v[232:233], 0, s[18:19]
	s_mov_b32 m0, s65
	s_nop 0
	global_load_lds_dwordx4 v[156:157], off
	s_waitcnt lgkmcnt(0)
	s_barrier
	s_nop 0
	s_setprio 1
	v_mfma_f32_16x16x32_bf16 v[62:65], v[152:155], v[196:199], v[62:65]
	v_mfma_f32_16x16x32_bf16 v[58:61], v[168:171], v[196:199], v[58:61]
	v_mfma_f32_16x16x32_bf16 v[46:49], v[152:155], v[206:209], v[46:49]
	v_mfma_f32_16x16x32_bf16 v[42:45], v[168:171], v[206:209], v[42:45]
	v_mfma_f32_16x16x32_bf16 v[30:33], v[152:155], v[214:217], v[30:33]
	v_mfma_f32_16x16x32_bf16 v[26:29], v[168:171], v[214:217], v[26:29]
	v_mfma_f32_16x16x32_bf16 v[14:17], v[152:155], v[222:225], v[14:17]
	v_mfma_f32_16x16x32_bf16 v[10:13], v[168:171], v[222:225], v[10:13]
	v_mfma_f32_16x16x32_bf16 v[62:65], v[164:167], v[200:203], v[62:65]
	v_mfma_f32_16x16x32_bf16 v[58:61], v[172:175], v[200:203], v[58:61]
	v_mfma_f32_16x16x32_bf16 v[46:49], v[164:167], v[210:213], v[46:49]
	v_mfma_f32_16x16x32_bf16 v[42:45], v[172:175], v[210:213], v[42:45]
	v_mfma_f32_16x16x32_bf16 v[30:33], v[164:167], v[218:221], v[30:33]
	v_mfma_f32_16x16x32_bf16 v[26:29], v[172:175], v[218:221], v[26:29]
	v_mfma_f32_16x16x32_bf16 v[14:17], v[164:167], v[226:229], v[14:17]
	v_mfma_f32_16x16x32_bf16 v[10:13], v[172:175], v[226:229], v[10:13]
	v_mfma_f32_16x16x32_bf16 v[54:57], v[176:179], v[196:199], v[54:57]
	v_mfma_f32_16x16x32_bf16 v[50:53], v[184:187], v[196:199], v[50:53]
	v_mfma_f32_16x16x32_bf16 v[38:41], v[176:179], v[206:209], v[38:41]
	v_mfma_f32_16x16x32_bf16 v[34:37], v[184:187], v[206:209], v[34:37]
	v_mfma_f32_16x16x32_bf16 v[22:25], v[176:179], v[214:217], v[22:25]
	v_mfma_f32_16x16x32_bf16 v[18:21], v[184:187], v[214:217], v[18:21]
	v_mfma_f32_16x16x32_bf16 v[6:9], v[176:179], v[222:225], v[6:9]
	v_mfma_f32_16x16x32_bf16 v[2:5], v[184:187], v[222:225], v[2:5]
	v_mfma_f32_16x16x32_bf16 v[54:57], v[180:183], v[200:203], v[54:57]
	v_mfma_f32_16x16x32_bf16 v[50:53], v[188:191], v[200:203], v[50:53]
	v_mfma_f32_16x16x32_bf16 v[38:41], v[180:183], v[210:213], v[38:41]
	v_mfma_f32_16x16x32_bf16 v[34:37], v[188:191], v[210:213], v[34:37]
	v_mfma_f32_16x16x32_bf16 v[22:25], v[180:183], v[218:221], v[22:25]
	v_mfma_f32_16x16x32_bf16 v[18:21], v[188:191], v[218:221], v[18:21]
	v_mfma_f32_16x16x32_bf16 v[6:9], v[180:183], v[226:229], v[6:9]
	v_mfma_f32_16x16x32_bf16 v[2:5], v[188:191], v[226:229], v[2:5]
	s_setprio 0
	s_waitcnt vmcnt(8)
	s_barrier
	s_add_u32 s52, s52, 0x100
	s_addc_u32 s53, s53, 0
	s_add_u32 s80, s80, 0x100
	s_addc_u32 s81, s81, 0
	s_cmp_ge_i32 s82, s78
	s_mov_b32 s48, s82
	s_cbranch_scc0 .Lkt_L_11
	s_branch .Lkt_exit_11
.Lkt_T_11:
	ds_read_b128 v[152:155], v160
	ds_read_b128 v[164:167], v160 offset:1024
	ds_read_b128 v[168:171], v160 offset:2048
	ds_read_b128 v[172:175], v160 offset:3072
	ds_read_b128 v[176:179], v161
	ds_read_b128 v[180:183], v161 offset:1024
	ds_read_b128 v[184:187], v161 offset:2048
	ds_read_b128 v[188:191], v161 offset:3072
	s_add_i32 s82, s48, 2
	s_add_u32 s49, s52, 0xffd50080
	s_addc_u32 s54, s53, -1
	s_cmp_eq_u32 s47, s48
	s_cselect_b32 s48, s50, s80
	s_cselect_b32 s55, s9, s54
	s_cselect_b32 s54, s8, s49
	s_cselect_b32 s49, s51, s81
	v_lshl_add_u64 v[156:157], s[52:53], 0, v[140:141]
	s_add_i32 m0, s57, 0xc000
	ds_read_b128 v[196:199], v162
	ds_read_b128 v[200:203], v162 offset:1024
	ds_read_b128 v[206:209], v162 offset:2048
	ds_read_b128 v[210:213], v162 offset:3072
	ds_read_b128 v[214:217], v162 offset:4096
	ds_read_b128 v[218:221], v162 offset:5120
	ds_read_b128 v[222:225], v162 offset:6144
	ds_read_b128 v[226:229], v162 offset:7168
	global_load_lds_dwordx4 v[156:157], off
	v_lshl_add_u64 v[156:157], s[52:53], 0, v[142:143]
	s_add_i32 m0, s57, 0xe000
	s_nop 0
	global_load_lds_dwordx4 v[156:157], off
	s_nop 0
	s_waitcnt vmcnt(8)
	s_waitcnt lgkmcnt(0)
	s_barrier
	s_setprio 1
	v_mfma_f32_16x16x32_bf16 v[126:129], v[152:155], v[196:199], v[126:129]
	v_mfma_f32_16x16x32_bf16 v[122:125], v[168:171], v[196:199], v[122:125]
	v_mfma_f32_16x16x32_bf16 v[110:113], v[152:155], v[206:209], v[110:113]
	v_mfma_f32_16x16x32_bf16 v[106:109], v[168:171], v[206:209], v[106:109]
	v_mfma_f32_16x16x32_bf16 v[94:97], v[152:155], v[214:217], v[94:97]
	v_mfma_f32_16x16x32_bf16 v[90:93], v[168:171], v[214:217], v[90:93]
	v_mfma_f32_16x16x32_bf16 v[78:81], v[152:155], v[222:225], v[78:81]
	v_mfma_f32_16x16x32_bf16 v[74:77], v[168:171], v[222:225], v[74:77]
	v_mfma_f32_16x16x32_bf16 v[126:129], v[164:167], v[200:203], v[126:129]
	v_mfma_f32_16x16x32_bf16 v[122:125], v[172:175], v[200:203], v[122:125]
	v_mfma_f32_16x16x32_bf16 v[110:113], v[164:167], v[210:213], v[110:113]
	v_mfma_f32_16x16x32_bf16 v[106:109], v[172:175], v[210:213], v[106:109]
	v_mfma_f32_16x16x32_bf16 v[94:97], v[164:167], v[218:221], v[94:97]
	v_mfma_f32_16x16x32_bf16 v[90:93], v[172:175], v[218:221], v[90:93]
	v_mfma_f32_16x16x32_bf16 v[78:81], v[164:167], v[226:229], v[78:81]
	v_mfma_f32_16x16x32_bf16 v[74:77], v[172:175], v[226:229], v[74:77]
	v_mfma_f32_16x16x32_bf16 v[118:121], v[176:179], v[196:199], v[118:121]
	v_mfma_f32_16x16x32_bf16 v[114:117], v[184:187], v[196:199], v[114:117]
	v_mfma_f32_16x16x32_bf16 v[102:105], v[176:179], v[206:209], v[102:105]
	v_mfma_f32_16x16x32_bf16 v[98:101], v[184:187], v[206:209], v[98:101]
	v_mfma_f32_16x16x32_bf16 v[86:89], v[176:179], v[214:217], v[86:89]
	v_mfma_f32_16x16x32_bf16 v[82:85], v[184:187], v[214:217], v[82:85]
	v_mfma_f32_16x16x32_bf16 v[70:73], v[176:179], v[222:225], v[70:73]
	v_mfma_f32_16x16x32_bf16 v[66:69], v[184:187], v[222:225], v[66:69]
	v_mfma_f32_16x16x32_bf16 v[118:121], v[180:183], v[200:203], v[118:121]
	v_mfma_f32_16x16x32_bf16 v[114:117], v[188:191], v[200:203], v[114:117]
	v_mfma_f32_16x16x32_bf16 v[102:105], v[180:183], v[210:213], v[102:105]
	v_mfma_f32_16x16x32_bf16 v[98:101], v[188:191], v[210:213], v[98:101]
	v_mfma_f32_16x16x32_bf16 v[86:89], v[180:183], v[218:221], v[86:89]
	v_mfma_f32_16x16x32_bf16 v[82:85], v[188:191], v[218:221], v[82:85]
	v_mfma_f32_16x16x32_bf16 v[70:73], v[180:183], v[226:229], v[70:73]
	v_mfma_f32_16x16x32_bf16 v[66:69], v[188:191], v[226:229], v[66:69]
	s_setprio 0
	s_barrier
	s_add_i32 s83, s67, s56
	v_lshl_add_u64 v[156:157], s[48:49], 0, v[134:135]
	s_mov_b32 m0, s83
	ds_read_b128 v[196:199], v162 offset:16384
	ds_read_b128 v[200:203], v162 offset:17408
	ds_read_b128 v[206:209], v162 offset:18432
	ds_read_b128 v[210:213], v162 offset:19456
	ds_read_b128 v[214:217], v162 offset:20480
	ds_read_b128 v[218:221], v162 offset:21504
	ds_read_b128 v[222:225], v162 offset:22528
	ds_read_b128 v[226:229], v162 offset:23552
	global_load_lds_dwordx4 v[156:157], off
	s_add_i32 m0, s83, 0x2000
	s_add_u32 s84, s48, 0x2b0000
	v_lshl_add_u64 v[192:193], s[48:49], 0, v[138:139]
	s_addc_u32 s85, s49, 0
	s_add_i32 s83, s68, s56
	global_load_lds_dwordx4 v[192:193], off
	v_lshl_add_u64 v[230:231], s[84:85], 0, v[134:135]
	s_mov_b32 m0, s83
	v_lshl_add_u64 v[232:233], s[54:55], 0, v[136:137]
	global_load_lds_dwordx4 v[230:231], off
	v_lshl_add_u64 v[230:231], s[84:85], 0, v[138:139]
	s_add_i32 m0, s83, 0x2000
	s_nop 0
	global_load_lds_dwordx4 v[230:231], off
	v_lshl_add_u64 v[230:231], s[54:55], 0, v[132:133]
	s_mov_b32 m0, s57
	s_nop 0
	global_load_lds_dwordx4 v[230:231], off
	s_mov_b32 m0, s58
	s_nop 0
	global_load_lds_dwordx4 v[232:233], off
	s_waitcnt vmcnt(8)
	s_waitcnt lgkmcnt(0)
	s_barrier
	s_setprio 1
	v_mfma_f32_16x16x32_bf16 v[62:65], v[152:155], v[196:199], v[62:65]
	v_mfma_f32_16x16x32_bf16 v[58:61], v[168:171], v[196:199], v[58:61]
	v_mfma_f32_16x16x32_bf16 v[46:49], v[152:155], v[206:209], v[46:49]
	v_mfma_f32_16x16x32_bf16 v[42:45], v[168:171], v[206:209], v[42:45]
	v_mfma_f32_16x16x32_bf16 v[30:33], v[152:155], v[214:217], v[30:33]
	v_mfma_f32_16x16x32_bf16 v[26:29], v[168:171], v[214:217], v[26:29]
	v_mfma_f32_16x16x32_bf16 v[14:17], v[152:155], v[222:225], v[14:17]
	v_mfma_f32_16x16x32_bf16 v[10:13], v[168:171], v[222:225], v[10:13]
	v_mfma_f32_16x16x32_bf16 v[62:65], v[164:167], v[200:203], v[62:65]
	v_mfma_f32_16x16x32_bf16 v[58:61], v[172:175], v[200:203], v[58:61]
	v_mfma_f32_16x16x32_bf16 v[46:49], v[164:167], v[210:213], v[46:49]
	v_mfma_f32_16x16x32_bf16 v[42:45], v[172:175], v[210:213], v[42:45]
	v_mfma_f32_16x16x32_bf16 v[30:33], v[164:167], v[218:221], v[30:33]
	v_mfma_f32_16x16x32_bf16 v[26:29], v[172:175], v[218:221], v[26:29]
	v_mfma_f32_16x16x32_bf16 v[14:17], v[164:167], v[226:229], v[14:17]
	v_mfma_f32_16x16x32_bf16 v[10:13], v[172:175], v[226:229], v[10:13]
	v_mfma_f32_16x16x32_bf16 v[54:57], v[176:179], v[196:199], v[54:57]
	v_mfma_f32_16x16x32_bf16 v[50:53], v[184:187], v[196:199], v[50:53]
	v_mfma_f32_16x16x32_bf16 v[38:41], v[176:179], v[206:209], v[38:41]
	v_mfma_f32_16x16x32_bf16 v[34:37], v[184:187], v[206:209], v[34:37]
	v_mfma_f32_16x16x32_bf16 v[22:25], v[176:179], v[214:217], v[22:25]
	v_mfma_f32_16x16x32_bf16 v[18:21], v[184:187], v[214:217], v[18:21]
	v_mfma_f32_16x16x32_bf16 v[6:9], v[176:179], v[222:225], v[6:9]
	v_mfma_f32_16x16x32_bf16 v[2:5], v[184:187], v[222:225], v[2:5]
	v_mfma_f32_16x16x32_bf16 v[54:57], v[180:183], v[200:203], v[54:57]
	v_mfma_f32_16x16x32_bf16 v[50:53], v[188:191], v[200:203], v[50:53]
	v_mfma_f32_16x16x32_bf16 v[38:41], v[180:183], v[210:213], v[38:41]
	v_mfma_f32_16x16x32_bf16 v[34:37], v[188:191], v[210:213], v[34:37]
	v_mfma_f32_16x16x32_bf16 v[22:25], v[180:183], v[218:221], v[22:25]
	v_mfma_f32_16x16x32_bf16 v[18:21], v[188:191], v[218:221], v[18:21]
	v_mfma_f32_16x16x32_bf16 v[6:9], v[180:183], v[226:229], v[6:9]
	v_mfma_f32_16x16x32_bf16 v[2:5], v[188:191], v[226:229], v[2:5]
	s_setprio 0
	s_barrier
	s_add_i32 s83, 0, 0x18000
	v_add_u32_e32 v163, s83, v158
	s_add_i32 s84, 0, 0x1c000
	ds_read_b128 v[152:155], v163
	ds_read_b128 v[164:167], v163 offset:1024
	ds_read_b128 v[168:171], v163 offset:2048
	ds_read_b128 v[172:175], v163 offset:3072
	v_add_u32_e32 v163, s84, v158
	ds_read_b128 v[176:179], v163
	ds_read_b128 v[180:183], v163 offset:1024
	ds_read_b128 v[184:187], v163 offset:2048
	ds_read_b128 v[188:191], v163 offset:3072
	s_add_u32 s54, s54, 0x2b0000
	s_addc_u32 s55, s55, 0
	s_mov_b32 m0, s59
	v_lshl_add_u64 v[234:235], s[54:55], 0, v[132:133]
	ds_read_b128 v[196:199], v162 offset:32768
	ds_read_b128 v[200:203], v162 offset:33792
	ds_read_b128 v[206:209], v162 offset:34816
	ds_read_b128 v[210:213], v162 offset:35840
	ds_read_b128 v[214:217], v162 offset:36864
	ds_read_b128 v[218:221], v162 offset:37888
	ds_read_b128 v[222:225], v162 offset:38912
	ds_read_b128 v[226:229], v162 offset:39936
	global_load_lds_dwordx4 v[234:235], off
	v_lshl_add_u64 v[234:235], s[54:55], 0, v[136:137]
	s_mov_b32 m0, s60
	s_nop 0
	global_load_lds_dwordx4 v[234:235], off
	s_waitcnt vmcnt(8)
	s_waitcnt lgkmcnt(0)
	s_barrier
	s_setprio 1
	v_mfma_f32_16x16x32_bf16 v[126:129], v[152:155], v[196:199], v[126:129]
	v_mfma_f32_16x16x32_bf16 v[122:125], v[168:171], v[196:199], v[122:125]
	v_mfma_f32_16x16x32_bf16 v[110:113], v[152:155], v[206:209], v[110:113]
	v_mfma_f32_16x16x32_bf16 v[106:109], v[168:171], v[206:209], v[106:109]
	v_mfma_f32_16x16x32_bf16 v[94:97], v[152:155], v[214:217], v[94:97]
	v_mfma_f32_16x16x32_bf16 v[90:93], v[168:171], v[214:217], v[90:93]
	v_mfma_f32_16x16x32_bf16 v[78:81], v[152:155], v[222:225], v[78:81]
	v_mfma_f32_16x16x32_bf16 v[74:77], v[168:171], v[222:225], v[74:77]
	v_mfma_f32_16x16x32_bf16 v[126:129], v[164:167], v[200:203], v[126:129]
	v_mfma_f32_16x16x32_bf16 v[122:125], v[172:175], v[200:203], v[122:125]
	v_mfma_f32_16x16x32_bf16 v[110:113], v[164:167], v[210:213], v[110:113]
	v_mfma_f32_16x16x32_bf16 v[106:109], v[172:175], v[210:213], v[106:109]
	v_mfma_f32_16x16x32_bf16 v[94:97], v[164:167], v[218:221], v[94:97]
	v_mfma_f32_16x16x32_bf16 v[90:93], v[172:175], v[218:221], v[90:93]
	v_mfma_f32_16x16x32_bf16 v[78:81], v[164:167], v[226:229], v[78:81]
	v_mfma_f32_16x16x32_bf16 v[74:77], v[172:175], v[226:229], v[74:77]
	v_mfma_f32_16x16x32_bf16 v[118:121], v[176:179], v[196:199], v[118:121]
	v_mfma_f32_16x16x32_bf16 v[114:117], v[184:187], v[196:199], v[114:117]
	v_mfma_f32_16x16x32_bf16 v[102:105], v[176:179], v[206:209], v[102:105]
	v_mfma_f32_16x16x32_bf16 v[98:101], v[184:187], v[206:209], v[98:101]
	v_mfma_f32_16x16x32_bf16 v[86:89], v[176:179], v[214:217], v[86:89]
	v_mfma_f32_16x16x32_bf16 v[82:85], v[184:187], v[214:217], v[82:85]
	v_mfma_f32_16x16x32_bf16 v[70:73], v[176:179], v[222:225], v[70:73]
	v_mfma_f32_16x16x32_bf16 v[66:69], v[184:187], v[222:225], v[66:69]
	v_mfma_f32_16x16x32_bf16 v[118:121], v[180:183], v[200:203], v[118:121]
	v_mfma_f32_16x16x32_bf16 v[114:117], v[188:191], v[200:203], v[114:117]
	v_mfma_f32_16x16x32_bf16 v[102:105], v[180:183], v[210:213], v[102:105]
	v_mfma_f32_16x16x32_bf16 v[98:101], v[188:191], v[210:213], v[98:101]
	v_mfma_f32_16x16x32_bf16 v[86:89], v[180:183], v[218:221], v[86:89]
	v_mfma_f32_16x16x32_bf16 v[82:85], v[188:191], v[218:221], v[82:85]
	v_mfma_f32_16x16x32_bf16 v[70:73], v[180:183], v[226:229], v[70:73]
	v_mfma_f32_16x16x32_bf16 v[66:69], v[188:191], v[226:229], v[66:69]
	s_setprio 0
	s_barrier
	s_add_i32 s54, s83, s56
	v_lshl_add_u64 v[156:157], v[156:157], 0, s[18:19]
	s_mov_b32 m0, s54
	ds_read_b128 v[196:199], v162 offset:49152
	ds_read_b128 v[200:203], v162 offset:50176
	ds_read_b128 v[206:209], v162 offset:51200
	ds_read_b128 v[210:213], v162 offset:52224
	ds_read_b128 v[214:217], v162 offset:53248
	ds_read_b128 v[218:221], v162 offset:54272
	ds_read_b128 v[222:225], v162 offset:55296
	ds_read_b128 v[226:229], v162 offset:56320
	global_load_lds_dwordx4 v[156:157], off
	s_add_i32 m0, s54, 0x2000
	s_add_u32 s48, s48, 0x2b0080
	v_lshl_add_u64 v[156:157], v[192:193], 0, s[18:19]
	s_addc_u32 s49, s49, 0
	s_add_i32 s54, s84, s56
	global_load_lds_dwordx4 v[156:157], off
	v_lshl_add_u64 v[156:157], s[48:49], 0, v[134:135]
	s_mov_b32 m0, s54
	s_nop 0
	global_load_lds_dwordx4 v[156:157], off
	v_lshl_add_u64 v[156:157], s[48:49], 0, v[138:139]
	s_add_i32 m0, s54, 0x2000
	s_nop 0
	global_load_lds_dwordx4 v[156:157], off
	v_lshl_add_u64 v[156:157], v[230:231], 0, s[18:19]
	s_mov_b32 m0, s64
	s_nop 0
	global_load_lds_dwordx4 v[156:157], off
	v_lshl_add_u64 v[156:157], v[232:233], 0, s[18:19]
	s_mov_b32 m0, s65
	s_nop 0
	global_load_lds_dwordx4 v[156:157], off
	s_nop 0
	s_waitcnt vmcnt(8)
	s_waitcnt lgkmcnt(0)
	s_barrier
	s_setprio 1
	v_mfma_f32_16x16x32_bf16 v[62:65], v[152:155], v[196:199], v[62:65]
	v_mfma_f32_16x16x32_bf16 v[58:61], v[168:171], v[196:199], v[58:61]
	v_mfma_f32_16x16x32_bf16 v[46:49], v[152:155], v[206:209], v[46:49]
	v_mfma_f32_16x16x32_bf16 v[42:45], v[168:171], v[206:209], v[42:45]
	v_mfma_f32_16x16x32_bf16 v[30:33], v[152:155], v[214:217], v[30:33]
	v_mfma_f32_16x16x32_bf16 v[26:29], v[168:171], v[214:217], v[26:29]
	v_mfma_f32_16x16x32_bf16 v[14:17], v[152:155], v[222:225], v[14:17]
	v_mfma_f32_16x16x32_bf16 v[10:13], v[168:171], v[222:225], v[10:13]
	v_mfma_f32_16x16x32_bf16 v[62:65], v[164:167], v[200:203], v[62:65]
	v_mfma_f32_16x16x32_bf16 v[58:61], v[172:175], v[200:203], v[58:61]
	v_mfma_f32_16x16x32_bf16 v[46:49], v[164:167], v[210:213], v[46:49]
	v_mfma_f32_16x16x32_bf16 v[42:45], v[172:175], v[210:213], v[42:45]
	v_mfma_f32_16x16x32_bf16 v[30:33], v[164:167], v[218:221], v[30:33]
	v_mfma_f32_16x16x32_bf16 v[26:29], v[172:175], v[218:221], v[26:29]
	v_mfma_f32_16x16x32_bf16 v[14:17], v[164:167], v[226:229], v[14:17]
	v_mfma_f32_16x16x32_bf16 v[10:13], v[172:175], v[226:229], v[10:13]
	v_mfma_f32_16x16x32_bf16 v[54:57], v[176:179], v[196:199], v[54:57]
	v_mfma_f32_16x16x32_bf16 v[50:53], v[184:187], v[196:199], v[50:53]
	v_mfma_f32_16x16x32_bf16 v[38:41], v[176:179], v[206:209], v[38:41]
	v_mfma_f32_16x16x32_bf16 v[34:37], v[184:187], v[206:209], v[34:37]
	v_mfma_f32_16x16x32_bf16 v[22:25], v[176:179], v[214:217], v[22:25]
	v_mfma_f32_16x16x32_bf16 v[18:21], v[184:187], v[214:217], v[18:21]
	v_mfma_f32_16x16x32_bf16 v[6:9], v[176:179], v[222:225], v[6:9]
	v_mfma_f32_16x16x32_bf16 v[2:5], v[184:187], v[222:225], v[2:5]
	v_mfma_f32_16x16x32_bf16 v[54:57], v[180:183], v[200:203], v[54:57]
	v_mfma_f32_16x16x32_bf16 v[50:53], v[188:191], v[200:203], v[50:53]
	v_mfma_f32_16x16x32_bf16 v[38:41], v[180:183], v[210:213], v[38:41]
	v_mfma_f32_16x16x32_bf16 v[34:37], v[188:191], v[210:213], v[34:37]
	v_mfma_f32_16x16x32_bf16 v[22:25], v[180:183], v[218:221], v[22:25]
	v_mfma_f32_16x16x32_bf16 v[18:21], v[188:191], v[218:221], v[18:21]
	v_mfma_f32_16x16x32_bf16 v[6:9], v[180:183], v[226:229], v[6:9]
	v_mfma_f32_16x16x32_bf16 v[2:5], v[188:191], v[226:229], v[2:5]
	s_setprio 0
	s_barrier
	s_add_u32 s52, s52, 0x100
	s_addc_u32 s53, s53, 0
	s_add_u32 s80, s80, 0x100
	s_addc_u32 s81, s81, 0
	s_cmp_ge_i32 s82, s78
	s_mov_b32 s48, s82
	s_cbranch_scc0 .Lkt_T_11
	s_nop 7

.Lkt_L_12:
	ds_read_b128 v[162:165], v168
	s_waitcnt vmcnt(0)
	ds_read_b128 v[172:175], v168 offset:1024
	ds_read_b128 v[176:179], v168 offset:2048
	ds_read_b128 v[180:183], v168 offset:3072
	ds_read_b128 v[184:187], v169
	ds_read_b128 v[188:191], v169 offset:1024
	ds_read_b128 v[196:199], v169 offset:2048
	ds_read_b128 v[200:203], v169 offset:3072
	s_add_i32 s55, s42, 2
	s_add_u32 s43, s8, 0xfff00080
	s_addc_u32 s46, s9, -1
	s_cmp_eq_u32 s48, s42
	s_cselect_b32 s42, s41, s49
	s_cselect_b32 s47, s31, s46
	s_cselect_b32 s46, s33, s43
	s_cselect_b32 s43, s35, s53
	v_lshl_add_u64 v[166:167], s[8:9], 0, v[150:151]
	s_add_i32 m0, s62, 0xc000
	ds_read_b128 v[206:209], v170
	ds_read_b128 v[210:213], v170 offset:1024
	ds_read_b128 v[214:217], v170 offset:2048
	ds_read_b128 v[218:221], v170 offset:3072
	ds_read_b128 v[222:225], v170 offset:4096
	ds_read_b128 v[226:229], v170 offset:5120
	ds_read_b128 v[230:233], v170 offset:6144
	ds_read_b128 v[234:237], v170 offset:7168
	global_load_lds_dwordx4 v[166:167], off
	v_lshl_add_u64 v[166:167], s[8:9], 0, v[152:153]
	s_add_i32 m0, s62, 0xe000
	s_nop 0
	global_load_lds_dwordx4 v[166:167], off
	s_waitcnt lgkmcnt(0)
	s_barrier
	s_setprio 1
	v_mfma_f32_16x16x32_bf16 v[66:69], v[162:165], v[206:209], v[66:69]
	v_mfma_f32_16x16x32_bf16 v[62:65], v[176:179], v[206:209], v[62:65]
	v_mfma_f32_16x16x32_bf16 v[58:61], v[162:165], v[214:217], v[58:61]
	v_mfma_f32_16x16x32_bf16 v[54:57], v[176:179], v[214:217], v[54:57]
	v_mfma_f32_16x16x32_bf16 v[50:53], v[162:165], v[222:225], v[50:53]
	v_mfma_f32_16x16x32_bf16 v[46:49], v[176:179], v[222:225], v[46:49]
	v_mfma_f32_16x16x32_bf16 v[38:41], v[162:165], v[230:233], v[38:41]
	v_mfma_f32_16x16x32_bf16 v[30:33], v[176:179], v[230:233], v[30:33]
	v_mfma_f32_16x16x32_bf16 v[66:69], v[172:175], v[210:213], v[66:69]
	v_mfma_f32_16x16x32_bf16 v[62:65], v[180:183], v[210:213], v[62:65]
	v_mfma_f32_16x16x32_bf16 v[58:61], v[172:175], v[218:221], v[58:61]
	v_mfma_f32_16x16x32_bf16 v[54:57], v[180:183], v[218:221], v[54:57]
	v_mfma_f32_16x16x32_bf16 v[50:53], v[172:175], v[226:229], v[50:53]
	v_mfma_f32_16x16x32_bf16 v[46:49], v[180:183], v[226:229], v[46:49]
	v_mfma_f32_16x16x32_bf16 v[38:41], v[172:175], v[234:237], v[38:41]
	v_mfma_f32_16x16x32_bf16 v[30:33], v[180:183], v[234:237], v[30:33]
	v_mfma_f32_16x16x32_bf16 v[42:45], v[184:187], v[206:209], v[42:45]
	v_mfma_f32_16x16x32_bf16 v[34:37], v[196:199], v[206:209], v[34:37]
	v_mfma_f32_16x16x32_bf16 v[26:29], v[184:187], v[214:217], v[26:29]
	v_mfma_f32_16x16x32_bf16 v[22:25], v[196:199], v[214:217], v[22:25]
	v_mfma_f32_16x16x32_bf16 v[18:21], v[184:187], v[222:225], v[18:21]
	v_mfma_f32_16x16x32_bf16 v[14:17], v[196:199], v[222:225], v[14:17]
	v_mfma_f32_16x16x32_bf16 v[10:13], v[184:187], v[230:233], v[10:13]
	v_mfma_f32_16x16x32_bf16 v[6:9], v[196:199], v[230:233], v[6:9]
	v_mfma_f32_16x16x32_bf16 v[42:45], v[188:191], v[210:213], v[42:45]
	v_mfma_f32_16x16x32_bf16 v[34:37], v[200:203], v[210:213], v[34:37]
	v_mfma_f32_16x16x32_bf16 v[26:29], v[188:191], v[218:221], v[26:29]
	v_mfma_f32_16x16x32_bf16 v[22:25], v[200:203], v[218:221], v[22:25]
	v_mfma_f32_16x16x32_bf16 v[18:21], v[188:191], v[226:229], v[18:21]
	v_mfma_f32_16x16x32_bf16 v[14:17], v[200:203], v[226:229], v[14:17]
	v_mfma_f32_16x16x32_bf16 v[10:13], v[188:191], v[234:237], v[10:13]
	v_mfma_f32_16x16x32_bf16 v[6:9], v[200:203], v[234:237], v[6:9]
	s_setprio 0
	s_waitcnt vmcnt(8)
	s_barrier
	s_add_i32 s80, s72, s61
	v_lshl_add_u64 v[166:167], s[42:43], 0, v[134:135]
	s_mov_b32 m0, s80
	ds_read_b128 v[206:209], v170 offset:16384
	ds_read_b128 v[210:213], v170 offset:17408
	ds_read_b128 v[214:217], v170 offset:18432
	ds_read_b128 v[218:221], v170 offset:19456
	ds_read_b128 v[222:225], v170 offset:20480
	ds_read_b128 v[226:229], v170 offset:21504
	ds_read_b128 v[230:233], v170 offset:22528
	ds_read_b128 v[234:237], v170 offset:23552
	global_load_lds_dwordx4 v[166:167], off
	s_add_i32 m0, s80, 0x2000
	s_add_u32 s80, s42, 0x100000
	v_lshl_add_u64 v[192:193], s[42:43], 0, v[138:139]
	s_addc_u32 s81, s43, 0
	s_add_i32 s82, s73, s61
	global_load_lds_dwordx4 v[192:193], off
	v_lshl_add_u64 v[238:239], s[80:81], 0, v[134:135]
	s_mov_b32 m0, s82
	v_lshl_add_u64 v[240:241], s[46:47], 0, v[136:137]
	global_load_lds_dwordx4 v[238:239], off
	v_lshl_add_u64 v[238:239], s[80:81], 0, v[138:139]
	s_add_i32 m0, s82, 0x2000
	s_nop 0
	global_load_lds_dwordx4 v[238:239], off
	v_lshl_add_u64 v[238:239], s[46:47], 0, v[132:133]
	s_mov_b32 m0, s62
	s_nop 0
	global_load_lds_dwordx4 v[238:239], off
	s_mov_b32 m0, s63
	s_nop 0
	global_load_lds_dwordx4 v[240:241], off
	s_waitcnt lgkmcnt(0)
	s_barrier
	s_setprio 1
	v_mfma_f32_16x16x32_bf16 v[126:129], v[162:165], v[206:209], v[126:129]
	v_mfma_f32_16x16x32_bf16 v[122:125], v[176:179], v[206:209], v[122:125]
	v_mfma_f32_16x16x32_bf16 v[110:113], v[162:165], v[214:217], v[110:113]
	v_mfma_f32_16x16x32_bf16 v[106:109], v[176:179], v[214:217], v[106:109]
	v_mfma_f32_16x16x32_bf16 v[94:97], v[162:165], v[222:225], v[94:97]
	v_mfma_f32_16x16x32_bf16 v[90:93], v[176:179], v[222:225], v[90:93]
	v_mfma_f32_16x16x32_bf16 v[78:81], v[162:165], v[230:233], v[78:81]
	v_mfma_f32_16x16x32_bf16 v[74:77], v[176:179], v[230:233], v[74:77]
	v_mfma_f32_16x16x32_bf16 v[126:129], v[172:175], v[210:213], v[126:129]
	v_mfma_f32_16x16x32_bf16 v[122:125], v[180:183], v[210:213], v[122:125]
	v_mfma_f32_16x16x32_bf16 v[110:113], v[172:175], v[218:221], v[110:113]
	v_mfma_f32_16x16x32_bf16 v[106:109], v[180:183], v[218:221], v[106:109]
	v_mfma_f32_16x16x32_bf16 v[94:97], v[172:175], v[226:229], v[94:97]
	v_mfma_f32_16x16x32_bf16 v[90:93], v[180:183], v[226:229], v[90:93]
	v_mfma_f32_16x16x32_bf16 v[78:81], v[172:175], v[234:237], v[78:81]
	v_mfma_f32_16x16x32_bf16 v[74:77], v[180:183], v[234:237], v[74:77]
	v_mfma_f32_16x16x32_bf16 v[118:121], v[184:187], v[206:209], v[118:121]
	v_mfma_f32_16x16x32_bf16 v[114:117], v[196:199], v[206:209], v[114:117]
	v_mfma_f32_16x16x32_bf16 v[102:105], v[184:187], v[214:217], v[102:105]
	v_mfma_f32_16x16x32_bf16 v[98:101], v[196:199], v[214:217], v[98:101]
	v_mfma_f32_16x16x32_bf16 v[86:89], v[184:187], v[222:225], v[86:89]
	v_mfma_f32_16x16x32_bf16 v[82:85], v[196:199], v[222:225], v[82:85]
	v_mfma_f32_16x16x32_bf16 v[70:73], v[184:187], v[230:233], v[70:73]
	v_mfma_f32_16x16x32_bf16 v[2:5], v[196:199], v[230:233], v[2:5]
	v_mfma_f32_16x16x32_bf16 v[118:121], v[188:191], v[210:213], v[118:121]
	v_mfma_f32_16x16x32_bf16 v[114:117], v[200:203], v[210:213], v[114:117]
	v_mfma_f32_16x16x32_bf16 v[102:105], v[188:191], v[218:221], v[102:105]
	v_mfma_f32_16x16x32_bf16 v[98:101], v[200:203], v[218:221], v[98:101]
	v_mfma_f32_16x16x32_bf16 v[86:89], v[188:191], v[226:229], v[86:89]
	v_mfma_f32_16x16x32_bf16 v[82:85], v[200:203], v[226:229], v[82:85]
	v_mfma_f32_16x16x32_bf16 v[70:73], v[188:191], v[234:237], v[70:73]
	v_mfma_f32_16x16x32_bf16 v[2:5], v[200:203], v[234:237], v[2:5]
	s_setprio 0
	s_waitcnt vmcnt(8)
	s_barrier
	s_add_i32 s80, 0, 0x18000
	s_add_i32 s81, 0, 0x1c000
	v_add_u32_e32 v180, s80, v131
	v_add_u32_e32 v200, s81, v131
	ds_read_b128 v[162:165], v180
	ds_read_b128 v[172:175], v180 offset:1024
	ds_read_b128 v[176:179], v180 offset:2048
	ds_read_b128 v[180:183], v180 offset:3072
	ds_read_b128 v[184:187], v200
	ds_read_b128 v[188:191], v200 offset:1024
	ds_read_b128 v[196:199], v200 offset:2048
	ds_read_b128 v[200:203], v200 offset:3072
	s_add_u32 s46, s46, 0x100000
	s_addc_u32 s47, s47, 0
	s_mov_b32 m0, s64
	v_lshl_add_u64 v[242:243], s[46:47], 0, v[132:133]
	ds_read_b128 v[206:209], v170 offset:32768
	ds_read_b128 v[210:213], v170 offset:33792
	ds_read_b128 v[214:217], v170 offset:34816
	ds_read_b128 v[218:221], v170 offset:35840
	ds_read_b128 v[222:225], v170 offset:36864
	ds_read_b128 v[226:229], v170 offset:37888
	ds_read_b128 v[230:233], v170 offset:38912
	ds_read_b128 v[234:237], v170 offset:39936
	global_load_lds_dwordx4 v[242:243], off
	v_lshl_add_u64 v[242:243], s[46:47], 0, v[136:137]
	s_mov_b32 m0, s65
	s_nop 0
	global_load_lds_dwordx4 v[242:243], off
	s_waitcnt lgkmcnt(0)
	s_barrier
	s_setprio 1
	v_mfma_f32_16x16x32_bf16 v[66:69], v[162:165], v[206:209], v[66:69]
	v_mfma_f32_16x16x32_bf16 v[62:65], v[176:179], v[206:209], v[62:65]
	v_mfma_f32_16x16x32_bf16 v[58:61], v[162:165], v[214:217], v[58:61]
	v_mfma_f32_16x16x32_bf16 v[54:57], v[176:179], v[214:217], v[54:57]
	v_mfma_f32_16x16x32_bf16 v[50:53], v[162:165], v[222:225], v[50:53]
	v_mfma_f32_16x16x32_bf16 v[46:49], v[176:179], v[222:225], v[46:49]
	v_mfma_f32_16x16x32_bf16 v[38:41], v[162:165], v[230:233], v[38:41]
	v_mfma_f32_16x16x32_bf16 v[30:33], v[176:179], v[230:233], v[30:33]
	v_mfma_f32_16x16x32_bf16 v[66:69], v[172:175], v[210:213], v[66:69]
	v_mfma_f32_16x16x32_bf16 v[62:65], v[180:183], v[210:213], v[62:65]
	v_mfma_f32_16x16x32_bf16 v[58:61], v[172:175], v[218:221], v[58:61]
	v_mfma_f32_16x16x32_bf16 v[54:57], v[180:183], v[218:221], v[54:57]
	v_mfma_f32_16x16x32_bf16 v[50:53], v[172:175], v[226:229], v[50:53]
	v_mfma_f32_16x16x32_bf16 v[46:49], v[180:183], v[226:229], v[46:49]
	v_mfma_f32_16x16x32_bf16 v[38:41], v[172:175], v[234:237], v[38:41]
	v_mfma_f32_16x16x32_bf16 v[30:33], v[180:183], v[234:237], v[30:33]
	v_mfma_f32_16x16x32_bf16 v[42:45], v[184:187], v[206:209], v[42:45]
	v_mfma_f32_16x16x32_bf16 v[34:37], v[196:199], v[206:209], v[34:37]
	v_mfma_f32_16x16x32_bf16 v[26:29], v[184:187], v[214:217], v[26:29]
	v_mfma_f32_16x16x32_bf16 v[22:25], v[196:199], v[214:217], v[22:25]
	v_mfma_f32_16x16x32_bf16 v[18:21], v[184:187], v[222:225], v[18:21]
	v_mfma_f32_16x16x32_bf16 v[14:17], v[196:199], v[222:225], v[14:17]
	v_mfma_f32_16x16x32_bf16 v[10:13], v[184:187], v[230:233], v[10:13]
	v_mfma_f32_16x16x32_bf16 v[6:9], v[196:199], v[230:233], v[6:9]
	v_mfma_f32_16x16x32_bf16 v[42:45], v[188:191], v[210:213], v[42:45]
	v_mfma_f32_16x16x32_bf16 v[34:37], v[200:203], v[210:213], v[34:37]
	v_mfma_f32_16x16x32_bf16 v[26:29], v[188:191], v[218:221], v[26:29]
	v_mfma_f32_16x16x32_bf16 v[22:25], v[200:203], v[218:221], v[22:25]
	v_mfma_f32_16x16x32_bf16 v[18:21], v[188:191], v[226:229], v[18:21]
	v_mfma_f32_16x16x32_bf16 v[14:17], v[200:203], v[226:229], v[14:17]
	v_mfma_f32_16x16x32_bf16 v[10:13], v[188:191], v[234:237], v[10:13]
	v_mfma_f32_16x16x32_bf16 v[6:9], v[200:203], v[234:237], v[6:9]
	s_setprio 0
	s_waitcnt vmcnt(8)
	s_barrier
	s_add_i32 s46, s80, s61
	v_lshl_add_u64 v[166:167], v[166:167], 0, s[18:19]
	s_mov_b32 m0, s46
	ds_read_b128 v[206:209], v170 offset:49152
	ds_read_b128 v[210:213], v170 offset:50176
	ds_read_b128 v[214:217], v170 offset:51200
	ds_read_b128 v[218:221], v170 offset:52224
	ds_read_b128 v[222:225], v170 offset:53248
	ds_read_b128 v[226:229], v170 offset:54272
	ds_read_b128 v[230:233], v170 offset:55296
	ds_read_b128 v[234:237], v170 offset:56320
	global_load_lds_dwordx4 v[166:167], off
	s_add_i32 m0, s46, 0x2000
	s_add_u32 s42, s42, 0x100080
	v_lshl_add_u64 v[166:167], v[192:193], 0, s[18:19]
	s_addc_u32 s43, s43, 0
	s_add_i32 s46, s81, s61
	global_load_lds_dwordx4 v[166:167], off
	v_lshl_add_u64 v[166:167], s[42:43], 0, v[134:135]
	s_mov_b32 m0, s46
	s_nop 0
	global_load_lds_dwordx4 v[166:167], off
	v_lshl_add_u64 v[166:167], s[42:43], 0, v[138:139]
	s_add_i32 m0, s46, 0x2000
	s_nop 0
	global_load_lds_dwordx4 v[166:167], off
	v_lshl_add_u64 v[166:167], v[238:239], 0, s[18:19]
	s_mov_b32 m0, s69
	s_nop 0
	global_load_lds_dwordx4 v[166:167], off
	v_lshl_add_u64 v[166:167], v[240:241], 0, s[18:19]
	s_mov_b32 m0, s70
	s_nop 0
	global_load_lds_dwordx4 v[166:167], off
	s_waitcnt lgkmcnt(0)
	s_barrier
	s_nop 0
	s_setprio 1
	v_mfma_f32_16x16x32_bf16 v[126:129], v[162:165], v[206:209], v[126:129]
	v_mfma_f32_16x16x32_bf16 v[122:125], v[176:179], v[206:209], v[122:125]
	v_mfma_f32_16x16x32_bf16 v[110:113], v[162:165], v[214:217], v[110:113]
	v_mfma_f32_16x16x32_bf16 v[106:109], v[176:179], v[214:217], v[106:109]
	v_mfma_f32_16x16x32_bf16 v[94:97], v[162:165], v[222:225], v[94:97]
	v_mfma_f32_16x16x32_bf16 v[90:93], v[176:179], v[222:225], v[90:93]
	v_mfma_f32_16x16x32_bf16 v[78:81], v[162:165], v[230:233], v[78:81]
	v_mfma_f32_16x16x32_bf16 v[74:77], v[176:179], v[230:233], v[74:77]
	v_mfma_f32_16x16x32_bf16 v[126:129], v[172:175], v[210:213], v[126:129]
	v_mfma_f32_16x16x32_bf16 v[122:125], v[180:183], v[210:213], v[122:125]
	v_mfma_f32_16x16x32_bf16 v[110:113], v[172:175], v[218:221], v[110:113]
	v_mfma_f32_16x16x32_bf16 v[106:109], v[180:183], v[218:221], v[106:109]
	v_mfma_f32_16x16x32_bf16 v[94:97], v[172:175], v[226:229], v[94:97]
	v_mfma_f32_16x16x32_bf16 v[90:93], v[180:183], v[226:229], v[90:93]
	v_mfma_f32_16x16x32_bf16 v[78:81], v[172:175], v[234:237], v[78:81]
	v_mfma_f32_16x16x32_bf16 v[74:77], v[180:183], v[234:237], v[74:77]
	v_mfma_f32_16x16x32_bf16 v[118:121], v[184:187], v[206:209], v[118:121]
	v_mfma_f32_16x16x32_bf16 v[114:117], v[196:199], v[206:209], v[114:117]
	v_mfma_f32_16x16x32_bf16 v[102:105], v[184:187], v[214:217], v[102:105]
	v_mfma_f32_16x16x32_bf16 v[98:101], v[196:199], v[214:217], v[98:101]
	v_mfma_f32_16x16x32_bf16 v[86:89], v[184:187], v[222:225], v[86:89]
	v_mfma_f32_16x16x32_bf16 v[82:85], v[196:199], v[222:225], v[82:85]
	v_mfma_f32_16x16x32_bf16 v[70:73], v[184:187], v[230:233], v[70:73]
	v_mfma_f32_16x16x32_bf16 v[2:5], v[196:199], v[230:233], v[2:5]
	v_mfma_f32_16x16x32_bf16 v[118:121], v[188:191], v[210:213], v[118:121]
	v_mfma_f32_16x16x32_bf16 v[114:117], v[200:203], v[210:213], v[114:117]
	v_mfma_f32_16x16x32_bf16 v[102:105], v[188:191], v[218:221], v[102:105]
	v_mfma_f32_16x16x32_bf16 v[98:101], v[200:203], v[218:221], v[98:101]
	v_mfma_f32_16x16x32_bf16 v[86:89], v[188:191], v[226:229], v[86:89]
	v_mfma_f32_16x16x32_bf16 v[82:85], v[200:203], v[226:229], v[82:85]
	v_mfma_f32_16x16x32_bf16 v[70:73], v[188:191], v[234:237], v[70:73]
	v_mfma_f32_16x16x32_bf16 v[2:5], v[200:203], v[234:237], v[2:5]
	s_setprio 0
	s_waitcnt vmcnt(8)
	s_barrier
	s_add_u32 s8, s8, 0x100
	s_addc_u32 s9, s9, 0
	s_add_u32 s49, s49, 0x100
	s_addc_u32 s53, s53, 0
	s_cmp_ge_i32 s55, s3
	s_mov_b32 s42, s55
	s_cbranch_scc0 .Lkt_L_12
	s_branch .Lkt_exit_12
.Lkt_T_12:
	ds_read_b128 v[162:165], v168
	s_waitcnt vmcnt(0)
	ds_read_b128 v[172:175], v168 offset:1024
	ds_read_b128 v[176:179], v168 offset:2048
	ds_read_b128 v[180:183], v168 offset:3072
	ds_read_b128 v[184:187], v169
	ds_read_b128 v[188:191], v169 offset:1024
	ds_read_b128 v[196:199], v169 offset:2048
	ds_read_b128 v[200:203], v169 offset:3072
	s_add_i32 s55, s42, 2
	s_add_u32 s43, s8, 0xfff00080
	s_addc_u32 s46, s9, -1
	s_cmp_eq_u32 s48, s42
	s_cselect_b32 s42, s41, s49
	s_cselect_b32 s47, s31, s46
	s_cselect_b32 s46, s33, s43
	s_cselect_b32 s43, s35, s53
	v_lshl_add_u64 v[166:167], s[8:9], 0, v[150:151]
	s_add_i32 m0, s62, 0xc000
	ds_read_b128 v[206:209], v170
	ds_read_b128 v[210:213], v170 offset:1024
	ds_read_b128 v[214:217], v170 offset:2048
	ds_read_b128 v[218:221], v170 offset:3072
	ds_read_b128 v[222:225], v170 offset:4096
	ds_read_b128 v[226:229], v170 offset:5120
	ds_read_b128 v[230:233], v170 offset:6144
	ds_read_b128 v[234:237], v170 offset:7168
	global_load_lds_dwordx4 v[166:167], off
	v_lshl_add_u64 v[166:167], s[8:9], 0, v[152:153]
	s_add_i32 m0, s62, 0xe000
	s_nop 0
	global_load_lds_dwordx4 v[166:167], off
	s_waitcnt vmcnt(8)
	s_waitcnt lgkmcnt(0)
	s_barrier
	s_setprio 1
	v_mfma_f32_16x16x32_bf16 v[66:69], v[162:165], v[206:209], v[66:69]
	v_mfma_f32_16x16x32_bf16 v[62:65], v[176:179], v[206:209], v[62:65]
	v_mfma_f32_16x16x32_bf16 v[58:61], v[162:165], v[214:217], v[58:61]
	v_mfma_f32_16x16x32_bf16 v[54:57], v[176:179], v[214:217], v[54:57]
	v_mfma_f32_16x16x32_bf16 v[50:53], v[162:165], v[222:225], v[50:53]
	v_mfma_f32_16x16x32_bf16 v[46:49], v[176:179], v[222:225], v[46:49]
	v_mfma_f32_16x16x32_bf16 v[38:41], v[162:165], v[230:233], v[38:41]
	v_mfma_f32_16x16x32_bf16 v[30:33], v[176:179], v[230:233], v[30:33]
	v_mfma_f32_16x16x32_bf16 v[66:69], v[172:175], v[210:213], v[66:69]
	v_mfma_f32_16x16x32_bf16 v[62:65], v[180:183], v[210:213], v[62:65]
	v_mfma_f32_16x16x32_bf16 v[58:61], v[172:175], v[218:221], v[58:61]
	v_mfma_f32_16x16x32_bf16 v[54:57], v[180:183], v[218:221], v[54:57]
	v_mfma_f32_16x16x32_bf16 v[50:53], v[172:175], v[226:229], v[50:53]
	v_mfma_f32_16x16x32_bf16 v[46:49], v[180:183], v[226:229], v[46:49]
	v_mfma_f32_16x16x32_bf16 v[38:41], v[172:175], v[234:237], v[38:41]
	v_mfma_f32_16x16x32_bf16 v[30:33], v[180:183], v[234:237], v[30:33]
	v_mfma_f32_16x16x32_bf16 v[42:45], v[184:187], v[206:209], v[42:45]
	v_mfma_f32_16x16x32_bf16 v[34:37], v[196:199], v[206:209], v[34:37]
	v_mfma_f32_16x16x32_bf16 v[26:29], v[184:187], v[214:217], v[26:29]
	v_mfma_f32_16x16x32_bf16 v[22:25], v[196:199], v[214:217], v[22:25]
	v_mfma_f32_16x16x32_bf16 v[18:21], v[184:187], v[222:225], v[18:21]
	v_mfma_f32_16x16x32_bf16 v[14:17], v[196:199], v[222:225], v[14:17]
	v_mfma_f32_16x16x32_bf16 v[10:13], v[184:187], v[230:233], v[10:13]
	v_mfma_f32_16x16x32_bf16 v[6:9], v[196:199], v[230:233], v[6:9]
	v_mfma_f32_16x16x32_bf16 v[42:45], v[188:191], v[210:213], v[42:45]
	v_mfma_f32_16x16x32_bf16 v[34:37], v[200:203], v[210:213], v[34:37]
	v_mfma_f32_16x16x32_bf16 v[26:29], v[188:191], v[218:221], v[26:29]
	v_mfma_f32_16x16x32_bf16 v[22:25], v[200:203], v[218:221], v[22:25]
	v_mfma_f32_16x16x32_bf16 v[18:21], v[188:191], v[226:229], v[18:21]
	v_mfma_f32_16x16x32_bf16 v[14:17], v[200:203], v[226:229], v[14:17]
	v_mfma_f32_16x16x32_bf16 v[10:13], v[188:191], v[234:237], v[10:13]
	v_mfma_f32_16x16x32_bf16 v[6:9], v[200:203], v[234:237], v[6:9]
	s_setprio 0
	s_barrier
	s_add_i32 s80, s72, s61
	v_lshl_add_u64 v[166:167], s[42:43], 0, v[134:135]
	s_mov_b32 m0, s80
	ds_read_b128 v[206:209], v170 offset:16384
	ds_read_b128 v[210:213], v170 offset:17408
	ds_read_b128 v[214:217], v170 offset:18432
	ds_read_b128 v[218:221], v170 offset:19456
	ds_read_b128 v[222:225], v170 offset:20480
	ds_read_b128 v[226:229], v170 offset:21504
	ds_read_b128 v[230:233], v170 offset:22528
	ds_read_b128 v[234:237], v170 offset:23552
	global_load_lds_dwordx4 v[166:167], off
	s_add_i32 m0, s80, 0x2000
	s_add_u32 s80, s42, 0x100000
	v_lshl_add_u64 v[192:193], s[42:43], 0, v[138:139]
	s_addc_u32 s81, s43, 0
	s_add_i32 s82, s73, s61
	global_load_lds_dwordx4 v[192:193], off
	v_lshl_add_u64 v[238:239], s[80:81], 0, v[134:135]
	s_mov_b32 m0, s82
	v_lshl_add_u64 v[240:241], s[46:47], 0, v[136:137]
	global_load_lds_dwordx4 v[238:239], off
	v_lshl_add_u64 v[238:239], s[80:81], 0, v[138:139]
	s_add_i32 m0, s82, 0x2000
	s_nop 0
	global_load_lds_dwordx4 v[238:239], off
	v_lshl_add_u64 v[238:239], s[46:47], 0, v[132:133]
	s_mov_b32 m0, s62
	s_nop 0
	global_load_lds_dwordx4 v[238:239], off
	s_mov_b32 m0, s63
	s_nop 0
	global_load_lds_dwordx4 v[240:241], off
	s_waitcnt vmcnt(8)
	s_waitcnt lgkmcnt(0)
	s_barrier
	s_setprio 1
	v_mfma_f32_16x16x32_bf16 v[126:129], v[162:165], v[206:209], v[126:129]
	v_mfma_f32_16x16x32_bf16 v[122:125], v[176:179], v[206:209], v[122:125]
	v_mfma_f32_16x16x32_bf16 v[110:113], v[162:165], v[214:217], v[110:113]
	v_mfma_f32_16x16x32_bf16 v[106:109], v[176:179], v[214:217], v[106:109]
	v_mfma_f32_16x16x32_bf16 v[94:97], v[162:165], v[222:225], v[94:97]
	v_mfma_f32_16x16x32_bf16 v[90:93], v[176:179], v[222:225], v[90:93]
	v_mfma_f32_16x16x32_bf16 v[78:81], v[162:165], v[230:233], v[78:81]
	v_mfma_f32_16x16x32_bf16 v[74:77], v[176:179], v[230:233], v[74:77]
	v_mfma_f32_16x16x32_bf16 v[126:129], v[172:175], v[210:213], v[126:129]
	v_mfma_f32_16x16x32_bf16 v[122:125], v[180:183], v[210:213], v[122:125]
	v_mfma_f32_16x16x32_bf16 v[110:113], v[172:175], v[218:221], v[110:113]
	v_mfma_f32_16x16x32_bf16 v[106:109], v[180:183], v[218:221], v[106:109]
	v_mfma_f32_16x16x32_bf16 v[94:97], v[172:175], v[226:229], v[94:97]
	v_mfma_f32_16x16x32_bf16 v[90:93], v[180:183], v[226:229], v[90:93]
	v_mfma_f32_16x16x32_bf16 v[78:81], v[172:175], v[234:237], v[78:81]
	v_mfma_f32_16x16x32_bf16 v[74:77], v[180:183], v[234:237], v[74:77]
	v_mfma_f32_16x16x32_bf16 v[118:121], v[184:187], v[206:209], v[118:121]
	v_mfma_f32_16x16x32_bf16 v[114:117], v[196:199], v[206:209], v[114:117]
	v_mfma_f32_16x16x32_bf16 v[102:105], v[184:187], v[214:217], v[102:105]
	v_mfma_f32_16x16x32_bf16 v[98:101], v[196:199], v[214:217], v[98:101]
	v_mfma_f32_16x16x32_bf16 v[86:89], v[184:187], v[222:225], v[86:89]
	v_mfma_f32_16x16x32_bf16 v[82:85], v[196:199], v[222:225], v[82:85]
	v_mfma_f32_16x16x32_bf16 v[70:73], v[184:187], v[230:233], v[70:73]
	v_mfma_f32_16x16x32_bf16 v[2:5], v[196:199], v[230:233], v[2:5]
	v_mfma_f32_16x16x32_bf16 v[118:121], v[188:191], v[210:213], v[118:121]
	v_mfma_f32_16x16x32_bf16 v[114:117], v[200:203], v[210:213], v[114:117]
	v_mfma_f32_16x16x32_bf16 v[102:105], v[188:191], v[218:221], v[102:105]
	v_mfma_f32_16x16x32_bf16 v[98:101], v[200:203], v[218:221], v[98:101]
	v_mfma_f32_16x16x32_bf16 v[86:89], v[188:191], v[226:229], v[86:89]
	v_mfma_f32_16x16x32_bf16 v[82:85], v[200:203], v[226:229], v[82:85]
	v_mfma_f32_16x16x32_bf16 v[70:73], v[188:191], v[234:237], v[70:73]
	v_mfma_f32_16x16x32_bf16 v[2:5], v[200:203], v[234:237], v[2:5]
	s_setprio 0
	s_barrier
	s_add_i32 s80, 0, 0x18000
	s_add_i32 s81, 0, 0x1c000
	v_add_u32_e32 v180, s80, v131
	v_add_u32_e32 v200, s81, v131
	ds_read_b128 v[162:165], v180
	ds_read_b128 v[172:175], v180 offset:1024
	ds_read_b128 v[176:179], v180 offset:2048
	ds_read_b128 v[180:183], v180 offset:3072
	ds_read_b128 v[184:187], v200
	ds_read_b128 v[188:191], v200 offset:1024
	ds_read_b128 v[196:199], v200 offset:2048
	ds_read_b128 v[200:203], v200 offset:3072
	s_add_u32 s46, s46, 0x100000
	s_addc_u32 s47, s47, 0
	s_mov_b32 m0, s64
	v_lshl_add_u64 v[242:243], s[46:47], 0, v[132:133]
	ds_read_b128 v[206:209], v170 offset:32768
	ds_read_b128 v[210:213], v170 offset:33792
	ds_read_b128 v[214:217], v170 offset:34816
	ds_read_b128 v[218:221], v170 offset:35840
	ds_read_b128 v[222:225], v170 offset:36864
	ds_read_b128 v[226:229], v170 offset:37888
	ds_read_b128 v[230:233], v170 offset:38912
	ds_read_b128 v[234:237], v170 offset:39936
	global_load_lds_dwordx4 v[242:243], off
	v_lshl_add_u64 v[242:243], s[46:47], 0, v[136:137]
	s_mov_b32 m0, s65
	s_nop 0
	global_load_lds_dwordx4 v[242:243], off
	s_waitcnt vmcnt(8)
	s_waitcnt lgkmcnt(0)
	s_barrier
	s_setprio 1
	v_mfma_f32_16x16x32_bf16 v[66:69], v[162:165], v[206:209], v[66:69]
	v_mfma_f32_16x16x32_bf16 v[62:65], v[176:179], v[206:209], v[62:65]
	v_mfma_f32_16x16x32_bf16 v[58:61], v[162:165], v[214:217], v[58:61]
	v_mfma_f32_16x16x32_bf16 v[54:57], v[176:179], v[214:217], v[54:57]
	v_mfma_f32_16x16x32_bf16 v[50:53], v[162:165], v[222:225], v[50:53]
	v_mfma_f32_16x16x32_bf16 v[46:49], v[176:179], v[222:225], v[46:49]
	v_mfma_f32_16x16x32_bf16 v[38:41], v[162:165], v[230:233], v[38:41]
	v_mfma_f32_16x16x32_bf16 v[30:33], v[176:179], v[230:233], v[30:33]
	v_mfma_f32_16x16x32_bf16 v[66:69], v[172:175], v[210:213], v[66:69]
	v_mfma_f32_16x16x32_bf16 v[62:65], v[180:183], v[210:213], v[62:65]
	v_mfma_f32_16x16x32_bf16 v[58:61], v[172:175], v[218:221], v[58:61]
	v_mfma_f32_16x16x32_bf16 v[54:57], v[180:183], v[218:221], v[54:57]
	v_mfma_f32_16x16x32_bf16 v[50:53], v[172:175], v[226:229], v[50:53]
	v_mfma_f32_16x16x32_bf16 v[46:49], v[180:183], v[226:229], v[46:49]
	v_mfma_f32_16x16x32_bf16 v[38:41], v[172:175], v[234:237], v[38:41]
	v_mfma_f32_16x16x32_bf16 v[30:33], v[180:183], v[234:237], v[30:33]
	v_mfma_f32_16x16x32_bf16 v[42:45], v[184:187], v[206:209], v[42:45]
	v_mfma_f32_16x16x32_bf16 v[34:37], v[196:199], v[206:209], v[34:37]
	v_mfma_f32_16x16x32_bf16 v[26:29], v[184:187], v[214:217], v[26:29]
	v_mfma_f32_16x16x32_bf16 v[22:25], v[196:199], v[214:217], v[22:25]
	v_mfma_f32_16x16x32_bf16 v[18:21], v[184:187], v[222:225], v[18:21]
	v_mfma_f32_16x16x32_bf16 v[14:17], v[196:199], v[222:225], v[14:17]
	v_mfma_f32_16x16x32_bf16 v[10:13], v[184:187], v[230:233], v[10:13]
	v_mfma_f32_16x16x32_bf16 v[6:9], v[196:199], v[230:233], v[6:9]
	v_mfma_f32_16x16x32_bf16 v[42:45], v[188:191], v[210:213], v[42:45]
	v_mfma_f32_16x16x32_bf16 v[34:37], v[200:203], v[210:213], v[34:37]
	v_mfma_f32_16x16x32_bf16 v[26:29], v[188:191], v[218:221], v[26:29]
	v_mfma_f32_16x16x32_bf16 v[22:25], v[200:203], v[218:221], v[22:25]
	v_mfma_f32_16x16x32_bf16 v[18:21], v[188:191], v[226:229], v[18:21]
	v_mfma_f32_16x16x32_bf16 v[14:17], v[200:203], v[226:229], v[14:17]
	v_mfma_f32_16x16x32_bf16 v[10:13], v[188:191], v[234:237], v[10:13]
	v_mfma_f32_16x16x32_bf16 v[6:9], v[200:203], v[234:237], v[6:9]
	s_setprio 0
	s_barrier
	s_add_i32 s46, s80, s61
	v_lshl_add_u64 v[166:167], v[166:167], 0, s[18:19]
	s_mov_b32 m0, s46
	ds_read_b128 v[206:209], v170 offset:49152
	ds_read_b128 v[210:213], v170 offset:50176
	ds_read_b128 v[214:217], v170 offset:51200
	ds_read_b128 v[218:221], v170 offset:52224
	ds_read_b128 v[222:225], v170 offset:53248
	ds_read_b128 v[226:229], v170 offset:54272
	ds_read_b128 v[230:233], v170 offset:55296
	ds_read_b128 v[234:237], v170 offset:56320
	global_load_lds_dwordx4 v[166:167], off
	s_add_i32 m0, s46, 0x2000
	s_add_u32 s42, s42, 0x100080
	v_lshl_add_u64 v[166:167], v[192:193], 0, s[18:19]
	s_addc_u32 s43, s43, 0
	s_add_i32 s46, s81, s61
	global_load_lds_dwordx4 v[166:167], off
	v_lshl_add_u64 v[166:167], s[42:43], 0, v[134:135]
	s_mov_b32 m0, s46
	s_nop 0
	global_load_lds_dwordx4 v[166:167], off
	v_lshl_add_u64 v[166:167], s[42:43], 0, v[138:139]
	s_add_i32 m0, s46, 0x2000
	s_nop 0
	global_load_lds_dwordx4 v[166:167], off
	v_lshl_add_u64 v[166:167], v[238:239], 0, s[18:19]
	s_mov_b32 m0, s69
	s_nop 0
	global_load_lds_dwordx4 v[166:167], off
	v_lshl_add_u64 v[166:167], v[240:241], 0, s[18:19]
	s_mov_b32 m0, s70
	s_nop 0
	global_load_lds_dwordx4 v[166:167], off
	s_nop 0
	s_waitcnt vmcnt(8)
	s_waitcnt lgkmcnt(0)
	s_barrier
	s_setprio 1
	v_mfma_f32_16x16x32_bf16 v[126:129], v[162:165], v[206:209], v[126:129]
	v_mfma_f32_16x16x32_bf16 v[122:125], v[176:179], v[206:209], v[122:125]
	v_mfma_f32_16x16x32_bf16 v[110:113], v[162:165], v[214:217], v[110:113]
	v_mfma_f32_16x16x32_bf16 v[106:109], v[176:179], v[214:217], v[106:109]
	v_mfma_f32_16x16x32_bf16 v[94:97], v[162:165], v[222:225], v[94:97]
	v_mfma_f32_16x16x32_bf16 v[90:93], v[176:179], v[222:225], v[90:93]
	v_mfma_f32_16x16x32_bf16 v[78:81], v[162:165], v[230:233], v[78:81]
	v_mfma_f32_16x16x32_bf16 v[74:77], v[176:179], v[230:233], v[74:77]
	v_mfma_f32_16x16x32_bf16 v[126:129], v[172:175], v[210:213], v[126:129]
	v_mfma_f32_16x16x32_bf16 v[122:125], v[180:183], v[210:213], v[122:125]
	v_mfma_f32_16x16x32_bf16 v[110:113], v[172:175], v[218:221], v[110:113]
	v_mfma_f32_16x16x32_bf16 v[106:109], v[180:183], v[218:221], v[106:109]
	v_mfma_f32_16x16x32_bf16 v[94:97], v[172:175], v[226:229], v[94:97]
	v_mfma_f32_16x16x32_bf16 v[90:93], v[180:183], v[226:229], v[90:93]
	v_mfma_f32_16x16x32_bf16 v[78:81], v[172:175], v[234:237], v[78:81]
	v_mfma_f32_16x16x32_bf16 v[74:77], v[180:183], v[234:237], v[74:77]
	v_mfma_f32_16x16x32_bf16 v[118:121], v[184:187], v[206:209], v[118:121]
	v_mfma_f32_16x16x32_bf16 v[114:117], v[196:199], v[206:209], v[114:117]
	v_mfma_f32_16x16x32_bf16 v[102:105], v[184:187], v[214:217], v[102:105]
	v_mfma_f32_16x16x32_bf16 v[98:101], v[196:199], v[214:217], v[98:101]
	v_mfma_f32_16x16x32_bf16 v[86:89], v[184:187], v[222:225], v[86:89]
	v_mfma_f32_16x16x32_bf16 v[82:85], v[196:199], v[222:225], v[82:85]
	v_mfma_f32_16x16x32_bf16 v[70:73], v[184:187], v[230:233], v[70:73]
	v_mfma_f32_16x16x32_bf16 v[2:5], v[196:199], v[230:233], v[2:5]
	v_mfma_f32_16x16x32_bf16 v[118:121], v[188:191], v[210:213], v[118:121]
	v_mfma_f32_16x16x32_bf16 v[114:117], v[200:203], v[210:213], v[114:117]
	v_mfma_f32_16x16x32_bf16 v[102:105], v[188:191], v[218:221], v[102:105]
	v_mfma_f32_16x16x32_bf16 v[98:101], v[200:203], v[218:221], v[98:101]
	v_mfma_f32_16x16x32_bf16 v[86:89], v[188:191], v[226:229], v[86:89]
	v_mfma_f32_16x16x32_bf16 v[82:85], v[200:203], v[226:229], v[82:85]
	v_mfma_f32_16x16x32_bf16 v[70:73], v[188:191], v[234:237], v[70:73]
	v_mfma_f32_16x16x32_bf16 v[2:5], v[200:203], v[234:237], v[2:5]
	s_setprio 0
	s_barrier
	s_add_u32 s8, s8, 0x100
	s_addc_u32 s9, s9, 0
	s_add_u32 s49, s49, 0x100
	s_addc_u32 s53, s53, 0
	s_cmp_ge_i32 s55, s3
	s_mov_b32 s42, s55
	s_cbranch_scc0 .Lkt_T_12
	s_nop 7
.Lkt_exit_12:
	s_and_b64 vcc, exec, s[20:21]
	s_cbranch_vccz .LBB0_1874
	s_barrier
	v_lshl_or_b32 v162, s40, 8, v141
	s_cmp_lt_i32 s10, 0
	s_mov_b64 s[8:9], -1
	s_cbranch_scc1 .LBB0_1875

.Lkt_L_13:
	ds_read_b128 v[152:155], v162
	ds_read_b128 v[156:159], v162 offset:1024
	ds_read_b128 v[168:171], v162 offset:2048
	ds_read_b128 v[172:175], v162 offset:3072
	ds_read_b128 v[176:179], v163
	ds_read_b128 v[180:183], v163 offset:1024
	ds_read_b128 v[184:187], v163 offset:2048
	ds_read_b128 v[188:191], v163 offset:3072
	s_add_i32 s86, s48, 2
	s_add_u32 s49, s6, 0xfff00080
	s_addc_u32 s64, s7, -1
	s_cmp_eq_u32 s51, s48
	s_cselect_b32 s48, s58, s53
	s_cselect_b32 s65, s57, s64
	s_cselect_b32 s64, s56, s49
	s_cselect_b32 s49, s59, s55
	v_lshl_add_u64 v[192:193], s[6:7], 0, v[140:141]
	s_add_i32 m0, s61, 0xc000
	ds_read_b128 v[196:199], v164
	ds_read_b128 v[200:203], v164 offset:1024
	ds_read_b128 v[206:209], v164 offset:2048
	ds_read_b128 v[210:213], v164 offset:3072
	ds_read_b128 v[214:217], v164 offset:4096
	ds_read_b128 v[218:221], v164 offset:5120
	ds_read_b128 v[222:225], v164 offset:6144
	ds_read_b128 v[226:229], v164 offset:7168
	global_load_lds_dwordx4 v[192:193], off
	v_lshl_add_u64 v[192:193], s[6:7], 0, v[142:143]
	s_add_i32 m0, s61, 0xe000
	s_nop 0
	global_load_lds_dwordx4 v[192:193], off
	s_waitcnt lgkmcnt(0)
	s_barrier
	s_nop 0
	s_setprio 1
	v_mfma_f32_16x16x32_bf16 v[126:129], v[152:155], v[196:199], v[126:129]
	v_mfma_f32_16x16x32_bf16 v[122:125], v[168:171], v[196:199], v[122:125]
	v_mfma_f32_16x16x32_bf16 v[110:113], v[152:155], v[206:209], v[110:113]
	v_mfma_f32_16x16x32_bf16 v[106:109], v[168:171], v[206:209], v[106:109]
	v_mfma_f32_16x16x32_bf16 v[94:97], v[152:155], v[214:217], v[94:97]
	v_mfma_f32_16x16x32_bf16 v[90:93], v[168:171], v[214:217], v[90:93]
	v_mfma_f32_16x16x32_bf16 v[78:81], v[152:155], v[222:225], v[78:81]
	v_mfma_f32_16x16x32_bf16 v[74:77], v[168:171], v[222:225], v[74:77]
	v_mfma_f32_16x16x32_bf16 v[126:129], v[156:159], v[200:203], v[126:129]
	v_mfma_f32_16x16x32_bf16 v[122:125], v[172:175], v[200:203], v[122:125]
	v_mfma_f32_16x16x32_bf16 v[110:113], v[156:159], v[210:213], v[110:113]
	v_mfma_f32_16x16x32_bf16 v[106:109], v[172:175], v[210:213], v[106:109]
	v_mfma_f32_16x16x32_bf16 v[94:97], v[156:159], v[218:221], v[94:97]
	v_mfma_f32_16x16x32_bf16 v[90:93], v[172:175], v[218:221], v[90:93]
	v_mfma_f32_16x16x32_bf16 v[78:81], v[156:159], v[226:229], v[78:81]
	v_mfma_f32_16x16x32_bf16 v[74:77], v[172:175], v[226:229], v[74:77]
	v_mfma_f32_16x16x32_bf16 v[118:121], v[176:179], v[196:199], v[118:121]
	v_mfma_f32_16x16x32_bf16 v[114:117], v[184:187], v[196:199], v[114:117]
	v_mfma_f32_16x16x32_bf16 v[102:105], v[176:179], v[206:209], v[102:105]
	v_mfma_f32_16x16x32_bf16 v[98:101], v[184:187], v[206:209], v[98:101]
	v_mfma_f32_16x16x32_bf16 v[86:89], v[176:179], v[214:217], v[86:89]
	v_mfma_f32_16x16x32_bf16 v[82:85], v[184:187], v[214:217], v[82:85]
	v_mfma_f32_16x16x32_bf16 v[70:73], v[176:179], v[222:225], v[70:73]
	v_mfma_f32_16x16x32_bf16 v[66:69], v[184:187], v[222:225], v[66:69]
	v_mfma_f32_16x16x32_bf16 v[118:121], v[180:183], v[200:203], v[118:121]
	v_mfma_f32_16x16x32_bf16 v[114:117], v[188:191], v[200:203], v[114:117]
	v_mfma_f32_16x16x32_bf16 v[102:105], v[180:183], v[210:213], v[102:105]
	v_mfma_f32_16x16x32_bf16 v[98:101], v[188:191], v[210:213], v[98:101]
	v_mfma_f32_16x16x32_bf16 v[86:89], v[180:183], v[218:221], v[86:89]
	v_mfma_f32_16x16x32_bf16 v[82:85], v[188:191], v[218:221], v[82:85]
	v_mfma_f32_16x16x32_bf16 v[70:73], v[180:183], v[226:229], v[70:73]
	v_mfma_f32_16x16x32_bf16 v[66:69], v[188:191], v[226:229], v[66:69]
	s_setprio 0
	s_waitcnt vmcnt(8)
	s_barrier
	s_add_i32 s87, s75, s66
	v_lshl_add_u64 v[192:193], s[48:49], 0, v[134:135]
	s_mov_b32 m0, s87
	ds_read_b128 v[196:199], v164 offset:16384
	ds_read_b128 v[200:203], v164 offset:17408
	ds_read_b128 v[206:209], v164 offset:18432
	ds_read_b128 v[210:213], v164 offset:19456
	ds_read_b128 v[214:217], v164 offset:20480
	ds_read_b128 v[218:221], v164 offset:21504
	ds_read_b128 v[222:225], v164 offset:22528
	ds_read_b128 v[226:229], v164 offset:23552
	global_load_lds_dwordx4 v[192:193], off
	s_add_i32 m0, s87, 0x2000
	s_add_u32 s88, s48, 0x100000
	v_lshl_add_u64 v[230:231], s[48:49], 0, v[138:139]
	s_addc_u32 s89, s49, 0
	s_add_i32 s87, s76, s66
	global_load_lds_dwordx4 v[230:231], off
	v_lshl_add_u64 v[232:233], s[88:89], 0, v[134:135]
	s_mov_b32 m0, s87
	v_lshl_add_u64 v[234:235], s[64:65], 0, v[136:137]
	global_load_lds_dwordx4 v[232:233], off
	v_lshl_add_u64 v[232:233], s[88:89], 0, v[138:139]
	s_add_i32 m0, s87, 0x2000
	s_nop 0
	global_load_lds_dwordx4 v[232:233], off
	v_lshl_add_u64 v[232:233], s[64:65], 0, v[132:133]
	s_mov_b32 m0, s61
	s_nop 0
	global_load_lds_dwordx4 v[232:233], off
	s_mov_b32 m0, s63
	s_nop 0
	global_load_lds_dwordx4 v[234:235], off
	s_waitcnt lgkmcnt(0)
	s_barrier
	s_setprio 1
	v_mfma_f32_16x16x32_bf16 v[62:65], v[152:155], v[196:199], v[62:65]
	v_mfma_f32_16x16x32_bf16 v[58:61], v[168:171], v[196:199], v[58:61]
	v_mfma_f32_16x16x32_bf16 v[46:49], v[152:155], v[206:209], v[46:49]
	v_mfma_f32_16x16x32_bf16 v[42:45], v[168:171], v[206:209], v[42:45]
	v_mfma_f32_16x16x32_bf16 v[30:33], v[152:155], v[214:217], v[30:33]
	v_mfma_f32_16x16x32_bf16 v[26:29], v[168:171], v[214:217], v[26:29]
	v_mfma_f32_16x16x32_bf16 v[14:17], v[152:155], v[222:225], v[14:17]
	v_mfma_f32_16x16x32_bf16 v[10:13], v[168:171], v[222:225], v[10:13]
	v_mfma_f32_16x16x32_bf16 v[62:65], v[156:159], v[200:203], v[62:65]
	v_mfma_f32_16x16x32_bf16 v[58:61], v[172:175], v[200:203], v[58:61]
	v_mfma_f32_16x16x32_bf16 v[46:49], v[156:159], v[210:213], v[46:49]
	v_mfma_f32_16x16x32_bf16 v[42:45], v[172:175], v[210:213], v[42:45]
	v_mfma_f32_16x16x32_bf16 v[30:33], v[156:159], v[218:221], v[30:33]
	v_mfma_f32_16x16x32_bf16 v[26:29], v[172:175], v[218:221], v[26:29]
	v_mfma_f32_16x16x32_bf16 v[14:17], v[156:159], v[226:229], v[14:17]
	v_mfma_f32_16x16x32_bf16 v[10:13], v[172:175], v[226:229], v[10:13]
	v_mfma_f32_16x16x32_bf16 v[54:57], v[176:179], v[196:199], v[54:57]
	v_mfma_f32_16x16x32_bf16 v[50:53], v[184:187], v[196:199], v[50:53]
	v_mfma_f32_16x16x32_bf16 v[38:41], v[176:179], v[206:209], v[38:41]
	v_mfma_f32_16x16x32_bf16 v[34:37], v[184:187], v[206:209], v[34:37]
	v_mfma_f32_16x16x32_bf16 v[22:25], v[176:179], v[214:217], v[22:25]
	v_mfma_f32_16x16x32_bf16 v[18:21], v[184:187], v[214:217], v[18:21]
	v_mfma_f32_16x16x32_bf16 v[6:9], v[176:179], v[222:225], v[6:9]
	v_mfma_f32_16x16x32_bf16 v[2:5], v[184:187], v[222:225], v[2:5]
	v_mfma_f32_16x16x32_bf16 v[54:57], v[180:183], v[200:203], v[54:57]
	v_mfma_f32_16x16x32_bf16 v[50:53], v[188:191], v[200:203], v[50:53]
	v_mfma_f32_16x16x32_bf16 v[38:41], v[180:183], v[210:213], v[38:41]
	v_mfma_f32_16x16x32_bf16 v[34:37], v[188:191], v[210:213], v[34:37]
	v_mfma_f32_16x16x32_bf16 v[22:25], v[180:183], v[218:221], v[22:25]
	v_mfma_f32_16x16x32_bf16 v[18:21], v[188:191], v[218:221], v[18:21]
	v_mfma_f32_16x16x32_bf16 v[6:9], v[180:183], v[226:229], v[6:9]
	v_mfma_f32_16x16x32_bf16 v[2:5], v[188:191], v[226:229], v[2:5]
	s_setprio 0
	s_waitcnt vmcnt(8)
	s_barrier
	s_add_i32 s87, 0, 0x18000
	v_add_u32_e32 v167, s87, v160
	s_add_i32 s88, 0, 0x1c000
	ds_read_b128 v[152:155], v167
	ds_read_b128 v[156:159], v167 offset:1024
	ds_read_b128 v[168:171], v167 offset:2048
	ds_read_b128 v[172:175], v167 offset:3072
	v_add_u32_e32 v167, s88, v160
	ds_read_b128 v[176:179], v167
	ds_read_b128 v[180:183], v167 offset:1024
	ds_read_b128 v[184:187], v167 offset:2048
	ds_read_b128 v[188:191], v167 offset:3072
	s_add_u32 s64, s64, 0x100000
	s_addc_u32 s65, s65, 0
	s_mov_b32 m0, s67
	v_lshl_add_u64 v[236:237], s[64:65], 0, v[132:133]
	ds_read_b128 v[196:199], v164 offset:32768
	ds_read_b128 v[200:203], v164 offset:33792
	ds_read_b128 v[206:209], v164 offset:34816
	ds_read_b128 v[210:213], v164 offset:35840
	ds_read_b128 v[214:217], v164 offset:36864
	ds_read_b128 v[218:221], v164 offset:37888
	ds_read_b128 v[222:225], v164 offset:38912
	ds_read_b128 v[226:229], v164 offset:39936
	global_load_lds_dwordx4 v[236:237], off
	v_lshl_add_u64 v[236:237], s[64:65], 0, v[136:137]
	s_mov_b32 m0, s68
	s_nop 0
	global_load_lds_dwordx4 v[236:237], off
	s_waitcnt lgkmcnt(0)
	s_barrier
	s_setprio 1
	v_mfma_f32_16x16x32_bf16 v[126:129], v[152:155], v[196:199], v[126:129]
	v_mfma_f32_16x16x32_bf16 v[122:125], v[168:171], v[196:199], v[122:125]
	v_mfma_f32_16x16x32_bf16 v[110:113], v[152:155], v[206:209], v[110:113]
	v_mfma_f32_16x16x32_bf16 v[106:109], v[168:171], v[206:209], v[106:109]
	v_mfma_f32_16x16x32_bf16 v[94:97], v[152:155], v[214:217], v[94:97]
	v_mfma_f32_16x16x32_bf16 v[90:93], v[168:171], v[214:217], v[90:93]
	v_mfma_f32_16x16x32_bf16 v[78:81], v[152:155], v[222:225], v[78:81]
	v_mfma_f32_16x16x32_bf16 v[74:77], v[168:171], v[222:225], v[74:77]
	v_mfma_f32_16x16x32_bf16 v[126:129], v[156:159], v[200:203], v[126:129]
	v_mfma_f32_16x16x32_bf16 v[122:125], v[172:175], v[200:203], v[122:125]
	v_mfma_f32_16x16x32_bf16 v[110:113], v[156:159], v[210:213], v[110:113]
	v_mfma_f32_16x16x32_bf16 v[106:109], v[172:175], v[210:213], v[106:109]
	v_mfma_f32_16x16x32_bf16 v[94:97], v[156:159], v[218:221], v[94:97]
	v_mfma_f32_16x16x32_bf16 v[90:93], v[172:175], v[218:221], v[90:93]
	v_mfma_f32_16x16x32_bf16 v[78:81], v[156:159], v[226:229], v[78:81]
	v_mfma_f32_16x16x32_bf16 v[74:77], v[172:175], v[226:229], v[74:77]
	v_mfma_f32_16x16x32_bf16 v[118:121], v[176:179], v[196:199], v[118:121]
	v_mfma_f32_16x16x32_bf16 v[114:117], v[184:187], v[196:199], v[114:117]
	v_mfma_f32_16x16x32_bf16 v[102:105], v[176:179], v[206:209], v[102:105]
	v_mfma_f32_16x16x32_bf16 v[98:101], v[184:187], v[206:209], v[98:101]
	v_mfma_f32_16x16x32_bf16 v[86:89], v[176:179], v[214:217], v[86:89]
	v_mfma_f32_16x16x32_bf16 v[82:85], v[184:187], v[214:217], v[82:85]
	v_mfma_f32_16x16x32_bf16 v[70:73], v[176:179], v[222:225], v[70:73]
	v_mfma_f32_16x16x32_bf16 v[66:69], v[184:187], v[222:225], v[66:69]
	v_mfma_f32_16x16x32_bf16 v[118:121], v[180:183], v[200:203], v[118:121]
	v_mfma_f32_16x16x32_bf16 v[114:117], v[188:191], v[200:203], v[114:117]
	v_mfma_f32_16x16x32_bf16 v[102:105], v[180:183], v[210:213], v[102:105]
	v_mfma_f32_16x16x32_bf16 v[98:101], v[188:191], v[210:213], v[98:101]
	v_mfma_f32_16x16x32_bf16 v[86:89], v[180:183], v[218:221], v[86:89]
	v_mfma_f32_16x16x32_bf16 v[82:85], v[188:191], v[218:221], v[82:85]
	v_mfma_f32_16x16x32_bf16 v[70:73], v[180:183], v[226:229], v[70:73]
	v_mfma_f32_16x16x32_bf16 v[66:69], v[188:191], v[226:229], v[66:69]
	s_setprio 0
	s_waitcnt vmcnt(8)
	s_barrier
	s_add_i32 s64, s87, s66
	v_lshl_add_u64 v[192:193], v[192:193], 0, s[20:21]
	s_mov_b32 m0, s64
	ds_read_b128 v[196:199], v164 offset:49152
	ds_read_b128 v[200:203], v164 offset:50176
	ds_read_b128 v[206:209], v164 offset:51200
	ds_read_b128 v[210:213], v164 offset:52224
	ds_read_b128 v[214:217], v164 offset:53248
	ds_read_b128 v[218:221], v164 offset:54272
	ds_read_b128 v[222:225], v164 offset:55296
	ds_read_b128 v[226:229], v164 offset:56320
	global_load_lds_dwordx4 v[192:193], off
	s_add_i32 m0, s64, 0x2000
	s_add_u32 s48, s48, 0x100080
	v_lshl_add_u64 v[192:193], v[230:231], 0, s[20:21]
	s_addc_u32 s49, s49, 0
	s_add_i32 s64, s88, s66
	global_load_lds_dwordx4 v[192:193], off
	v_lshl_add_u64 v[192:193], s[48:49], 0, v[134:135]
	s_mov_b32 m0, s64
	s_nop 0
	global_load_lds_dwordx4 v[192:193], off
	v_lshl_add_u64 v[192:193], s[48:49], 0, v[138:139]
	s_add_i32 m0, s64, 0x2000
	s_nop 0
	global_load_lds_dwordx4 v[192:193], off
	v_lshl_add_u64 v[192:193], v[232:233], 0, s[20:21]
	s_mov_b32 m0, s72
	s_nop 0
	global_load_lds_dwordx4 v[192:193], off
	v_lshl_add_u64 v[192:193], v[234:235], 0, s[20:21]
	s_mov_b32 m0, s73
	s_nop 0
	global_load_lds_dwordx4 v[192:193], off
	s_waitcnt lgkmcnt(0)
	s_barrier
	s_nop 0
	s_setprio 1
	v_mfma_f32_16x16x32_bf16 v[62:65], v[152:155], v[196:199], v[62:65]
	v_mfma_f32_16x16x32_bf16 v[58:61], v[168:171], v[196:199], v[58:61]
	v_mfma_f32_16x16x32_bf16 v[46:49], v[152:155], v[206:209], v[46:49]
	v_mfma_f32_16x16x32_bf16 v[42:45], v[168:171], v[206:209], v[42:45]
	v_mfma_f32_16x16x32_bf16 v[30:33], v[152:155], v[214:217], v[30:33]
	v_mfma_f32_16x16x32_bf16 v[26:29], v[168:171], v[214:217], v[26:29]
	v_mfma_f32_16x16x32_bf16 v[14:17], v[152:155], v[222:225], v[14:17]
	v_mfma_f32_16x16x32_bf16 v[10:13], v[168:171], v[222:225], v[10:13]
	v_mfma_f32_16x16x32_bf16 v[62:65], v[156:159], v[200:203], v[62:65]
	v_mfma_f32_16x16x32_bf16 v[58:61], v[172:175], v[200:203], v[58:61]
	v_mfma_f32_16x16x32_bf16 v[46:49], v[156:159], v[210:213], v[46:49]
	v_mfma_f32_16x16x32_bf16 v[42:45], v[172:175], v[210:213], v[42:45]
	v_mfma_f32_16x16x32_bf16 v[30:33], v[156:159], v[218:221], v[30:33]
	v_mfma_f32_16x16x32_bf16 v[26:29], v[172:175], v[218:221], v[26:29]
	v_mfma_f32_16x16x32_bf16 v[14:17], v[156:159], v[226:229], v[14:17]
	v_mfma_f32_16x16x32_bf16 v[10:13], v[172:175], v[226:229], v[10:13]
	v_mfma_f32_16x16x32_bf16 v[54:57], v[176:179], v[196:199], v[54:57]
	v_mfma_f32_16x16x32_bf16 v[50:53], v[184:187], v[196:199], v[50:53]
	v_mfma_f32_16x16x32_bf16 v[38:41], v[176:179], v[206:209], v[38:41]
	v_mfma_f32_16x16x32_bf16 v[34:37], v[184:187], v[206:209], v[34:37]
	v_mfma_f32_16x16x32_bf16 v[22:25], v[176:179], v[214:217], v[22:25]
	v_mfma_f32_16x16x32_bf16 v[18:21], v[184:187], v[214:217], v[18:21]
	v_mfma_f32_16x16x32_bf16 v[6:9], v[176:179], v[222:225], v[6:9]
	v_mfma_f32_16x16x32_bf16 v[2:5], v[184:187], v[222:225], v[2:5]
	v_mfma_f32_16x16x32_bf16 v[54:57], v[180:183], v[200:203], v[54:57]
	v_mfma_f32_16x16x32_bf16 v[50:53], v[188:191], v[200:203], v[50:53]
	v_mfma_f32_16x16x32_bf16 v[38:41], v[180:183], v[210:213], v[38:41]
	v_mfma_f32_16x16x32_bf16 v[34:37], v[188:191], v[210:213], v[34:37]
	v_mfma_f32_16x16x32_bf16 v[22:25], v[180:183], v[218:221], v[22:25]
	v_mfma_f32_16x16x32_bf16 v[18:21], v[188:191], v[218:221], v[18:21]
	v_mfma_f32_16x16x32_bf16 v[6:9], v[180:183], v[226:229], v[6:9]
	v_mfma_f32_16x16x32_bf16 v[2:5], v[188:191], v[226:229], v[2:5]
	s_setprio 0
	s_waitcnt vmcnt(8)
	s_barrier
	s_add_u32 s6, s6, 0x100
	s_addc_u32 s7, s7, 0
	s_add_u32 s53, s53, 0x100
	s_addc_u32 s55, s55, 0
	s_cmp_ge_i32 s86, s85
	s_mov_b32 s48, s86
	s_cbranch_scc0 .Lkt_L_13
	s_branch .Lkt_exit_13
.Lkt_T_13:
	ds_read_b128 v[152:155], v162
	ds_read_b128 v[156:159], v162 offset:1024
	ds_read_b128 v[168:171], v162 offset:2048
	ds_read_b128 v[172:175], v162 offset:3072
	ds_read_b128 v[176:179], v163
	ds_read_b128 v[180:183], v163 offset:1024
	ds_read_b128 v[184:187], v163 offset:2048
	ds_read_b128 v[188:191], v163 offset:3072
	s_add_i32 s86, s48, 2
	s_add_u32 s49, s6, 0xfff00080
	s_addc_u32 s64, s7, -1
	s_cmp_eq_u32 s51, s48
	s_cselect_b32 s48, s58, s53
	s_cselect_b32 s65, s57, s64
	s_cselect_b32 s64, s56, s49
	s_cselect_b32 s49, s59, s55
	v_lshl_add_u64 v[192:193], s[6:7], 0, v[140:141]
	s_add_i32 m0, s61, 0xc000
	ds_read_b128 v[196:199], v164
	ds_read_b128 v[200:203], v164 offset:1024
	ds_read_b128 v[206:209], v164 offset:2048
	ds_read_b128 v[210:213], v164 offset:3072
	ds_read_b128 v[214:217], v164 offset:4096
	ds_read_b128 v[218:221], v164 offset:5120
	ds_read_b128 v[222:225], v164 offset:6144
	ds_read_b128 v[226:229], v164 offset:7168
	global_load_lds_dwordx4 v[192:193], off
	v_lshl_add_u64 v[192:193], s[6:7], 0, v[142:143]
	s_add_i32 m0, s61, 0xe000
	s_nop 0
	global_load_lds_dwordx4 v[192:193], off
	s_nop 0
	s_waitcnt vmcnt(8)
	s_waitcnt lgkmcnt(0)
	s_barrier
	s_setprio 1
	v_mfma_f32_16x16x32_bf16 v[126:129], v[152:155], v[196:199], v[126:129]
	v_mfma_f32_16x16x32_bf16 v[122:125], v[168:171], v[196:199], v[122:125]
	v_mfma_f32_16x16x32_bf16 v[110:113], v[152:155], v[206:209], v[110:113]
	v_mfma_f32_16x16x32_bf16 v[106:109], v[168:171], v[206:209], v[106:109]
	v_mfma_f32_16x16x32_bf16 v[94:97], v[152:155], v[214:217], v[94:97]
	v_mfma_f32_16x16x32_bf16 v[90:93], v[168:171], v[214:217], v[90:93]
	v_mfma_f32_16x16x32_bf16 v[78:81], v[152:155], v[222:225], v[78:81]
	v_mfma_f32_16x16x32_bf16 v[74:77], v[168:171], v[222:225], v[74:77]
	v_mfma_f32_16x16x32_bf16 v[126:129], v[156:159], v[200:203], v[126:129]
	v_mfma_f32_16x16x32_bf16 v[122:125], v[172:175], v[200:203], v[122:125]
	v_mfma_f32_16x16x32_bf16 v[110:113], v[156:159], v[210:213], v[110:113]
	v_mfma_f32_16x16x32_bf16 v[106:109], v[172:175], v[210:213], v[106:109]
	v_mfma_f32_16x16x32_bf16 v[94:97], v[156:159], v[218:221], v[94:97]
	v_mfma_f32_16x16x32_bf16 v[90:93], v[172:175], v[218:221], v[90:93]
	v_mfma_f32_16x16x32_bf16 v[78:81], v[156:159], v[226:229], v[78:81]
	v_mfma_f32_16x16x32_bf16 v[74:77], v[172:175], v[226:229], v[74:77]
	v_mfma_f32_16x16x32_bf16 v[118:121], v[176:179], v[196:199], v[118:121]
	v_mfma_f32_16x16x32_bf16 v[114:117], v[184:187], v[196:199], v[114:117]
	v_mfma_f32_16x16x32_bf16 v[102:105], v[176:179], v[206:209], v[102:105]
	v_mfma_f32_16x16x32_bf16 v[98:101], v[184:187], v[206:209], v[98:101]
	v_mfma_f32_16x16x32_bf16 v[86:89], v[176:179], v[214:217], v[86:89]
	v_mfma_f32_16x16x32_bf16 v[82:85], v[184:187], v[214:217], v[82:85]
	v_mfma_f32_16x16x32_bf16 v[70:73], v[176:179], v[222:225], v[70:73]
	v_mfma_f32_16x16x32_bf16 v[66:69], v[184:187], v[222:225], v[66:69]
	v_mfma_f32_16x16x32_bf16 v[118:121], v[180:183], v[200:203], v[118:121]
	v_mfma_f32_16x16x32_bf16 v[114:117], v[188:191], v[200:203], v[114:117]
	v_mfma_f32_16x16x32_bf16 v[102:105], v[180:183], v[210:213], v[102:105]
	v_mfma_f32_16x16x32_bf16 v[98:101], v[188:191], v[210:213], v[98:101]
	v_mfma_f32_16x16x32_bf16 v[86:89], v[180:183], v[218:221], v[86:89]
	v_mfma_f32_16x16x32_bf16 v[82:85], v[188:191], v[218:221], v[82:85]
	v_mfma_f32_16x16x32_bf16 v[70:73], v[180:183], v[226:229], v[70:73]
	v_mfma_f32_16x16x32_bf16 v[66:69], v[188:191], v[226:229], v[66:69]
	s_setprio 0
	s_barrier
	s_add_i32 s87, s75, s66
	v_lshl_add_u64 v[192:193], s[48:49], 0, v[134:135]
	s_mov_b32 m0, s87
	ds_read_b128 v[196:199], v164 offset:16384
	ds_read_b128 v[200:203], v164 offset:17408
	ds_read_b128 v[206:209], v164 offset:18432
	ds_read_b128 v[210:213], v164 offset:19456
	ds_read_b128 v[214:217], v164 offset:20480
	ds_read_b128 v[218:221], v164 offset:21504
	ds_read_b128 v[222:225], v164 offset:22528
	ds_read_b128 v[226:229], v164 offset:23552
	global_load_lds_dwordx4 v[192:193], off
	s_add_i32 m0, s87, 0x2000
	s_add_u32 s88, s48, 0x100000
	v_lshl_add_u64 v[230:231], s[48:49], 0, v[138:139]
	s_addc_u32 s89, s49, 0
	s_add_i32 s87, s76, s66
	global_load_lds_dwordx4 v[230:231], off
	v_lshl_add_u64 v[232:233], s[88:89], 0, v[134:135]
	s_mov_b32 m0, s87
	v_lshl_add_u64 v[234:235], s[64:65], 0, v[136:137]
	global_load_lds_dwordx4 v[232:233], off
	v_lshl_add_u64 v[232:233], s[88:89], 0, v[138:139]
	s_add_i32 m0, s87, 0x2000
	s_nop 0
	global_load_lds_dwordx4 v[232:233], off
	v_lshl_add_u64 v[232:233], s[64:65], 0, v[132:133]
	s_mov_b32 m0, s61
	s_nop 0
	global_load_lds_dwordx4 v[232:233], off
	s_mov_b32 m0, s63
	s_nop 0
	global_load_lds_dwordx4 v[234:235], off
	s_waitcnt vmcnt(8)
	s_waitcnt lgkmcnt(0)
	s_barrier
	s_setprio 1
	v_mfma_f32_16x16x32_bf16 v[62:65], v[152:155], v[196:199], v[62:65]
	v_mfma_f32_16x16x32_bf16 v[58:61], v[168:171], v[196:199], v[58:61]
	v_mfma_f32_16x16x32_bf16 v[46:49], v[152:155], v[206:209], v[46:49]
	v_mfma_f32_16x16x32_bf16 v[42:45], v[168:171], v[206:209], v[42:45]
	v_mfma_f32_16x16x32_bf16 v[30:33], v[152:155], v[214:217], v[30:33]
	v_mfma_f32_16x16x32_bf16 v[26:29], v[168:171], v[214:217], v[26:29]
	v_mfma_f32_16x16x32_bf16 v[14:17], v[152:155], v[222:225], v[14:17]
	v_mfma_f32_16x16x32_bf16 v[10:13], v[168:171], v[222:225], v[10:13]
	v_mfma_f32_16x16x32_bf16 v[62:65], v[156:159], v[200:203], v[62:65]
	v_mfma_f32_16x16x32_bf16 v[58:61], v[172:175], v[200:203], v[58:61]
	v_mfma_f32_16x16x32_bf16 v[46:49], v[156:159], v[210:213], v[46:49]
	v_mfma_f32_16x16x32_bf16 v[42:45], v[172:175], v[210:213], v[42:45]
	v_mfma_f32_16x16x32_bf16 v[30:33], v[156:159], v[218:221], v[30:33]
	v_mfma_f32_16x16x32_bf16 v[26:29], v[172:175], v[218:221], v[26:29]
	v_mfma_f32_16x16x32_bf16 v[14:17], v[156:159], v[226:229], v[14:17]
	v_mfma_f32_16x16x32_bf16 v[10:13], v[172:175], v[226:229], v[10:13]
	v_mfma_f32_16x16x32_bf16 v[54:57], v[176:179], v[196:199], v[54:57]
	v_mfma_f32_16x16x32_bf16 v[50:53], v[184:187], v[196:199], v[50:53]
	v_mfma_f32_16x16x32_bf16 v[38:41], v[176:179], v[206:209], v[38:41]
	v_mfma_f32_16x16x32_bf16 v[34:37], v[184:187], v[206:209], v[34:37]
	v_mfma_f32_16x16x32_bf16 v[22:25], v[176:179], v[214:217], v[22:25]
	v_mfma_f32_16x16x32_bf16 v[18:21], v[184:187], v[214:217], v[18:21]
	v_mfma_f32_16x16x32_bf16 v[6:9], v[176:179], v[222:225], v[6:9]
	v_mfma_f32_16x16x32_bf16 v[2:5], v[184:187], v[222:225], v[2:5]
	v_mfma_f32_16x16x32_bf16 v[54:57], v[180:183], v[200:203], v[54:57]
	v_mfma_f32_16x16x32_bf16 v[50:53], v[188:191], v[200:203], v[50:53]
	v_mfma_f32_16x16x32_bf16 v[38:41], v[180:183], v[210:213], v[38:41]
	v_mfma_f32_16x16x32_bf16 v[34:37], v[188:191], v[210:213], v[34:37]
	v_mfma_f32_16x16x32_bf16 v[22:25], v[180:183], v[218:221], v[22:25]
	v_mfma_f32_16x16x32_bf16 v[18:21], v[188:191], v[218:221], v[18:21]
	v_mfma_f32_16x16x32_bf16 v[6:9], v[180:183], v[226:229], v[6:9]
	v_mfma_f32_16x16x32_bf16 v[2:5], v[188:191], v[226:229], v[2:5]
	s_setprio 0
	s_barrier
	s_add_i32 s87, 0, 0x18000
	v_add_u32_e32 v167, s87, v160
	s_add_i32 s88, 0, 0x1c000
	ds_read_b128 v[152:155], v167
	ds_read_b128 v[156:159], v167 offset:1024
	ds_read_b128 v[168:171], v167 offset:2048
	ds_read_b128 v[172:175], v167 offset:3072
	v_add_u32_e32 v167, s88, v160
	ds_read_b128 v[176:179], v167
	ds_read_b128 v[180:183], v167 offset:1024
	ds_read_b128 v[184:187], v167 offset:2048
	ds_read_b128 v[188:191], v167 offset:3072
	s_add_u32 s64, s64, 0x100000
	s_addc_u32 s65, s65, 0
	s_mov_b32 m0, s67
	v_lshl_add_u64 v[236:237], s[64:65], 0, v[132:133]
	ds_read_b128 v[196:199], v164 offset:32768
	ds_read_b128 v[200:203], v164 offset:33792
	ds_read_b128 v[206:209], v164 offset:34816
	ds_read_b128 v[210:213], v164 offset:35840
	ds_read_b128 v[214:217], v164 offset:36864
	ds_read_b128 v[218:221], v164 offset:37888
	ds_read_b128 v[222:225], v164 offset:38912
	ds_read_b128 v[226:229], v164 offset:39936
	global_load_lds_dwordx4 v[236:237], off
	v_lshl_add_u64 v[236:237], s[64:65], 0, v[136:137]
	s_mov_b32 m0, s68
	s_nop 0
	global_load_lds_dwordx4 v[236:237], off
	s_waitcnt vmcnt(8)
	s_waitcnt lgkmcnt(0)
	s_barrier
	s_setprio 1
	v_mfma_f32_16x16x32_bf16 v[126:129], v[152:155], v[196:199], v[126:129]
	v_mfma_f32_16x16x32_bf16 v[122:125], v[168:171], v[196:199], v[122:125]
	v_mfma_f32_16x16x32_bf16 v[110:113], v[152:155], v[206:209], v[110:113]
	v_mfma_f32_16x16x32_bf16 v[106:109], v[168:171], v[206:209], v[106:109]
	v_mfma_f32_16x16x32_bf16 v[94:97], v[152:155], v[214:217], v[94:97]
	v_mfma_f32_16x16x32_bf16 v[90:93], v[168:171], v[214:217], v[90:93]
	v_mfma_f32_16x16x32_bf16 v[78:81], v[152:155], v[222:225], v[78:81]
	v_mfma_f32_16x16x32_bf16 v[74:77], v[168:171], v[222:225], v[74:77]
	v_mfma_f32_16x16x32_bf16 v[126:129], v[156:159], v[200:203], v[126:129]
	v_mfma_f32_16x16x32_bf16 v[122:125], v[172:175], v[200:203], v[122:125]
	v_mfma_f32_16x16x32_bf16 v[110:113], v[156:159], v[210:213], v[110:113]
	v_mfma_f32_16x16x32_bf16 v[106:109], v[172:175], v[210:213], v[106:109]
	v_mfma_f32_16x16x32_bf16 v[94:97], v[156:159], v[218:221], v[94:97]
	v_mfma_f32_16x16x32_bf16 v[90:93], v[172:175], v[218:221], v[90:93]
	v_mfma_f32_16x16x32_bf16 v[78:81], v[156:159], v[226:229], v[78:81]
	v_mfma_f32_16x16x32_bf16 v[74:77], v[172:175], v[226:229], v[74:77]
	v_mfma_f32_16x16x32_bf16 v[118:121], v[176:179], v[196:199], v[118:121]
	v_mfma_f32_16x16x32_bf16 v[114:117], v[184:187], v[196:199], v[114:117]
	v_mfma_f32_16x16x32_bf16 v[102:105], v[176:179], v[206:209], v[102:105]
	v_mfma_f32_16x16x32_bf16 v[98:101], v[184:187], v[206:209], v[98:101]
	v_mfma_f32_16x16x32_bf16 v[86:89], v[176:179], v[214:217], v[86:89]
	v_mfma_f32_16x16x32_bf16 v[82:85], v[184:187], v[214:217], v[82:85]
	v_mfma_f32_16x16x32_bf16 v[70:73], v[176:179], v[222:225], v[70:73]
	v_mfma_f32_16x16x32_bf16 v[66:69], v[184:187], v[222:225], v[66:69]
	v_mfma_f32_16x16x32_bf16 v[118:121], v[180:183], v[200:203], v[118:121]
	v_mfma_f32_16x16x32_bf16 v[114:117], v[188:191], v[200:203], v[114:117]
	v_mfma_f32_16x16x32_bf16 v[102:105], v[180:183], v[210:213], v[102:105]
	v_mfma_f32_16x16x32_bf16 v[98:101], v[188:191], v[210:213], v[98:101]
	v_mfma_f32_16x16x32_bf16 v[86:89], v[180:183], v[218:221], v[86:89]
	v_mfma_f32_16x16x32_bf16 v[82:85], v[188:191], v[218:221], v[82:85]
	v_mfma_f32_16x16x32_bf16 v[70:73], v[180:183], v[226:229], v[70:73]
	v_mfma_f32_16x16x32_bf16 v[66:69], v[188:191], v[226:229], v[66:69]
	s_setprio 0
	s_barrier
	s_add_i32 s64, s87, s66
	v_lshl_add_u64 v[192:193], v[192:193], 0, s[20:21]
	s_mov_b32 m0, s64
	ds_read_b128 v[196:199], v164 offset:49152
	ds_read_b128 v[200:203], v164 offset:50176
	ds_read_b128 v[206:209], v164 offset:51200
	ds_read_b128 v[210:213], v164 offset:52224
	ds_read_b128 v[214:217], v164 offset:53248
	ds_read_b128 v[218:221], v164 offset:54272
	ds_read_b128 v[222:225], v164 offset:55296
	ds_read_b128 v[226:229], v164 offset:56320
	global_load_lds_dwordx4 v[192:193], off
	s_add_i32 m0, s64, 0x2000
	s_add_u32 s48, s48, 0x100080
	v_lshl_add_u64 v[192:193], v[230:231], 0, s[20:21]
	s_addc_u32 s49, s49, 0
	s_add_i32 s64, s88, s66
	global_load_lds_dwordx4 v[192:193], off
	v_lshl_add_u64 v[192:193], s[48:49], 0, v[134:135]
	s_mov_b32 m0, s64
	s_nop 0
	global_load_lds_dwordx4 v[192:193], off
	v_lshl_add_u64 v[192:193], s[48:49], 0, v[138:139]
	s_add_i32 m0, s64, 0x2000
	s_nop 0
	global_load_lds_dwordx4 v[192:193], off
	v_lshl_add_u64 v[192:193], v[232:233], 0, s[20:21]
	s_mov_b32 m0, s72
	s_nop 0
	global_load_lds_dwordx4 v[192:193], off
	v_lshl_add_u64 v[192:193], v[234:235], 0, s[20:21]
	s_mov_b32 m0, s73
	s_nop 0
	global_load_lds_dwordx4 v[192:193], off
	s_nop 0
	s_waitcnt vmcnt(8)
	s_waitcnt lgkmcnt(0)
	s_barrier
	s_setprio 1
	v_mfma_f32_16x16x32_bf16 v[62:65], v[152:155], v[196:199], v[62:65]
	v_mfma_f32_16x16x32_bf16 v[58:61], v[168:171], v[196:199], v[58:61]
	v_mfma_f32_16x16x32_bf16 v[46:49], v[152:155], v[206:209], v[46:49]
	v_mfma_f32_16x16x32_bf16 v[42:45], v[168:171], v[206:209], v[42:45]
	v_mfma_f32_16x16x32_bf16 v[30:33], v[152:155], v[214:217], v[30:33]
	v_mfma_f32_16x16x32_bf16 v[26:29], v[168:171], v[214:217], v[26:29]
	v_mfma_f32_16x16x32_bf16 v[14:17], v[152:155], v[222:225], v[14:17]
	v_mfma_f32_16x16x32_bf16 v[10:13], v[168:171], v[222:225], v[10:13]
	v_mfma_f32_16x16x32_bf16 v[62:65], v[156:159], v[200:203], v[62:65]
	v_mfma_f32_16x16x32_bf16 v[58:61], v[172:175], v[200:203], v[58:61]
	v_mfma_f32_16x16x32_bf16 v[46:49], v[156:159], v[210:213], v[46:49]
	v_mfma_f32_16x16x32_bf16 v[42:45], v[172:175], v[210:213], v[42:45]
	v_mfma_f32_16x16x32_bf16 v[30:33], v[156:159], v[218:221], v[30:33]
	v_mfma_f32_16x16x32_bf16 v[26:29], v[172:175], v[218:221], v[26:29]
	v_mfma_f32_16x16x32_bf16 v[14:17], v[156:159], v[226:229], v[14:17]
	v_mfma_f32_16x16x32_bf16 v[10:13], v[172:175], v[226:229], v[10:13]
	v_mfma_f32_16x16x32_bf16 v[54:57], v[176:179], v[196:199], v[54:57]
	v_mfma_f32_16x16x32_bf16 v[50:53], v[184:187], v[196:199], v[50:53]
	v_mfma_f32_16x16x32_bf16 v[38:41], v[176:179], v[206:209], v[38:41]
	v_mfma_f32_16x16x32_bf16 v[34:37], v[184:187], v[206:209], v[34:37]
	v_mfma_f32_16x16x32_bf16 v[22:25], v[176:179], v[214:217], v[22:25]
	v_mfma_f32_16x16x32_bf16 v[18:21], v[184:187], v[214:217], v[18:21]
	v_mfma_f32_16x16x32_bf16 v[6:9], v[176:179], v[222:225], v[6:9]
	v_mfma_f32_16x16x32_bf16 v[2:5], v[184:187], v[222:225], v[2:5]
	v_mfma_f32_16x16x32_bf16 v[54:57], v[180:183], v[200:203], v[54:57]
	v_mfma_f32_16x16x32_bf16 v[50:53], v[188:191], v[200:203], v[50:53]
	v_mfma_f32_16x16x32_bf16 v[38:41], v[180:183], v[210:213], v[38:41]
	v_mfma_f32_16x16x32_bf16 v[34:37], v[188:191], v[210:213], v[34:37]
	v_mfma_f32_16x16x32_bf16 v[22:25], v[180:183], v[218:221], v[22:25]
	v_mfma_f32_16x16x32_bf16 v[18:21], v[188:191], v[218:221], v[18:21]
	v_mfma_f32_16x16x32_bf16 v[6:9], v[180:183], v[226:229], v[6:9]
	v_mfma_f32_16x16x32_bf16 v[2:5], v[188:191], v[226:229], v[2:5]
	s_setprio 0
	s_barrier
	s_add_u32 s6, s6, 0x100
	s_addc_u32 s7, s7, 0
	s_add_u32 s53, s53, 0x100
	s_addc_u32 s55, s55, 0
	s_cmp_ge_i32 s86, s85
	s_mov_b32 s48, s86
	s_cbranch_scc0 .Lkt_T_13
	s_nop 7

.Lkt_L_14:
	ds_read_b128 v[162:165], v145
	ds_read_b128 v[166:169], v145 offset:1024
	ds_read_b128 v[170:173], v145 offset:2048
	ds_read_b128 v[174:177], v145 offset:3072
	ds_read_b128 v[178:181], v160
	ds_read_b128 v[182:185], v160 offset:1024
	ds_read_b128 v[186:189], v160 offset:2048
	ds_read_b128 v[190:193], v160 offset:3072
	s_add_i32 s63, s30, 2
	s_add_u32 s31, s28, 0xfff00080
	s_addc_u32 s34, s29, -1
	s_cmp_eq_u32 s60, s30
	s_cselect_b32 s30, s59, s61
	s_cselect_b32 s35, s19, s34
	s_cselect_b32 s34, s23, s31
	s_cselect_b32 s31, s21, s62
	v_lshl_add_u64 v[158:159], s[28:29], 0, v[148:149]
	s_add_i32 m0, s6, 0xc000
	ds_read_b128 v[196:199], v161
	ds_read_b128 v[200:203], v161 offset:1024
	ds_read_b128 v[206:209], v161 offset:2048
	ds_read_b128 v[210:213], v161 offset:3072
	ds_read_b128 v[214:217], v161 offset:4096
	ds_read_b128 v[218:221], v161 offset:5120
	ds_read_b128 v[222:225], v161 offset:6144
	ds_read_b128 v[226:229], v161 offset:7168
	global_load_lds_dwordx4 v[158:159], off
	v_lshl_add_u64 v[158:159], s[28:29], 0, v[150:151]
	s_add_i32 m0, s6, 0xe000
	s_nop 0
	global_load_lds_dwordx4 v[158:159], off
	s_waitcnt lgkmcnt(0)
	s_barrier
	s_setprio 1
	v_mfma_f32_16x16x32_bf16 v[126:129], v[162:165], v[196:199], v[126:129]
	v_mfma_f32_16x16x32_bf16 v[122:125], v[170:173], v[196:199], v[122:125]
	v_mfma_f32_16x16x32_bf16 v[118:121], v[162:165], v[206:209], v[118:121]
	v_mfma_f32_16x16x32_bf16 v[114:117], v[170:173], v[206:209], v[114:117]
	v_mfma_f32_16x16x32_bf16 v[102:105], v[162:165], v[214:217], v[102:105]
	v_mfma_f32_16x16x32_bf16 v[98:101], v[170:173], v[214:217], v[98:101]
	v_mfma_f32_16x16x32_bf16 v[42:45], v[162:165], v[222:225], v[42:45]
	v_mfma_f32_16x16x32_bf16 v[34:37], v[170:173], v[222:225], v[34:37]
	v_mfma_f32_16x16x32_bf16 v[126:129], v[166:169], v[200:203], v[126:129]
	v_mfma_f32_16x16x32_bf16 v[122:125], v[174:177], v[200:203], v[122:125]
	v_mfma_f32_16x16x32_bf16 v[118:121], v[166:169], v[210:213], v[118:121]
	v_mfma_f32_16x16x32_bf16 v[114:117], v[174:177], v[210:213], v[114:117]
	v_mfma_f32_16x16x32_bf16 v[102:105], v[166:169], v[218:221], v[102:105]
	v_mfma_f32_16x16x32_bf16 v[98:101], v[174:177], v[218:221], v[98:101]
	v_mfma_f32_16x16x32_bf16 v[42:45], v[166:169], v[226:229], v[42:45]
	v_mfma_f32_16x16x32_bf16 v[34:37], v[174:177], v[226:229], v[34:37]
	v_mfma_f32_16x16x32_bf16 v[110:113], v[178:181], v[196:199], v[110:113]
	v_mfma_f32_16x16x32_bf16 v[106:109], v[186:189], v[196:199], v[106:109]
	v_mfma_f32_16x16x32_bf16 v[94:97], v[178:181], v[206:209], v[94:97]
	v_mfma_f32_16x16x32_bf16 v[90:93], v[186:189], v[206:209], v[90:93]
	v_mfma_f32_16x16x32_bf16 v[86:89], v[178:181], v[214:217], v[86:89]
	v_mfma_f32_16x16x32_bf16 v[82:85], v[186:189], v[214:217], v[82:85]
	v_mfma_f32_16x16x32_bf16 v[30:33], v[178:181], v[222:225], v[30:33]
	v_mfma_f32_16x16x32_bf16 v[26:29], v[186:189], v[222:225], v[26:29]
	v_mfma_f32_16x16x32_bf16 v[110:113], v[182:185], v[200:203], v[110:113]
	v_mfma_f32_16x16x32_bf16 v[106:109], v[190:193], v[200:203], v[106:109]
	v_mfma_f32_16x16x32_bf16 v[94:97], v[182:185], v[210:213], v[94:97]
	v_mfma_f32_16x16x32_bf16 v[90:93], v[190:193], v[210:213], v[90:93]
	v_mfma_f32_16x16x32_bf16 v[86:89], v[182:185], v[218:221], v[86:89]
	v_mfma_f32_16x16x32_bf16 v[82:85], v[190:193], v[218:221], v[82:85]
	v_mfma_f32_16x16x32_bf16 v[30:33], v[182:185], v[226:229], v[30:33]
	v_mfma_f32_16x16x32_bf16 v[26:29], v[190:193], v[226:229], v[26:29]
	s_setprio 0
	s_waitcnt vmcnt(8)
	s_barrier
	s_add_i32 s64, s54, s40
	v_lshl_add_u64 v[158:159], s[30:31], 0, v[134:135]
	s_mov_b32 m0, s64
	ds_read_b128 v[196:199], v161 offset:16384
	ds_read_b128 v[200:203], v161 offset:17408
	ds_read_b128 v[206:209], v161 offset:18432
	ds_read_b128 v[210:213], v161 offset:19456
	ds_read_b128 v[214:217], v161 offset:20480
	ds_read_b128 v[218:221], v161 offset:21504
	ds_read_b128 v[222:225], v161 offset:22528
	ds_read_b128 v[226:229], v161 offset:23552
	global_load_lds_dwordx4 v[158:159], off
	s_add_i32 m0, s64, 0x2000
	s_add_u32 s64, s30, 0x100000
	v_lshl_add_u64 v[230:231], s[30:31], 0, v[132:133]
	s_addc_u32 s65, s31, 0
	s_add_i32 s66, s55, s40
	global_load_lds_dwordx4 v[230:231], off
	v_lshl_add_u64 v[232:233], s[64:65], 0, v[134:135]
	s_mov_b32 m0, s66
	v_lshl_add_u64 v[234:235], s[34:35], 0, v[132:133]
	global_load_lds_dwordx4 v[232:233], off
	v_lshl_add_u64 v[232:233], s[64:65], 0, v[132:133]
	s_add_i32 m0, s66, 0x2000
	s_nop 0
	global_load_lds_dwordx4 v[232:233], off
	v_lshl_add_u64 v[232:233], s[34:35], 0, v[134:135]
	s_mov_b32 m0, s6
	s_nop 0
	global_load_lds_dwordx4 v[232:233], off
	s_mov_b32 m0, s13
	s_nop 0
	global_load_lds_dwordx4 v[234:235], off
	s_waitcnt lgkmcnt(0)
	s_barrier
	s_setprio 1
	v_mfma_f32_16x16x32_bf16 v[78:81], v[162:165], v[196:199], v[78:81]
	v_mfma_f32_16x16x32_bf16 v[74:77], v[170:173], v[196:199], v[74:77]
	v_mfma_f32_16x16x32_bf16 v[70:73], v[162:165], v[206:209], v[70:73]
	v_mfma_f32_16x16x32_bf16 v[66:69], v[170:173], v[206:209], v[66:69]
	v_mfma_f32_16x16x32_bf16 v[54:57], v[162:165], v[214:217], v[54:57]
	v_mfma_f32_16x16x32_bf16 v[50:53], v[170:173], v[214:217], v[50:53]
	v_mfma_f32_16x16x32_bf16 v[14:17], v[162:165], v[222:225], v[14:17]
	v_mfma_f32_16x16x32_bf16 v[10:13], v[170:173], v[222:225], v[10:13]
	v_mfma_f32_16x16x32_bf16 v[78:81], v[166:169], v[200:203], v[78:81]
	v_mfma_f32_16x16x32_bf16 v[74:77], v[174:177], v[200:203], v[74:77]
	v_mfma_f32_16x16x32_bf16 v[70:73], v[166:169], v[210:213], v[70:73]
	v_mfma_f32_16x16x32_bf16 v[66:69], v[174:177], v[210:213], v[66:69]
	v_mfma_f32_16x16x32_bf16 v[54:57], v[166:169], v[218:221], v[54:57]
	v_mfma_f32_16x16x32_bf16 v[50:53], v[174:177], v[218:221], v[50:53]
	v_mfma_f32_16x16x32_bf16 v[14:17], v[166:169], v[226:229], v[14:17]
	v_mfma_f32_16x16x32_bf16 v[10:13], v[174:177], v[226:229], v[10:13]
	v_mfma_f32_16x16x32_bf16 v[62:65], v[178:181], v[196:199], v[62:65]
	v_mfma_f32_16x16x32_bf16 v[58:61], v[186:189], v[196:199], v[58:61]
	v_mfma_f32_16x16x32_bf16 v[46:49], v[178:181], v[206:209], v[46:49]
	v_mfma_f32_16x16x32_bf16 v[38:41], v[186:189], v[206:209], v[38:41]
	v_mfma_f32_16x16x32_bf16 v[22:25], v[178:181], v[214:217], v[22:25]
	v_mfma_f32_16x16x32_bf16 v[18:21], v[186:189], v[214:217], v[18:21]
	v_mfma_f32_16x16x32_bf16 v[6:9], v[178:181], v[222:225], v[6:9]
	v_mfma_f32_16x16x32_bf16 v[2:5], v[186:189], v[222:225], v[2:5]
	v_mfma_f32_16x16x32_bf16 v[62:65], v[182:185], v[200:203], v[62:65]
	v_mfma_f32_16x16x32_bf16 v[58:61], v[190:193], v[200:203], v[58:61]
	v_mfma_f32_16x16x32_bf16 v[46:49], v[182:185], v[210:213], v[46:49]
	v_mfma_f32_16x16x32_bf16 v[38:41], v[190:193], v[210:213], v[38:41]
	v_mfma_f32_16x16x32_bf16 v[22:25], v[182:185], v[218:221], v[22:25]
	v_mfma_f32_16x16x32_bf16 v[18:21], v[190:193], v[218:221], v[18:21]
	v_mfma_f32_16x16x32_bf16 v[6:9], v[182:185], v[226:229], v[6:9]
	v_mfma_f32_16x16x32_bf16 v[2:5], v[190:193], v[226:229], v[2:5]
	s_setprio 0
	s_waitcnt vmcnt(8)
	s_barrier
	s_add_i32 s64, 0, 0x18000
	s_add_i32 s65, 0, 0x1c000
	v_add_u32_e32 v174, s64, v131
	v_add_u32_e32 v190, s65, v131
	ds_read_b128 v[162:165], v174
	ds_read_b128 v[166:169], v174 offset:1024
	ds_read_b128 v[170:173], v174 offset:2048
	ds_read_b128 v[174:177], v174 offset:3072
	ds_read_b128 v[178:181], v190
	ds_read_b128 v[182:185], v190 offset:1024
	ds_read_b128 v[186:189], v190 offset:2048
	ds_read_b128 v[190:193], v190 offset:3072
	s_add_u32 s34, s34, 0x100000
	s_addc_u32 s35, s35, 0
	s_mov_b32 m0, s43
	v_lshl_add_u64 v[236:237], s[34:35], 0, v[134:135]
	ds_read_b128 v[196:199], v161 offset:32768
	ds_read_b128 v[200:203], v161 offset:33792
	ds_read_b128 v[206:209], v161 offset:34816
	ds_read_b128 v[210:213], v161 offset:35840
	ds_read_b128 v[214:217], v161 offset:36864
	ds_read_b128 v[218:221], v161 offset:37888
	ds_read_b128 v[222:225], v161 offset:38912
	ds_read_b128 v[226:229], v161 offset:39936
	global_load_lds_dwordx4 v[236:237], off
	v_lshl_add_u64 v[236:237], s[34:35], 0, v[132:133]
	s_mov_b32 m0, s45
	s_nop 0
	global_load_lds_dwordx4 v[236:237], off
	s_waitcnt lgkmcnt(0)
	s_barrier
	s_setprio 1
	v_mfma_f32_16x16x32_bf16 v[126:129], v[162:165], v[196:199], v[126:129]
	v_mfma_f32_16x16x32_bf16 v[122:125], v[170:173], v[196:199], v[122:125]
	v_mfma_f32_16x16x32_bf16 v[118:121], v[162:165], v[206:209], v[118:121]
	v_mfma_f32_16x16x32_bf16 v[114:117], v[170:173], v[206:209], v[114:117]
	v_mfma_f32_16x16x32_bf16 v[102:105], v[162:165], v[214:217], v[102:105]
	v_mfma_f32_16x16x32_bf16 v[98:101], v[170:173], v[214:217], v[98:101]
	v_mfma_f32_16x16x32_bf16 v[42:45], v[162:165], v[222:225], v[42:45]
	v_mfma_f32_16x16x32_bf16 v[34:37], v[170:173], v[222:225], v[34:37]
	v_mfma_f32_16x16x32_bf16 v[126:129], v[166:169], v[200:203], v[126:129]
	v_mfma_f32_16x16x32_bf16 v[122:125], v[174:177], v[200:203], v[122:125]
	v_mfma_f32_16x16x32_bf16 v[118:121], v[166:169], v[210:213], v[118:121]
	v_mfma_f32_16x16x32_bf16 v[114:117], v[174:177], v[210:213], v[114:117]
	v_mfma_f32_16x16x32_bf16 v[102:105], v[166:169], v[218:221], v[102:105]
	v_mfma_f32_16x16x32_bf16 v[98:101], v[174:177], v[218:221], v[98:101]
	v_mfma_f32_16x16x32_bf16 v[42:45], v[166:169], v[226:229], v[42:45]
	v_mfma_f32_16x16x32_bf16 v[34:37], v[174:177], v[226:229], v[34:37]
	v_mfma_f32_16x16x32_bf16 v[110:113], v[178:181], v[196:199], v[110:113]
	v_mfma_f32_16x16x32_bf16 v[106:109], v[186:189], v[196:199], v[106:109]
	v_mfma_f32_16x16x32_bf16 v[94:97], v[178:181], v[206:209], v[94:97]
	v_mfma_f32_16x16x32_bf16 v[90:93], v[186:189], v[206:209], v[90:93]
	v_mfma_f32_16x16x32_bf16 v[86:89], v[178:181], v[214:217], v[86:89]
	v_mfma_f32_16x16x32_bf16 v[82:85], v[186:189], v[214:217], v[82:85]
	v_mfma_f32_16x16x32_bf16 v[30:33], v[178:181], v[222:225], v[30:33]
	v_mfma_f32_16x16x32_bf16 v[26:29], v[186:189], v[222:225], v[26:29]
	v_mfma_f32_16x16x32_bf16 v[110:113], v[182:185], v[200:203], v[110:113]
	v_mfma_f32_16x16x32_bf16 v[106:109], v[190:193], v[200:203], v[106:109]
	v_mfma_f32_16x16x32_bf16 v[94:97], v[182:185], v[210:213], v[94:97]
	v_mfma_f32_16x16x32_bf16 v[90:93], v[190:193], v[210:213], v[90:93]
	v_mfma_f32_16x16x32_bf16 v[86:89], v[182:185], v[218:221], v[86:89]
	v_mfma_f32_16x16x32_bf16 v[82:85], v[190:193], v[218:221], v[82:85]
	v_mfma_f32_16x16x32_bf16 v[30:33], v[182:185], v[226:229], v[30:33]
	v_mfma_f32_16x16x32_bf16 v[26:29], v[190:193], v[226:229], v[26:29]
	s_setprio 0
	s_waitcnt vmcnt(8)
	s_barrier
	s_add_i32 s34, s64, s40
	v_lshl_add_u64 v[158:159], v[158:159], 0, s[10:11]
	s_mov_b32 m0, s34
	ds_read_b128 v[196:199], v161 offset:49152
	ds_read_b128 v[200:203], v161 offset:50176
	ds_read_b128 v[206:209], v161 offset:51200
	ds_read_b128 v[210:213], v161 offset:52224
	ds_read_b128 v[214:217], v161 offset:53248
	ds_read_b128 v[218:221], v161 offset:54272
	ds_read_b128 v[222:225], v161 offset:55296
	ds_read_b128 v[226:229], v161 offset:56320
	global_load_lds_dwordx4 v[158:159], off
	s_add_i32 m0, s34, 0x2000
	s_add_u32 s30, s30, 0x100080
	v_lshl_add_u64 v[158:159], v[230:231], 0, s[10:11]
	s_addc_u32 s31, s31, 0
	s_add_i32 s34, s65, s40
	global_load_lds_dwordx4 v[158:159], off
	v_lshl_add_u64 v[158:159], s[30:31], 0, v[134:135]
	s_mov_b32 m0, s34
	s_nop 0
	global_load_lds_dwordx4 v[158:159], off
	v_lshl_add_u64 v[158:159], s[30:31], 0, v[132:133]
	s_add_i32 m0, s34, 0x2000
	s_nop 0
	global_load_lds_dwordx4 v[158:159], off
	v_lshl_add_u64 v[158:159], v[232:233], 0, s[10:11]
	s_mov_b32 m0, s50
	s_nop 0
	global_load_lds_dwordx4 v[158:159], off
	v_lshl_add_u64 v[158:159], v[234:235], 0, s[10:11]
	s_mov_b32 m0, s51
	s_nop 0
	global_load_lds_dwordx4 v[158:159], off
	s_waitcnt lgkmcnt(0)
	s_barrier
	s_nop 0
	s_setprio 1
	v_mfma_f32_16x16x32_bf16 v[78:81], v[162:165], v[196:199], v[78:81]
	v_mfma_f32_16x16x32_bf16 v[74:77], v[170:173], v[196:199], v[74:77]
	v_mfma_f32_16x16x32_bf16 v[70:73], v[162:165], v[206:209], v[70:73]
	v_mfma_f32_16x16x32_bf16 v[66:69], v[170:173], v[206:209], v[66:69]
	v_mfma_f32_16x16x32_bf16 v[54:57], v[162:165], v[214:217], v[54:57]
	v_mfma_f32_16x16x32_bf16 v[50:53], v[170:173], v[214:217], v[50:53]
	v_mfma_f32_16x16x32_bf16 v[14:17], v[162:165], v[222:225], v[14:17]
	v_mfma_f32_16x16x32_bf16 v[10:13], v[170:173], v[222:225], v[10:13]
	v_mfma_f32_16x16x32_bf16 v[78:81], v[166:169], v[200:203], v[78:81]
	v_mfma_f32_16x16x32_bf16 v[74:77], v[174:177], v[200:203], v[74:77]
	v_mfma_f32_16x16x32_bf16 v[70:73], v[166:169], v[210:213], v[70:73]
	v_mfma_f32_16x16x32_bf16 v[66:69], v[174:177], v[210:213], v[66:69]
	v_mfma_f32_16x16x32_bf16 v[54:57], v[166:169], v[218:221], v[54:57]
	v_mfma_f32_16x16x32_bf16 v[50:53], v[174:177], v[218:221], v[50:53]
	v_mfma_f32_16x16x32_bf16 v[14:17], v[166:169], v[226:229], v[14:17]
	v_mfma_f32_16x16x32_bf16 v[10:13], v[174:177], v[226:229], v[10:13]
	v_mfma_f32_16x16x32_bf16 v[62:65], v[178:181], v[196:199], v[62:65]
	v_mfma_f32_16x16x32_bf16 v[58:61], v[186:189], v[196:199], v[58:61]
	v_mfma_f32_16x16x32_bf16 v[46:49], v[178:181], v[206:209], v[46:49]
	v_mfma_f32_16x16x32_bf16 v[38:41], v[186:189], v[206:209], v[38:41]
	v_mfma_f32_16x16x32_bf16 v[22:25], v[178:181], v[214:217], v[22:25]
	v_mfma_f32_16x16x32_bf16 v[18:21], v[186:189], v[214:217], v[18:21]
	v_mfma_f32_16x16x32_bf16 v[6:9], v[178:181], v[222:225], v[6:9]
	v_mfma_f32_16x16x32_bf16 v[2:5], v[186:189], v[222:225], v[2:5]
	v_mfma_f32_16x16x32_bf16 v[62:65], v[182:185], v[200:203], v[62:65]
	v_mfma_f32_16x16x32_bf16 v[58:61], v[190:193], v[200:203], v[58:61]
	v_mfma_f32_16x16x32_bf16 v[46:49], v[182:185], v[210:213], v[46:49]
	v_mfma_f32_16x16x32_bf16 v[38:41], v[190:193], v[210:213], v[38:41]
	v_mfma_f32_16x16x32_bf16 v[22:25], v[182:185], v[218:221], v[22:25]
	v_mfma_f32_16x16x32_bf16 v[18:21], v[190:193], v[218:221], v[18:21]
	v_mfma_f32_16x16x32_bf16 v[6:9], v[182:185], v[226:229], v[6:9]
	v_mfma_f32_16x16x32_bf16 v[2:5], v[190:193], v[226:229], v[2:5]
	s_setprio 0
	s_waitcnt vmcnt(8)
	s_barrier
	s_add_u32 s28, s28, 0x100
	s_addc_u32 s29, s29, 0
	s_add_u32 s61, s61, 0x100
	s_addc_u32 s62, s62, 0
	s_cmp_ge_i32 s63, s58
	s_mov_b32 s30, s63
	s_cbranch_scc0 .Lkt_L_14
	s_branch .Lkt_exit_14
.Lkt_T_14:
	ds_read_b128 v[162:165], v145
	ds_read_b128 v[166:169], v145 offset:1024
	ds_read_b128 v[170:173], v145 offset:2048
	ds_read_b128 v[174:177], v145 offset:3072
	ds_read_b128 v[178:181], v160
	ds_read_b128 v[182:185], v160 offset:1024
	ds_read_b128 v[186:189], v160 offset:2048
	ds_read_b128 v[190:193], v160 offset:3072
	s_add_i32 s63, s30, 2
	s_add_u32 s31, s28, 0xfff00080
	s_addc_u32 s34, s29, -1
	s_cmp_eq_u32 s60, s30
	s_cselect_b32 s30, s59, s61
	s_cselect_b32 s35, s19, s34
	s_cselect_b32 s34, s23, s31
	s_cselect_b32 s31, s21, s62
	v_lshl_add_u64 v[158:159], s[28:29], 0, v[148:149]
	s_add_i32 m0, s6, 0xc000
	ds_read_b128 v[196:199], v161
	ds_read_b128 v[200:203], v161 offset:1024
	ds_read_b128 v[206:209], v161 offset:2048
	ds_read_b128 v[210:213], v161 offset:3072
	ds_read_b128 v[214:217], v161 offset:4096
	ds_read_b128 v[218:221], v161 offset:5120
	ds_read_b128 v[222:225], v161 offset:6144
	ds_read_b128 v[226:229], v161 offset:7168
	global_load_lds_dwordx4 v[158:159], off
	v_lshl_add_u64 v[158:159], s[28:29], 0, v[150:151]
	s_add_i32 m0, s6, 0xe000
	s_nop 0
	global_load_lds_dwordx4 v[158:159], off
	s_nop 0
	s_waitcnt vmcnt(8)
	s_waitcnt lgkmcnt(0)
	s_barrier
	s_setprio 1
	v_mfma_f32_16x16x32_bf16 v[126:129], v[162:165], v[196:199], v[126:129]
	v_mfma_f32_16x16x32_bf16 v[122:125], v[170:173], v[196:199], v[122:125]
	v_mfma_f32_16x16x32_bf16 v[118:121], v[162:165], v[206:209], v[118:121]
	v_mfma_f32_16x16x32_bf16 v[114:117], v[170:173], v[206:209], v[114:117]
	v_mfma_f32_16x16x32_bf16 v[102:105], v[162:165], v[214:217], v[102:105]
	v_mfma_f32_16x16x32_bf16 v[98:101], v[170:173], v[214:217], v[98:101]
	v_mfma_f32_16x16x32_bf16 v[42:45], v[162:165], v[222:225], v[42:45]
	v_mfma_f32_16x16x32_bf16 v[34:37], v[170:173], v[222:225], v[34:37]
	v_mfma_f32_16x16x32_bf16 v[126:129], v[166:169], v[200:203], v[126:129]
	v_mfma_f32_16x16x32_bf16 v[122:125], v[174:177], v[200:203], v[122:125]
	v_mfma_f32_16x16x32_bf16 v[118:121], v[166:169], v[210:213], v[118:121]
	v_mfma_f32_16x16x32_bf16 v[114:117], v[174:177], v[210:213], v[114:117]
	v_mfma_f32_16x16x32_bf16 v[102:105], v[166:169], v[218:221], v[102:105]
	v_mfma_f32_16x16x32_bf16 v[98:101], v[174:177], v[218:221], v[98:101]
	v_mfma_f32_16x16x32_bf16 v[42:45], v[166:169], v[226:229], v[42:45]
	v_mfma_f32_16x16x32_bf16 v[34:37], v[174:177], v[226:229], v[34:37]
	v_mfma_f32_16x16x32_bf16 v[110:113], v[178:181], v[196:199], v[110:113]
	v_mfma_f32_16x16x32_bf16 v[106:109], v[186:189], v[196:199], v[106:109]
	v_mfma_f32_16x16x32_bf16 v[94:97], v[178:181], v[206:209], v[94:97]
	v_mfma_f32_16x16x32_bf16 v[90:93], v[186:189], v[206:209], v[90:93]
	v_mfma_f32_16x16x32_bf16 v[86:89], v[178:181], v[214:217], v[86:89]
	v_mfma_f32_16x16x32_bf16 v[82:85], v[186:189], v[214:217], v[82:85]
	v_mfma_f32_16x16x32_bf16 v[30:33], v[178:181], v[222:225], v[30:33]
	v_mfma_f32_16x16x32_bf16 v[26:29], v[186:189], v[222:225], v[26:29]
	v_mfma_f32_16x16x32_bf16 v[110:113], v[182:185], v[200:203], v[110:113]
	v_mfma_f32_16x16x32_bf16 v[106:109], v[190:193], v[200:203], v[106:109]
	v_mfma_f32_16x16x32_bf16 v[94:97], v[182:185], v[210:213], v[94:97]
	v_mfma_f32_16x16x32_bf16 v[90:93], v[190:193], v[210:213], v[90:93]
	v_mfma_f32_16x16x32_bf16 v[86:89], v[182:185], v[218:221], v[86:89]
	v_mfma_f32_16x16x32_bf16 v[82:85], v[190:193], v[218:221], v[82:85]
	v_mfma_f32_16x16x32_bf16 v[30:33], v[182:185], v[226:229], v[30:33]
	v_mfma_f32_16x16x32_bf16 v[26:29], v[190:193], v[226:229], v[26:29]
	s_setprio 0
	s_barrier
	s_add_i32 s64, s54, s40
	v_lshl_add_u64 v[158:159], s[30:31], 0, v[134:135]
	s_mov_b32 m0, s64
	ds_read_b128 v[196:199], v161 offset:16384
	ds_read_b128 v[200:203], v161 offset:17408
	ds_read_b128 v[206:209], v161 offset:18432
	ds_read_b128 v[210:213], v161 offset:19456
	ds_read_b128 v[214:217], v161 offset:20480
	ds_read_b128 v[218:221], v161 offset:21504
	ds_read_b128 v[222:225], v161 offset:22528
	ds_read_b128 v[226:229], v161 offset:23552
	global_load_lds_dwordx4 v[158:159], off
	s_add_i32 m0, s64, 0x2000
	s_add_u32 s64, s30, 0x100000
	v_lshl_add_u64 v[230:231], s[30:31], 0, v[132:133]
	s_addc_u32 s65, s31, 0
	s_add_i32 s66, s55, s40
	global_load_lds_dwordx4 v[230:231], off
	v_lshl_add_u64 v[232:233], s[64:65], 0, v[134:135]
	s_mov_b32 m0, s66
	v_lshl_add_u64 v[234:235], s[34:35], 0, v[132:133]
	global_load_lds_dwordx4 v[232:233], off
	v_lshl_add_u64 v[232:233], s[64:65], 0, v[132:133]
	s_add_i32 m0, s66, 0x2000
	s_nop 0
	global_load_lds_dwordx4 v[232:233], off
	v_lshl_add_u64 v[232:233], s[34:35], 0, v[134:135]
	s_mov_b32 m0, s6
	s_nop 0
	global_load_lds_dwordx4 v[232:233], off
	s_mov_b32 m0, s13
	s_nop 0
	global_load_lds_dwordx4 v[234:235], off
	s_waitcnt vmcnt(8)
	s_waitcnt lgkmcnt(0)
	s_barrier
	s_setprio 1
	v_mfma_f32_16x16x32_bf16 v[78:81], v[162:165], v[196:199], v[78:81]
	v_mfma_f32_16x16x32_bf16 v[74:77], v[170:173], v[196:199], v[74:77]
	v_mfma_f32_16x16x32_bf16 v[70:73], v[162:165], v[206:209], v[70:73]
	v_mfma_f32_16x16x32_bf16 v[66:69], v[170:173], v[206:209], v[66:69]
	v_mfma_f32_16x16x32_bf16 v[54:57], v[162:165], v[214:217], v[54:57]
	v_mfma_f32_16x16x32_bf16 v[50:53], v[170:173], v[214:217], v[50:53]
	v_mfma_f32_16x16x32_bf16 v[14:17], v[162:165], v[222:225], v[14:17]
	v_mfma_f32_16x16x32_bf16 v[10:13], v[170:173], v[222:225], v[10:13]
	v_mfma_f32_16x16x32_bf16 v[78:81], v[166:169], v[200:203], v[78:81]
	v_mfma_f32_16x16x32_bf16 v[74:77], v[174:177], v[200:203], v[74:77]
	v_mfma_f32_16x16x32_bf16 v[70:73], v[166:169], v[210:213], v[70:73]
	v_mfma_f32_16x16x32_bf16 v[66:69], v[174:177], v[210:213], v[66:69]
	v_mfma_f32_16x16x32_bf16 v[54:57], v[166:169], v[218:221], v[54:57]
	v_mfma_f32_16x16x32_bf16 v[50:53], v[174:177], v[218:221], v[50:53]
	v_mfma_f32_16x16x32_bf16 v[14:17], v[166:169], v[226:229], v[14:17]
	v_mfma_f32_16x16x32_bf16 v[10:13], v[174:177], v[226:229], v[10:13]
	v_mfma_f32_16x16x32_bf16 v[62:65], v[178:181], v[196:199], v[62:65]
	v_mfma_f32_16x16x32_bf16 v[58:61], v[186:189], v[196:199], v[58:61]
	v_mfma_f32_16x16x32_bf16 v[46:49], v[178:181], v[206:209], v[46:49]
	v_mfma_f32_16x16x32_bf16 v[38:41], v[186:189], v[206:209], v[38:41]
	v_mfma_f32_16x16x32_bf16 v[22:25], v[178:181], v[214:217], v[22:25]
	v_mfma_f32_16x16x32_bf16 v[18:21], v[186:189], v[214:217], v[18:21]
	v_mfma_f32_16x16x32_bf16 v[6:9], v[178:181], v[222:225], v[6:9]
	v_mfma_f32_16x16x32_bf16 v[2:5], v[186:189], v[222:225], v[2:5]
	v_mfma_f32_16x16x32_bf16 v[62:65], v[182:185], v[200:203], v[62:65]
	v_mfma_f32_16x16x32_bf16 v[58:61], v[190:193], v[200:203], v[58:61]
	v_mfma_f32_16x16x32_bf16 v[46:49], v[182:185], v[210:213], v[46:49]
	v_mfma_f32_16x16x32_bf16 v[38:41], v[190:193], v[210:213], v[38:41]
	v_mfma_f32_16x16x32_bf16 v[22:25], v[182:185], v[218:221], v[22:25]
	v_mfma_f32_16x16x32_bf16 v[18:21], v[190:193], v[218:221], v[18:21]
	v_mfma_f32_16x16x32_bf16 v[6:9], v[182:185], v[226:229], v[6:9]
	v_mfma_f32_16x16x32_bf16 v[2:5], v[190:193], v[226:229], v[2:5]
	s_setprio 0
	s_barrier
	s_add_i32 s64, 0, 0x18000
	s_add_i32 s65, 0, 0x1c000
	v_add_u32_e32 v174, s64, v131
	v_add_u32_e32 v190, s65, v131
	ds_read_b128 v[162:165], v174
	ds_read_b128 v[166:169], v174 offset:1024
	ds_read_b128 v[170:173], v174 offset:2048
	ds_read_b128 v[174:177], v174 offset:3072
	ds_read_b128 v[178:181], v190
	ds_read_b128 v[182:185], v190 offset:1024
	ds_read_b128 v[186:189], v190 offset:2048
	ds_read_b128 v[190:193], v190 offset:3072
	s_add_u32 s34, s34, 0x100000
	s_addc_u32 s35, s35, 0
	s_mov_b32 m0, s43
	v_lshl_add_u64 v[236:237], s[34:35], 0, v[134:135]
	ds_read_b128 v[196:199], v161 offset:32768
	ds_read_b128 v[200:203], v161 offset:33792
	ds_read_b128 v[206:209], v161 offset:34816
	ds_read_b128 v[210:213], v161 offset:35840
	ds_read_b128 v[214:217], v161 offset:36864
	ds_read_b128 v[218:221], v161 offset:37888
	ds_read_b128 v[222:225], v161 offset:38912
	ds_read_b128 v[226:229], v161 offset:39936
	global_load_lds_dwordx4 v[236:237], off
	v_lshl_add_u64 v[236:237], s[34:35], 0, v[132:133]
	s_mov_b32 m0, s45
	s_nop 0
	global_load_lds_dwordx4 v[236:237], off
	s_waitcnt vmcnt(8)
	s_waitcnt lgkmcnt(0)
	s_barrier
	s_setprio 1
	v_mfma_f32_16x16x32_bf16 v[126:129], v[162:165], v[196:199], v[126:129]
	v_mfma_f32_16x16x32_bf16 v[122:125], v[170:173], v[196:199], v[122:125]
	v_mfma_f32_16x16x32_bf16 v[118:121], v[162:165], v[206:209], v[118:121]
	v_mfma_f32_16x16x32_bf16 v[114:117], v[170:173], v[206:209], v[114:117]
	v_mfma_f32_16x16x32_bf16 v[102:105], v[162:165], v[214:217], v[102:105]
	v_mfma_f32_16x16x32_bf16 v[98:101], v[170:173], v[214:217], v[98:101]
	v_mfma_f32_16x16x32_bf16 v[42:45], v[162:165], v[222:225], v[42:45]
	v_mfma_f32_16x16x32_bf16 v[34:37], v[170:173], v[222:225], v[34:37]
	v_mfma_f32_16x16x32_bf16 v[126:129], v[166:169], v[200:203], v[126:129]
	v_mfma_f32_16x16x32_bf16 v[122:125], v[174:177], v[200:203], v[122:125]
	v_mfma_f32_16x16x32_bf16 v[118:121], v[166:169], v[210:213], v[118:121]
	v_mfma_f32_16x16x32_bf16 v[114:117], v[174:177], v[210:213], v[114:117]
	v_mfma_f32_16x16x32_bf16 v[102:105], v[166:169], v[218:221], v[102:105]
	v_mfma_f32_16x16x32_bf16 v[98:101], v[174:177], v[218:221], v[98:101]
	v_mfma_f32_16x16x32_bf16 v[42:45], v[166:169], v[226:229], v[42:45]
	v_mfma_f32_16x16x32_bf16 v[34:37], v[174:177], v[226:229], v[34:37]
	v_mfma_f32_16x16x32_bf16 v[110:113], v[178:181], v[196:199], v[110:113]
	v_mfma_f32_16x16x32_bf16 v[106:109], v[186:189], v[196:199], v[106:109]
	v_mfma_f32_16x16x32_bf16 v[94:97], v[178:181], v[206:209], v[94:97]
	v_mfma_f32_16x16x32_bf16 v[90:93], v[186:189], v[206:209], v[90:93]
	v_mfma_f32_16x16x32_bf16 v[86:89], v[178:181], v[214:217], v[86:89]
	v_mfma_f32_16x16x32_bf16 v[82:85], v[186:189], v[214:217], v[82:85]
	v_mfma_f32_16x16x32_bf16 v[30:33], v[178:181], v[222:225], v[30:33]
	v_mfma_f32_16x16x32_bf16 v[26:29], v[186:189], v[222:225], v[26:29]
	v_mfma_f32_16x16x32_bf16 v[110:113], v[182:185], v[200:203], v[110:113]
	v_mfma_f32_16x16x32_bf16 v[106:109], v[190:193], v[200:203], v[106:109]
	v_mfma_f32_16x16x32_bf16 v[94:97], v[182:185], v[210:213], v[94:97]
	v_mfma_f32_16x16x32_bf16 v[90:93], v[190:193], v[210:213], v[90:93]
	v_mfma_f32_16x16x32_bf16 v[86:89], v[182:185], v[218:221], v[86:89]
	v_mfma_f32_16x16x32_bf16 v[82:85], v[190:193], v[218:221], v[82:85]
	v_mfma_f32_16x16x32_bf16 v[30:33], v[182:185], v[226:229], v[30:33]
	v_mfma_f32_16x16x32_bf16 v[26:29], v[190:193], v[226:229], v[26:29]
	s_setprio 0
	s_barrier
	s_add_i32 s34, s64, s40
	v_lshl_add_u64 v[158:159], v[158:159], 0, s[10:11]
	s_mov_b32 m0, s34
	ds_read_b128 v[196:199], v161 offset:49152
	ds_read_b128 v[200:203], v161 offset:50176
	ds_read_b128 v[206:209], v161 offset:51200
	ds_read_b128 v[210:213], v161 offset:52224
	ds_read_b128 v[214:217], v161 offset:53248
	ds_read_b128 v[218:221], v161 offset:54272
	ds_read_b128 v[222:225], v161 offset:55296
	ds_read_b128 v[226:229], v161 offset:56320
	global_load_lds_dwordx4 v[158:159], off
	s_add_i32 m0, s34, 0x2000
	s_add_u32 s30, s30, 0x100080
	v_lshl_add_u64 v[158:159], v[230:231], 0, s[10:11]
	s_addc_u32 s31, s31, 0
	s_add_i32 s34, s65, s40
	global_load_lds_dwordx4 v[158:159], off
	v_lshl_add_u64 v[158:159], s[30:31], 0, v[134:135]
	s_mov_b32 m0, s34
	s_nop 0
	global_load_lds_dwordx4 v[158:159], off
	v_lshl_add_u64 v[158:159], s[30:31], 0, v[132:133]
	s_add_i32 m0, s34, 0x2000
	s_nop 0
	global_load_lds_dwordx4 v[158:159], off
	v_lshl_add_u64 v[158:159], v[232:233], 0, s[10:11]
	s_mov_b32 m0, s50
	s_nop 0
	global_load_lds_dwordx4 v[158:159], off
	v_lshl_add_u64 v[158:159], v[234:235], 0, s[10:11]
	s_mov_b32 m0, s51
	s_nop 0
	global_load_lds_dwordx4 v[158:159], off
	s_nop 0
	s_waitcnt vmcnt(8)
	s_waitcnt lgkmcnt(0)
	s_barrier
	s_setprio 1
	v_mfma_f32_16x16x32_bf16 v[78:81], v[162:165], v[196:199], v[78:81]
	v_mfma_f32_16x16x32_bf16 v[74:77], v[170:173], v[196:199], v[74:77]
	v_mfma_f32_16x16x32_bf16 v[70:73], v[162:165], v[206:209], v[70:73]
	v_mfma_f32_16x16x32_bf16 v[66:69], v[170:173], v[206:209], v[66:69]
	v_mfma_f32_16x16x32_bf16 v[54:57], v[162:165], v[214:217], v[54:57]
	v_mfma_f32_16x16x32_bf16 v[50:53], v[170:173], v[214:217], v[50:53]
	v_mfma_f32_16x16x32_bf16 v[14:17], v[162:165], v[222:225], v[14:17]
	v_mfma_f32_16x16x32_bf16 v[10:13], v[170:173], v[222:225], v[10:13]
	v_mfma_f32_16x16x32_bf16 v[78:81], v[166:169], v[200:203], v[78:81]
	v_mfma_f32_16x16x32_bf16 v[74:77], v[174:177], v[200:203], v[74:77]
	v_mfma_f32_16x16x32_bf16 v[70:73], v[166:169], v[210:213], v[70:73]
	v_mfma_f32_16x16x32_bf16 v[66:69], v[174:177], v[210:213], v[66:69]
	v_mfma_f32_16x16x32_bf16 v[54:57], v[166:169], v[218:221], v[54:57]
	v_mfma_f32_16x16x32_bf16 v[50:53], v[174:177], v[218:221], v[50:53]
	v_mfma_f32_16x16x32_bf16 v[14:17], v[166:169], v[226:229], v[14:17]
	v_mfma_f32_16x16x32_bf16 v[10:13], v[174:177], v[226:229], v[10:13]
	v_mfma_f32_16x16x32_bf16 v[62:65], v[178:181], v[196:199], v[62:65]
	v_mfma_f32_16x16x32_bf16 v[58:61], v[186:189], v[196:199], v[58:61]
	v_mfma_f32_16x16x32_bf16 v[46:49], v[178:181], v[206:209], v[46:49]
	v_mfma_f32_16x16x32_bf16 v[38:41], v[186:189], v[206:209], v[38:41]
	v_mfma_f32_16x16x32_bf16 v[22:25], v[178:181], v[214:217], v[22:25]
	v_mfma_f32_16x16x32_bf16 v[18:21], v[186:189], v[214:217], v[18:21]
	v_mfma_f32_16x16x32_bf16 v[6:9], v[178:181], v[222:225], v[6:9]
	v_mfma_f32_16x16x32_bf16 v[2:5], v[186:189], v[222:225], v[2:5]
	v_mfma_f32_16x16x32_bf16 v[62:65], v[182:185], v[200:203], v[62:65]
	v_mfma_f32_16x16x32_bf16 v[58:61], v[190:193], v[200:203], v[58:61]
	v_mfma_f32_16x16x32_bf16 v[46:49], v[182:185], v[210:213], v[46:49]
	v_mfma_f32_16x16x32_bf16 v[38:41], v[190:193], v[210:213], v[38:41]
	v_mfma_f32_16x16x32_bf16 v[22:25], v[182:185], v[218:221], v[22:25]
	v_mfma_f32_16x16x32_bf16 v[18:21], v[190:193], v[218:221], v[18:21]
	v_mfma_f32_16x16x32_bf16 v[6:9], v[182:185], v[226:229], v[6:9]
	v_mfma_f32_16x16x32_bf16 v[2:5], v[190:193], v[226:229], v[2:5]
	s_setprio 0
	s_barrier
	s_add_u32 s28, s28, 0x100
	s_addc_u32 s29, s29, 0
	s_add_u32 s61, s61, 0x100
	s_addc_u32 s62, s62, 0
	s_cmp_ge_i32 s63, s58
	s_mov_b32 s30, s63
	s_cbranch_scc0 .Lkt_T_14
	s_nop 7

.Lkt_L_15:
	ds_read_b128 v[152:155], v160
	ds_read_b128 v[164:167], v160 offset:1024
	ds_read_b128 v[168:171], v160 offset:2048
	ds_read_b128 v[172:175], v160 offset:3072
	ds_read_b128 v[176:179], v161
	ds_read_b128 v[180:183], v161 offset:1024
	ds_read_b128 v[184:187], v161 offset:2048
	ds_read_b128 v[188:191], v161 offset:3072
	s_add_i32 s80, s48, 2
	s_add_u32 s49, s58, 0xfffe0080
	s_addc_u32 s60, s59, -1
	s_cmp_eq_u32 s43, s48
	s_cselect_b32 s48, s52, s47
	s_cselect_b32 s61, s5, s60
	s_cselect_b32 s60, s4, s49
	s_cselect_b32 s49, s53, s51
	v_lshl_add_u64 v[156:157], s[58:59], 0, v[140:141]
	s_add_i32 m0, s55, 0xc000
	ds_read_b128 v[196:199], v162
	ds_read_b128 v[200:203], v162 offset:1024
	ds_read_b128 v[204:207], v162 offset:2048
	ds_read_b128 v[208:211], v162 offset:3072
	ds_read_b128 v[212:215], v162 offset:4096
	ds_read_b128 v[216:219], v162 offset:5120
	ds_read_b128 v[220:223], v162 offset:6144
	ds_read_b128 v[224:227], v162 offset:7168
	global_load_lds_dwordx4 v[156:157], off
	v_lshl_add_u64 v[156:157], s[58:59], 0, v[142:143]
	s_add_i32 m0, s55, 0xe000
	s_nop 0
	global_load_lds_dwordx4 v[156:157], off
	s_waitcnt lgkmcnt(0)
	s_barrier
	s_setprio 1
	v_mfma_f32_16x16x32_bf16 v[126:129], v[152:155], v[196:199], v[126:129]
	v_mfma_f32_16x16x32_bf16 v[122:125], v[168:171], v[196:199], v[122:125]
	v_mfma_f32_16x16x32_bf16 v[110:113], v[152:155], v[204:207], v[110:113]
	v_mfma_f32_16x16x32_bf16 v[106:109], v[168:171], v[204:207], v[106:109]
	v_mfma_f32_16x16x32_bf16 v[94:97], v[152:155], v[212:215], v[94:97]
	v_mfma_f32_16x16x32_bf16 v[90:93], v[168:171], v[212:215], v[90:93]
	v_mfma_f32_16x16x32_bf16 v[78:81], v[152:155], v[220:223], v[78:81]
	v_mfma_f32_16x16x32_bf16 v[74:77], v[168:171], v[220:223], v[74:77]
	v_mfma_f32_16x16x32_bf16 v[126:129], v[164:167], v[200:203], v[126:129]
	v_mfma_f32_16x16x32_bf16 v[122:125], v[172:175], v[200:203], v[122:125]
	v_mfma_f32_16x16x32_bf16 v[110:113], v[164:167], v[208:211], v[110:113]
	v_mfma_f32_16x16x32_bf16 v[106:109], v[172:175], v[208:211], v[106:109]
	v_mfma_f32_16x16x32_bf16 v[94:97], v[164:167], v[216:219], v[94:97]
	v_mfma_f32_16x16x32_bf16 v[90:93], v[172:175], v[216:219], v[90:93]
	v_mfma_f32_16x16x32_bf16 v[78:81], v[164:167], v[224:227], v[78:81]
	v_mfma_f32_16x16x32_bf16 v[74:77], v[172:175], v[224:227], v[74:77]
	v_mfma_f32_16x16x32_bf16 v[118:121], v[176:179], v[196:199], v[118:121]
	v_mfma_f32_16x16x32_bf16 v[114:117], v[184:187], v[196:199], v[114:117]
	v_mfma_f32_16x16x32_bf16 v[102:105], v[176:179], v[204:207], v[102:105]
	v_mfma_f32_16x16x32_bf16 v[98:101], v[184:187], v[204:207], v[98:101]
	v_mfma_f32_16x16x32_bf16 v[86:89], v[176:179], v[212:215], v[86:89]
	v_mfma_f32_16x16x32_bf16 v[82:85], v[184:187], v[212:215], v[82:85]
	v_mfma_f32_16x16x32_bf16 v[70:73], v[176:179], v[220:223], v[70:73]
	v_mfma_f32_16x16x32_bf16 v[66:69], v[184:187], v[220:223], v[66:69]
	v_mfma_f32_16x16x32_bf16 v[118:121], v[180:183], v[200:203], v[118:121]
	v_mfma_f32_16x16x32_bf16 v[114:117], v[188:191], v[200:203], v[114:117]
	v_mfma_f32_16x16x32_bf16 v[102:105], v[180:183], v[208:211], v[102:105]
	v_mfma_f32_16x16x32_bf16 v[98:101], v[188:191], v[208:211], v[98:101]
	v_mfma_f32_16x16x32_bf16 v[86:89], v[180:183], v[216:219], v[86:89]
	v_mfma_f32_16x16x32_bf16 v[82:85], v[188:191], v[216:219], v[82:85]
	v_mfma_f32_16x16x32_bf16 v[70:73], v[180:183], v[224:227], v[70:73]
	v_mfma_f32_16x16x32_bf16 v[66:69], v[188:191], v[224:227], v[66:69]
	s_setprio 0
	s_waitcnt vmcnt(8)
	s_barrier
	s_add_i32 s81, s71, s62
	v_lshl_add_u64 v[156:157], s[48:49], 0, v[134:135]
	s_mov_b32 m0, s81
	ds_read_b128 v[196:199], v162 offset:16384
	ds_read_b128 v[200:203], v162 offset:17408
	ds_read_b128 v[204:207], v162 offset:18432
	ds_read_b128 v[208:211], v162 offset:19456
	ds_read_b128 v[212:215], v162 offset:20480
	ds_read_b128 v[216:219], v162 offset:21504
	ds_read_b128 v[220:223], v162 offset:22528
	ds_read_b128 v[224:227], v162 offset:23552
	global_load_lds_dwordx4 v[156:157], off
	s_add_i32 m0, s81, 0x2000
	s_add_u32 s82, s48, 0x20000
	v_lshl_add_u64 v[192:193], s[48:49], 0, v[138:139]
	s_addc_u32 s83, s49, 0
	s_add_i32 s81, s72, s62
	global_load_lds_dwordx4 v[192:193], off
	v_lshl_add_u64 v[228:229], s[82:83], 0, v[134:135]
	s_mov_b32 m0, s81
	v_lshl_add_u64 v[230:231], s[60:61], 0, v[136:137]
	global_load_lds_dwordx4 v[228:229], off
	v_lshl_add_u64 v[228:229], s[82:83], 0, v[138:139]
	s_add_i32 m0, s81, 0x2000
	s_nop 0
	global_load_lds_dwordx4 v[228:229], off
	v_lshl_add_u64 v[228:229], s[60:61], 0, v[132:133]
	s_mov_b32 m0, s55
	s_nop 0
	global_load_lds_dwordx4 v[228:229], off
	s_mov_b32 m0, s57
	s_nop 0
	global_load_lds_dwordx4 v[230:231], off
	s_waitcnt lgkmcnt(0)
	s_barrier
	s_setprio 1
	v_mfma_f32_16x16x32_bf16 v[62:65], v[152:155], v[196:199], v[62:65]
	v_mfma_f32_16x16x32_bf16 v[58:61], v[168:171], v[196:199], v[58:61]
	v_mfma_f32_16x16x32_bf16 v[46:49], v[152:155], v[204:207], v[46:49]
	v_mfma_f32_16x16x32_bf16 v[42:45], v[168:171], v[204:207], v[42:45]
	v_mfma_f32_16x16x32_bf16 v[30:33], v[152:155], v[212:215], v[30:33]
	v_mfma_f32_16x16x32_bf16 v[26:29], v[168:171], v[212:215], v[26:29]
	v_mfma_f32_16x16x32_bf16 v[14:17], v[152:155], v[220:223], v[14:17]
	v_mfma_f32_16x16x32_bf16 v[10:13], v[168:171], v[220:223], v[10:13]
	v_mfma_f32_16x16x32_bf16 v[62:65], v[164:167], v[200:203], v[62:65]
	v_mfma_f32_16x16x32_bf16 v[58:61], v[172:175], v[200:203], v[58:61]
	v_mfma_f32_16x16x32_bf16 v[46:49], v[164:167], v[208:211], v[46:49]
	v_mfma_f32_16x16x32_bf16 v[42:45], v[172:175], v[208:211], v[42:45]
	v_mfma_f32_16x16x32_bf16 v[30:33], v[164:167], v[216:219], v[30:33]
	v_mfma_f32_16x16x32_bf16 v[26:29], v[172:175], v[216:219], v[26:29]
	v_mfma_f32_16x16x32_bf16 v[14:17], v[164:167], v[224:227], v[14:17]
	v_mfma_f32_16x16x32_bf16 v[10:13], v[172:175], v[224:227], v[10:13]
	v_mfma_f32_16x16x32_bf16 v[54:57], v[176:179], v[196:199], v[54:57]
	v_mfma_f32_16x16x32_bf16 v[50:53], v[184:187], v[196:199], v[50:53]
	v_mfma_f32_16x16x32_bf16 v[38:41], v[176:179], v[204:207], v[38:41]
	v_mfma_f32_16x16x32_bf16 v[34:37], v[184:187], v[204:207], v[34:37]
	v_mfma_f32_16x16x32_bf16 v[22:25], v[176:179], v[212:215], v[22:25]
	v_mfma_f32_16x16x32_bf16 v[18:21], v[184:187], v[212:215], v[18:21]
	v_mfma_f32_16x16x32_bf16 v[6:9], v[176:179], v[220:223], v[6:9]
	v_mfma_f32_16x16x32_bf16 v[2:5], v[184:187], v[220:223], v[2:5]
	v_mfma_f32_16x16x32_bf16 v[54:57], v[180:183], v[200:203], v[54:57]
	v_mfma_f32_16x16x32_bf16 v[50:53], v[188:191], v[200:203], v[50:53]
	v_mfma_f32_16x16x32_bf16 v[38:41], v[180:183], v[208:211], v[38:41]
	v_mfma_f32_16x16x32_bf16 v[34:37], v[188:191], v[208:211], v[34:37]
	v_mfma_f32_16x16x32_bf16 v[22:25], v[180:183], v[216:219], v[22:25]
	v_mfma_f32_16x16x32_bf16 v[18:21], v[188:191], v[216:219], v[18:21]
	v_mfma_f32_16x16x32_bf16 v[6:9], v[180:183], v[224:227], v[6:9]
	v_mfma_f32_16x16x32_bf16 v[2:5], v[188:191], v[224:227], v[2:5]
	s_setprio 0
	s_waitcnt vmcnt(8)
	s_barrier
	s_add_i32 s81, 0, 0x18000
	v_add_u32_e32 v163, s81, v158
	s_add_i32 s82, 0, 0x1c000
	ds_read_b128 v[152:155], v163
	ds_read_b128 v[164:167], v163 offset:1024
	ds_read_b128 v[168:171], v163 offset:2048
	ds_read_b128 v[172:175], v163 offset:3072
	v_add_u32_e32 v163, s82, v158
	ds_read_b128 v[176:179], v163
	ds_read_b128 v[180:183], v163 offset:1024
	ds_read_b128 v[184:187], v163 offset:2048
	ds_read_b128 v[188:191], v163 offset:3072
	s_add_u32 s60, s60, 0x20000
	s_addc_u32 s61, s61, 0
	s_mov_b32 m0, s63
	v_lshl_add_u64 v[232:233], s[60:61], 0, v[132:133]
	ds_read_b128 v[196:199], v162 offset:32768
	ds_read_b128 v[200:203], v162 offset:33792
	ds_read_b128 v[204:207], v162 offset:34816
	ds_read_b128 v[208:211], v162 offset:35840
	ds_read_b128 v[212:215], v162 offset:36864
	ds_read_b128 v[216:219], v162 offset:37888
	ds_read_b128 v[220:223], v162 offset:38912
	ds_read_b128 v[224:227], v162 offset:39936
	global_load_lds_dwordx4 v[232:233], off
	v_lshl_add_u64 v[232:233], s[60:61], 0, v[136:137]
	s_mov_b32 m0, s64
	s_nop 0
	global_load_lds_dwordx4 v[232:233], off
	s_waitcnt lgkmcnt(0)
	s_barrier
	s_setprio 1
	v_mfma_f32_16x16x32_bf16 v[126:129], v[152:155], v[196:199], v[126:129]
	v_mfma_f32_16x16x32_bf16 v[122:125], v[168:171], v[196:199], v[122:125]
	v_mfma_f32_16x16x32_bf16 v[110:113], v[152:155], v[204:207], v[110:113]
	v_mfma_f32_16x16x32_bf16 v[106:109], v[168:171], v[204:207], v[106:109]
	v_mfma_f32_16x16x32_bf16 v[94:97], v[152:155], v[212:215], v[94:97]
	v_mfma_f32_16x16x32_bf16 v[90:93], v[168:171], v[212:215], v[90:93]
	v_mfma_f32_16x16x32_bf16 v[78:81], v[152:155], v[220:223], v[78:81]
	v_mfma_f32_16x16x32_bf16 v[74:77], v[168:171], v[220:223], v[74:77]
	v_mfma_f32_16x16x32_bf16 v[126:129], v[164:167], v[200:203], v[126:129]
	v_mfma_f32_16x16x32_bf16 v[122:125], v[172:175], v[200:203], v[122:125]
	v_mfma_f32_16x16x32_bf16 v[110:113], v[164:167], v[208:211], v[110:113]
	v_mfma_f32_16x16x32_bf16 v[106:109], v[172:175], v[208:211], v[106:109]
	v_mfma_f32_16x16x32_bf16 v[94:97], v[164:167], v[216:219], v[94:97]
	v_mfma_f32_16x16x32_bf16 v[90:93], v[172:175], v[216:219], v[90:93]
	v_mfma_f32_16x16x32_bf16 v[78:81], v[164:167], v[224:227], v[78:81]
	v_mfma_f32_16x16x32_bf16 v[74:77], v[172:175], v[224:227], v[74:77]
	v_mfma_f32_16x16x32_bf16 v[118:121], v[176:179], v[196:199], v[118:121]
	v_mfma_f32_16x16x32_bf16 v[114:117], v[184:187], v[196:199], v[114:117]
	v_mfma_f32_16x16x32_bf16 v[102:105], v[176:179], v[204:207], v[102:105]
	v_mfma_f32_16x16x32_bf16 v[98:101], v[184:187], v[204:207], v[98:101]
	v_mfma_f32_16x16x32_bf16 v[86:89], v[176:179], v[212:215], v[86:89]
	v_mfma_f32_16x16x32_bf16 v[82:85], v[184:187], v[212:215], v[82:85]
	v_mfma_f32_16x16x32_bf16 v[70:73], v[176:179], v[220:223], v[70:73]
	v_mfma_f32_16x16x32_bf16 v[66:69], v[184:187], v[220:223], v[66:69]
	v_mfma_f32_16x16x32_bf16 v[118:121], v[180:183], v[200:203], v[118:121]
	v_mfma_f32_16x16x32_bf16 v[114:117], v[188:191], v[200:203], v[114:117]
	v_mfma_f32_16x16x32_bf16 v[102:105], v[180:183], v[208:211], v[102:105]
	v_mfma_f32_16x16x32_bf16 v[98:101], v[188:191], v[208:211], v[98:101]
	v_mfma_f32_16x16x32_bf16 v[86:89], v[180:183], v[216:219], v[86:89]
	v_mfma_f32_16x16x32_bf16 v[82:85], v[188:191], v[216:219], v[82:85]
	v_mfma_f32_16x16x32_bf16 v[70:73], v[180:183], v[224:227], v[70:73]
	v_mfma_f32_16x16x32_bf16 v[66:69], v[188:191], v[224:227], v[66:69]
	s_setprio 0
	s_waitcnt vmcnt(8)
	s_barrier
	s_add_i32 s60, s81, s62
	v_lshl_add_u64 v[156:157], v[156:157], 0, s[14:15]
	s_mov_b32 m0, s60
	ds_read_b128 v[196:199], v162 offset:49152
	ds_read_b128 v[200:203], v162 offset:50176
	ds_read_b128 v[204:207], v162 offset:51200
	ds_read_b128 v[208:211], v162 offset:52224
	ds_read_b128 v[212:215], v162 offset:53248
	ds_read_b128 v[216:219], v162 offset:54272
	ds_read_b128 v[220:223], v162 offset:55296
	ds_read_b128 v[224:227], v162 offset:56320
	global_load_lds_dwordx4 v[156:157], off
	s_add_i32 m0, s60, 0x2000
	s_add_u32 s48, s48, 0x20080
	v_lshl_add_u64 v[156:157], v[192:193], 0, s[14:15]
	s_addc_u32 s49, s49, 0
	s_add_i32 s60, s82, s62
	global_load_lds_dwordx4 v[156:157], off
	v_lshl_add_u64 v[156:157], s[48:49], 0, v[134:135]
	s_mov_b32 m0, s60
	s_nop 0
	global_load_lds_dwordx4 v[156:157], off
	v_lshl_add_u64 v[156:157], s[48:49], 0, v[138:139]
	s_add_i32 m0, s60, 0x2000
	s_nop 0
	global_load_lds_dwordx4 v[156:157], off
	v_lshl_add_u64 v[156:157], v[228:229], 0, s[14:15]
	s_mov_b32 m0, s68
	s_nop 0
	global_load_lds_dwordx4 v[156:157], off
	v_lshl_add_u64 v[156:157], v[230:231], 0, s[14:15]
	s_mov_b32 m0, s69
	s_nop 0
	global_load_lds_dwordx4 v[156:157], off
	s_waitcnt lgkmcnt(0)
	s_barrier
	s_nop 0
	s_setprio 1
	v_mfma_f32_16x16x32_bf16 v[62:65], v[152:155], v[196:199], v[62:65]
	v_mfma_f32_16x16x32_bf16 v[58:61], v[168:171], v[196:199], v[58:61]
	v_mfma_f32_16x16x32_bf16 v[46:49], v[152:155], v[204:207], v[46:49]
	v_mfma_f32_16x16x32_bf16 v[42:45], v[168:171], v[204:207], v[42:45]
	v_mfma_f32_16x16x32_bf16 v[30:33], v[152:155], v[212:215], v[30:33]
	v_mfma_f32_16x16x32_bf16 v[26:29], v[168:171], v[212:215], v[26:29]
	v_mfma_f32_16x16x32_bf16 v[14:17], v[152:155], v[220:223], v[14:17]
	v_mfma_f32_16x16x32_bf16 v[10:13], v[168:171], v[220:223], v[10:13]
	v_mfma_f32_16x16x32_bf16 v[62:65], v[164:167], v[200:203], v[62:65]
	v_mfma_f32_16x16x32_bf16 v[58:61], v[172:175], v[200:203], v[58:61]
	v_mfma_f32_16x16x32_bf16 v[46:49], v[164:167], v[208:211], v[46:49]
	v_mfma_f32_16x16x32_bf16 v[42:45], v[172:175], v[208:211], v[42:45]
	v_mfma_f32_16x16x32_bf16 v[30:33], v[164:167], v[216:219], v[30:33]
	v_mfma_f32_16x16x32_bf16 v[26:29], v[172:175], v[216:219], v[26:29]
	v_mfma_f32_16x16x32_bf16 v[14:17], v[164:167], v[224:227], v[14:17]
	v_mfma_f32_16x16x32_bf16 v[10:13], v[172:175], v[224:227], v[10:13]
	v_mfma_f32_16x16x32_bf16 v[54:57], v[176:179], v[196:199], v[54:57]
	v_mfma_f32_16x16x32_bf16 v[50:53], v[184:187], v[196:199], v[50:53]
	v_mfma_f32_16x16x32_bf16 v[38:41], v[176:179], v[204:207], v[38:41]
	v_mfma_f32_16x16x32_bf16 v[34:37], v[184:187], v[204:207], v[34:37]
	v_mfma_f32_16x16x32_bf16 v[22:25], v[176:179], v[212:215], v[22:25]
	v_mfma_f32_16x16x32_bf16 v[18:21], v[184:187], v[212:215], v[18:21]
	v_mfma_f32_16x16x32_bf16 v[6:9], v[176:179], v[220:223], v[6:9]
	v_mfma_f32_16x16x32_bf16 v[2:5], v[184:187], v[220:223], v[2:5]
	v_mfma_f32_16x16x32_bf16 v[54:57], v[180:183], v[200:203], v[54:57]
	v_mfma_f32_16x16x32_bf16 v[50:53], v[188:191], v[200:203], v[50:53]
	v_mfma_f32_16x16x32_bf16 v[38:41], v[180:183], v[208:211], v[38:41]
	v_mfma_f32_16x16x32_bf16 v[34:37], v[188:191], v[208:211], v[34:37]
	v_mfma_f32_16x16x32_bf16 v[22:25], v[180:183], v[216:219], v[22:25]
	v_mfma_f32_16x16x32_bf16 v[18:21], v[188:191], v[216:219], v[18:21]
	v_mfma_f32_16x16x32_bf16 v[6:9], v[180:183], v[224:227], v[6:9]
	v_mfma_f32_16x16x32_bf16 v[2:5], v[188:191], v[224:227], v[2:5]
	s_setprio 0
	s_waitcnt vmcnt(8)
	s_barrier
	s_add_u32 s58, s58, 0x100
	s_addc_u32 s59, s59, 0
	s_add_u32 s47, s47, 0x100
	s_addc_u32 s51, s51, 0
	s_cmp_ge_i32 s80, s79
	s_mov_b32 s48, s80
	s_cbranch_scc0 .Lkt_L_15
	s_branch .Lkt_exit_15
.Lkt_T_15:
	ds_read_b128 v[152:155], v160
	ds_read_b128 v[164:167], v160 offset:1024
	ds_read_b128 v[168:171], v160 offset:2048
	ds_read_b128 v[172:175], v160 offset:3072
	ds_read_b128 v[176:179], v161
	ds_read_b128 v[180:183], v161 offset:1024
	ds_read_b128 v[184:187], v161 offset:2048
	ds_read_b128 v[188:191], v161 offset:3072
	s_add_i32 s80, s48, 2
	s_add_u32 s49, s58, 0xfffe0080
	s_addc_u32 s60, s59, -1
	s_cmp_eq_u32 s43, s48
	s_cselect_b32 s48, s52, s47
	s_cselect_b32 s61, s5, s60
	s_cselect_b32 s60, s4, s49
	s_cselect_b32 s49, s53, s51
	v_lshl_add_u64 v[156:157], s[58:59], 0, v[140:141]
	s_add_i32 m0, s55, 0xc000
	ds_read_b128 v[196:199], v162
	ds_read_b128 v[200:203], v162 offset:1024
	ds_read_b128 v[204:207], v162 offset:2048
	ds_read_b128 v[208:211], v162 offset:3072
	ds_read_b128 v[212:215], v162 offset:4096
	ds_read_b128 v[216:219], v162 offset:5120
	ds_read_b128 v[220:223], v162 offset:6144
	ds_read_b128 v[224:227], v162 offset:7168
	global_load_lds_dwordx4 v[156:157], off
	v_lshl_add_u64 v[156:157], s[58:59], 0, v[142:143]
	s_add_i32 m0, s55, 0xe000
	s_nop 0
	global_load_lds_dwordx4 v[156:157], off
	s_nop 0
	s_waitcnt vmcnt(8)
	s_waitcnt lgkmcnt(0)
	s_barrier
	s_setprio 1
	v_mfma_f32_16x16x32_bf16 v[126:129], v[152:155], v[196:199], v[126:129]
	v_mfma_f32_16x16x32_bf16 v[122:125], v[168:171], v[196:199], v[122:125]
	v_mfma_f32_16x16x32_bf16 v[110:113], v[152:155], v[204:207], v[110:113]
	v_mfma_f32_16x16x32_bf16 v[106:109], v[168:171], v[204:207], v[106:109]
	v_mfma_f32_16x16x32_bf16 v[94:97], v[152:155], v[212:215], v[94:97]
	v_mfma_f32_16x16x32_bf16 v[90:93], v[168:171], v[212:215], v[90:93]
	v_mfma_f32_16x16x32_bf16 v[78:81], v[152:155], v[220:223], v[78:81]
	v_mfma_f32_16x16x32_bf16 v[74:77], v[168:171], v[220:223], v[74:77]
	v_mfma_f32_16x16x32_bf16 v[126:129], v[164:167], v[200:203], v[126:129]
	v_mfma_f32_16x16x32_bf16 v[122:125], v[172:175], v[200:203], v[122:125]
	v_mfma_f32_16x16x32_bf16 v[110:113], v[164:167], v[208:211], v[110:113]
	v_mfma_f32_16x16x32_bf16 v[106:109], v[172:175], v[208:211], v[106:109]
	v_mfma_f32_16x16x32_bf16 v[94:97], v[164:167], v[216:219], v[94:97]
	v_mfma_f32_16x16x32_bf16 v[90:93], v[172:175], v[216:219], v[90:93]
	v_mfma_f32_16x16x32_bf16 v[78:81], v[164:167], v[224:227], v[78:81]
	v_mfma_f32_16x16x32_bf16 v[74:77], v[172:175], v[224:227], v[74:77]
	v_mfma_f32_16x16x32_bf16 v[118:121], v[176:179], v[196:199], v[118:121]
	v_mfma_f32_16x16x32_bf16 v[114:117], v[184:187], v[196:199], v[114:117]
	v_mfma_f32_16x16x32_bf16 v[102:105], v[176:179], v[204:207], v[102:105]
	v_mfma_f32_16x16x32_bf16 v[98:101], v[184:187], v[204:207], v[98:101]
	v_mfma_f32_16x16x32_bf16 v[86:89], v[176:179], v[212:215], v[86:89]
	v_mfma_f32_16x16x32_bf16 v[82:85], v[184:187], v[212:215], v[82:85]
	v_mfma_f32_16x16x32_bf16 v[70:73], v[176:179], v[220:223], v[70:73]
	v_mfma_f32_16x16x32_bf16 v[66:69], v[184:187], v[220:223], v[66:69]
	v_mfma_f32_16x16x32_bf16 v[118:121], v[180:183], v[200:203], v[118:121]
	v_mfma_f32_16x16x32_bf16 v[114:117], v[188:191], v[200:203], v[114:117]
	v_mfma_f32_16x16x32_bf16 v[102:105], v[180:183], v[208:211], v[102:105]
	v_mfma_f32_16x16x32_bf16 v[98:101], v[188:191], v[208:211], v[98:101]
	v_mfma_f32_16x16x32_bf16 v[86:89], v[180:183], v[216:219], v[86:89]
	v_mfma_f32_16x16x32_bf16 v[82:85], v[188:191], v[216:219], v[82:85]
	v_mfma_f32_16x16x32_bf16 v[70:73], v[180:183], v[224:227], v[70:73]
	v_mfma_f32_16x16x32_bf16 v[66:69], v[188:191], v[224:227], v[66:69]
	s_setprio 0
	s_barrier
	s_add_i32 s81, s71, s62
	v_lshl_add_u64 v[156:157], s[48:49], 0, v[134:135]
	s_mov_b32 m0, s81
	ds_read_b128 v[196:199], v162 offset:16384
	ds_read_b128 v[200:203], v162 offset:17408
	ds_read_b128 v[204:207], v162 offset:18432
	ds_read_b128 v[208:211], v162 offset:19456
	ds_read_b128 v[212:215], v162 offset:20480
	ds_read_b128 v[216:219], v162 offset:21504
	ds_read_b128 v[220:223], v162 offset:22528
	ds_read_b128 v[224:227], v162 offset:23552
	global_load_lds_dwordx4 v[156:157], off
	s_add_i32 m0, s81, 0x2000
	s_add_u32 s82, s48, 0x20000
	v_lshl_add_u64 v[192:193], s[48:49], 0, v[138:139]
	s_addc_u32 s83, s49, 0
	s_add_i32 s81, s72, s62
	global_load_lds_dwordx4 v[192:193], off
	v_lshl_add_u64 v[228:229], s[82:83], 0, v[134:135]
	s_mov_b32 m0, s81
	v_lshl_add_u64 v[230:231], s[60:61], 0, v[136:137]
	global_load_lds_dwordx4 v[228:229], off
	v_lshl_add_u64 v[228:229], s[82:83], 0, v[138:139]
	s_add_i32 m0, s81, 0x2000
	s_nop 0
	global_load_lds_dwordx4 v[228:229], off
	v_lshl_add_u64 v[228:229], s[60:61], 0, v[132:133]
	s_mov_b32 m0, s55
	s_nop 0
	global_load_lds_dwordx4 v[228:229], off
	s_mov_b32 m0, s57
	s_nop 0
	global_load_lds_dwordx4 v[230:231], off
	s_waitcnt vmcnt(8)
	s_waitcnt lgkmcnt(0)
	s_barrier
	s_setprio 1
	v_mfma_f32_16x16x32_bf16 v[62:65], v[152:155], v[196:199], v[62:65]
	v_mfma_f32_16x16x32_bf16 v[58:61], v[168:171], v[196:199], v[58:61]
	v_mfma_f32_16x16x32_bf16 v[46:49], v[152:155], v[204:207], v[46:49]
	v_mfma_f32_16x16x32_bf16 v[42:45], v[168:171], v[204:207], v[42:45]
	v_mfma_f32_16x16x32_bf16 v[30:33], v[152:155], v[212:215], v[30:33]
	v_mfma_f32_16x16x32_bf16 v[26:29], v[168:171], v[212:215], v[26:29]
	v_mfma_f32_16x16x32_bf16 v[14:17], v[152:155], v[220:223], v[14:17]
	v_mfma_f32_16x16x32_bf16 v[10:13], v[168:171], v[220:223], v[10:13]
	v_mfma_f32_16x16x32_bf16 v[62:65], v[164:167], v[200:203], v[62:65]
	v_mfma_f32_16x16x32_bf16 v[58:61], v[172:175], v[200:203], v[58:61]
	v_mfma_f32_16x16x32_bf16 v[46:49], v[164:167], v[208:211], v[46:49]
	v_mfma_f32_16x16x32_bf16 v[42:45], v[172:175], v[208:211], v[42:45]
	v_mfma_f32_16x16x32_bf16 v[30:33], v[164:167], v[216:219], v[30:33]
	v_mfma_f32_16x16x32_bf16 v[26:29], v[172:175], v[216:219], v[26:29]
	v_mfma_f32_16x16x32_bf16 v[14:17], v[164:167], v[224:227], v[14:17]
	v_mfma_f32_16x16x32_bf16 v[10:13], v[172:175], v[224:227], v[10:13]
	v_mfma_f32_16x16x32_bf16 v[54:57], v[176:179], v[196:199], v[54:57]
	v_mfma_f32_16x16x32_bf16 v[50:53], v[184:187], v[196:199], v[50:53]
	v_mfma_f32_16x16x32_bf16 v[38:41], v[176:179], v[204:207], v[38:41]
	v_mfma_f32_16x16x32_bf16 v[34:37], v[184:187], v[204:207], v[34:37]
	v_mfma_f32_16x16x32_bf16 v[22:25], v[176:179], v[212:215], v[22:25]
	v_mfma_f32_16x16x32_bf16 v[18:21], v[184:187], v[212:215], v[18:21]
	v_mfma_f32_16x16x32_bf16 v[6:9], v[176:179], v[220:223], v[6:9]
	v_mfma_f32_16x16x32_bf16 v[2:5], v[184:187], v[220:223], v[2:5]
	v_mfma_f32_16x16x32_bf16 v[54:57], v[180:183], v[200:203], v[54:57]
	v_mfma_f32_16x16x32_bf16 v[50:53], v[188:191], v[200:203], v[50:53]
	v_mfma_f32_16x16x32_bf16 v[38:41], v[180:183], v[208:211], v[38:41]
	v_mfma_f32_16x16x32_bf16 v[34:37], v[188:191], v[208:211], v[34:37]
	v_mfma_f32_16x16x32_bf16 v[22:25], v[180:183], v[216:219], v[22:25]
	v_mfma_f32_16x16x32_bf16 v[18:21], v[188:191], v[216:219], v[18:21]
	v_mfma_f32_16x16x32_bf16 v[6:9], v[180:183], v[224:227], v[6:9]
	v_mfma_f32_16x16x32_bf16 v[2:5], v[188:191], v[224:227], v[2:5]
	s_setprio 0
	s_barrier
	s_add_i32 s81, 0, 0x18000
	v_add_u32_e32 v163, s81, v158
	s_add_i32 s82, 0, 0x1c000
	ds_read_b128 v[152:155], v163
	ds_read_b128 v[164:167], v163 offset:1024
	ds_read_b128 v[168:171], v163 offset:2048
	ds_read_b128 v[172:175], v163 offset:3072
	v_add_u32_e32 v163, s82, v158
	ds_read_b128 v[176:179], v163
	ds_read_b128 v[180:183], v163 offset:1024
	ds_read_b128 v[184:187], v163 offset:2048
	ds_read_b128 v[188:191], v163 offset:3072
	s_add_u32 s60, s60, 0x20000
	s_addc_u32 s61, s61, 0
	s_mov_b32 m0, s63
	v_lshl_add_u64 v[232:233], s[60:61], 0, v[132:133]
	ds_read_b128 v[196:199], v162 offset:32768
	ds_read_b128 v[200:203], v162 offset:33792
	ds_read_b128 v[204:207], v162 offset:34816
	ds_read_b128 v[208:211], v162 offset:35840
	ds_read_b128 v[212:215], v162 offset:36864
	ds_read_b128 v[216:219], v162 offset:37888
	ds_read_b128 v[220:223], v162 offset:38912
	ds_read_b128 v[224:227], v162 offset:39936
	global_load_lds_dwordx4 v[232:233], off
	v_lshl_add_u64 v[232:233], s[60:61], 0, v[136:137]
	s_mov_b32 m0, s64
	s_nop 0
	global_load_lds_dwordx4 v[232:233], off
	s_waitcnt vmcnt(8)
	s_waitcnt lgkmcnt(0)
	s_barrier
	s_setprio 1
	v_mfma_f32_16x16x32_bf16 v[126:129], v[152:155], v[196:199], v[126:129]
	v_mfma_f32_16x16x32_bf16 v[122:125], v[168:171], v[196:199], v[122:125]
	v_mfma_f32_16x16x32_bf16 v[110:113], v[152:155], v[204:207], v[110:113]
	v_mfma_f32_16x16x32_bf16 v[106:109], v[168:171], v[204:207], v[106:109]
	v_mfma_f32_16x16x32_bf16 v[94:97], v[152:155], v[212:215], v[94:97]
	v_mfma_f32_16x16x32_bf16 v[90:93], v[168:171], v[212:215], v[90:93]
	v_mfma_f32_16x16x32_bf16 v[78:81], v[152:155], v[220:223], v[78:81]
	v_mfma_f32_16x16x32_bf16 v[74:77], v[168:171], v[220:223], v[74:77]
	v_mfma_f32_16x16x32_bf16 v[126:129], v[164:167], v[200:203], v[126:129]
	v_mfma_f32_16x16x32_bf16 v[122:125], v[172:175], v[200:203], v[122:125]
	v_mfma_f32_16x16x32_bf16 v[110:113], v[164:167], v[208:211], v[110:113]
	v_mfma_f32_16x16x32_bf16 v[106:109], v[172:175], v[208:211], v[106:109]
	v_mfma_f32_16x16x32_bf16 v[94:97], v[164:167], v[216:219], v[94:97]
	v_mfma_f32_16x16x32_bf16 v[90:93], v[172:175], v[216:219], v[90:93]
	v_mfma_f32_16x16x32_bf16 v[78:81], v[164:167], v[224:227], v[78:81]
	v_mfma_f32_16x16x32_bf16 v[74:77], v[172:175], v[224:227], v[74:77]
	v_mfma_f32_16x16x32_bf16 v[118:121], v[176:179], v[196:199], v[118:121]
	v_mfma_f32_16x16x32_bf16 v[114:117], v[184:187], v[196:199], v[114:117]
	v_mfma_f32_16x16x32_bf16 v[102:105], v[176:179], v[204:207], v[102:105]
	v_mfma_f32_16x16x32_bf16 v[98:101], v[184:187], v[204:207], v[98:101]
	v_mfma_f32_16x16x32_bf16 v[86:89], v[176:179], v[212:215], v[86:89]
	v_mfma_f32_16x16x32_bf16 v[82:85], v[184:187], v[212:215], v[82:85]
	v_mfma_f32_16x16x32_bf16 v[70:73], v[176:179], v[220:223], v[70:73]
	v_mfma_f32_16x16x32_bf16 v[66:69], v[184:187], v[220:223], v[66:69]
	v_mfma_f32_16x16x32_bf16 v[118:121], v[180:183], v[200:203], v[118:121]
	v_mfma_f32_16x16x32_bf16 v[114:117], v[188:191], v[200:203], v[114:117]
	v_mfma_f32_16x16x32_bf16 v[102:105], v[180:183], v[208:211], v[102:105]
	v_mfma_f32_16x16x32_bf16 v[98:101], v[188:191], v[208:211], v[98:101]
	v_mfma_f32_16x16x32_bf16 v[86:89], v[180:183], v[216:219], v[86:89]
	v_mfma_f32_16x16x32_bf16 v[82:85], v[188:191], v[216:219], v[82:85]
	v_mfma_f32_16x16x32_bf16 v[70:73], v[180:183], v[224:227], v[70:73]
	v_mfma_f32_16x16x32_bf16 v[66:69], v[188:191], v[224:227], v[66:69]
	s_setprio 0
	s_barrier
	s_add_i32 s60, s81, s62
	v_lshl_add_u64 v[156:157], v[156:157], 0, s[14:15]
	s_mov_b32 m0, s60
	ds_read_b128 v[196:199], v162 offset:49152
	ds_read_b128 v[200:203], v162 offset:50176
	ds_read_b128 v[204:207], v162 offset:51200
	ds_read_b128 v[208:211], v162 offset:52224
	ds_read_b128 v[212:215], v162 offset:53248
	ds_read_b128 v[216:219], v162 offset:54272
	ds_read_b128 v[220:223], v162 offset:55296
	ds_read_b128 v[224:227], v162 offset:56320
	global_load_lds_dwordx4 v[156:157], off
	s_add_i32 m0, s60, 0x2000
	s_add_u32 s48, s48, 0x20080
	v_lshl_add_u64 v[156:157], v[192:193], 0, s[14:15]
	s_addc_u32 s49, s49, 0
	s_add_i32 s60, s82, s62
	global_load_lds_dwordx4 v[156:157], off
	v_lshl_add_u64 v[156:157], s[48:49], 0, v[134:135]
	s_mov_b32 m0, s60
	s_nop 0
	global_load_lds_dwordx4 v[156:157], off
	v_lshl_add_u64 v[156:157], s[48:49], 0, v[138:139]
	s_add_i32 m0, s60, 0x2000
	s_nop 0
	global_load_lds_dwordx4 v[156:157], off
	v_lshl_add_u64 v[156:157], v[228:229], 0, s[14:15]
	s_mov_b32 m0, s68
	s_nop 0
	global_load_lds_dwordx4 v[156:157], off
	v_lshl_add_u64 v[156:157], v[230:231], 0, s[14:15]
	s_mov_b32 m0, s69
	s_nop 0
	global_load_lds_dwordx4 v[156:157], off
	s_nop 0
	s_waitcnt vmcnt(8)
	s_waitcnt lgkmcnt(0)
	s_barrier
	s_setprio 1
	v_mfma_f32_16x16x32_bf16 v[62:65], v[152:155], v[196:199], v[62:65]
	v_mfma_f32_16x16x32_bf16 v[58:61], v[168:171], v[196:199], v[58:61]
	v_mfma_f32_16x16x32_bf16 v[46:49], v[152:155], v[204:207], v[46:49]
	v_mfma_f32_16x16x32_bf16 v[42:45], v[168:171], v[204:207], v[42:45]
	v_mfma_f32_16x16x32_bf16 v[30:33], v[152:155], v[212:215], v[30:33]
	v_mfma_f32_16x16x32_bf16 v[26:29], v[168:171], v[212:215], v[26:29]
	v_mfma_f32_16x16x32_bf16 v[14:17], v[152:155], v[220:223], v[14:17]
	v_mfma_f32_16x16x32_bf16 v[10:13], v[168:171], v[220:223], v[10:13]
	v_mfma_f32_16x16x32_bf16 v[62:65], v[164:167], v[200:203], v[62:65]
	v_mfma_f32_16x16x32_bf16 v[58:61], v[172:175], v[200:203], v[58:61]
	v_mfma_f32_16x16x32_bf16 v[46:49], v[164:167], v[208:211], v[46:49]
	v_mfma_f32_16x16x32_bf16 v[42:45], v[172:175], v[208:211], v[42:45]
	v_mfma_f32_16x16x32_bf16 v[30:33], v[164:167], v[216:219], v[30:33]
	v_mfma_f32_16x16x32_bf16 v[26:29], v[172:175], v[216:219], v[26:29]
	v_mfma_f32_16x16x32_bf16 v[14:17], v[164:167], v[224:227], v[14:17]
	v_mfma_f32_16x16x32_bf16 v[10:13], v[172:175], v[224:227], v[10:13]
	v_mfma_f32_16x16x32_bf16 v[54:57], v[176:179], v[196:199], v[54:57]
	v_mfma_f32_16x16x32_bf16 v[50:53], v[184:187], v[196:199], v[50:53]
	v_mfma_f32_16x16x32_bf16 v[38:41], v[176:179], v[204:207], v[38:41]
	v_mfma_f32_16x16x32_bf16 v[34:37], v[184:187], v[204:207], v[34:37]
	v_mfma_f32_16x16x32_bf16 v[22:25], v[176:179], v[212:215], v[22:25]
	v_mfma_f32_16x16x32_bf16 v[18:21], v[184:187], v[212:215], v[18:21]
	v_mfma_f32_16x16x32_bf16 v[6:9], v[176:179], v[220:223], v[6:9]
	v_mfma_f32_16x16x32_bf16 v[2:5], v[184:187], v[220:223], v[2:5]
	v_mfma_f32_16x16x32_bf16 v[54:57], v[180:183], v[200:203], v[54:57]
	v_mfma_f32_16x16x32_bf16 v[50:53], v[188:191], v[200:203], v[50:53]
	v_mfma_f32_16x16x32_bf16 v[38:41], v[180:183], v[208:211], v[38:41]
	v_mfma_f32_16x16x32_bf16 v[34:37], v[188:191], v[208:211], v[34:37]
	v_mfma_f32_16x16x32_bf16 v[22:25], v[180:183], v[216:219], v[22:25]
	v_mfma_f32_16x16x32_bf16 v[18:21], v[188:191], v[216:219], v[18:21]
	v_mfma_f32_16x16x32_bf16 v[6:9], v[180:183], v[224:227], v[6:9]
	v_mfma_f32_16x16x32_bf16 v[2:5], v[188:191], v[224:227], v[2:5]
	s_setprio 0
	s_barrier
	s_add_u32 s58, s58, 0x100
	s_addc_u32 s59, s59, 0
	s_add_u32 s47, s47, 0x100
	s_addc_u32 s51, s51, 0
	s_cmp_ge_i32 s80, s79
	s_mov_b32 s48, s80
	s_cbranch_scc0 .Lkt_T_15
	s_nop 7

.Lkt_L_16:
	ds_read_b128 v[156:159], v162
	ds_read_b128 v[166:169], v162 offset:1024
	ds_read_b128 v[170:173], v162 offset:2048
	ds_read_b128 v[174:177], v162 offset:3072
	ds_read_b128 v[178:181], v163
	ds_read_b128 v[182:185], v163 offset:1024
	ds_read_b128 v[186:189], v163 offset:2048
	ds_read_b128 v[190:193], v163 offset:3072
	s_add_i32 s72, s42, 2
	s_add_u32 s43, s40, 0xfff00080
	s_addc_u32 s46, s41, -1
	s_cmp_eq_u32 s69, s42
	s_cselect_b32 s42, s25, s70
	s_cselect_b32 s47, s5, s46
	s_cselect_b32 s46, s23, s43
	s_cselect_b32 s43, s21, s71
	v_lshl_add_u64 v[228:229], s[40:41], 0, v[148:149]
	s_add_i32 m0, s35, 0xc000
	ds_read_b128 v[196:199], v164
	ds_read_b128 v[200:203], v164 offset:1024
	ds_read_b128 v[204:207], v164 offset:2048
	ds_read_b128 v[208:211], v164 offset:3072
	ds_read_b128 v[212:215], v164 offset:4096
	ds_read_b128 v[216:219], v164 offset:5120
	ds_read_b128 v[220:223], v164 offset:6144
	ds_read_b128 v[224:227], v164 offset:7168
	global_load_lds_dwordx4 v[228:229], off
	v_lshl_add_u64 v[228:229], s[40:41], 0, v[150:151]
	s_add_i32 m0, s35, 0xe000
	s_nop 0
	global_load_lds_dwordx4 v[228:229], off
	s_waitcnt lgkmcnt(0)
	s_barrier
	s_nop 0
	s_setprio 1
	v_mfma_f32_16x16x32_bf16 v[78:81], v[156:159], v[196:199], v[78:81]
	v_mfma_f32_16x16x32_bf16 v[74:77], v[170:173], v[196:199], v[74:77]
	v_mfma_f32_16x16x32_bf16 v[70:73], v[156:159], v[204:207], v[70:73]
	v_mfma_f32_16x16x32_bf16 v[62:65], v[170:173], v[204:207], v[62:65]
	v_mfma_f32_16x16x32_bf16 v[58:61], v[156:159], v[212:215], v[58:61]
	v_mfma_f32_16x16x32_bf16 v[54:57], v[170:173], v[212:215], v[54:57]
	v_mfma_f32_16x16x32_bf16 v[46:49], v[156:159], v[220:223], v[46:49]
	v_mfma_f32_16x16x32_bf16 v[38:41], v[170:173], v[220:223], v[38:41]
	v_mfma_f32_16x16x32_bf16 v[78:81], v[166:169], v[200:203], v[78:81]
	v_mfma_f32_16x16x32_bf16 v[74:77], v[174:177], v[200:203], v[74:77]
	v_mfma_f32_16x16x32_bf16 v[70:73], v[166:169], v[208:211], v[70:73]
	v_mfma_f32_16x16x32_bf16 v[62:65], v[174:177], v[208:211], v[62:65]
	v_mfma_f32_16x16x32_bf16 v[58:61], v[166:169], v[216:219], v[58:61]
	v_mfma_f32_16x16x32_bf16 v[54:57], v[174:177], v[216:219], v[54:57]
	v_mfma_f32_16x16x32_bf16 v[46:49], v[166:169], v[224:227], v[46:49]
	v_mfma_f32_16x16x32_bf16 v[38:41], v[174:177], v[224:227], v[38:41]
	v_mfma_f32_16x16x32_bf16 v[50:53], v[178:181], v[196:199], v[50:53]
	v_mfma_f32_16x16x32_bf16 v[42:45], v[186:189], v[196:199], v[42:45]
	v_mfma_f32_16x16x32_bf16 v[34:37], v[178:181], v[204:207], v[34:37]
	v_mfma_f32_16x16x32_bf16 v[26:29], v[186:189], v[204:207], v[26:29]
	v_mfma_f32_16x16x32_bf16 v[18:21], v[178:181], v[212:215], v[18:21]
	v_mfma_f32_16x16x32_bf16 v[14:17], v[186:189], v[212:215], v[14:17]
	v_mfma_f32_16x16x32_bf16 v[10:13], v[178:181], v[220:223], v[10:13]
	v_mfma_f32_16x16x32_bf16 v[6:9], v[186:189], v[220:223], v[6:9]
	v_mfma_f32_16x16x32_bf16 v[50:53], v[182:185], v[200:203], v[50:53]
	v_mfma_f32_16x16x32_bf16 v[42:45], v[190:193], v[200:203], v[42:45]
	v_mfma_f32_16x16x32_bf16 v[34:37], v[182:185], v[208:211], v[34:37]
	v_mfma_f32_16x16x32_bf16 v[26:29], v[190:193], v[208:211], v[26:29]
	v_mfma_f32_16x16x32_bf16 v[18:21], v[182:185], v[216:219], v[18:21]
	v_mfma_f32_16x16x32_bf16 v[14:17], v[190:193], v[216:219], v[14:17]
	v_mfma_f32_16x16x32_bf16 v[10:13], v[182:185], v[224:227], v[10:13]
	v_mfma_f32_16x16x32_bf16 v[6:9], v[190:193], v[224:227], v[6:9]
	s_setprio 0
	s_waitcnt vmcnt(8)
	s_barrier
	s_add_i32 s73, s62, s49
	v_lshl_add_u64 v[228:229], s[42:43], 0, v[134:135]
	s_mov_b32 m0, s73
	ds_read_b128 v[196:199], v164 offset:16384
	ds_read_b128 v[200:203], v164 offset:17408
	ds_read_b128 v[204:207], v164 offset:18432
	ds_read_b128 v[208:211], v164 offset:19456
	ds_read_b128 v[212:215], v164 offset:20480
	ds_read_b128 v[216:219], v164 offset:21504
	ds_read_b128 v[220:223], v164 offset:22528
	ds_read_b128 v[224:227], v164 offset:23552
	global_load_lds_dwordx4 v[228:229], off
	s_add_i32 m0, s73, 0x2000
	s_add_u32 s74, s42, 0x100000
	v_lshl_add_u64 v[230:231], s[42:43], 0, v[138:139]
	s_addc_u32 s75, s43, 0
	s_add_i32 s73, s63, s49
	global_load_lds_dwordx4 v[230:231], off
	v_lshl_add_u64 v[232:233], s[74:75], 0, v[134:135]
	s_mov_b32 m0, s73
	v_lshl_add_u64 v[234:235], s[46:47], 0, v[136:137]
	global_load_lds_dwordx4 v[232:233], off
	v_lshl_add_u64 v[232:233], s[74:75], 0, v[138:139]
	s_add_i32 m0, s73, 0x2000
	s_nop 0
	global_load_lds_dwordx4 v[232:233], off
	v_lshl_add_u64 v[232:233], s[46:47], 0, v[132:133]
	s_mov_b32 m0, s35
	s_nop 0
	global_load_lds_dwordx4 v[232:233], off
	s_mov_b32 m0, s50
	s_nop 0
	global_load_lds_dwordx4 v[234:235], off
	s_waitcnt lgkmcnt(0)
	s_barrier
	s_setprio 1
	v_mfma_f32_16x16x32_bf16 v[126:129], v[156:159], v[196:199], v[126:129]
	v_mfma_f32_16x16x32_bf16 v[118:121], v[170:173], v[196:199], v[118:121]
	v_mfma_f32_16x16x32_bf16 v[110:113], v[156:159], v[204:207], v[110:113]
	v_mfma_f32_16x16x32_bf16 v[102:105], v[170:173], v[204:207], v[102:105]
	v_mfma_f32_16x16x32_bf16 v[94:97], v[156:159], v[212:215], v[94:97]
	v_mfma_f32_16x16x32_bf16 v[86:89], v[170:173], v[212:215], v[86:89]
	v_mfma_f32_16x16x32_bf16 v[66:69], v[156:159], v[220:223], v[66:69]
	v_mfma_f32_16x16x32_bf16 v[22:25], v[170:173], v[220:223], v[22:25]
	v_mfma_f32_16x16x32_bf16 v[126:129], v[166:169], v[200:203], v[126:129]
	v_mfma_f32_16x16x32_bf16 v[118:121], v[174:177], v[200:203], v[118:121]
	v_mfma_f32_16x16x32_bf16 v[110:113], v[166:169], v[208:211], v[110:113]
	v_mfma_f32_16x16x32_bf16 v[102:105], v[174:177], v[208:211], v[102:105]
	v_mfma_f32_16x16x32_bf16 v[94:97], v[166:169], v[216:219], v[94:97]
	v_mfma_f32_16x16x32_bf16 v[86:89], v[174:177], v[216:219], v[86:89]
	v_mfma_f32_16x16x32_bf16 v[66:69], v[166:169], v[224:227], v[66:69]
	v_mfma_f32_16x16x32_bf16 v[22:25], v[174:177], v[224:227], v[22:25]
	v_mfma_f32_16x16x32_bf16 v[122:125], v[178:181], v[196:199], v[122:125]
	v_mfma_f32_16x16x32_bf16 v[114:117], v[186:189], v[196:199], v[114:117]
	v_mfma_f32_16x16x32_bf16 v[106:109], v[178:181], v[204:207], v[106:109]
	v_mfma_f32_16x16x32_bf16 v[98:101], v[186:189], v[204:207], v[98:101]
	v_mfma_f32_16x16x32_bf16 v[90:93], v[178:181], v[212:215], v[90:93]
	v_mfma_f32_16x16x32_bf16 v[82:85], v[186:189], v[212:215], v[82:85]
	v_mfma_f32_16x16x32_bf16 v[30:33], v[178:181], v[220:223], v[30:33]
	v_mfma_f32_16x16x32_bf16 v[2:5], v[186:189], v[220:223], v[2:5]
	v_mfma_f32_16x16x32_bf16 v[122:125], v[182:185], v[200:203], v[122:125]
	v_mfma_f32_16x16x32_bf16 v[114:117], v[190:193], v[200:203], v[114:117]
	v_mfma_f32_16x16x32_bf16 v[106:109], v[182:185], v[208:211], v[106:109]
	v_mfma_f32_16x16x32_bf16 v[98:101], v[190:193], v[208:211], v[98:101]
	v_mfma_f32_16x16x32_bf16 v[90:93], v[182:185], v[216:219], v[90:93]
	v_mfma_f32_16x16x32_bf16 v[82:85], v[190:193], v[216:219], v[82:85]
	v_mfma_f32_16x16x32_bf16 v[30:33], v[182:185], v[224:227], v[30:33]
	v_mfma_f32_16x16x32_bf16 v[2:5], v[190:193], v[224:227], v[2:5]
	s_setprio 0
	s_waitcnt vmcnt(8)
	s_barrier
	s_add_i32 s73, 0, 0x18000
	v_add_u32_e32 v165, s73, v160
	s_add_i32 s74, 0, 0x1c000
	ds_read_b128 v[156:159], v165
	ds_read_b128 v[166:169], v165 offset:1024
	ds_read_b128 v[170:173], v165 offset:2048
	ds_read_b128 v[174:177], v165 offset:3072
	v_add_u32_e32 v165, s74, v160
	ds_read_b128 v[178:181], v165
	ds_read_b128 v[182:185], v165 offset:1024
	ds_read_b128 v[186:189], v165 offset:2048
	ds_read_b128 v[190:193], v165 offset:3072
	s_add_u32 s46, s46, 0x100000
	s_addc_u32 s47, s47, 0
	s_mov_b32 m0, s51
	v_lshl_add_u64 v[236:237], s[46:47], 0, v[132:133]
	ds_read_b128 v[196:199], v164 offset:32768
	ds_read_b128 v[200:203], v164 offset:33792
	ds_read_b128 v[204:207], v164 offset:34816
	ds_read_b128 v[208:211], v164 offset:35840
	ds_read_b128 v[212:215], v164 offset:36864
	ds_read_b128 v[216:219], v164 offset:37888
	ds_read_b128 v[220:223], v164 offset:38912
	ds_read_b128 v[224:227], v164 offset:39936
	global_load_lds_dwordx4 v[236:237], off
	v_lshl_add_u64 v[236:237], s[46:47], 0, v[136:137]
	s_mov_b32 m0, s52
	s_nop 0
	global_load_lds_dwordx4 v[236:237], off
	s_waitcnt lgkmcnt(0)
	s_barrier
	s_setprio 1
	v_mfma_f32_16x16x32_bf16 v[78:81], v[156:159], v[196:199], v[78:81]
	v_mfma_f32_16x16x32_bf16 v[74:77], v[170:173], v[196:199], v[74:77]
	v_mfma_f32_16x16x32_bf16 v[70:73], v[156:159], v[204:207], v[70:73]
	v_mfma_f32_16x16x32_bf16 v[62:65], v[170:173], v[204:207], v[62:65]
	v_mfma_f32_16x16x32_bf16 v[58:61], v[156:159], v[212:215], v[58:61]
	v_mfma_f32_16x16x32_bf16 v[54:57], v[170:173], v[212:215], v[54:57]
	v_mfma_f32_16x16x32_bf16 v[46:49], v[156:159], v[220:223], v[46:49]
	v_mfma_f32_16x16x32_bf16 v[38:41], v[170:173], v[220:223], v[38:41]
	v_mfma_f32_16x16x32_bf16 v[78:81], v[166:169], v[200:203], v[78:81]
	v_mfma_f32_16x16x32_bf16 v[74:77], v[174:177], v[200:203], v[74:77]
	v_mfma_f32_16x16x32_bf16 v[70:73], v[166:169], v[208:211], v[70:73]
	v_mfma_f32_16x16x32_bf16 v[62:65], v[174:177], v[208:211], v[62:65]
	v_mfma_f32_16x16x32_bf16 v[58:61], v[166:169], v[216:219], v[58:61]
	v_mfma_f32_16x16x32_bf16 v[54:57], v[174:177], v[216:219], v[54:57]
	v_mfma_f32_16x16x32_bf16 v[46:49], v[166:169], v[224:227], v[46:49]
	v_mfma_f32_16x16x32_bf16 v[38:41], v[174:177], v[224:227], v[38:41]
	v_mfma_f32_16x16x32_bf16 v[50:53], v[178:181], v[196:199], v[50:53]
	v_mfma_f32_16x16x32_bf16 v[42:45], v[186:189], v[196:199], v[42:45]
	v_mfma_f32_16x16x32_bf16 v[34:37], v[178:181], v[204:207], v[34:37]
	v_mfma_f32_16x16x32_bf16 v[26:29], v[186:189], v[204:207], v[26:29]
	v_mfma_f32_16x16x32_bf16 v[18:21], v[178:181], v[212:215], v[18:21]
	v_mfma_f32_16x16x32_bf16 v[14:17], v[186:189], v[212:215], v[14:17]
	v_mfma_f32_16x16x32_bf16 v[10:13], v[178:181], v[220:223], v[10:13]
	v_mfma_f32_16x16x32_bf16 v[6:9], v[186:189], v[220:223], v[6:9]
	v_mfma_f32_16x16x32_bf16 v[50:53], v[182:185], v[200:203], v[50:53]
	v_mfma_f32_16x16x32_bf16 v[42:45], v[190:193], v[200:203], v[42:45]
	v_mfma_f32_16x16x32_bf16 v[34:37], v[182:185], v[208:211], v[34:37]
	v_mfma_f32_16x16x32_bf16 v[26:29], v[190:193], v[208:211], v[26:29]
	v_mfma_f32_16x16x32_bf16 v[18:21], v[182:185], v[216:219], v[18:21]
	v_mfma_f32_16x16x32_bf16 v[14:17], v[190:193], v[216:219], v[14:17]
	v_mfma_f32_16x16x32_bf16 v[10:13], v[182:185], v[224:227], v[10:13]
	v_mfma_f32_16x16x32_bf16 v[6:9], v[190:193], v[224:227], v[6:9]
	s_setprio 0
	s_waitcnt vmcnt(8)
	s_barrier
	s_add_i32 s46, s73, s49
	v_lshl_add_u64 v[228:229], v[228:229], 0, s[10:11]
	s_mov_b32 m0, s46
	ds_read_b128 v[196:199], v164 offset:49152
	ds_read_b128 v[200:203], v164 offset:50176
	ds_read_b128 v[204:207], v164 offset:51200
	ds_read_b128 v[208:211], v164 offset:52224
	ds_read_b128 v[212:215], v164 offset:53248
	ds_read_b128 v[216:219], v164 offset:54272
	ds_read_b128 v[220:223], v164 offset:55296
	ds_read_b128 v[224:227], v164 offset:56320
	global_load_lds_dwordx4 v[228:229], off
	s_add_i32 m0, s46, 0x2000
	s_add_u32 s42, s42, 0x100080
	v_lshl_add_u64 v[228:229], v[230:231], 0, s[10:11]
	s_addc_u32 s43, s43, 0
	s_add_i32 s46, s74, s49
	global_load_lds_dwordx4 v[228:229], off
	v_lshl_add_u64 v[228:229], s[42:43], 0, v[134:135]
	s_mov_b32 m0, s46
	s_nop 0
	global_load_lds_dwordx4 v[228:229], off
	v_lshl_add_u64 v[228:229], s[42:43], 0, v[138:139]
	s_add_i32 m0, s46, 0x2000
	s_nop 0
	global_load_lds_dwordx4 v[228:229], off
	v_lshl_add_u64 v[228:229], v[232:233], 0, s[10:11]
	s_mov_b32 m0, s55
	s_nop 0
	global_load_lds_dwordx4 v[228:229], off
	v_lshl_add_u64 v[228:229], v[234:235], 0, s[10:11]
	s_mov_b32 m0, s56
	s_nop 0
	global_load_lds_dwordx4 v[228:229], off
	s_waitcnt lgkmcnt(0)
	s_barrier
	s_nop 0
	s_setprio 1
	v_mfma_f32_16x16x32_bf16 v[126:129], v[156:159], v[196:199], v[126:129]
	v_mfma_f32_16x16x32_bf16 v[118:121], v[170:173], v[196:199], v[118:121]
	v_mfma_f32_16x16x32_bf16 v[110:113], v[156:159], v[204:207], v[110:113]
	v_mfma_f32_16x16x32_bf16 v[102:105], v[170:173], v[204:207], v[102:105]
	v_mfma_f32_16x16x32_bf16 v[94:97], v[156:159], v[212:215], v[94:97]
	v_mfma_f32_16x16x32_bf16 v[86:89], v[170:173], v[212:215], v[86:89]
	v_mfma_f32_16x16x32_bf16 v[66:69], v[156:159], v[220:223], v[66:69]
	v_mfma_f32_16x16x32_bf16 v[22:25], v[170:173], v[220:223], v[22:25]
	v_mfma_f32_16x16x32_bf16 v[126:129], v[166:169], v[200:203], v[126:129]
	v_mfma_f32_16x16x32_bf16 v[118:121], v[174:177], v[200:203], v[118:121]
	v_mfma_f32_16x16x32_bf16 v[110:113], v[166:169], v[208:211], v[110:113]
	v_mfma_f32_16x16x32_bf16 v[102:105], v[174:177], v[208:211], v[102:105]
	v_mfma_f32_16x16x32_bf16 v[94:97], v[166:169], v[216:219], v[94:97]
	v_mfma_f32_16x16x32_bf16 v[86:89], v[174:177], v[216:219], v[86:89]
	v_mfma_f32_16x16x32_bf16 v[66:69], v[166:169], v[224:227], v[66:69]
	v_mfma_f32_16x16x32_bf16 v[22:25], v[174:177], v[224:227], v[22:25]
	v_mfma_f32_16x16x32_bf16 v[122:125], v[178:181], v[196:199], v[122:125]
	v_mfma_f32_16x16x32_bf16 v[114:117], v[186:189], v[196:199], v[114:117]
	v_mfma_f32_16x16x32_bf16 v[106:109], v[178:181], v[204:207], v[106:109]
	v_mfma_f32_16x16x32_bf16 v[98:101], v[186:189], v[204:207], v[98:101]
	v_mfma_f32_16x16x32_bf16 v[90:93], v[178:181], v[212:215], v[90:93]
	v_mfma_f32_16x16x32_bf16 v[82:85], v[186:189], v[212:215], v[82:85]
	v_mfma_f32_16x16x32_bf16 v[30:33], v[178:181], v[220:223], v[30:33]
	v_mfma_f32_16x16x32_bf16 v[2:5], v[186:189], v[220:223], v[2:5]
	v_mfma_f32_16x16x32_bf16 v[122:125], v[182:185], v[200:203], v[122:125]
	v_mfma_f32_16x16x32_bf16 v[114:117], v[190:193], v[200:203], v[114:117]
	v_mfma_f32_16x16x32_bf16 v[106:109], v[182:185], v[208:211], v[106:109]
	v_mfma_f32_16x16x32_bf16 v[98:101], v[190:193], v[208:211], v[98:101]
	v_mfma_f32_16x16x32_bf16 v[90:93], v[182:185], v[216:219], v[90:93]
	v_mfma_f32_16x16x32_bf16 v[82:85], v[190:193], v[216:219], v[82:85]
	v_mfma_f32_16x16x32_bf16 v[30:33], v[182:185], v[224:227], v[30:33]
	v_mfma_f32_16x16x32_bf16 v[2:5], v[190:193], v[224:227], v[2:5]
	s_setprio 0
	s_waitcnt vmcnt(8)
	s_barrier
	s_add_u32 s40, s40, 0x100
	s_addc_u32 s41, s41, 0
	s_add_u32 s70, s70, 0x100
	s_addc_u32 s71, s71, 0
	s_cmp_ge_i32 s72, s68
	s_mov_b32 s42, s72
	s_cbranch_scc0 .Lkt_L_16
	s_branch .Lkt_exit_16
.Lkt_T_16:
	ds_read_b128 v[156:159], v162
	ds_read_b128 v[166:169], v162 offset:1024
	ds_read_b128 v[170:173], v162 offset:2048
	ds_read_b128 v[174:177], v162 offset:3072
	ds_read_b128 v[178:181], v163
	ds_read_b128 v[182:185], v163 offset:1024
	ds_read_b128 v[186:189], v163 offset:2048
	ds_read_b128 v[190:193], v163 offset:3072
	s_add_i32 s72, s42, 2
	s_add_u32 s43, s40, 0xfff00080
	s_addc_u32 s46, s41, -1
	s_cmp_eq_u32 s69, s42
	s_cselect_b32 s42, s25, s70
	s_cselect_b32 s47, s5, s46
	s_cselect_b32 s46, s23, s43
	s_cselect_b32 s43, s21, s71
	v_lshl_add_u64 v[228:229], s[40:41], 0, v[148:149]
	s_add_i32 m0, s35, 0xc000
	ds_read_b128 v[196:199], v164
	ds_read_b128 v[200:203], v164 offset:1024
	ds_read_b128 v[204:207], v164 offset:2048
	ds_read_b128 v[208:211], v164 offset:3072
	ds_read_b128 v[212:215], v164 offset:4096
	ds_read_b128 v[216:219], v164 offset:5120
	ds_read_b128 v[220:223], v164 offset:6144
	ds_read_b128 v[224:227], v164 offset:7168
	global_load_lds_dwordx4 v[228:229], off
	v_lshl_add_u64 v[228:229], s[40:41], 0, v[150:151]
	s_add_i32 m0, s35, 0xe000
	s_nop 0
	global_load_lds_dwordx4 v[228:229], off
	s_nop 0
	s_waitcnt vmcnt(8)
	s_waitcnt lgkmcnt(0)
	s_barrier
	s_setprio 1
	v_mfma_f32_16x16x32_bf16 v[78:81], v[156:159], v[196:199], v[78:81]
	v_mfma_f32_16x16x32_bf16 v[74:77], v[170:173], v[196:199], v[74:77]
	v_mfma_f32_16x16x32_bf16 v[70:73], v[156:159], v[204:207], v[70:73]
	v_mfma_f32_16x16x32_bf16 v[62:65], v[170:173], v[204:207], v[62:65]
	v_mfma_f32_16x16x32_bf16 v[58:61], v[156:159], v[212:215], v[58:61]
	v_mfma_f32_16x16x32_bf16 v[54:57], v[170:173], v[212:215], v[54:57]
	v_mfma_f32_16x16x32_bf16 v[46:49], v[156:159], v[220:223], v[46:49]
	v_mfma_f32_16x16x32_bf16 v[38:41], v[170:173], v[220:223], v[38:41]
	v_mfma_f32_16x16x32_bf16 v[78:81], v[166:169], v[200:203], v[78:81]
	v_mfma_f32_16x16x32_bf16 v[74:77], v[174:177], v[200:203], v[74:77]
	v_mfma_f32_16x16x32_bf16 v[70:73], v[166:169], v[208:211], v[70:73]
	v_mfma_f32_16x16x32_bf16 v[62:65], v[174:177], v[208:211], v[62:65]
	v_mfma_f32_16x16x32_bf16 v[58:61], v[166:169], v[216:219], v[58:61]
	v_mfma_f32_16x16x32_bf16 v[54:57], v[174:177], v[216:219], v[54:57]
	v_mfma_f32_16x16x32_bf16 v[46:49], v[166:169], v[224:227], v[46:49]
	v_mfma_f32_16x16x32_bf16 v[38:41], v[174:177], v[224:227], v[38:41]
	v_mfma_f32_16x16x32_bf16 v[50:53], v[178:181], v[196:199], v[50:53]
	v_mfma_f32_16x16x32_bf16 v[42:45], v[186:189], v[196:199], v[42:45]
	v_mfma_f32_16x16x32_bf16 v[34:37], v[178:181], v[204:207], v[34:37]
	v_mfma_f32_16x16x32_bf16 v[26:29], v[186:189], v[204:207], v[26:29]
	v_mfma_f32_16x16x32_bf16 v[18:21], v[178:181], v[212:215], v[18:21]
	v_mfma_f32_16x16x32_bf16 v[14:17], v[186:189], v[212:215], v[14:17]
	v_mfma_f32_16x16x32_bf16 v[10:13], v[178:181], v[220:223], v[10:13]
	v_mfma_f32_16x16x32_bf16 v[6:9], v[186:189], v[220:223], v[6:9]
	v_mfma_f32_16x16x32_bf16 v[50:53], v[182:185], v[200:203], v[50:53]
	v_mfma_f32_16x16x32_bf16 v[42:45], v[190:193], v[200:203], v[42:45]
	v_mfma_f32_16x16x32_bf16 v[34:37], v[182:185], v[208:211], v[34:37]
	v_mfma_f32_16x16x32_bf16 v[26:29], v[190:193], v[208:211], v[26:29]
	v_mfma_f32_16x16x32_bf16 v[18:21], v[182:185], v[216:219], v[18:21]
	v_mfma_f32_16x16x32_bf16 v[14:17], v[190:193], v[216:219], v[14:17]
	v_mfma_f32_16x16x32_bf16 v[10:13], v[182:185], v[224:227], v[10:13]
	v_mfma_f32_16x16x32_bf16 v[6:9], v[190:193], v[224:227], v[6:9]
	s_setprio 0
	s_barrier
	s_add_i32 s73, s62, s49
	v_lshl_add_u64 v[228:229], s[42:43], 0, v[134:135]
	s_mov_b32 m0, s73
	ds_read_b128 v[196:199], v164 offset:16384
	ds_read_b128 v[200:203], v164 offset:17408
	ds_read_b128 v[204:207], v164 offset:18432
	ds_read_b128 v[208:211], v164 offset:19456
	ds_read_b128 v[212:215], v164 offset:20480
	ds_read_b128 v[216:219], v164 offset:21504
	ds_read_b128 v[220:223], v164 offset:22528
	ds_read_b128 v[224:227], v164 offset:23552
	global_load_lds_dwordx4 v[228:229], off
	s_add_i32 m0, s73, 0x2000
	s_add_u32 s74, s42, 0x100000
	v_lshl_add_u64 v[230:231], s[42:43], 0, v[138:139]
	s_addc_u32 s75, s43, 0
	s_add_i32 s73, s63, s49
	global_load_lds_dwordx4 v[230:231], off
	v_lshl_add_u64 v[232:233], s[74:75], 0, v[134:135]
	s_mov_b32 m0, s73
	v_lshl_add_u64 v[234:235], s[46:47], 0, v[136:137]
	global_load_lds_dwordx4 v[232:233], off
	v_lshl_add_u64 v[232:233], s[74:75], 0, v[138:139]
	s_add_i32 m0, s73, 0x2000
	s_nop 0
	global_load_lds_dwordx4 v[232:233], off
	v_lshl_add_u64 v[232:233], s[46:47], 0, v[132:133]
	s_mov_b32 m0, s35
	s_nop 0
	global_load_lds_dwordx4 v[232:233], off
	s_mov_b32 m0, s50
	s_nop 0
	global_load_lds_dwordx4 v[234:235], off
	s_waitcnt vmcnt(8)
	s_waitcnt lgkmcnt(0)
	s_barrier
	s_setprio 1
	v_mfma_f32_16x16x32_bf16 v[126:129], v[156:159], v[196:199], v[126:129]
	v_mfma_f32_16x16x32_bf16 v[118:121], v[170:173], v[196:199], v[118:121]
	v_mfma_f32_16x16x32_bf16 v[110:113], v[156:159], v[204:207], v[110:113]
	v_mfma_f32_16x16x32_bf16 v[102:105], v[170:173], v[204:207], v[102:105]
	v_mfma_f32_16x16x32_bf16 v[94:97], v[156:159], v[212:215], v[94:97]
	v_mfma_f32_16x16x32_bf16 v[86:89], v[170:173], v[212:215], v[86:89]
	v_mfma_f32_16x16x32_bf16 v[66:69], v[156:159], v[220:223], v[66:69]
	v_mfma_f32_16x16x32_bf16 v[22:25], v[170:173], v[220:223], v[22:25]
	v_mfma_f32_16x16x32_bf16 v[126:129], v[166:169], v[200:203], v[126:129]
	v_mfma_f32_16x16x32_bf16 v[118:121], v[174:177], v[200:203], v[118:121]
	v_mfma_f32_16x16x32_bf16 v[110:113], v[166:169], v[208:211], v[110:113]
	v_mfma_f32_16x16x32_bf16 v[102:105], v[174:177], v[208:211], v[102:105]
	v_mfma_f32_16x16x32_bf16 v[94:97], v[166:169], v[216:219], v[94:97]
	v_mfma_f32_16x16x32_bf16 v[86:89], v[174:177], v[216:219], v[86:89]
	v_mfma_f32_16x16x32_bf16 v[66:69], v[166:169], v[224:227], v[66:69]
	v_mfma_f32_16x16x32_bf16 v[22:25], v[174:177], v[224:227], v[22:25]
	v_mfma_f32_16x16x32_bf16 v[122:125], v[178:181], v[196:199], v[122:125]
	v_mfma_f32_16x16x32_bf16 v[114:117], v[186:189], v[196:199], v[114:117]
	v_mfma_f32_16x16x32_bf16 v[106:109], v[178:181], v[204:207], v[106:109]
	v_mfma_f32_16x16x32_bf16 v[98:101], v[186:189], v[204:207], v[98:101]
	v_mfma_f32_16x16x32_bf16 v[90:93], v[178:181], v[212:215], v[90:93]
	v_mfma_f32_16x16x32_bf16 v[82:85], v[186:189], v[212:215], v[82:85]
	v_mfma_f32_16x16x32_bf16 v[30:33], v[178:181], v[220:223], v[30:33]
	v_mfma_f32_16x16x32_bf16 v[2:5], v[186:189], v[220:223], v[2:5]
	v_mfma_f32_16x16x32_bf16 v[122:125], v[182:185], v[200:203], v[122:125]
	v_mfma_f32_16x16x32_bf16 v[114:117], v[190:193], v[200:203], v[114:117]
	v_mfma_f32_16x16x32_bf16 v[106:109], v[182:185], v[208:211], v[106:109]
	v_mfma_f32_16x16x32_bf16 v[98:101], v[190:193], v[208:211], v[98:101]
	v_mfma_f32_16x16x32_bf16 v[90:93], v[182:185], v[216:219], v[90:93]
	v_mfma_f32_16x16x32_bf16 v[82:85], v[190:193], v[216:219], v[82:85]
	v_mfma_f32_16x16x32_bf16 v[30:33], v[182:185], v[224:227], v[30:33]
	v_mfma_f32_16x16x32_bf16 v[2:5], v[190:193], v[224:227], v[2:5]
	s_setprio 0
	s_barrier
	s_add_i32 s73, 0, 0x18000
	v_add_u32_e32 v165, s73, v160
	s_add_i32 s74, 0, 0x1c000
	ds_read_b128 v[156:159], v165
	ds_read_b128 v[166:169], v165 offset:1024
	ds_read_b128 v[170:173], v165 offset:2048
	ds_read_b128 v[174:177], v165 offset:3072
	v_add_u32_e32 v165, s74, v160
	ds_read_b128 v[178:181], v165
	ds_read_b128 v[182:185], v165 offset:1024
	ds_read_b128 v[186:189], v165 offset:2048
	ds_read_b128 v[190:193], v165 offset:3072
	s_add_u32 s46, s46, 0x100000
	s_addc_u32 s47, s47, 0
	s_mov_b32 m0, s51
	v_lshl_add_u64 v[236:237], s[46:47], 0, v[132:133]
	ds_read_b128 v[196:199], v164 offset:32768
	ds_read_b128 v[200:203], v164 offset:33792
	ds_read_b128 v[204:207], v164 offset:34816
	ds_read_b128 v[208:211], v164 offset:35840
	ds_read_b128 v[212:215], v164 offset:36864
	ds_read_b128 v[216:219], v164 offset:37888
	ds_read_b128 v[220:223], v164 offset:38912
	ds_read_b128 v[224:227], v164 offset:39936
	global_load_lds_dwordx4 v[236:237], off
	v_lshl_add_u64 v[236:237], s[46:47], 0, v[136:137]
	s_mov_b32 m0, s52
	s_nop 0
	global_load_lds_dwordx4 v[236:237], off
	s_waitcnt vmcnt(8)
	s_waitcnt lgkmcnt(0)
	s_barrier
	s_setprio 1
	v_mfma_f32_16x16x32_bf16 v[78:81], v[156:159], v[196:199], v[78:81]
	v_mfma_f32_16x16x32_bf16 v[74:77], v[170:173], v[196:199], v[74:77]
	v_mfma_f32_16x16x32_bf16 v[70:73], v[156:159], v[204:207], v[70:73]
	v_mfma_f32_16x16x32_bf16 v[62:65], v[170:173], v[204:207], v[62:65]
	v_mfma_f32_16x16x32_bf16 v[58:61], v[156:159], v[212:215], v[58:61]
	v_mfma_f32_16x16x32_bf16 v[54:57], v[170:173], v[212:215], v[54:57]
	v_mfma_f32_16x16x32_bf16 v[46:49], v[156:159], v[220:223], v[46:49]
	v_mfma_f32_16x16x32_bf16 v[38:41], v[170:173], v[220:223], v[38:41]
	v_mfma_f32_16x16x32_bf16 v[78:81], v[166:169], v[200:203], v[78:81]
	v_mfma_f32_16x16x32_bf16 v[74:77], v[174:177], v[200:203], v[74:77]
	v_mfma_f32_16x16x32_bf16 v[70:73], v[166:169], v[208:211], v[70:73]
	v_mfma_f32_16x16x32_bf16 v[62:65], v[174:177], v[208:211], v[62:65]
	v_mfma_f32_16x16x32_bf16 v[58:61], v[166:169], v[216:219], v[58:61]
	v_mfma_f32_16x16x32_bf16 v[54:57], v[174:177], v[216:219], v[54:57]
	v_mfma_f32_16x16x32_bf16 v[46:49], v[166:169], v[224:227], v[46:49]
	v_mfma_f32_16x16x32_bf16 v[38:41], v[174:177], v[224:227], v[38:41]
	v_mfma_f32_16x16x32_bf16 v[50:53], v[178:181], v[196:199], v[50:53]
	v_mfma_f32_16x16x32_bf16 v[42:45], v[186:189], v[196:199], v[42:45]
	v_mfma_f32_16x16x32_bf16 v[34:37], v[178:181], v[204:207], v[34:37]
	v_mfma_f32_16x16x32_bf16 v[26:29], v[186:189], v[204:207], v[26:29]
	v_mfma_f32_16x16x32_bf16 v[18:21], v[178:181], v[212:215], v[18:21]
	v_mfma_f32_16x16x32_bf16 v[14:17], v[186:189], v[212:215], v[14:17]
	v_mfma_f32_16x16x32_bf16 v[10:13], v[178:181], v[220:223], v[10:13]
	v_mfma_f32_16x16x32_bf16 v[6:9], v[186:189], v[220:223], v[6:9]
	v_mfma_f32_16x16x32_bf16 v[50:53], v[182:185], v[200:203], v[50:53]
	v_mfma_f32_16x16x32_bf16 v[42:45], v[190:193], v[200:203], v[42:45]
	v_mfma_f32_16x16x32_bf16 v[34:37], v[182:185], v[208:211], v[34:37]
	v_mfma_f32_16x16x32_bf16 v[26:29], v[190:193], v[208:211], v[26:29]
	v_mfma_f32_16x16x32_bf16 v[18:21], v[182:185], v[216:219], v[18:21]
	v_mfma_f32_16x16x32_bf16 v[14:17], v[190:193], v[216:219], v[14:17]
	v_mfma_f32_16x16x32_bf16 v[10:13], v[182:185], v[224:227], v[10:13]
	v_mfma_f32_16x16x32_bf16 v[6:9], v[190:193], v[224:227], v[6:9]
	s_setprio 0
	s_barrier
	s_add_i32 s46, s73, s49
	v_lshl_add_u64 v[228:229], v[228:229], 0, s[10:11]
	s_mov_b32 m0, s46
	ds_read_b128 v[196:199], v164 offset:49152
	ds_read_b128 v[200:203], v164 offset:50176
	ds_read_b128 v[204:207], v164 offset:51200
	ds_read_b128 v[208:211], v164 offset:52224
	ds_read_b128 v[212:215], v164 offset:53248
	ds_read_b128 v[216:219], v164 offset:54272
	ds_read_b128 v[220:223], v164 offset:55296
	ds_read_b128 v[224:227], v164 offset:56320
	global_load_lds_dwordx4 v[228:229], off
	s_add_i32 m0, s46, 0x2000
	s_add_u32 s42, s42, 0x100080
	v_lshl_add_u64 v[228:229], v[230:231], 0, s[10:11]
	s_addc_u32 s43, s43, 0
	s_add_i32 s46, s74, s49
	global_load_lds_dwordx4 v[228:229], off
	v_lshl_add_u64 v[228:229], s[42:43], 0, v[134:135]
	s_mov_b32 m0, s46
	s_nop 0
	global_load_lds_dwordx4 v[228:229], off
	v_lshl_add_u64 v[228:229], s[42:43], 0, v[138:139]
	s_add_i32 m0, s46, 0x2000
	s_nop 0
	global_load_lds_dwordx4 v[228:229], off
	v_lshl_add_u64 v[228:229], v[232:233], 0, s[10:11]
	s_mov_b32 m0, s55
	s_nop 0
	global_load_lds_dwordx4 v[228:229], off
	v_lshl_add_u64 v[228:229], v[234:235], 0, s[10:11]
	s_mov_b32 m0, s56
	s_nop 0
	global_load_lds_dwordx4 v[228:229], off
	s_nop 0
	s_waitcnt vmcnt(8)
	s_waitcnt lgkmcnt(0)
	s_barrier
	s_setprio 1
	v_mfma_f32_16x16x32_bf16 v[126:129], v[156:159], v[196:199], v[126:129]
	v_mfma_f32_16x16x32_bf16 v[118:121], v[170:173], v[196:199], v[118:121]
	v_mfma_f32_16x16x32_bf16 v[110:113], v[156:159], v[204:207], v[110:113]
	v_mfma_f32_16x16x32_bf16 v[102:105], v[170:173], v[204:207], v[102:105]
	v_mfma_f32_16x16x32_bf16 v[94:97], v[156:159], v[212:215], v[94:97]
	v_mfma_f32_16x16x32_bf16 v[86:89], v[170:173], v[212:215], v[86:89]
	v_mfma_f32_16x16x32_bf16 v[66:69], v[156:159], v[220:223], v[66:69]
	v_mfma_f32_16x16x32_bf16 v[22:25], v[170:173], v[220:223], v[22:25]
	v_mfma_f32_16x16x32_bf16 v[126:129], v[166:169], v[200:203], v[126:129]
	v_mfma_f32_16x16x32_bf16 v[118:121], v[174:177], v[200:203], v[118:121]
	v_mfma_f32_16x16x32_bf16 v[110:113], v[166:169], v[208:211], v[110:113]
	v_mfma_f32_16x16x32_bf16 v[102:105], v[174:177], v[208:211], v[102:105]
	v_mfma_f32_16x16x32_bf16 v[94:97], v[166:169], v[216:219], v[94:97]
	v_mfma_f32_16x16x32_bf16 v[86:89], v[174:177], v[216:219], v[86:89]
	v_mfma_f32_16x16x32_bf16 v[66:69], v[166:169], v[224:227], v[66:69]
	v_mfma_f32_16x16x32_bf16 v[22:25], v[174:177], v[224:227], v[22:25]
	v_mfma_f32_16x16x32_bf16 v[122:125], v[178:181], v[196:199], v[122:125]
	v_mfma_f32_16x16x32_bf16 v[114:117], v[186:189], v[196:199], v[114:117]
	v_mfma_f32_16x16x32_bf16 v[106:109], v[178:181], v[204:207], v[106:109]
	v_mfma_f32_16x16x32_bf16 v[98:101], v[186:189], v[204:207], v[98:101]
	v_mfma_f32_16x16x32_bf16 v[90:93], v[178:181], v[212:215], v[90:93]
	v_mfma_f32_16x16x32_bf16 v[82:85], v[186:189], v[212:215], v[82:85]
	v_mfma_f32_16x16x32_bf16 v[30:33], v[178:181], v[220:223], v[30:33]
	v_mfma_f32_16x16x32_bf16 v[2:5], v[186:189], v[220:223], v[2:5]
	v_mfma_f32_16x16x32_bf16 v[122:125], v[182:185], v[200:203], v[122:125]
	v_mfma_f32_16x16x32_bf16 v[114:117], v[190:193], v[200:203], v[114:117]
	v_mfma_f32_16x16x32_bf16 v[106:109], v[182:185], v[208:211], v[106:109]
	v_mfma_f32_16x16x32_bf16 v[98:101], v[190:193], v[208:211], v[98:101]
	v_mfma_f32_16x16x32_bf16 v[90:93], v[182:185], v[216:219], v[90:93]
	v_mfma_f32_16x16x32_bf16 v[82:85], v[190:193], v[216:219], v[82:85]
	v_mfma_f32_16x16x32_bf16 v[30:33], v[182:185], v[224:227], v[30:33]
	v_mfma_f32_16x16x32_bf16 v[2:5], v[190:193], v[224:227], v[2:5]
	s_setprio 0
	s_barrier
	s_add_u32 s40, s40, 0x100
	s_addc_u32 s41, s41, 0
	s_add_u32 s70, s70, 0x100
	s_addc_u32 s71, s71, 0
	s_cmp_ge_i32 s72, s68
	s_mov_b32 s42, s72
	s_cbranch_scc0 .Lkt_T_16
	s_nop 7
.Lkt_exit_16:
	s_and_b64 vcc, exec, s[12:13]
	s_cbranch_vccz .LBB0_4150
	s_barrier
	s_cmp_lt_i32 s48, 0
	s_mov_b64 s[40:41], -1
	s_cbranch_scc1 .LBB0_4151

.Lkt_L_17:
	ds_read_b128 v[150:153], v158
	ds_read_b128 v[162:165], v158 offset:1024
	ds_read_b128 v[166:169], v158 offset:2048
	ds_read_b128 v[170:173], v158 offset:3072
	ds_read_b128 v[174:177], v159
	ds_read_b128 v[178:181], v159 offset:1024
	ds_read_b128 v[182:185], v159 offset:2048
	ds_read_b128 v[186:189], v159 offset:3072
	s_add_i32 s80, s48, 2
	s_add_u32 s49, s50, 0xffd50080
	s_addc_u32 s52, s51, -1
	s_cmp_eq_u32 s43, s48
	s_cselect_b32 s48, s46, s78
	s_cselect_b32 s53, s5, s52
	s_cselect_b32 s52, s4, s49
	s_cselect_b32 s49, s47, s79
	v_lshl_add_u64 v[154:155], s[50:51], 0, v[138:139]
	s_add_i32 m0, s55, 0xc000
	ds_read_b128 v[190:193], v160
	ds_read_b128 v[196:199], v160 offset:1024
	ds_read_b128 v[200:203], v160 offset:2048
	ds_read_b128 v[204:207], v160 offset:3072
	ds_read_b128 v[208:211], v160 offset:4096
	ds_read_b128 v[212:215], v160 offset:5120
	ds_read_b128 v[216:219], v160 offset:6144
	ds_read_b128 v[220:223], v160 offset:7168
	global_load_lds_dwordx4 v[154:155], off
	v_lshl_add_u64 v[154:155], s[50:51], 0, v[140:141]
	s_add_i32 m0, s55, 0xe000
	s_nop 0
	global_load_lds_dwordx4 v[154:155], off
	s_waitcnt lgkmcnt(0)
	s_barrier
	s_nop 0
	s_setprio 1
	v_mfma_f32_16x16x32_bf16 v[124:127], v[150:153], v[190:193], v[124:127]
	v_mfma_f32_16x16x32_bf16 v[120:123], v[166:169], v[190:193], v[120:123]
	v_mfma_f32_16x16x32_bf16 v[108:111], v[150:153], v[200:203], v[108:111]
	v_mfma_f32_16x16x32_bf16 v[104:107], v[166:169], v[200:203], v[104:107]
	v_mfma_f32_16x16x32_bf16 v[92:95], v[150:153], v[208:211], v[92:95]
	v_mfma_f32_16x16x32_bf16 v[88:91], v[166:169], v[208:211], v[88:91]
	v_mfma_f32_16x16x32_bf16 v[76:79], v[150:153], v[216:219], v[76:79]
	v_mfma_f32_16x16x32_bf16 v[72:75], v[166:169], v[216:219], v[72:75]
	v_mfma_f32_16x16x32_bf16 v[124:127], v[162:165], v[196:199], v[124:127]
	v_mfma_f32_16x16x32_bf16 v[120:123], v[170:173], v[196:199], v[120:123]
	v_mfma_f32_16x16x32_bf16 v[108:111], v[162:165], v[204:207], v[108:111]
	v_mfma_f32_16x16x32_bf16 v[104:107], v[170:173], v[204:207], v[104:107]
	v_mfma_f32_16x16x32_bf16 v[92:95], v[162:165], v[212:215], v[92:95]
	v_mfma_f32_16x16x32_bf16 v[88:91], v[170:173], v[212:215], v[88:91]
	v_mfma_f32_16x16x32_bf16 v[76:79], v[162:165], v[220:223], v[76:79]
	v_mfma_f32_16x16x32_bf16 v[72:75], v[170:173], v[220:223], v[72:75]
	v_mfma_f32_16x16x32_bf16 v[116:119], v[174:177], v[190:193], v[116:119]
	v_mfma_f32_16x16x32_bf16 v[112:115], v[182:185], v[190:193], v[112:115]
	v_mfma_f32_16x16x32_bf16 v[100:103], v[174:177], v[200:203], v[100:103]
	v_mfma_f32_16x16x32_bf16 v[96:99], v[182:185], v[200:203], v[96:99]
	v_mfma_f32_16x16x32_bf16 v[84:87], v[174:177], v[208:211], v[84:87]
	v_mfma_f32_16x16x32_bf16 v[80:83], v[182:185], v[208:211], v[80:83]
	v_mfma_f32_16x16x32_bf16 v[68:71], v[174:177], v[216:219], v[68:71]
	v_mfma_f32_16x16x32_bf16 v[64:67], v[182:185], v[216:219], v[64:67]
	v_mfma_f32_16x16x32_bf16 v[116:119], v[178:181], v[196:199], v[116:119]
	v_mfma_f32_16x16x32_bf16 v[112:115], v[186:189], v[196:199], v[112:115]
	v_mfma_f32_16x16x32_bf16 v[100:103], v[178:181], v[204:207], v[100:103]
	v_mfma_f32_16x16x32_bf16 v[96:99], v[186:189], v[204:207], v[96:99]
	v_mfma_f32_16x16x32_bf16 v[84:87], v[178:181], v[212:215], v[84:87]
	v_mfma_f32_16x16x32_bf16 v[80:83], v[186:189], v[212:215], v[80:83]
	v_mfma_f32_16x16x32_bf16 v[68:71], v[178:181], v[220:223], v[68:71]
	v_mfma_f32_16x16x32_bf16 v[64:67], v[186:189], v[220:223], v[64:67]
	s_setprio 0
	s_waitcnt vmcnt(8)
	s_barrier
	s_add_i32 s81, s65, s54
	v_lshl_add_u64 v[154:155], s[48:49], 0, v[132:133]
	s_mov_b32 m0, s81
	ds_read_b128 v[190:193], v160 offset:16384
	ds_read_b128 v[196:199], v160 offset:17408
	ds_read_b128 v[200:203], v160 offset:18432
	ds_read_b128 v[204:207], v160 offset:19456
	ds_read_b128 v[208:211], v160 offset:20480
	ds_read_b128 v[212:215], v160 offset:21504
	ds_read_b128 v[216:219], v160 offset:22528
	ds_read_b128 v[220:223], v160 offset:23552
	global_load_lds_dwordx4 v[154:155], off
	s_add_i32 m0, s81, 0x2000
	s_add_u32 s82, s48, 0x2b0000
	v_lshl_add_u64 v[224:225], s[48:49], 0, v[136:137]
	s_addc_u32 s83, s49, 0
	s_add_i32 s81, s66, s54
	global_load_lds_dwordx4 v[224:225], off
	v_lshl_add_u64 v[226:227], s[82:83], 0, v[132:133]
	s_mov_b32 m0, s81
	v_lshl_add_u64 v[228:229], s[52:53], 0, v[134:135]
	global_load_lds_dwordx4 v[226:227], off
	v_lshl_add_u64 v[226:227], s[82:83], 0, v[136:137]
	s_add_i32 m0, s81, 0x2000
	s_nop 0
	global_load_lds_dwordx4 v[226:227], off
	v_lshl_add_u64 v[226:227], s[52:53], 0, v[128:129]
	s_mov_b32 m0, s55
	s_nop 0
	global_load_lds_dwordx4 v[226:227], off
	s_mov_b32 m0, s56
	s_nop 0
	global_load_lds_dwordx4 v[228:229], off
	s_waitcnt lgkmcnt(0)
	s_barrier
	s_setprio 1
	v_mfma_f32_16x16x32_bf16 v[60:63], v[150:153], v[190:193], v[60:63]
	v_mfma_f32_16x16x32_bf16 v[56:59], v[166:169], v[190:193], v[56:59]
	v_mfma_f32_16x16x32_bf16 v[44:47], v[150:153], v[200:203], v[44:47]
	v_mfma_f32_16x16x32_bf16 v[40:43], v[166:169], v[200:203], v[40:43]
	v_mfma_f32_16x16x32_bf16 v[28:31], v[150:153], v[208:211], v[28:31]
	v_mfma_f32_16x16x32_bf16 v[24:27], v[166:169], v[208:211], v[24:27]
	v_mfma_f32_16x16x32_bf16 v[12:15], v[150:153], v[216:219], v[12:15]
	v_mfma_f32_16x16x32_bf16 v[8:11], v[166:169], v[216:219], v[8:11]
	v_mfma_f32_16x16x32_bf16 v[60:63], v[162:165], v[196:199], v[60:63]
	v_mfma_f32_16x16x32_bf16 v[56:59], v[170:173], v[196:199], v[56:59]
	v_mfma_f32_16x16x32_bf16 v[44:47], v[162:165], v[204:207], v[44:47]
	v_mfma_f32_16x16x32_bf16 v[40:43], v[170:173], v[204:207], v[40:43]
	v_mfma_f32_16x16x32_bf16 v[28:31], v[162:165], v[212:215], v[28:31]
	v_mfma_f32_16x16x32_bf16 v[24:27], v[170:173], v[212:215], v[24:27]
	v_mfma_f32_16x16x32_bf16 v[12:15], v[162:165], v[220:223], v[12:15]
	v_mfma_f32_16x16x32_bf16 v[8:11], v[170:173], v[220:223], v[8:11]
	v_mfma_f32_16x16x32_bf16 v[52:55], v[174:177], v[190:193], v[52:55]
	v_mfma_f32_16x16x32_bf16 v[48:51], v[182:185], v[190:193], v[48:51]
	v_mfma_f32_16x16x32_bf16 v[36:39], v[174:177], v[200:203], v[36:39]
	v_mfma_f32_16x16x32_bf16 v[32:35], v[182:185], v[200:203], v[32:35]
	v_mfma_f32_16x16x32_bf16 v[20:23], v[174:177], v[208:211], v[20:23]
	v_mfma_f32_16x16x32_bf16 v[16:19], v[182:185], v[208:211], v[16:19]
	v_mfma_f32_16x16x32_bf16 v[4:7], v[174:177], v[216:219], v[4:7]
	v_mfma_f32_16x16x32_bf16 v[0:3], v[182:185], v[216:219], v[0:3]
	v_mfma_f32_16x16x32_bf16 v[52:55], v[178:181], v[196:199], v[52:55]
	v_mfma_f32_16x16x32_bf16 v[48:51], v[186:189], v[196:199], v[48:51]
	v_mfma_f32_16x16x32_bf16 v[36:39], v[178:181], v[204:207], v[36:39]
	v_mfma_f32_16x16x32_bf16 v[32:35], v[186:189], v[204:207], v[32:35]
	v_mfma_f32_16x16x32_bf16 v[20:23], v[178:181], v[212:215], v[20:23]
	v_mfma_f32_16x16x32_bf16 v[16:19], v[186:189], v[212:215], v[16:19]
	v_mfma_f32_16x16x32_bf16 v[4:7], v[178:181], v[220:223], v[4:7]
	v_mfma_f32_16x16x32_bf16 v[0:3], v[186:189], v[220:223], v[0:3]
	s_setprio 0
	s_waitcnt vmcnt(8)
	s_barrier
	s_add_i32 s81, 0, 0x18000
	v_add_u32_e32 v161, s81, v156
	s_add_i32 s82, 0, 0x1c000
	ds_read_b128 v[150:153], v161
	ds_read_b128 v[162:165], v161 offset:1024
	ds_read_b128 v[166:169], v161 offset:2048
	ds_read_b128 v[170:173], v161 offset:3072
	v_add_u32_e32 v161, s82, v156
	ds_read_b128 v[174:177], v161
	ds_read_b128 v[178:181], v161 offset:1024
	ds_read_b128 v[182:185], v161 offset:2048
	ds_read_b128 v[186:189], v161 offset:3072
	s_add_u32 s52, s52, 0x2b0000
	s_addc_u32 s53, s53, 0
	s_mov_b32 m0, s57
	v_lshl_add_u64 v[230:231], s[52:53], 0, v[128:129]
	ds_read_b128 v[190:193], v160 offset:32768
	ds_read_b128 v[196:199], v160 offset:33792
	ds_read_b128 v[200:203], v160 offset:34816
	ds_read_b128 v[204:207], v160 offset:35840
	ds_read_b128 v[208:211], v160 offset:36864
	ds_read_b128 v[212:215], v160 offset:37888
	ds_read_b128 v[216:219], v160 offset:38912
	ds_read_b128 v[220:223], v160 offset:39936
	global_load_lds_dwordx4 v[230:231], off
	v_lshl_add_u64 v[230:231], s[52:53], 0, v[134:135]
	s_mov_b32 m0, s58
	s_nop 0
	global_load_lds_dwordx4 v[230:231], off
	s_waitcnt lgkmcnt(0)
	s_barrier
	s_setprio 1
	v_mfma_f32_16x16x32_bf16 v[124:127], v[150:153], v[190:193], v[124:127]
	v_mfma_f32_16x16x32_bf16 v[120:123], v[166:169], v[190:193], v[120:123]
	v_mfma_f32_16x16x32_bf16 v[108:111], v[150:153], v[200:203], v[108:111]
	v_mfma_f32_16x16x32_bf16 v[104:107], v[166:169], v[200:203], v[104:107]
	v_mfma_f32_16x16x32_bf16 v[92:95], v[150:153], v[208:211], v[92:95]
	v_mfma_f32_16x16x32_bf16 v[88:91], v[166:169], v[208:211], v[88:91]
	v_mfma_f32_16x16x32_bf16 v[76:79], v[150:153], v[216:219], v[76:79]
	v_mfma_f32_16x16x32_bf16 v[72:75], v[166:169], v[216:219], v[72:75]
	v_mfma_f32_16x16x32_bf16 v[124:127], v[162:165], v[196:199], v[124:127]
	v_mfma_f32_16x16x32_bf16 v[120:123], v[170:173], v[196:199], v[120:123]
	v_mfma_f32_16x16x32_bf16 v[108:111], v[162:165], v[204:207], v[108:111]
	v_mfma_f32_16x16x32_bf16 v[104:107], v[170:173], v[204:207], v[104:107]
	v_mfma_f32_16x16x32_bf16 v[92:95], v[162:165], v[212:215], v[92:95]
	v_mfma_f32_16x16x32_bf16 v[88:91], v[170:173], v[212:215], v[88:91]
	v_mfma_f32_16x16x32_bf16 v[76:79], v[162:165], v[220:223], v[76:79]
	v_mfma_f32_16x16x32_bf16 v[72:75], v[170:173], v[220:223], v[72:75]
	v_mfma_f32_16x16x32_bf16 v[116:119], v[174:177], v[190:193], v[116:119]
	v_mfma_f32_16x16x32_bf16 v[112:115], v[182:185], v[190:193], v[112:115]
	v_mfma_f32_16x16x32_bf16 v[100:103], v[174:177], v[200:203], v[100:103]
	v_mfma_f32_16x16x32_bf16 v[96:99], v[182:185], v[200:203], v[96:99]
	v_mfma_f32_16x16x32_bf16 v[84:87], v[174:177], v[208:211], v[84:87]
	v_mfma_f32_16x16x32_bf16 v[80:83], v[182:185], v[208:211], v[80:83]
	v_mfma_f32_16x16x32_bf16 v[68:71], v[174:177], v[216:219], v[68:71]
	v_mfma_f32_16x16x32_bf16 v[64:67], v[182:185], v[216:219], v[64:67]
	v_mfma_f32_16x16x32_bf16 v[116:119], v[178:181], v[196:199], v[116:119]
	v_mfma_f32_16x16x32_bf16 v[112:115], v[186:189], v[196:199], v[112:115]
	v_mfma_f32_16x16x32_bf16 v[100:103], v[178:181], v[204:207], v[100:103]
	v_mfma_f32_16x16x32_bf16 v[96:99], v[186:189], v[204:207], v[96:99]
	v_mfma_f32_16x16x32_bf16 v[84:87], v[178:181], v[212:215], v[84:87]
	v_mfma_f32_16x16x32_bf16 v[80:83], v[186:189], v[212:215], v[80:83]
	v_mfma_f32_16x16x32_bf16 v[68:71], v[178:181], v[220:223], v[68:71]
	v_mfma_f32_16x16x32_bf16 v[64:67], v[186:189], v[220:223], v[64:67]
	s_setprio 0
	s_waitcnt vmcnt(8)
	s_barrier
	s_add_i32 s52, s81, s54
	v_lshl_add_u64 v[154:155], v[154:155], 0, s[14:15]
	s_mov_b32 m0, s52
	ds_read_b128 v[190:193], v160 offset:49152
	ds_read_b128 v[196:199], v160 offset:50176
	ds_read_b128 v[200:203], v160 offset:51200
	ds_read_b128 v[204:207], v160 offset:52224
	ds_read_b128 v[208:211], v160 offset:53248
	ds_read_b128 v[212:215], v160 offset:54272
	ds_read_b128 v[216:219], v160 offset:55296
	ds_read_b128 v[220:223], v160 offset:56320
	global_load_lds_dwordx4 v[154:155], off
	s_add_i32 m0, s52, 0x2000
	s_add_u32 s48, s48, 0x2b0080
	v_lshl_add_u64 v[154:155], v[224:225], 0, s[14:15]
	s_addc_u32 s49, s49, 0
	s_add_i32 s52, s82, s54
	global_load_lds_dwordx4 v[154:155], off
	v_lshl_add_u64 v[154:155], s[48:49], 0, v[132:133]
	s_mov_b32 m0, s52
	s_nop 0
	global_load_lds_dwordx4 v[154:155], off
	v_lshl_add_u64 v[154:155], s[48:49], 0, v[136:137]
	s_add_i32 m0, s52, 0x2000
	s_nop 0
	global_load_lds_dwordx4 v[154:155], off
	v_lshl_add_u64 v[154:155], v[226:227], 0, s[14:15]
	s_mov_b32 m0, s62
	s_nop 0
	global_load_lds_dwordx4 v[154:155], off
	v_lshl_add_u64 v[154:155], v[228:229], 0, s[14:15]
	s_mov_b32 m0, s63
	s_nop 0
	global_load_lds_dwordx4 v[154:155], off
	s_waitcnt lgkmcnt(0)
	s_barrier
	s_nop 0
	s_setprio 1
	v_mfma_f32_16x16x32_bf16 v[60:63], v[150:153], v[190:193], v[60:63]
	v_mfma_f32_16x16x32_bf16 v[56:59], v[166:169], v[190:193], v[56:59]
	v_mfma_f32_16x16x32_bf16 v[44:47], v[150:153], v[200:203], v[44:47]
	v_mfma_f32_16x16x32_bf16 v[40:43], v[166:169], v[200:203], v[40:43]
	v_mfma_f32_16x16x32_bf16 v[28:31], v[150:153], v[208:211], v[28:31]
	v_mfma_f32_16x16x32_bf16 v[24:27], v[166:169], v[208:211], v[24:27]
	v_mfma_f32_16x16x32_bf16 v[12:15], v[150:153], v[216:219], v[12:15]
	v_mfma_f32_16x16x32_bf16 v[8:11], v[166:169], v[216:219], v[8:11]
	v_mfma_f32_16x16x32_bf16 v[60:63], v[162:165], v[196:199], v[60:63]
	v_mfma_f32_16x16x32_bf16 v[56:59], v[170:173], v[196:199], v[56:59]
	v_mfma_f32_16x16x32_bf16 v[44:47], v[162:165], v[204:207], v[44:47]
	v_mfma_f32_16x16x32_bf16 v[40:43], v[170:173], v[204:207], v[40:43]
	v_mfma_f32_16x16x32_bf16 v[28:31], v[162:165], v[212:215], v[28:31]
	v_mfma_f32_16x16x32_bf16 v[24:27], v[170:173], v[212:215], v[24:27]
	v_mfma_f32_16x16x32_bf16 v[12:15], v[162:165], v[220:223], v[12:15]
	v_mfma_f32_16x16x32_bf16 v[8:11], v[170:173], v[220:223], v[8:11]
	v_mfma_f32_16x16x32_bf16 v[52:55], v[174:177], v[190:193], v[52:55]
	v_mfma_f32_16x16x32_bf16 v[48:51], v[182:185], v[190:193], v[48:51]
	v_mfma_f32_16x16x32_bf16 v[36:39], v[174:177], v[200:203], v[36:39]
	v_mfma_f32_16x16x32_bf16 v[32:35], v[182:185], v[200:203], v[32:35]
	v_mfma_f32_16x16x32_bf16 v[20:23], v[174:177], v[208:211], v[20:23]
	v_mfma_f32_16x16x32_bf16 v[16:19], v[182:185], v[208:211], v[16:19]
	v_mfma_f32_16x16x32_bf16 v[4:7], v[174:177], v[216:219], v[4:7]
	v_mfma_f32_16x16x32_bf16 v[0:3], v[182:185], v[216:219], v[0:3]
	v_mfma_f32_16x16x32_bf16 v[52:55], v[178:181], v[196:199], v[52:55]
	v_mfma_f32_16x16x32_bf16 v[48:51], v[186:189], v[196:199], v[48:51]
	v_mfma_f32_16x16x32_bf16 v[36:39], v[178:181], v[204:207], v[36:39]
	v_mfma_f32_16x16x32_bf16 v[32:35], v[186:189], v[204:207], v[32:35]
	v_mfma_f32_16x16x32_bf16 v[20:23], v[178:181], v[212:215], v[20:23]
	v_mfma_f32_16x16x32_bf16 v[16:19], v[186:189], v[212:215], v[16:19]
	v_mfma_f32_16x16x32_bf16 v[4:7], v[178:181], v[220:223], v[4:7]
	v_mfma_f32_16x16x32_bf16 v[0:3], v[186:189], v[220:223], v[0:3]
	s_setprio 0
	s_waitcnt vmcnt(8)
	s_barrier
	s_add_u32 s50, s50, 0x100
	s_addc_u32 s51, s51, 0
	s_add_u32 s78, s78, 0x100
	s_addc_u32 s79, s79, 0
	s_cmp_ge_i32 s80, s76
	s_mov_b32 s48, s80
	s_cbranch_scc0 .Lkt_L_17
	s_branch .Lkt_exit_17
.Lkt_T_17:
	ds_read_b128 v[150:153], v158
	ds_read_b128 v[162:165], v158 offset:1024
	ds_read_b128 v[166:169], v158 offset:2048
	ds_read_b128 v[170:173], v158 offset:3072
	ds_read_b128 v[174:177], v159
	ds_read_b128 v[178:181], v159 offset:1024
	ds_read_b128 v[182:185], v159 offset:2048
	ds_read_b128 v[186:189], v159 offset:3072
	s_add_i32 s80, s48, 2
	s_add_u32 s49, s50, 0xffd50080
	s_addc_u32 s52, s51, -1
	s_cmp_eq_u32 s43, s48
	s_cselect_b32 s48, s46, s78
	s_cselect_b32 s53, s5, s52
	s_cselect_b32 s52, s4, s49
	s_cselect_b32 s49, s47, s79
	v_lshl_add_u64 v[154:155], s[50:51], 0, v[138:139]
	s_add_i32 m0, s55, 0xc000
	ds_read_b128 v[190:193], v160
	ds_read_b128 v[196:199], v160 offset:1024
	ds_read_b128 v[200:203], v160 offset:2048
	ds_read_b128 v[204:207], v160 offset:3072
	ds_read_b128 v[208:211], v160 offset:4096
	ds_read_b128 v[212:215], v160 offset:5120
	ds_read_b128 v[216:219], v160 offset:6144
	ds_read_b128 v[220:223], v160 offset:7168
	global_load_lds_dwordx4 v[154:155], off
	v_lshl_add_u64 v[154:155], s[50:51], 0, v[140:141]
	s_add_i32 m0, s55, 0xe000
	s_nop 0
	global_load_lds_dwordx4 v[154:155], off
	s_nop 0
	s_waitcnt vmcnt(8)
	s_waitcnt lgkmcnt(0)
	s_barrier
	s_setprio 1
	v_mfma_f32_16x16x32_bf16 v[124:127], v[150:153], v[190:193], v[124:127]
	v_mfma_f32_16x16x32_bf16 v[120:123], v[166:169], v[190:193], v[120:123]
	v_mfma_f32_16x16x32_bf16 v[108:111], v[150:153], v[200:203], v[108:111]
	v_mfma_f32_16x16x32_bf16 v[104:107], v[166:169], v[200:203], v[104:107]
	v_mfma_f32_16x16x32_bf16 v[92:95], v[150:153], v[208:211], v[92:95]
	v_mfma_f32_16x16x32_bf16 v[88:91], v[166:169], v[208:211], v[88:91]
	v_mfma_f32_16x16x32_bf16 v[76:79], v[150:153], v[216:219], v[76:79]
	v_mfma_f32_16x16x32_bf16 v[72:75], v[166:169], v[216:219], v[72:75]
	v_mfma_f32_16x16x32_bf16 v[124:127], v[162:165], v[196:199], v[124:127]
	v_mfma_f32_16x16x32_bf16 v[120:123], v[170:173], v[196:199], v[120:123]
	v_mfma_f32_16x16x32_bf16 v[108:111], v[162:165], v[204:207], v[108:111]
	v_mfma_f32_16x16x32_bf16 v[104:107], v[170:173], v[204:207], v[104:107]
	v_mfma_f32_16x16x32_bf16 v[92:95], v[162:165], v[212:215], v[92:95]
	v_mfma_f32_16x16x32_bf16 v[88:91], v[170:173], v[212:215], v[88:91]
	v_mfma_f32_16x16x32_bf16 v[76:79], v[162:165], v[220:223], v[76:79]
	v_mfma_f32_16x16x32_bf16 v[72:75], v[170:173], v[220:223], v[72:75]
	v_mfma_f32_16x16x32_bf16 v[116:119], v[174:177], v[190:193], v[116:119]
	v_mfma_f32_16x16x32_bf16 v[112:115], v[182:185], v[190:193], v[112:115]
	v_mfma_f32_16x16x32_bf16 v[100:103], v[174:177], v[200:203], v[100:103]
	v_mfma_f32_16x16x32_bf16 v[96:99], v[182:185], v[200:203], v[96:99]
	v_mfma_f32_16x16x32_bf16 v[84:87], v[174:177], v[208:211], v[84:87]
	v_mfma_f32_16x16x32_bf16 v[80:83], v[182:185], v[208:211], v[80:83]
	v_mfma_f32_16x16x32_bf16 v[68:71], v[174:177], v[216:219], v[68:71]
	v_mfma_f32_16x16x32_bf16 v[64:67], v[182:185], v[216:219], v[64:67]
	v_mfma_f32_16x16x32_bf16 v[116:119], v[178:181], v[196:199], v[116:119]
	v_mfma_f32_16x16x32_bf16 v[112:115], v[186:189], v[196:199], v[112:115]
	v_mfma_f32_16x16x32_bf16 v[100:103], v[178:181], v[204:207], v[100:103]
	v_mfma_f32_16x16x32_bf16 v[96:99], v[186:189], v[204:207], v[96:99]
	v_mfma_f32_16x16x32_bf16 v[84:87], v[178:181], v[212:215], v[84:87]
	v_mfma_f32_16x16x32_bf16 v[80:83], v[186:189], v[212:215], v[80:83]
	v_mfma_f32_16x16x32_bf16 v[68:71], v[178:181], v[220:223], v[68:71]
	v_mfma_f32_16x16x32_bf16 v[64:67], v[186:189], v[220:223], v[64:67]
	s_setprio 0
	s_barrier
	s_add_i32 s81, s65, s54
	v_lshl_add_u64 v[154:155], s[48:49], 0, v[132:133]
	s_mov_b32 m0, s81
	ds_read_b128 v[190:193], v160 offset:16384
	ds_read_b128 v[196:199], v160 offset:17408
	ds_read_b128 v[200:203], v160 offset:18432
	ds_read_b128 v[204:207], v160 offset:19456
	ds_read_b128 v[208:211], v160 offset:20480
	ds_read_b128 v[212:215], v160 offset:21504
	ds_read_b128 v[216:219], v160 offset:22528
	ds_read_b128 v[220:223], v160 offset:23552
	global_load_lds_dwordx4 v[154:155], off
	s_add_i32 m0, s81, 0x2000
	s_add_u32 s82, s48, 0x2b0000
	v_lshl_add_u64 v[224:225], s[48:49], 0, v[136:137]
	s_addc_u32 s83, s49, 0
	s_add_i32 s81, s66, s54
	global_load_lds_dwordx4 v[224:225], off
	v_lshl_add_u64 v[226:227], s[82:83], 0, v[132:133]
	s_mov_b32 m0, s81
	v_lshl_add_u64 v[228:229], s[52:53], 0, v[134:135]
	global_load_lds_dwordx4 v[226:227], off
	v_lshl_add_u64 v[226:227], s[82:83], 0, v[136:137]
	s_add_i32 m0, s81, 0x2000
	s_nop 0
	global_load_lds_dwordx4 v[226:227], off
	v_lshl_add_u64 v[226:227], s[52:53], 0, v[128:129]
	s_mov_b32 m0, s55
	s_nop 0
	global_load_lds_dwordx4 v[226:227], off
	s_mov_b32 m0, s56
	s_nop 0
	global_load_lds_dwordx4 v[228:229], off
	s_waitcnt vmcnt(8)
	s_waitcnt lgkmcnt(0)
	s_barrier
	s_setprio 1
	v_mfma_f32_16x16x32_bf16 v[60:63], v[150:153], v[190:193], v[60:63]
	v_mfma_f32_16x16x32_bf16 v[56:59], v[166:169], v[190:193], v[56:59]
	v_mfma_f32_16x16x32_bf16 v[44:47], v[150:153], v[200:203], v[44:47]
	v_mfma_f32_16x16x32_bf16 v[40:43], v[166:169], v[200:203], v[40:43]
	v_mfma_f32_16x16x32_bf16 v[28:31], v[150:153], v[208:211], v[28:31]
	v_mfma_f32_16x16x32_bf16 v[24:27], v[166:169], v[208:211], v[24:27]
	v_mfma_f32_16x16x32_bf16 v[12:15], v[150:153], v[216:219], v[12:15]
	v_mfma_f32_16x16x32_bf16 v[8:11], v[166:169], v[216:219], v[8:11]
	v_mfma_f32_16x16x32_bf16 v[60:63], v[162:165], v[196:199], v[60:63]
	v_mfma_f32_16x16x32_bf16 v[56:59], v[170:173], v[196:199], v[56:59]
	v_mfma_f32_16x16x32_bf16 v[44:47], v[162:165], v[204:207], v[44:47]
	v_mfma_f32_16x16x32_bf16 v[40:43], v[170:173], v[204:207], v[40:43]
	v_mfma_f32_16x16x32_bf16 v[28:31], v[162:165], v[212:215], v[28:31]
	v_mfma_f32_16x16x32_bf16 v[24:27], v[170:173], v[212:215], v[24:27]
	v_mfma_f32_16x16x32_bf16 v[12:15], v[162:165], v[220:223], v[12:15]
	v_mfma_f32_16x16x32_bf16 v[8:11], v[170:173], v[220:223], v[8:11]
	v_mfma_f32_16x16x32_bf16 v[52:55], v[174:177], v[190:193], v[52:55]
	v_mfma_f32_16x16x32_bf16 v[48:51], v[182:185], v[190:193], v[48:51]
	v_mfma_f32_16x16x32_bf16 v[36:39], v[174:177], v[200:203], v[36:39]
	v_mfma_f32_16x16x32_bf16 v[32:35], v[182:185], v[200:203], v[32:35]
	v_mfma_f32_16x16x32_bf16 v[20:23], v[174:177], v[208:211], v[20:23]
	v_mfma_f32_16x16x32_bf16 v[16:19], v[182:185], v[208:211], v[16:19]
	v_mfma_f32_16x16x32_bf16 v[4:7], v[174:177], v[216:219], v[4:7]
	v_mfma_f32_16x16x32_bf16 v[0:3], v[182:185], v[216:219], v[0:3]
	v_mfma_f32_16x16x32_bf16 v[52:55], v[178:181], v[196:199], v[52:55]
	v_mfma_f32_16x16x32_bf16 v[48:51], v[186:189], v[196:199], v[48:51]
	v_mfma_f32_16x16x32_bf16 v[36:39], v[178:181], v[204:207], v[36:39]
	v_mfma_f32_16x16x32_bf16 v[32:35], v[186:189], v[204:207], v[32:35]
	v_mfma_f32_16x16x32_bf16 v[20:23], v[178:181], v[212:215], v[20:23]
	v_mfma_f32_16x16x32_bf16 v[16:19], v[186:189], v[212:215], v[16:19]
	v_mfma_f32_16x16x32_bf16 v[4:7], v[178:181], v[220:223], v[4:7]
	v_mfma_f32_16x16x32_bf16 v[0:3], v[186:189], v[220:223], v[0:3]
	s_setprio 0
	s_barrier
	s_add_i32 s81, 0, 0x18000
	v_add_u32_e32 v161, s81, v156
	s_add_i32 s82, 0, 0x1c000
	ds_read_b128 v[150:153], v161
	ds_read_b128 v[162:165], v161 offset:1024
	ds_read_b128 v[166:169], v161 offset:2048
	ds_read_b128 v[170:173], v161 offset:3072
	v_add_u32_e32 v161, s82, v156
	ds_read_b128 v[174:177], v161
	ds_read_b128 v[178:181], v161 offset:1024
	ds_read_b128 v[182:185], v161 offset:2048
	ds_read_b128 v[186:189], v161 offset:3072
	s_add_u32 s52, s52, 0x2b0000
	s_addc_u32 s53, s53, 0
	s_mov_b32 m0, s57
	v_lshl_add_u64 v[230:231], s[52:53], 0, v[128:129]
	ds_read_b128 v[190:193], v160 offset:32768
	ds_read_b128 v[196:199], v160 offset:33792
	ds_read_b128 v[200:203], v160 offset:34816
	ds_read_b128 v[204:207], v160 offset:35840
	ds_read_b128 v[208:211], v160 offset:36864
	ds_read_b128 v[212:215], v160 offset:37888
	ds_read_b128 v[216:219], v160 offset:38912
	ds_read_b128 v[220:223], v160 offset:39936
	global_load_lds_dwordx4 v[230:231], off
	v_lshl_add_u64 v[230:231], s[52:53], 0, v[134:135]
	s_mov_b32 m0, s58
	s_nop 0
	global_load_lds_dwordx4 v[230:231], off
	s_waitcnt vmcnt(8)
	s_waitcnt lgkmcnt(0)
	s_barrier
	s_setprio 1
	v_mfma_f32_16x16x32_bf16 v[124:127], v[150:153], v[190:193], v[124:127]
	v_mfma_f32_16x16x32_bf16 v[120:123], v[166:169], v[190:193], v[120:123]
	v_mfma_f32_16x16x32_bf16 v[108:111], v[150:153], v[200:203], v[108:111]
	v_mfma_f32_16x16x32_bf16 v[104:107], v[166:169], v[200:203], v[104:107]
	v_mfma_f32_16x16x32_bf16 v[92:95], v[150:153], v[208:211], v[92:95]
	v_mfma_f32_16x16x32_bf16 v[88:91], v[166:169], v[208:211], v[88:91]
	v_mfma_f32_16x16x32_bf16 v[76:79], v[150:153], v[216:219], v[76:79]
	v_mfma_f32_16x16x32_bf16 v[72:75], v[166:169], v[216:219], v[72:75]
	v_mfma_f32_16x16x32_bf16 v[124:127], v[162:165], v[196:199], v[124:127]
	v_mfma_f32_16x16x32_bf16 v[120:123], v[170:173], v[196:199], v[120:123]
	v_mfma_f32_16x16x32_bf16 v[108:111], v[162:165], v[204:207], v[108:111]
	v_mfma_f32_16x16x32_bf16 v[104:107], v[170:173], v[204:207], v[104:107]
	v_mfma_f32_16x16x32_bf16 v[92:95], v[162:165], v[212:215], v[92:95]
	v_mfma_f32_16x16x32_bf16 v[88:91], v[170:173], v[212:215], v[88:91]
	v_mfma_f32_16x16x32_bf16 v[76:79], v[162:165], v[220:223], v[76:79]
	v_mfma_f32_16x16x32_bf16 v[72:75], v[170:173], v[220:223], v[72:75]
	v_mfma_f32_16x16x32_bf16 v[116:119], v[174:177], v[190:193], v[116:119]
	v_mfma_f32_16x16x32_bf16 v[112:115], v[182:185], v[190:193], v[112:115]
	v_mfma_f32_16x16x32_bf16 v[100:103], v[174:177], v[200:203], v[100:103]
	v_mfma_f32_16x16x32_bf16 v[96:99], v[182:185], v[200:203], v[96:99]
	v_mfma_f32_16x16x32_bf16 v[84:87], v[174:177], v[208:211], v[84:87]
	v_mfma_f32_16x16x32_bf16 v[80:83], v[182:185], v[208:211], v[80:83]
	v_mfma_f32_16x16x32_bf16 v[68:71], v[174:177], v[216:219], v[68:71]
	v_mfma_f32_16x16x32_bf16 v[64:67], v[182:185], v[216:219], v[64:67]
	v_mfma_f32_16x16x32_bf16 v[116:119], v[178:181], v[196:199], v[116:119]
	v_mfma_f32_16x16x32_bf16 v[112:115], v[186:189], v[196:199], v[112:115]
	v_mfma_f32_16x16x32_bf16 v[100:103], v[178:181], v[204:207], v[100:103]
	v_mfma_f32_16x16x32_bf16 v[96:99], v[186:189], v[204:207], v[96:99]
	v_mfma_f32_16x16x32_bf16 v[84:87], v[178:181], v[212:215], v[84:87]
	v_mfma_f32_16x16x32_bf16 v[80:83], v[186:189], v[212:215], v[80:83]
	v_mfma_f32_16x16x32_bf16 v[68:71], v[178:181], v[220:223], v[68:71]
	v_mfma_f32_16x16x32_bf16 v[64:67], v[186:189], v[220:223], v[64:67]
	s_setprio 0
	s_barrier
	s_add_i32 s52, s81, s54
	v_lshl_add_u64 v[154:155], v[154:155], 0, s[14:15]
	s_mov_b32 m0, s52
	ds_read_b128 v[190:193], v160 offset:49152
	ds_read_b128 v[196:199], v160 offset:50176
	ds_read_b128 v[200:203], v160 offset:51200
	ds_read_b128 v[204:207], v160 offset:52224
	ds_read_b128 v[208:211], v160 offset:53248
	ds_read_b128 v[212:215], v160 offset:54272
	ds_read_b128 v[216:219], v160 offset:55296
	ds_read_b128 v[220:223], v160 offset:56320
	global_load_lds_dwordx4 v[154:155], off
	s_add_i32 m0, s52, 0x2000
	s_add_u32 s48, s48, 0x2b0080
	v_lshl_add_u64 v[154:155], v[224:225], 0, s[14:15]
	s_addc_u32 s49, s49, 0
	s_add_i32 s52, s82, s54
	global_load_lds_dwordx4 v[154:155], off
	v_lshl_add_u64 v[154:155], s[48:49], 0, v[132:133]
	s_mov_b32 m0, s52
	s_nop 0
	global_load_lds_dwordx4 v[154:155], off
	v_lshl_add_u64 v[154:155], s[48:49], 0, v[136:137]
	s_add_i32 m0, s52, 0x2000
	s_nop 0
	global_load_lds_dwordx4 v[154:155], off
	v_lshl_add_u64 v[154:155], v[226:227], 0, s[14:15]
	s_mov_b32 m0, s62
	s_nop 0
	global_load_lds_dwordx4 v[154:155], off
	v_lshl_add_u64 v[154:155], v[228:229], 0, s[14:15]
	s_mov_b32 m0, s63
	s_nop 0
	global_load_lds_dwordx4 v[154:155], off
	s_nop 0
	s_waitcnt vmcnt(8)
	s_waitcnt lgkmcnt(0)
	s_barrier
	s_setprio 1
	v_mfma_f32_16x16x32_bf16 v[60:63], v[150:153], v[190:193], v[60:63]
	v_mfma_f32_16x16x32_bf16 v[56:59], v[166:169], v[190:193], v[56:59]
	v_mfma_f32_16x16x32_bf16 v[44:47], v[150:153], v[200:203], v[44:47]
	v_mfma_f32_16x16x32_bf16 v[40:43], v[166:169], v[200:203], v[40:43]
	v_mfma_f32_16x16x32_bf16 v[28:31], v[150:153], v[208:211], v[28:31]
	v_mfma_f32_16x16x32_bf16 v[24:27], v[166:169], v[208:211], v[24:27]
	v_mfma_f32_16x16x32_bf16 v[12:15], v[150:153], v[216:219], v[12:15]
	v_mfma_f32_16x16x32_bf16 v[8:11], v[166:169], v[216:219], v[8:11]
	v_mfma_f32_16x16x32_bf16 v[60:63], v[162:165], v[196:199], v[60:63]
	v_mfma_f32_16x16x32_bf16 v[56:59], v[170:173], v[196:199], v[56:59]
	v_mfma_f32_16x16x32_bf16 v[44:47], v[162:165], v[204:207], v[44:47]
	v_mfma_f32_16x16x32_bf16 v[40:43], v[170:173], v[204:207], v[40:43]
	v_mfma_f32_16x16x32_bf16 v[28:31], v[162:165], v[212:215], v[28:31]
	v_mfma_f32_16x16x32_bf16 v[24:27], v[170:173], v[212:215], v[24:27]
	v_mfma_f32_16x16x32_bf16 v[12:15], v[162:165], v[220:223], v[12:15]
	v_mfma_f32_16x16x32_bf16 v[8:11], v[170:173], v[220:223], v[8:11]
	v_mfma_f32_16x16x32_bf16 v[52:55], v[174:177], v[190:193], v[52:55]
	v_mfma_f32_16x16x32_bf16 v[48:51], v[182:185], v[190:193], v[48:51]
	v_mfma_f32_16x16x32_bf16 v[36:39], v[174:177], v[200:203], v[36:39]
	v_mfma_f32_16x16x32_bf16 v[32:35], v[182:185], v[200:203], v[32:35]
	v_mfma_f32_16x16x32_bf16 v[20:23], v[174:177], v[208:211], v[20:23]
	v_mfma_f32_16x16x32_bf16 v[16:19], v[182:185], v[208:211], v[16:19]
	v_mfma_f32_16x16x32_bf16 v[4:7], v[174:177], v[216:219], v[4:7]
	v_mfma_f32_16x16x32_bf16 v[0:3], v[182:185], v[216:219], v[0:3]
	v_mfma_f32_16x16x32_bf16 v[52:55], v[178:181], v[196:199], v[52:55]
	v_mfma_f32_16x16x32_bf16 v[48:51], v[186:189], v[196:199], v[48:51]
	v_mfma_f32_16x16x32_bf16 v[36:39], v[178:181], v[204:207], v[36:39]
	v_mfma_f32_16x16x32_bf16 v[32:35], v[186:189], v[204:207], v[32:35]
	v_mfma_f32_16x16x32_bf16 v[20:23], v[178:181], v[212:215], v[20:23]
	v_mfma_f32_16x16x32_bf16 v[16:19], v[186:189], v[212:215], v[16:19]
	v_mfma_f32_16x16x32_bf16 v[4:7], v[178:181], v[220:223], v[4:7]
	v_mfma_f32_16x16x32_bf16 v[0:3], v[186:189], v[220:223], v[0:3]
	s_setprio 0
	s_barrier
	s_add_u32 s50, s50, 0x100
	s_addc_u32 s51, s51, 0
	s_add_u32 s78, s78, 0x100
	s_addc_u32 s79, s79, 0
	s_cmp_ge_i32 s80, s76
	s_mov_b32 s48, s80
	s_cbranch_scc0 .Lkt_T_17
	s_nop 7
